# second task of a decode pair reuses the first one's page-table entry (no dependent load, no vmcnt(0) drain at its start)
# baseline (speedup 1.0000x reference)
; __device__ __forceinline__ float bf2f(bf16_t b) { return __uint_as_float(((unsigned)b) << 16); }
; template <int NB>
; __device__ __forceinline__ void sb_decode_task(const Params& P, float* lds, int task) {
;     const int tid = threadIdx.x, lane = tid & 63, wave = tid >> 6;
;     const bf16_t* qb = (const bf16_t*)(P.ws + WS_QB);
;     float* dpart = (float*)(P.ws + WS_DPART); float* dl = (float*)(P.ws + WS_DL);
;     float* zl = lds + DEC_LDS_OFF / 4 + wave * 256; float* wl = zl + 128;
;     const int c = lane & 15, g = lane >> 4;
;     constexpr int NBT = 32 / NB;
;     const int h = task % SH, bj = task / SH, b = bj / NPAGES;
;     const int page = P.page_table[bj];
;     const float* Kp = P.cache_k + ((size_t)page * PAGE * SH + h) * HD + 4 * c;
;     const float* Vp = P.cache_v + ((size_t)page * PAGE * SH + h) * HD + 4 * c;
;     const bf16_t* qp = qb + (size_t)(NTOK + b) * SBW + h * 64 + 4 * c;
;     const float q0 = bf2f(qp[0]), q1 = bf2f(qp[1]), q2 = bf2f(qp[2]), q3 = bf2f(qp[3]);
;     const float bias = P.sb_bias[h] * LOG2E;
;     float4 cur[NB], nx[NB];
; #pragma unroll
;     for (int i = 0; i < NB; ++i) cur[i] = *(const float4*)(Kp + (size_t)(4 * i + g) * (SH * HD));
; #pragma unroll
;     for (int kb = 0; kb < NBT; ++kb) {
;         const float* np = (kb + 1 < NBT) ? Kp + (size_t)(4 * NB * (kb + 1)) * (SH * HD) : Vp;
; #pragma unroll
;         for (int i = 0; i < NB; ++i) nx[i] = *(const float4*)(np + (size_t)(4 * i + g) * (SH * HD));
; #pragma unroll
;         for (int i = 0; i < NB; ++i) { const int s = 4 * NB * kb + 4 * i + g;
;             float part = q0 * cur[i].x + q1 * cur[i].y + q2 * cur[i].z + q3 * cur[i].w; part = sum16(part);
;             if (c == 0) zl[s] = part + bias; }
.LBB0_956:
	s_or_b64 exec, exec, s[0:1]
	v_readlane_b32 s36, v252, 48
	v_readlane_b32 s37, v252, 49
	s_mul_hi_i32 s1, s34, 0x2aaaaaab
	s_load_dwordx16 s[56:71], s[36:37], 0x0
	s_lshr_b32 s3, s1, 31
	s_add_i32 s0, s1, s3
	s_ashr_i32 s1, s1, 7
	s_mul_i32 s2, s0, 6
	s_add_i32 s33, s1, s3
	s_ashr_i32 s1, s0, 31
	s_sub_i32 s2, s34, s2
	s_lshl_b64 s[0:1], s[0:1], 2
	s_waitcnt lgkmcnt(0)
	s_add_u32 s0, s66, s0
	s_addc_u32 s1, s67, s1
	global_load_dword v2, v83, s[0:1]
	s_add_i32 s0, s33, 0x4000
	s_ashr_i32 s3, s2, 31
	s_mul_hi_i32 s1, s0, 0x300
	s_mulk_i32 s0, 0x300
	s_add_u32 s33, s38, s0
	s_addc_u32 s35, s39, s1
	s_lshl_b32 s0, s2, 6
	s_ashr_i32 s1, s0, 31
	s_lshl_b64 s[0:1], s[0:1], 1
	s_add_u32 s0, s33, s0
	s_addc_u32 s1, s35, s1
	v_readlane_b32 s56, v252, 16
	v_readlane_b32 s57, v252, 17
	v_readlane_b32 s64, v252, 24
	v_readlane_b32 s65, v252, 25
	s_mov_b64 s[56:57], s[64:65]
	v_mov_b32_e32 v91, v83
	v_readlane_b32 s58, v252, 18
	v_readlane_b32 s59, v252, 19
	v_readlane_b32 s60, v252, 20
	v_readlane_b32 s61, v252, 21
	v_readlane_b32 s62, v252, 22
	v_readlane_b32 s63, v252, 23
	v_readlane_b32 s66, v252, 26
	v_readlane_b32 s67, v252, 27
	v_readlane_b32 s68, v252, 28
	v_readlane_b32 s69, v252, 29
	v_readlane_b32 s70, v252, 30
	v_readlane_b32 s71, v252, 31
	s_waitcnt vmcnt(0)
	v_mov_b32_e32 v253, v2
	v_mul_hi_i32 v3, v2, s42
	v_mul_lo_u32 v2, v2, s42
	v_lshl_add_u64 v[92:93], v[2:3], 0, s[2:3]
	v_lshlrev_b64 v[2:3], 8, v[92:93]
	v_lshl_add_u64 v[66:67], v[84:85], 0, v[2:3]
	global_load_dwordx2 v[2:3], v99, s[0:1]
	s_lshl_b64 s[0:1], s[2:3], 2
	s_add_u32 s0, s56, s0
	s_addc_u32 s1, s57, s1
	global_load_dword v22, v83, s[0:1]
	v_lshl_add_u64 v[18:19], v[66:67], 0, v[82:83]
	v_lshl_add_u64 v[20:21], v[66:67], 0, v[90:91]
	global_load_dwordx4 v[14:17], v[18:19], off
	global_load_dwordx4 v[62:65], v[20:21], off
	s_waitcnt vmcnt(3)
	v_lshlrev_b32_e32 v105, 16, v2
	v_and_b32_e32 v107, 0xffff0000, v2
	v_add_co_u32_e32 v2, vcc, s44, v18
	v_lshlrev_b32_e32 v106, 16, v3
	v_and_b32_e32 v104, 0xffff0000, v3
	v_addc_co_u32_e32 v3, vcc, 0, v19, vcc
	global_load_dwordx4 v[10:13], v[2:3], off offset:2048
	v_add_co_u32_e32 v2, vcc, s45, v18
	s_waitcnt vmcnt(3)
	v_mul_f32_e32 v108, 0x3fb8aa3b, v22
	v_addc_co_u32_e32 v3, vcc, 0, v19, vcc
	global_load_dwordx4 v[6:9], v[2:3], off
	v_add_co_u32_e32 v2, vcc, s43, v18
	v_lshl_add_u64 v[22:23], v[66:67], 0, s[26:27]
	s_nop 0
	v_addc_co_u32_e32 v3, vcc, 0, v19, vcc
	v_add_co_u32_e32 v20, vcc, s46, v18
	v_lshl_add_u64 v[30:31], v[22:23], 0, v[82:83]
	s_nop 0
	v_addc_co_u32_e32 v21, vcc, 0, v19, vcc
	global_load_dwordx4 v[58:61], v[20:21], off offset:2048
	v_add_co_u32_e32 v20, vcc, s47, v18
	v_lshl_add_u64 v[22:23], v[22:23], 0, v[90:91]
	s_nop 0
	v_addc_co_u32_e32 v21, vcc, 0, v19, vcc
	v_add_co_u32_e32 v18, vcc, s48, v18
	global_load_dwordx4 v[54:57], v[20:21], off
	s_nop 0
	v_addc_co_u32_e32 v19, vcc, 0, v19, vcc
	global_load_dwordx4 v[50:53], v[18:19], off offset:2048
	v_add_co_u32_e32 v18, vcc, s44, v30
	global_load_dwordx4 v[22:25], v[22:23], off
	s_nop 0
	v_addc_co_u32_e32 v19, vcc, 0, v31, vcc
	global_load_dwordx4 v[34:37], v[18:19], off offset:2048
	v_add_co_u32_e32 v18, vcc, s45, v30
	global_load_dwordx4 v[2:5], v[2:3], off offset:2048
	s_nop 0
	v_addc_co_u32_e32 v19, vcc, 0, v31, vcc
	global_load_dwordx4 v[26:29], v[18:19], off
	v_add_co_u32_e32 v18, vcc, s43, v30
	global_load_dwordx4 v[46:49], v[30:31], off
	s_nop 0
	v_addc_co_u32_e32 v19, vcc, 0, v31, vcc
	v_add_co_u32_e32 v32, vcc, s46, v30
	global_load_dwordx4 v[18:21], v[18:19], off offset:2048
	s_nop 0
	v_addc_co_u32_e32 v33, vcc, 0, v31, vcc
	global_load_dwordx4 v[38:41], v[32:33], off offset:2048
	v_add_co_u32_e32 v32, vcc, s47, v30
	s_waitcnt vmcnt(13)
	v_mul_f32_e32 v15, v15, v107
	v_addc_co_u32_e32 v33, vcc, 0, v31, vcc
	v_add_co_u32_e32 v30, vcc, s48, v30
	global_load_dwordx4 v[42:45], v[32:33], off
	s_nop 0
	v_addc_co_u32_e32 v31, vcc, 0, v31, vcc
	global_load_dwordx4 v[30:33], v[30:31], off offset:2048
	v_fmac_f32_e32 v15, v14, v105
	v_fmac_f32_e32 v15, v16, v106
	v_fmac_f32_e32 v15, v17, v104
	s_nop 1
	v_add_f32_dpp v14, v15, v15 quad_perm:[1,0,3,2] row_mask:0xf bank_mask:0xf bound_ctrl:1
	s_nop 1
	v_add_f32_dpp v14, v14, v14 quad_perm:[2,3,0,1] row_mask:0xf bank_mask:0xf bound_ctrl:1
	s_nop 1
	v_add_f32_dpp v14, v14, v14 row_ror:4 row_mask:0xf bank_mask:0xf bound_ctrl:1
	s_nop 1
	v_mov_b32_dpp v15, v14 row_ror:8 row_mask:0xf bank_mask:0xf bound_ctrl:1
	s_and_saveexec_b64 s[0:1], s[6:7]
	v_add_f32_e32 v14, v14, v15
	v_add_f32_e32 v14, v108, v14
	ds_write_b32 v96, v14
	s_or_b64 exec, exec, s[0:1]
	s_waitcnt vmcnt(13)
	v_mul_f32_e32 v11, v11, v107
	v_fmac_f32_e32 v11, v10, v105
	v_fmac_f32_e32 v11, v12, v106
	v_fmac_f32_e32 v11, v13, v104
	s_nop 1
	v_add_f32_dpp v10, v11, v11 quad_perm:[1,0,3,2] row_mask:0xf bank_mask:0xf bound_ctrl:1
	s_nop 1
	v_add_f32_dpp v10, v10, v10 quad_perm:[2,3,0,1] row_mask:0xf bank_mask:0xf bound_ctrl:1
	s_nop 1
	v_add_f32_dpp v10, v10, v10 row_ror:4 row_mask:0xf bank_mask:0xf bound_ctrl:1
	s_nop 1
	v_mov_b32_dpp v11, v10 row_ror:8 row_mask:0xf bank_mask:0xf bound_ctrl:1
	s_and_saveexec_b64 s[0:1], s[6:7]
	v_add_f32_e32 v10, v10, v11
	v_add_f32_e32 v10, v108, v10
	ds_write_b32 v96, v10 offset:16
	s_or_b64 exec, exec, s[0:1]
	s_waitcnt vmcnt(12)
	v_mul_f32_e32 v7, v7, v107
	v_fmac_f32_e32 v7, v6, v105
	v_fmac_f32_e32 v7, v8, v106
	v_fmac_f32_e32 v7, v9, v104
	s_nop 1
	v_add_f32_dpp v6, v7, v7 quad_perm:[1,0,3,2] row_mask:0xf bank_mask:0xf bound_ctrl:1
	s_nop 1
	v_add_f32_dpp v6, v6, v6 quad_perm:[2,3,0,1] row_mask:0xf bank_mask:0xf bound_ctrl:1
	s_nop 1
	v_add_f32_dpp v6, v6, v6 row_ror:4 row_mask:0xf bank_mask:0xf bound_ctrl:1
	s_nop 1
	v_mov_b32_dpp v7, v6 row_ror:8 row_mask:0xf bank_mask:0xf bound_ctrl:1
	s_and_saveexec_b64 s[0:1], s[6:7]
	v_add_f32_e32 v6, v6, v7
	v_add_f32_e32 v6, v108, v6
	ds_write_b32 v96, v6 offset:32
	s_or_b64 exec, exec, s[0:1]
	s_waitcnt vmcnt(6)
; template <int NB>
; __device__ __forceinline__ void sb_decode_task(const Params& P, float* lds, int task) {
;     ...
;     for (int i = 0; i < NB; ++i) cur[i] = *(const float4*)(Kp + (size_t)(4 * i + g) * (SH * HD));
; #pragma unroll
;     for (int kb = 0; kb < NBT; ++kb) {
;         const float* np = (kb + 1 < NBT) ? Kp + (size_t)(4 * NB * (kb + 1)) * (SH * HD) : Vp;
; #pragma unroll
;         for (int i = 0; i < NB; ++i) nx[i] = *(const float4*)(np + (size_t)(4 * i + g) * (SH * HD));
; #pragma unroll
;         for (int i = 0; i < NB; ++i) { const int s = 4 * NB * kb + 4 * i + g;
;             float part = q0 * cur[i].x + q1 * cur[i].y + q2 * cur[i].z + q3 * cur[i].w; part = sum16(part);
;             if (c == 0) zl[s] = part + bias; }
	v_mul_f32_e32 v3, v3, v107
	v_fmac_f32_e32 v3, v2, v105
	v_fmac_f32_e32 v3, v4, v106
	v_fmac_f32_e32 v3, v5, v104
	s_nop 1
	v_add_f32_dpp v2, v3, v3 quad_perm:[1,0,3,2] row_mask:0xf bank_mask:0xf bound_ctrl:1
	s_nop 1
	v_add_f32_dpp v2, v2, v2 quad_perm:[2,3,0,1] row_mask:0xf bank_mask:0xf bound_ctrl:1
	s_nop 1
	v_add_f32_dpp v2, v2, v2 row_ror:4 row_mask:0xf bank_mask:0xf bound_ctrl:1
	s_nop 1
	v_mov_b32_dpp v3, v2 row_ror:8 row_mask:0xf bank_mask:0xf bound_ctrl:1
	s_and_saveexec_b64 s[0:1], s[6:7]
	v_add_f32_e32 v2, v2, v3
	v_add_f32_e32 v2, v108, v2
	ds_write_b32 v96, v2 offset:48
	s_or_b64 exec, exec, s[0:1]
	v_mul_f32_e32 v2, v63, v107
	v_fmac_f32_e32 v2, v62, v105
	v_fmac_f32_e32 v2, v64, v106
	v_fmac_f32_e32 v2, v65, v104
	s_nop 1
	v_add_f32_dpp v2, v2, v2 quad_perm:[1,0,3,2] row_mask:0xf bank_mask:0xf bound_ctrl:1
	s_nop 1
	v_add_f32_dpp v2, v2, v2 quad_perm:[2,3,0,1] row_mask:0xf bank_mask:0xf bound_ctrl:1
	s_nop 1
	v_add_f32_dpp v2, v2, v2 row_ror:4 row_mask:0xf bank_mask:0xf bound_ctrl:1
	s_nop 1
	v_mov_b32_dpp v3, v2 row_ror:8 row_mask:0xf bank_mask:0xf bound_ctrl:1
	s_and_saveexec_b64 s[0:1], s[6:7]
	v_add_f32_e32 v2, v2, v3
	v_add_f32_e32 v2, v108, v2
	ds_write_b32 v96, v2 offset:64
	s_or_b64 exec, exec, s[0:1]
	v_mul_f32_e32 v2, v59, v107
	v_fmac_f32_e32 v2, v58, v105
	v_fmac_f32_e32 v2, v60, v106
	v_fmac_f32_e32 v2, v61, v104
	s_nop 1
	v_add_f32_dpp v2, v2, v2 quad_perm:[1,0,3,2] row_mask:0xf bank_mask:0xf bound_ctrl:1
	s_nop 1
	v_add_f32_dpp v2, v2, v2 quad_perm:[2,3,0,1] row_mask:0xf bank_mask:0xf bound_ctrl:1
	s_nop 1
	v_add_f32_dpp v2, v2, v2 row_ror:4 row_mask:0xf bank_mask:0xf bound_ctrl:1
	s_nop 1
	v_mov_b32_dpp v3, v2 row_ror:8 row_mask:0xf bank_mask:0xf bound_ctrl:1
	s_and_saveexec_b64 s[0:1], s[6:7]
	v_add_f32_e32 v2, v2, v3
	v_add_f32_e32 v2, v108, v2
	ds_write_b32 v96, v2 offset:80
	s_or_b64 exec, exec, s[0:1]
	v_mul_f32_e32 v2, v55, v107
	v_fmac_f32_e32 v2, v54, v105
	v_fmac_f32_e32 v2, v56, v106
	v_fmac_f32_e32 v2, v57, v104
	s_nop 1
	v_add_f32_dpp v2, v2, v2 quad_perm:[1,0,3,2] row_mask:0xf bank_mask:0xf bound_ctrl:1
	s_nop 1
	v_add_f32_dpp v2, v2, v2 quad_perm:[2,3,0,1] row_mask:0xf bank_mask:0xf bound_ctrl:1
	s_nop 1
	v_add_f32_dpp v2, v2, v2 row_ror:4 row_mask:0xf bank_mask:0xf bound_ctrl:1
	s_nop 1
	v_mov_b32_dpp v3, v2 row_ror:8 row_mask:0xf bank_mask:0xf bound_ctrl:1
	s_and_saveexec_b64 s[0:1], s[6:7]
	v_add_f32_e32 v2, v2, v3
	v_add_f32_e32 v2, v108, v2
	ds_write_b32 v96, v2 offset:96
	s_or_b64 exec, exec, s[0:1]
	v_mul_f32_e32 v2, v51, v107
	v_fmac_f32_e32 v2, v50, v105
	v_fmac_f32_e32 v2, v52, v106
	v_fmac_f32_e32 v2, v53, v104
	s_nop 1
	v_add_f32_dpp v2, v2, v2 quad_perm:[1,0,3,2] row_mask:0xf bank_mask:0xf bound_ctrl:1
	s_nop 1
	v_add_f32_dpp v2, v2, v2 quad_perm:[2,3,0,1] row_mask:0xf bank_mask:0xf bound_ctrl:1
	s_nop 1
	v_add_f32_dpp v2, v2, v2 row_ror:4 row_mask:0xf bank_mask:0xf bound_ctrl:1
	s_nop 1
	v_mov_b32_dpp v3, v2 row_ror:8 row_mask:0xf bank_mask:0xf bound_ctrl:1
	s_and_saveexec_b64 s[0:1], s[6:7]
	v_add_f32_e32 v2, v2, v3
	v_add_f32_e32 v2, v108, v2
	ds_write_b32 v96, v2 offset:112
	s_or_b64 exec, exec, s[0:1]
	v_lshl_add_u64 v[2:3], v[66:67], 0, s[28:29]
	v_lshl_add_u64 v[4:5], v[2:3], 0, v[82:83]
	v_add_co_u32_e32 v6, vcc, 0x1000, v4
	v_mov_b32_e32 v91, v83
	s_nop 0
	v_addc_co_u32_e32 v7, vcc, 0, v5, vcc
	global_load_dwordx4 v[78:81], v[4:5], off
	global_load_dwordx4 v[70:73], v[6:7], off offset:2048
	v_add_co_u32_e32 v6, vcc, 0x3000, v4
	v_lshl_add_u64 v[2:3], v[2:3], 0, v[90:91]
	s_nop 0
	v_addc_co_u32_e32 v7, vcc, 0, v5, vcc
	v_add_co_u32_e32 v8, vcc, s43, v4
	s_waitcnt vmcnt(6)
	v_mul_f32_e32 v47, v47, v107
	v_addc_co_u32_e32 v9, vcc, 0, v5, vcc
	global_load_dwordx4 v[62:65], v[6:7], off
	global_load_dwordx4 v[54:57], v[8:9], off offset:2048
	v_add_co_u32_e32 v6, vcc, 0x7000, v4
	v_fmac_f32_e32 v47, v46, v105
	s_nop 0
	v_addc_co_u32_e32 v7, vcc, 0, v5, vcc
	global_load_dwordx4 v[14:17], v[2:3], off
	global_load_dwordx4 v[10:13], v[6:7], off offset:2048
	v_add_co_u32_e32 v2, vcc, 0x9000, v4
	v_fmac_f32_e32 v47, v48, v106
	s_nop 0
	v_addc_co_u32_e32 v3, vcc, 0, v5, vcc
	v_add_co_u32_e32 v4, vcc, 0xa000, v4
	v_fmac_f32_e32 v47, v49, v104
	s_nop 0
	v_addc_co_u32_e32 v5, vcc, 0, v5, vcc
	global_load_dwordx4 v[6:9], v[2:3], off
	s_nop 0
	global_load_dwordx4 v[2:5], v[4:5], off offset:2048
	v_add_f32_dpp v46, v47, v47 quad_perm:[1,0,3,2] row_mask:0xf bank_mask:0xf bound_ctrl:1
	s_nop 1
	v_add_f32_dpp v46, v46, v46 quad_perm:[2,3,0,1] row_mask:0xf bank_mask:0xf bound_ctrl:1
	s_nop 1
	v_add_f32_dpp v46, v46, v46 row_ror:4 row_mask:0xf bank_mask:0xf bound_ctrl:1
	s_nop 1
	v_mov_b32_dpp v47, v46 row_ror:8 row_mask:0xf bank_mask:0xf bound_ctrl:1
	s_and_saveexec_b64 s[0:1], s[6:7]
	v_add_f32_e32 v46, v46, v47
	v_add_f32_e32 v46, v108, v46
	ds_write_b32 v96, v46 offset:128
	s_or_b64 exec, exec, s[0:1]
	v_mul_f32_e32 v35, v35, v107
	v_fmac_f32_e32 v35, v34, v105
	v_fmac_f32_e32 v35, v36, v106
	v_fmac_f32_e32 v35, v37, v104
	s_nop 1
	v_add_f32_dpp v34, v35, v35 quad_perm:[1,0,3,2] row_mask:0xf bank_mask:0xf bound_ctrl:1
	s_nop 1
	v_add_f32_dpp v34, v34, v34 quad_perm:[2,3,0,1] row_mask:0xf bank_mask:0xf bound_ctrl:1
	s_nop 1
	v_add_f32_dpp v34, v34, v34 row_ror:4 row_mask:0xf bank_mask:0xf bound_ctrl:1
	s_nop 1
	v_mov_b32_dpp v35, v34 row_ror:8 row_mask:0xf bank_mask:0xf bound_ctrl:1
	s_and_saveexec_b64 s[0:1], s[6:7]
	v_add_f32_e32 v34, v34, v35
	v_add_f32_e32 v34, v108, v34
	ds_write_b32 v96, v34 offset:144
	s_or_b64 exec, exec, s[0:1]
	v_mul_f32_e32 v27, v27, v107
	v_fmac_f32_e32 v27, v26, v105
	v_fmac_f32_e32 v27, v28, v106
	v_fmac_f32_e32 v27, v29, v104
	s_nop 1
	v_add_f32_dpp v26, v27, v27 quad_perm:[1,0,3,2] row_mask:0xf bank_mask:0xf bound_ctrl:1
	s_nop 1
	v_add_f32_dpp v26, v26, v26 quad_perm:[2,3,0,1] row_mask:0xf bank_mask:0xf bound_ctrl:1
	s_nop 1
	v_add_f32_dpp v26, v26, v26 row_ror:4 row_mask:0xf bank_mask:0xf bound_ctrl:1
	s_nop 1
	v_mov_b32_dpp v27, v26 row_ror:8 row_mask:0xf bank_mask:0xf bound_ctrl:1
	s_and_saveexec_b64 s[0:1], s[6:7]
	v_add_f32_e32 v26, v26, v27
	v_add_f32_e32 v26, v108, v26
	ds_write_b32 v96, v26 offset:160
	s_or_b64 exec, exec, s[0:1]
	s_waitcnt vmcnt(11)
; template <int NB>
; __device__ __forceinline__ void sb_decode_task(const Params& P, float* lds, int task) {
;     ...
;     for (int i = 0; i < NB; ++i) cur[i] = *(const float4*)(Kp + (size_t)(4 * i + g) * (SH * HD));
; #pragma unroll
;     for (int kb = 0; kb < NBT; ++kb) {
;         const float* np = (kb + 1 < NBT) ? Kp + (size_t)(4 * NB * (kb + 1)) * (SH * HD) : Vp;
; #pragma unroll
;         for (int i = 0; i < NB; ++i) nx[i] = *(const float4*)(np + (size_t)(4 * i + g) * (SH * HD));
; #pragma unroll
;         for (int i = 0; i < NB; ++i) { const int s = 4 * NB * kb + 4 * i + g;
;             float part = q0 * cur[i].x + q1 * cur[i].y + q2 * cur[i].z + q3 * cur[i].w; part = sum16(part);
;             if (c == 0) zl[s] = part + bias; }
	v_mul_f32_e32 v19, v19, v107
	v_fmac_f32_e32 v19, v18, v105
	v_fmac_f32_e32 v19, v20, v106
	v_fmac_f32_e32 v19, v21, v104
	s_nop 1
	v_add_f32_dpp v18, v19, v19 quad_perm:[1,0,3,2] row_mask:0xf bank_mask:0xf bound_ctrl:1
	s_nop 1
	v_add_f32_dpp v18, v18, v18 quad_perm:[2,3,0,1] row_mask:0xf bank_mask:0xf bound_ctrl:1
	s_nop 1
	v_add_f32_dpp v18, v18, v18 row_ror:4 row_mask:0xf bank_mask:0xf bound_ctrl:1
	s_nop 1
	v_mov_b32_dpp v19, v18 row_ror:8 row_mask:0xf bank_mask:0xf bound_ctrl:1
	s_and_saveexec_b64 s[0:1], s[6:7]
	v_add_f32_e32 v18, v18, v19
	v_add_f32_e32 v18, v108, v18
	ds_write_b32 v96, v18 offset:176
	s_or_b64 exec, exec, s[0:1]
	v_mul_f32_e32 v18, v23, v107
	v_fmac_f32_e32 v18, v22, v105
	v_fmac_f32_e32 v18, v24, v106
	v_fmac_f32_e32 v18, v25, v104
	s_nop 1
	v_add_f32_dpp v18, v18, v18 quad_perm:[1,0,3,2] row_mask:0xf bank_mask:0xf bound_ctrl:1
	s_nop 1
	v_add_f32_dpp v18, v18, v18 quad_perm:[2,3,0,1] row_mask:0xf bank_mask:0xf bound_ctrl:1
	s_nop 1
	v_add_f32_dpp v18, v18, v18 row_ror:4 row_mask:0xf bank_mask:0xf bound_ctrl:1
	s_nop 1
	v_mov_b32_dpp v19, v18 row_ror:8 row_mask:0xf bank_mask:0xf bound_ctrl:1
	s_and_saveexec_b64 s[0:1], s[6:7]
	v_add_f32_e32 v18, v18, v19
	v_add_f32_e32 v18, v108, v18
	ds_write_b32 v96, v18 offset:192
	s_or_b64 exec, exec, s[0:1]
	s_waitcnt vmcnt(10)
	v_mul_f32_e32 v18, v39, v107
	v_fmac_f32_e32 v18, v38, v105
	v_fmac_f32_e32 v18, v40, v106
	v_fmac_f32_e32 v18, v41, v104
	s_nop 1
	v_add_f32_dpp v18, v18, v18 quad_perm:[1,0,3,2] row_mask:0xf bank_mask:0xf bound_ctrl:1
	s_nop 1
	v_add_f32_dpp v18, v18, v18 quad_perm:[2,3,0,1] row_mask:0xf bank_mask:0xf bound_ctrl:1
	s_nop 1
	v_add_f32_dpp v18, v18, v18 row_ror:4 row_mask:0xf bank_mask:0xf bound_ctrl:1
	s_nop 1
	v_mov_b32_dpp v19, v18 row_ror:8 row_mask:0xf bank_mask:0xf bound_ctrl:1
	s_and_saveexec_b64 s[0:1], s[6:7]
	v_add_f32_e32 v18, v18, v19
	v_add_f32_e32 v18, v108, v18
	ds_write_b32 v96, v18 offset:208
	s_or_b64 exec, exec, s[0:1]
	s_waitcnt vmcnt(9)
	v_mul_f32_e32 v18, v43, v107
	v_fmac_f32_e32 v18, v42, v105
	v_fmac_f32_e32 v18, v44, v106
	v_fmac_f32_e32 v18, v45, v104
	s_nop 1
	v_add_f32_dpp v18, v18, v18 quad_perm:[1,0,3,2] row_mask:0xf bank_mask:0xf bound_ctrl:1
	s_nop 1
	v_add_f32_dpp v18, v18, v18 quad_perm:[2,3,0,1] row_mask:0xf bank_mask:0xf bound_ctrl:1
	s_nop 1
	v_add_f32_dpp v18, v18, v18 row_ror:4 row_mask:0xf bank_mask:0xf bound_ctrl:1
	s_nop 1
	v_mov_b32_dpp v19, v18 row_ror:8 row_mask:0xf bank_mask:0xf bound_ctrl:1
	s_and_saveexec_b64 s[0:1], s[6:7]
	v_add_f32_e32 v18, v18, v19
	v_add_f32_e32 v18, v108, v18
	ds_write_b32 v96, v18 offset:224
	s_or_b64 exec, exec, s[0:1]
	s_waitcnt vmcnt(8)
	v_mul_f32_e32 v18, v31, v107
	v_fmac_f32_e32 v18, v30, v105
	v_fmac_f32_e32 v18, v32, v106
	v_fmac_f32_e32 v18, v33, v104
	s_nop 1
	v_add_f32_dpp v18, v18, v18 quad_perm:[1,0,3,2] row_mask:0xf bank_mask:0xf bound_ctrl:1
	s_nop 1
	v_add_f32_dpp v18, v18, v18 quad_perm:[2,3,0,1] row_mask:0xf bank_mask:0xf bound_ctrl:1
	s_nop 1
	v_add_f32_dpp v18, v18, v18 row_ror:4 row_mask:0xf bank_mask:0xf bound_ctrl:1
	s_nop 1
	v_mov_b32_dpp v19, v18 row_ror:8 row_mask:0xf bank_mask:0xf bound_ctrl:1
	s_and_saveexec_b64 s[0:1], s[6:7]
	v_add_f32_e32 v18, v18, v19
	v_add_f32_e32 v18, v108, v18
	ds_write_b32 v96, v18 offset:240
	s_or_b64 exec, exec, s[0:1]
	v_lshl_add_u64 v[18:19], v[66:67], 0, s[30:31]
	v_lshl_add_u64 v[20:21], v[18:19], 0, v[82:83]
	v_add_co_u32_e32 v22, vcc, 0x1000, v20
	v_mov_b32_e32 v91, v83
	s_nop 0
	v_addc_co_u32_e32 v23, vcc, 0, v21, vcc
	global_load_dwordx4 v[74:77], v[20:21], off
	global_load_dwordx4 v[66:69], v[22:23], off offset:2048
	v_add_co_u32_e32 v22, vcc, 0x3000, v20
	v_lshl_add_u64 v[18:19], v[18:19], 0, v[90:91]
	s_nop 0
	v_addc_co_u32_e32 v23, vcc, 0, v21, vcc
	v_add_co_u32_e32 v24, vcc, s43, v20
	s_nop 1
	v_addc_co_u32_e32 v25, vcc, 0, v21, vcc
	global_load_dwordx4 v[58:61], v[22:23], off
	global_load_dwordx4 v[50:53], v[24:25], off offset:2048
	v_add_co_u32_e32 v22, vcc, 0x7000, v20
	s_nop 1
	v_addc_co_u32_e32 v23, vcc, 0, v21, vcc
	global_load_dwordx4 v[46:49], v[18:19], off
	global_load_dwordx4 v[42:45], v[22:23], off offset:2048
	v_add_co_u32_e32 v18, vcc, 0x9000, v20
	s_nop 1
	v_addc_co_u32_e32 v19, vcc, 0, v21, vcc
	v_add_co_u32_e32 v20, vcc, 0xa000, v20
	s_nop 1
	v_addc_co_u32_e32 v21, vcc, 0, v21, vcc
	global_load_dwordx4 v[38:41], v[18:19], off
	global_load_dwordx4 v[34:37], v[20:21], off offset:2048
	s_waitcnt vmcnt(15)
	v_mul_f32_e32 v18, v79, v107
	v_fmac_f32_e32 v18, v78, v105
	v_fmac_f32_e32 v18, v80, v106
	v_fmac_f32_e32 v18, v81, v104
	s_nop 1
	v_add_f32_dpp v18, v18, v18 quad_perm:[1,0,3,2] row_mask:0xf bank_mask:0xf bound_ctrl:1
	s_nop 1
	v_add_f32_dpp v18, v18, v18 quad_perm:[2,3,0,1] row_mask:0xf bank_mask:0xf bound_ctrl:1
	s_nop 1
	v_add_f32_dpp v18, v18, v18 row_ror:4 row_mask:0xf bank_mask:0xf bound_ctrl:1
	s_nop 1
	v_mov_b32_dpp v19, v18 row_ror:8 row_mask:0xf bank_mask:0xf bound_ctrl:1
	s_and_saveexec_b64 s[0:1], s[6:7]
	v_add_f32_e32 v18, v18, v19
	v_add_f32_e32 v18, v108, v18
	ds_write_b32 v96, v18 offset:256
	s_or_b64 exec, exec, s[0:1]
	s_waitcnt vmcnt(14)
	v_mul_f32_e32 v18, v71, v107
	v_fmac_f32_e32 v18, v70, v105
	v_fmac_f32_e32 v18, v72, v106
	v_fmac_f32_e32 v18, v73, v104
	s_nop 1
	v_add_f32_dpp v18, v18, v18 quad_perm:[1,0,3,2] row_mask:0xf bank_mask:0xf bound_ctrl:1
	s_nop 1
	v_add_f32_dpp v18, v18, v18 quad_perm:[2,3,0,1] row_mask:0xf bank_mask:0xf bound_ctrl:1
	s_nop 1
	v_add_f32_dpp v18, v18, v18 row_ror:4 row_mask:0xf bank_mask:0xf bound_ctrl:1
	s_nop 1
	v_mov_b32_dpp v19, v18 row_ror:8 row_mask:0xf bank_mask:0xf bound_ctrl:1
	s_and_saveexec_b64 s[0:1], s[6:7]
	v_add_f32_e32 v18, v18, v19
	v_add_f32_e32 v18, v108, v18
	ds_write_b32 v96, v18 offset:272
	s_or_b64 exec, exec, s[0:1]
	s_waitcnt vmcnt(13)
; template <int NB>
; __device__ __forceinline__ void sb_decode_task(const Params& P, float* lds, int task) {
;     ...
;     for (int i = 0; i < NB; ++i) cur[i] = *(const float4*)(Kp + (size_t)(4 * i + g) * (SH * HD));
; #pragma unroll
;     for (int kb = 0; kb < NBT; ++kb) {
;         const float* np = (kb + 1 < NBT) ? Kp + (size_t)(4 * NB * (kb + 1)) * (SH * HD) : Vp;
; #pragma unroll
;         for (int i = 0; i < NB; ++i) nx[i] = *(const float4*)(np + (size_t)(4 * i + g) * (SH * HD));
; #pragma unroll
;         for (int i = 0; i < NB; ++i) { const int s = 4 * NB * kb + 4 * i + g;
;             float part = q0 * cur[i].x + q1 * cur[i].y + q2 * cur[i].z + q3 * cur[i].w; part = sum16(part);
;             if (c == 0) zl[s] = part + bias; }
;     ...
;     for (int vb = 0; vb < NBT; ++vb) {
;         if (vb + 1 < NBT) {
; #pragma unroll
;             for (int i = 0; i < NB; ++i) nx[i] = *(const float4*)(Vp + (size_t)(4 * NB * (vb + 1) + 4 * i + g) * (SH * HD)); }
	v_mul_f32_e32 v18, v63, v107
	v_fmac_f32_e32 v18, v62, v105
	v_fmac_f32_e32 v18, v64, v106
	v_fmac_f32_e32 v18, v65, v104
	s_nop 1
	v_add_f32_dpp v18, v18, v18 quad_perm:[1,0,3,2] row_mask:0xf bank_mask:0xf bound_ctrl:1
	s_nop 1
	v_add_f32_dpp v18, v18, v18 quad_perm:[2,3,0,1] row_mask:0xf bank_mask:0xf bound_ctrl:1
	s_nop 1
	v_add_f32_dpp v18, v18, v18 row_ror:4 row_mask:0xf bank_mask:0xf bound_ctrl:1
	s_nop 1
	v_mov_b32_dpp v19, v18 row_ror:8 row_mask:0xf bank_mask:0xf bound_ctrl:1
	s_and_saveexec_b64 s[0:1], s[6:7]
	v_add_f32_e32 v18, v18, v19
	v_add_f32_e32 v18, v108, v18
	ds_write_b32 v96, v18 offset:288
	s_or_b64 exec, exec, s[0:1]
	s_waitcnt vmcnt(12)
	v_mul_f32_e32 v18, v55, v107
	v_fmac_f32_e32 v18, v54, v105
	v_fmac_f32_e32 v18, v56, v106
	v_fmac_f32_e32 v18, v57, v104
	s_nop 1
	v_add_f32_dpp v18, v18, v18 quad_perm:[1,0,3,2] row_mask:0xf bank_mask:0xf bound_ctrl:1
	s_nop 1
	v_add_f32_dpp v18, v18, v18 quad_perm:[2,3,0,1] row_mask:0xf bank_mask:0xf bound_ctrl:1
	s_nop 1
	v_add_f32_dpp v18, v18, v18 row_ror:4 row_mask:0xf bank_mask:0xf bound_ctrl:1
	s_nop 1
	v_mov_b32_dpp v19, v18 row_ror:8 row_mask:0xf bank_mask:0xf bound_ctrl:1
	s_and_saveexec_b64 s[0:1], s[6:7]
	v_add_f32_e32 v18, v18, v19
	v_add_f32_e32 v18, v108, v18
	ds_write_b32 v96, v18 offset:304
	s_or_b64 exec, exec, s[0:1]
	s_waitcnt vmcnt(11)
	v_mul_f32_e32 v15, v15, v107
	v_fmac_f32_e32 v15, v14, v105
	v_fmac_f32_e32 v15, v16, v106
	v_fmac_f32_e32 v15, v17, v104
	s_nop 1
	v_add_f32_dpp v14, v15, v15 quad_perm:[1,0,3,2] row_mask:0xf bank_mask:0xf bound_ctrl:1
	s_nop 1
	v_add_f32_dpp v14, v14, v14 quad_perm:[2,3,0,1] row_mask:0xf bank_mask:0xf bound_ctrl:1
	s_nop 1
	v_add_f32_dpp v14, v14, v14 row_ror:4 row_mask:0xf bank_mask:0xf bound_ctrl:1
	s_nop 1
	v_mov_b32_dpp v15, v14 row_ror:8 row_mask:0xf bank_mask:0xf bound_ctrl:1
	s_and_saveexec_b64 s[0:1], s[6:7]
	v_add_f32_e32 v14, v14, v15
	v_add_f32_e32 v14, v108, v14
	ds_write_b32 v96, v14 offset:320
	s_or_b64 exec, exec, s[0:1]
	s_waitcnt vmcnt(10)
	v_mul_f32_e32 v11, v11, v107
	v_fmac_f32_e32 v11, v10, v105
	v_fmac_f32_e32 v11, v12, v106
	v_fmac_f32_e32 v11, v13, v104
	s_nop 1
	v_add_f32_dpp v10, v11, v11 quad_perm:[1,0,3,2] row_mask:0xf bank_mask:0xf bound_ctrl:1
	s_nop 1
	v_add_f32_dpp v10, v10, v10 quad_perm:[2,3,0,1] row_mask:0xf bank_mask:0xf bound_ctrl:1
	s_nop 1
	v_add_f32_dpp v10, v10, v10 row_ror:4 row_mask:0xf bank_mask:0xf bound_ctrl:1
	s_nop 1
	v_mov_b32_dpp v11, v10 row_ror:8 row_mask:0xf bank_mask:0xf bound_ctrl:1
	s_and_saveexec_b64 s[0:1], s[6:7]
	v_add_f32_e32 v10, v10, v11
	v_add_f32_e32 v10, v108, v10
	ds_write_b32 v96, v10 offset:336
	s_or_b64 exec, exec, s[0:1]
	s_waitcnt vmcnt(9)
	v_mul_f32_e32 v7, v7, v107
	v_fmac_f32_e32 v7, v6, v105
	v_fmac_f32_e32 v7, v8, v106
	v_fmac_f32_e32 v7, v9, v104
	s_nop 1
	v_add_f32_dpp v6, v7, v7 quad_perm:[1,0,3,2] row_mask:0xf bank_mask:0xf bound_ctrl:1
	s_nop 1
	v_add_f32_dpp v6, v6, v6 quad_perm:[2,3,0,1] row_mask:0xf bank_mask:0xf bound_ctrl:1
	s_nop 1
	v_add_f32_dpp v6, v6, v6 row_ror:4 row_mask:0xf bank_mask:0xf bound_ctrl:1
	s_nop 1
	v_mov_b32_dpp v7, v6 row_ror:8 row_mask:0xf bank_mask:0xf bound_ctrl:1
	s_and_saveexec_b64 s[0:1], s[6:7]
	v_add_f32_e32 v6, v6, v7
	v_add_f32_e32 v6, v108, v6
	ds_write_b32 v96, v6 offset:352
	s_or_b64 exec, exec, s[0:1]
	s_waitcnt vmcnt(8)
	v_mul_f32_e32 v3, v3, v107
	v_fmac_f32_e32 v3, v2, v105
	v_fmac_f32_e32 v3, v4, v106
	v_fmac_f32_e32 v3, v5, v104
	s_nop 1
	v_add_f32_dpp v2, v3, v3 quad_perm:[1,0,3,2] row_mask:0xf bank_mask:0xf bound_ctrl:1
	s_nop 1
	v_add_f32_dpp v2, v2, v2 quad_perm:[2,3,0,1] row_mask:0xf bank_mask:0xf bound_ctrl:1
	s_nop 1
	v_add_f32_dpp v2, v2, v2 row_ror:4 row_mask:0xf bank_mask:0xf bound_ctrl:1
	s_nop 1
	v_mov_b32_dpp v3, v2 row_ror:8 row_mask:0xf bank_mask:0xf bound_ctrl:1
	s_and_saveexec_b64 s[0:1], s[6:7]
	v_add_f32_e32 v2, v2, v3
	v_add_f32_e32 v2, v108, v2
	ds_write_b32 v96, v2 offset:368
	s_or_b64 exec, exec, s[0:1]
	v_lshlrev_b64 v[2:3], 6, v[92:93]
	v_lshl_add_u64 v[6:7], v[2:3], 2, v[86:87]
	v_lshl_add_u64 v[54:55], v[6:7], 0, v[82:83]
	v_add_co_u32_e32 v2, vcc, 0x1000, v54
	v_mov_b32_e32 v91, v83
	s_nop 0
	v_addc_co_u32_e32 v3, vcc, 0, v55, vcc
	v_add_co_u32_e32 v8, vcc, 0x3000, v54
	v_lshl_add_u64 v[10:11], v[6:7], 0, v[90:91]
	s_nop 0
	v_addc_co_u32_e32 v9, vcc, 0, v55, vcc
	v_add_co_u32_e32 v14, vcc, s43, v54
	global_load_dwordx4 v[30:33], v[54:55], off
	s_nop 0
	global_load_dwordx4 v[2:5], v[2:3], off offset:2048
	v_addc_co_u32_e32 v15, vcc, 0, v55, vcc
	v_add_co_u32_e32 v18, vcc, 0x7000, v54
	global_load_dwordx4 v[6:9], v[8:9], off
	s_nop 0
	global_load_dwordx4 v[10:13], v[10:11], off
	v_addc_co_u32_e32 v19, vcc, 0, v55, vcc
	v_add_co_u32_e32 v22, vcc, 0x9000, v54
	global_load_dwordx4 v[14:17], v[14:15], off offset:2048
	s_nop 0
	global_load_dwordx4 v[18:21], v[18:19], off offset:2048
	v_addc_co_u32_e32 v23, vcc, 0, v55, vcc
	v_add_co_u32_e32 v26, vcc, 0xa000, v54
	s_waitcnt vmcnt(13)
	v_mul_f32_e32 v56, v75, v107
	v_addc_co_u32_e32 v27, vcc, 0, v55, vcc
	global_load_dwordx4 v[22:25], v[22:23], off
	s_nop 0
	global_load_dwordx4 v[26:29], v[26:27], off offset:2048
	v_fmac_f32_e32 v56, v74, v105
	v_fmac_f32_e32 v56, v76, v106
	v_fmac_f32_e32 v56, v77, v104
	s_nop 1
	v_add_f32_dpp v56, v56, v56 quad_perm:[1,0,3,2] row_mask:0xf bank_mask:0xf bound_ctrl:1
	s_nop 1
	v_add_f32_dpp v56, v56, v56 quad_perm:[2,3,0,1] row_mask:0xf bank_mask:0xf bound_ctrl:1
	s_nop 1
	v_add_f32_dpp v56, v56, v56 row_ror:4 row_mask:0xf bank_mask:0xf bound_ctrl:1
	s_nop 1
	v_mov_b32_dpp v57, v56 row_ror:8 row_mask:0xf bank_mask:0xf bound_ctrl:1
	s_and_saveexec_b64 s[0:1], s[6:7]
	v_add_f32_e32 v56, v56, v57
	v_add_f32_e32 v56, v108, v56
	ds_write_b32 v96, v56 offset:384
	s_or_b64 exec, exec, s[0:1]
	s_waitcnt vmcnt(14)
; template <int NB>
; __device__ __forceinline__ void sb_decode_task(const Params& P, float* lds, int task) {
;     ...
;         for (int i = 0; i < NB; ++i) { const int s = 4 * NB * kb + 4 * i + g;
;             float part = q0 * cur[i].x + q1 * cur[i].y + q2 * cur[i].z + q3 * cur[i].w; part = sum16(part);
;             if (c == 0) zl[s] = part + bias; }
; #pragma unroll
;         for (int i = 0; i < NB; ++i) cur[i] = nx[i];
;     }
;     asm volatile("s_waitcnt lgkmcnt(0)" ::: "memory");
;     __builtin_amdgcn_wave_barrier();
;     const float z0 = zl[2 * lane], z1 = zl[2 * lane + 1];
	v_mul_f32_e32 v56, v67, v107
	v_fmac_f32_e32 v56, v66, v105
	v_fmac_f32_e32 v56, v68, v106
	v_fmac_f32_e32 v56, v69, v104
	s_nop 1
	v_add_f32_dpp v56, v56, v56 quad_perm:[1,0,3,2] row_mask:0xf bank_mask:0xf bound_ctrl:1
	s_nop 1
	v_add_f32_dpp v56, v56, v56 quad_perm:[2,3,0,1] row_mask:0xf bank_mask:0xf bound_ctrl:1
	s_nop 1
	v_add_f32_dpp v56, v56, v56 row_ror:4 row_mask:0xf bank_mask:0xf bound_ctrl:1
	s_nop 1
	v_mov_b32_dpp v57, v56 row_ror:8 row_mask:0xf bank_mask:0xf bound_ctrl:1
	s_and_saveexec_b64 s[0:1], s[6:7]
	v_add_f32_e32 v56, v56, v57
	v_add_f32_e32 v56, v108, v56
	ds_write_b32 v96, v56 offset:400
	s_or_b64 exec, exec, s[0:1]
	s_waitcnt vmcnt(13)
	v_mul_f32_e32 v56, v59, v107
	v_fmac_f32_e32 v56, v58, v105
	v_fmac_f32_e32 v56, v60, v106
	v_fmac_f32_e32 v56, v61, v104
	s_nop 1
	v_add_f32_dpp v56, v56, v56 quad_perm:[1,0,3,2] row_mask:0xf bank_mask:0xf bound_ctrl:1
	s_nop 1
	v_add_f32_dpp v56, v56, v56 quad_perm:[2,3,0,1] row_mask:0xf bank_mask:0xf bound_ctrl:1
	s_nop 1
	v_add_f32_dpp v56, v56, v56 row_ror:4 row_mask:0xf bank_mask:0xf bound_ctrl:1
	s_nop 1
	v_mov_b32_dpp v57, v56 row_ror:8 row_mask:0xf bank_mask:0xf bound_ctrl:1
	s_and_saveexec_b64 s[0:1], s[6:7]
	v_add_f32_e32 v56, v56, v57
	v_add_f32_e32 v56, v108, v56
	ds_write_b32 v96, v56 offset:416
	s_or_b64 exec, exec, s[0:1]
	s_waitcnt vmcnt(12)
	v_mul_f32_e32 v51, v51, v107
	v_fmac_f32_e32 v51, v50, v105
	v_fmac_f32_e32 v51, v52, v106
	v_fmac_f32_e32 v51, v53, v104
	s_nop 1
	v_add_f32_dpp v50, v51, v51 quad_perm:[1,0,3,2] row_mask:0xf bank_mask:0xf bound_ctrl:1
	s_nop 1
	v_add_f32_dpp v50, v50, v50 quad_perm:[2,3,0,1] row_mask:0xf bank_mask:0xf bound_ctrl:1
	s_nop 1
	v_add_f32_dpp v50, v50, v50 row_ror:4 row_mask:0xf bank_mask:0xf bound_ctrl:1
	s_nop 1
	v_mov_b32_dpp v51, v50 row_ror:8 row_mask:0xf bank_mask:0xf bound_ctrl:1
	s_and_saveexec_b64 s[0:1], s[6:7]
	v_add_f32_e32 v50, v50, v51
	v_add_f32_e32 v50, v108, v50
	ds_write_b32 v96, v50 offset:432
	s_or_b64 exec, exec, s[0:1]
	s_waitcnt vmcnt(11)
	v_mul_f32_e32 v47, v47, v107
	v_fmac_f32_e32 v47, v46, v105
	v_fmac_f32_e32 v47, v48, v106
	v_fmac_f32_e32 v47, v49, v104
	s_nop 1
	v_add_f32_dpp v46, v47, v47 quad_perm:[1,0,3,2] row_mask:0xf bank_mask:0xf bound_ctrl:1
	s_nop 1
	v_add_f32_dpp v46, v46, v46 quad_perm:[2,3,0,1] row_mask:0xf bank_mask:0xf bound_ctrl:1
	s_nop 1
	v_add_f32_dpp v46, v46, v46 row_ror:4 row_mask:0xf bank_mask:0xf bound_ctrl:1
	s_nop 1
	v_mov_b32_dpp v47, v46 row_ror:8 row_mask:0xf bank_mask:0xf bound_ctrl:1
	s_and_saveexec_b64 s[0:1], s[6:7]
	v_add_f32_e32 v46, v46, v47
	v_add_f32_e32 v46, v108, v46
	ds_write_b32 v96, v46 offset:448
	s_or_b64 exec, exec, s[0:1]
	s_waitcnt vmcnt(10)
	v_mul_f32_e32 v43, v43, v107
	v_fmac_f32_e32 v43, v42, v105
	v_fmac_f32_e32 v43, v44, v106
	v_fmac_f32_e32 v43, v45, v104
	s_nop 1
	v_add_f32_dpp v42, v43, v43 quad_perm:[1,0,3,2] row_mask:0xf bank_mask:0xf bound_ctrl:1
	s_nop 1
	v_add_f32_dpp v42, v42, v42 quad_perm:[2,3,0,1] row_mask:0xf bank_mask:0xf bound_ctrl:1
	s_nop 1
	v_add_f32_dpp v42, v42, v42 row_ror:4 row_mask:0xf bank_mask:0xf bound_ctrl:1
	s_nop 1
	v_mov_b32_dpp v43, v42 row_ror:8 row_mask:0xf bank_mask:0xf bound_ctrl:1
	s_and_saveexec_b64 s[0:1], s[6:7]
	v_add_f32_e32 v42, v42, v43
	v_add_f32_e32 v42, v108, v42
	ds_write_b32 v96, v42 offset:464
	s_or_b64 exec, exec, s[0:1]
	s_waitcnt vmcnt(9)
	v_mul_f32_e32 v39, v39, v107
	v_fmac_f32_e32 v39, v38, v105
	v_fmac_f32_e32 v39, v40, v106
	v_fmac_f32_e32 v39, v41, v104
	s_nop 1
	v_add_f32_dpp v38, v39, v39 quad_perm:[1,0,3,2] row_mask:0xf bank_mask:0xf bound_ctrl:1
	s_nop 1
	v_add_f32_dpp v38, v38, v38 quad_perm:[2,3,0,1] row_mask:0xf bank_mask:0xf bound_ctrl:1
	s_nop 1
	v_add_f32_dpp v38, v38, v38 row_ror:4 row_mask:0xf bank_mask:0xf bound_ctrl:1
	s_nop 1
	v_mov_b32_dpp v39, v38 row_ror:8 row_mask:0xf bank_mask:0xf bound_ctrl:1
	s_and_saveexec_b64 s[0:1], s[6:7]
	v_add_f32_e32 v38, v38, v39
	v_add_f32_e32 v38, v108, v38
	ds_write_b32 v96, v38 offset:480
	s_or_b64 exec, exec, s[0:1]
	s_waitcnt vmcnt(8)
	v_mul_f32_e32 v35, v35, v107
	v_fmac_f32_e32 v35, v34, v105
	v_fmac_f32_e32 v35, v36, v106
	v_fmac_f32_e32 v35, v37, v104
	s_nop 1
	v_add_f32_dpp v34, v35, v35 quad_perm:[1,0,3,2] row_mask:0xf bank_mask:0xf bound_ctrl:1
	s_nop 1
	v_add_f32_dpp v34, v34, v34 quad_perm:[2,3,0,1] row_mask:0xf bank_mask:0xf bound_ctrl:1
	s_nop 1
	v_add_f32_dpp v34, v34, v34 row_ror:4 row_mask:0xf bank_mask:0xf bound_ctrl:1
	s_nop 1
	v_mov_b32_dpp v35, v34 row_ror:8 row_mask:0xf bank_mask:0xf bound_ctrl:1
	s_and_saveexec_b64 s[0:1], s[6:7]
	v_add_f32_e32 v34, v34, v35
	v_add_f32_e32 v34, v108, v34
	ds_write_b32 v96, v34 offset:496
	s_or_b64 exec, exec, s[0:1]
	s_waitcnt lgkmcnt(0)
	ds_read_b64 v[34:35], v97
	s_waitcnt lgkmcnt(0)
; __device__ __forceinline__ float softplus2_(float z2) { return fmaxf(z2, 0.f) + log1pf(exp2f(-fabsf(z2))) * LOG2E; }
; template <int NB>
; __device__ __forceinline__ void sb_decode_task(const Params& P, float* lds, int task) {
;     ...
;     const float sp0 = softplus2_(z0), sp1 = softplus2_(z1);
	v_cmp_gt_f32_e64 vcc, |v34|, s49
	s_nop 1
	v_cndmask_b32_e32 v37, 0, v101, vcc
	v_sub_f32_e64 v37, v37, |v34|
	v_exp_f32_e32 v37, v37
	v_max_f32_e32 v36, v34, v34
	v_max_f32_e32 v38, 0, v36
	v_cndmask_b32_e32 v36, 0, v100, vcc
	v_ldexp_f32 v39, v37, v36
	v_add_f32_e32 v40, 1.0, v39
	v_add_f32_e32 v36, -1.0, v40
	v_sub_f32_e32 v37, v36, v40
	v_add_f32_e32 v37, 1.0, v37
	v_sub_f32_e32 v36, v39, v36
	v_add_f32_e32 v41, v36, v37
	v_frexp_mant_f32_e32 v36, v40
	v_cmp_gt_f32_e32 vcc, s50, v36
	v_cvt_f64_f32_e32 v[36:37], v40
	v_frexp_exp_i32_f64_e32 v36, v[36:37]
	v_subbrev_co_u32_e32 v36, vcc, 0, v36, vcc
	v_sub_u32_e32 v37, 0, v36
	v_ldexp_f32 v40, v40, v37
	v_ldexp_f32 v37, v41, v37
	v_add_f32_e32 v41, -1.0, v40
	v_add_f32_e32 v42, 1.0, v41
	v_sub_f32_e32 v42, v40, v42
	v_add_f32_e32 v42, v37, v42
	v_add_f32_e32 v43, v41, v42
	v_sub_f32_e32 v41, v41, v43
	v_add_f32_e32 v41, v42, v41
	v_add_f32_e32 v42, 1.0, v40
	v_add_f32_e32 v44, -1.0, v42
	v_sub_f32_e32 v40, v40, v44
	v_add_f32_e32 v37, v37, v40
	v_add_f32_e32 v40, v42, v37
	v_sub_f32_e32 v42, v42, v40
	v_add_f32_e32 v37, v37, v42
	v_rcp_f32_e32 v42, v40
	v_cvt_f32_i32_e32 v36, v36
	v_cmp_neq_f32_e32 vcc, s52, v39
	v_mul_f32_e32 v44, v43, v42
	v_mul_f32_e32 v45, v40, v44
	v_fma_f32 v46, v44, v40, -v45
	v_fmac_f32_e32 v46, v44, v37
	v_add_f32_e32 v47, v45, v46
	v_sub_f32_e32 v48, v43, v47
	v_sub_f32_e32 v43, v43, v48
	v_sub_f32_e32 v45, v47, v45
	v_sub_f32_e32 v43, v43, v47
	v_add_f32_e32 v41, v41, v43
	v_sub_f32_e32 v43, v45, v46
	v_add_f32_e32 v41, v43, v41
	v_add_f32_e32 v43, v48, v41
	v_mul_f32_e32 v45, v42, v43
	v_mul_f32_e32 v46, v40, v45
	v_fma_f32 v40, v45, v40, -v46
	v_fmac_f32_e32 v40, v45, v37
	v_sub_f32_e32 v37, v48, v43
	v_add_f32_e32 v37, v41, v37
	v_add_f32_e32 v41, v46, v40
	v_sub_f32_e32 v47, v43, v41
	v_sub_f32_e32 v43, v43, v47
	v_sub_f32_e32 v46, v41, v46
	v_sub_f32_e32 v41, v43, v41
	v_add_f32_e32 v37, v37, v41
	v_sub_f32_e32 v40, v46, v40
	v_add_f32_e32 v37, v40, v37
	v_add_f32_e32 v40, v44, v45
	v_add_f32_e32 v37, v47, v37
	v_sub_f32_e32 v41, v40, v44
	v_mul_f32_e32 v37, v42, v37
	v_sub_f32_e32 v41, v45, v41
	v_add_f32_e32 v37, v41, v37
	v_mul_f32_e32 v44, 0x3f317218, v36
	v_add_f32_e32 v41, v40, v37
	v_fma_f32 v45, v36, s51, -v44
	v_mul_f32_e32 v42, v41, v41
	v_fmac_f32_e32 v45, 0xb102e308, v36
	v_sub_f32_e32 v36, v41, v40
	v_fmamk_f32 v43, v42, 0x3e9b6dac, v98
	v_sub_f32_e32 v36, v37, v36
	v_add_f32_e32 v37, v44, v45
	v_fmaak_f32 v43, v42, v43, 0x3f2aaada
	v_sub_f32_e32 v40, v37, v44
	v_ldexp_f32 v44, v41, 1
	v_mul_f32_e32 v41, v41, v42
	v_mul_f32_e32 v41, v41, v43
	v_add_f32_e32 v42, v44, v41
	v_sub_f32_e32 v43, v42, v44
	v_ldexp_f32 v36, v36, 1
	v_sub_f32_e32 v41, v41, v43
	v_add_f32_e32 v36, v36, v41
	v_add_f32_e32 v41, v42, v36
	v_sub_f32_e32 v42, v41, v42
	v_sub_f32_e32 v36, v36, v42
	v_add_f32_e32 v42, v37, v41
	v_sub_f32_e32 v43, v42, v37
	v_sub_f32_e32 v44, v42, v43
	v_sub_f32_e32 v40, v45, v40
	v_sub_f32_e32 v37, v37, v44
	v_sub_f32_e32 v41, v41, v43
	v_add_f32_e32 v37, v41, v37
	v_add_f32_e32 v41, v40, v36
	v_sub_f32_e32 v43, v41, v40
	v_sub_f32_e32 v44, v41, v43
	v_sub_f32_e32 v40, v40, v44
	v_sub_f32_e32 v36, v36, v43
	v_add_f32_e32 v37, v41, v37
	v_add_f32_e32 v36, v36, v40
	v_add_f32_e32 v40, v42, v37
	v_sub_f32_e32 v41, v40, v42
	v_sub_f32_e32 v37, v37, v41
	v_add_f32_e32 v36, v36, v37
	v_add_f32_e32 v36, v40, v36
	v_cndmask_b32_e32 v36, v102, v36, vcc
	v_cmp_lt_f32_e64 vcc, |v39|, s53
	s_nop 1
	v_cndmask_b32_e32 v36, v36, v39, vcc
	v_cmp_gt_f32_e64 vcc, |v35|, s49
	v_fmac_f32_e32 v38, 0x3fb8aa3b, v36
	v_max_f32_e32 v36, v35, v35
	v_cndmask_b32_e32 v37, 0, v101, vcc
	v_sub_f32_e64 v37, v37, |v35|
	v_exp_f32_e32 v37, v37
	v_max_f32_e32 v39, 0, v36
	v_cndmask_b32_e32 v36, 0, v100, vcc
	v_sub_f32_e32 v34, v34, v38
	v_ldexp_f32 v40, v37, v36
	v_add_f32_e32 v41, 1.0, v40
	v_add_f32_e32 v36, -1.0, v41
	v_sub_f32_e32 v37, v36, v41
	v_add_f32_e32 v37, 1.0, v37
	v_sub_f32_e32 v36, v40, v36
	v_add_f32_e32 v42, v36, v37
	v_frexp_mant_f32_e32 v36, v41
	v_cmp_gt_f32_e32 vcc, s50, v36
	v_cvt_f64_f32_e32 v[36:37], v41
	v_frexp_exp_i32_f64_e32 v36, v[36:37]
	v_subbrev_co_u32_e32 v36, vcc, 0, v36, vcc
	v_sub_u32_e32 v37, 0, v36
	v_ldexp_f32 v41, v41, v37
	v_ldexp_f32 v37, v42, v37
	v_add_f32_e32 v42, -1.0, v41
	v_add_f32_e32 v43, 1.0, v42
	v_sub_f32_e32 v43, v41, v43
	v_add_f32_e32 v43, v37, v43
	v_add_f32_e32 v44, v42, v43
	v_sub_f32_e32 v42, v42, v44
	v_add_f32_e32 v42, v43, v42
	v_add_f32_e32 v43, 1.0, v41
	v_add_f32_e32 v45, -1.0, v43
	v_sub_f32_e32 v41, v41, v45
	v_add_f32_e32 v37, v37, v41
	v_add_f32_e32 v41, v43, v37
	v_sub_f32_e32 v43, v43, v41
	v_add_f32_e32 v37, v37, v43
	v_rcp_f32_e32 v43, v41
	v_cvt_f32_i32_e32 v36, v36
	v_cmp_neq_f32_e32 vcc, s52, v40
	v_mul_f32_e32 v45, v44, v43
	v_mul_f32_e32 v46, v41, v45
	v_fma_f32 v47, v45, v41, -v46
	v_fmac_f32_e32 v47, v45, v37
	v_add_f32_e32 v48, v46, v47
	v_sub_f32_e32 v49, v44, v48
	v_sub_f32_e32 v44, v44, v49
	v_sub_f32_e32 v46, v48, v46
	v_sub_f32_e32 v44, v44, v48
	v_add_f32_e32 v42, v42, v44
	v_sub_f32_e32 v44, v46, v47
	v_add_f32_e32 v42, v44, v42
	v_add_f32_e32 v44, v49, v42
	v_mul_f32_e32 v46, v43, v44
	v_mul_f32_e32 v47, v41, v46
	v_fma_f32 v41, v46, v41, -v47
	v_fmac_f32_e32 v41, v46, v37
	v_sub_f32_e32 v37, v49, v44
	v_add_f32_e32 v37, v42, v37
	v_add_f32_e32 v42, v47, v41
	v_sub_f32_e32 v48, v44, v42
	v_sub_f32_e32 v44, v44, v48
	v_sub_f32_e32 v47, v42, v47
	v_sub_f32_e32 v42, v44, v42
	v_add_f32_e32 v37, v37, v42
	v_sub_f32_e32 v41, v47, v41
	v_add_f32_e32 v37, v41, v37
	v_add_f32_e32 v41, v45, v46
	v_add_f32_e32 v37, v48, v37
	v_sub_f32_e32 v42, v41, v45
	v_mul_f32_e32 v37, v43, v37
; __device__ __forceinline__ float softplus2_(float z2) { return fmaxf(z2, 0.f) + log1pf(exp2f(-fabsf(z2))) * LOG2E; }
; template <int NB>
; __device__ __forceinline__ void sb_decode_task(const Params& P, float* lds, int task) {
;     ...
;     const float sp0 = softplus2_(z0), sp1 = softplus2_(z1);
;     float incl = sp0 + sp1;
; #pragma unroll
;     for (int off = 1; off < 64; off <<= 1) { const float t = __shfl_down(incl, off); if (lane + off < 64) incl += t; }
;     const float excl = incl - (sp0 + sp1);
;     wl[2 * lane] = exp2f(z0 - sp0 - (excl + sp1));
;     wl[2 * lane + 1] = exp2f(z1 - sp1 - excl);
;     const float Ltot = __shfl(incl, 0);
;     asm volatile("s_waitcnt lgkmcnt(0)" ::: "memory");
;     __builtin_amdgcn_wave_barrier();
;     float4 o4 = make_float4(0.f, 0.f, 0.f, 0.f);
; #pragma unroll
;     for (int vb = 0; vb < NBT; ++vb) {
;         if (vb + 1 < NBT) {
; #pragma unroll
;             for (int i = 0; i < NB; ++i) nx[i] = *(const float4*)(Vp + (size_t)(4 * NB * (vb + 1) + 4 * i + g) * (SH * HD)); }
; #pragma unroll
;         for (int i = 0; i < NB; ++i) { const float w = wl[4 * NB * vb + 4 * i + g]; o4.x += w * cur[i].x; o4.y += w * cur[i].y; o4.z += w * cur[i].z; o4.w += w * cur[i].w; }
	v_sub_f32_e32 v42, v46, v42
	v_add_f32_e32 v37, v42, v37
	v_mul_f32_e32 v45, 0x3f317218, v36
	v_add_f32_e32 v42, v41, v37
	v_fma_f32 v46, v36, s51, -v45
	v_mul_f32_e32 v43, v42, v42
	v_fmac_f32_e32 v46, 0xb102e308, v36
	v_sub_f32_e32 v36, v42, v41
	v_fmamk_f32 v44, v43, 0x3e9b6dac, v98
	v_sub_f32_e32 v36, v37, v36
	v_add_f32_e32 v37, v45, v46
	v_fmaak_f32 v44, v43, v44, 0x3f2aaada
	v_sub_f32_e32 v41, v37, v45
	v_ldexp_f32 v45, v42, 1
	v_mul_f32_e32 v42, v42, v43
	v_mul_f32_e32 v42, v42, v44
	v_add_f32_e32 v43, v45, v42
	v_sub_f32_e32 v44, v43, v45
	v_ldexp_f32 v36, v36, 1
	v_sub_f32_e32 v42, v42, v44
	v_add_f32_e32 v36, v36, v42
	v_add_f32_e32 v42, v43, v36
	v_sub_f32_e32 v43, v42, v43
	v_sub_f32_e32 v36, v36, v43
	v_add_f32_e32 v43, v37, v42
	v_sub_f32_e32 v44, v43, v37
	v_sub_f32_e32 v45, v43, v44
	v_sub_f32_e32 v41, v46, v41
	v_sub_f32_e32 v37, v37, v45
	v_sub_f32_e32 v42, v42, v44
	v_add_f32_e32 v37, v42, v37
	v_add_f32_e32 v42, v41, v36
	v_sub_f32_e32 v44, v42, v41
	v_sub_f32_e32 v45, v42, v44
	v_sub_f32_e32 v41, v41, v45
	v_sub_f32_e32 v36, v36, v44
	v_add_f32_e32 v37, v42, v37
	v_add_f32_e32 v36, v36, v41
	v_add_f32_e32 v41, v43, v37
	v_sub_f32_e32 v42, v41, v43
	v_sub_f32_e32 v37, v37, v42
	v_add_f32_e32 v36, v36, v37
	v_add_f32_e32 v36, v41, v36
	v_cndmask_b32_e32 v36, v102, v36, vcc
	v_cmp_lt_f32_e64 vcc, |v40|, s53
	v_and_b32_e32 v37, 63, v103
	s_nop 0
	v_cndmask_b32_e32 v36, v36, v40, vcc
	v_cmp_ne_u32_e32 vcc, 63, v37
	v_fmac_f32_e32 v39, 0x3fb8aa3b, v36
	v_add_f32_e32 v36, v38, v39
	v_addc_co_u32_e32 v40, vcc, 0, v103, vcc
	v_lshlrev_b32_e32 v106, 2, v40
	ds_bpermute_b32 v40, v106, v36
	v_cmp_gt_u32_e32 vcc, 62, v37
	v_sub_f32_e32 v35, v35, v39
	s_waitcnt lgkmcnt(0)
	v_add_f32_e32 v40, v36, v40
	v_cndmask_b32_e64 v41, 0, 2, vcc
	v_cndmask_b32_e64 v40, v40, v36, s[8:9]
	v_add_lshl_u32 v107, v41, v103, 2
	ds_bpermute_b32 v41, v107, v40
	v_cmp_gt_u32_e32 vcc, 60, v37
	s_waitcnt lgkmcnt(0)
	v_add_f32_e32 v41, v40, v41
	v_cndmask_b32_e64 v40, v40, v41, s[10:11]
	v_cndmask_b32_e64 v41, 0, 4, vcc
	v_add_lshl_u32 v108, v41, v103, 2
	ds_bpermute_b32 v41, v108, v40
	v_cmp_gt_u32_e32 vcc, 56, v37
	s_waitcnt lgkmcnt(0)
	v_add_f32_e32 v41, v40, v41
	v_cndmask_b32_e64 v40, v40, v41, s[12:13]
	v_cndmask_b32_e64 v41, 0, 8, vcc
	v_add_lshl_u32 v109, v41, v103, 2
	ds_bpermute_b32 v41, v109, v40
	v_cmp_gt_u32_e32 vcc, 48, v37
	s_waitcnt lgkmcnt(0)
	v_add_f32_e32 v41, v40, v41
	v_cndmask_b32_e64 v37, 0, 16, vcc
	v_cndmask_b32_e64 v40, v40, v41, s[14:15]
	v_add_lshl_u32 v110, v37, v103, 2
	ds_bpermute_b32 v37, v110, v40
	s_waitcnt lgkmcnt(0)
	v_add_f32_e32 v37, v40, v37
	v_cndmask_b32_e64 v37, v40, v37, s[16:17]
	v_lshlrev_b32_e32 v40, 2, v103
	v_or_b32_e32 v111, 0x80, v40
	ds_bpermute_b32 v41, v111, v37
	v_and_b32_e32 v104, 0x100, v40
	s_waitcnt lgkmcnt(0)
	v_add_f32_e32 v41, v37, v41
	v_cndmask_b32_e64 v44, v37, v41, s[18:19]
	v_sub_f32_e32 v36, v44, v36
	v_add_f32_e32 v37, v39, v36
	v_sub_f32_e32 v34, v34, v37
	v_cmp_gt_f32_e32 vcc, s54, v34
	v_sub_f32_e32 v35, v35, v36
	s_nop 0
	v_cndmask_b32_e32 v37, 0, v101, vcc
	v_add_f32_e32 v34, v34, v37
	v_cndmask_b32_e32 v37, 0, v100, vcc
	v_cmp_gt_f32_e32 vcc, s54, v35
	v_exp_f32_e32 v34, v34
	s_nop 0
	v_cndmask_b32_e32 v36, 0, v101, vcc
	v_add_f32_e32 v35, v35, v36
	v_exp_f32_e32 v35, v35
	v_cndmask_b32_e32 v36, 0, v100, vcc
	v_ldexp_f32 v34, v34, v37
	v_ldexp_f32 v35, v35, v36
	ds_write_b64 v97, v[34:35] offset:512
	s_waitcnt lgkmcnt(0)
	ds_read2_b32 v[34:35], v96 offset0:128 offset1:132
	ds_read2_b32 v[42:43], v96 offset0:136 offset1:140
	ds_read2_b32 v[66:67], v96 offset0:144 offset1:148
	ds_read2_b32 v[68:69], v96 offset0:152 offset1:156
	ds_read2_b32 v[74:75], v96 offset0:160 offset1:164
	ds_read2_b32 v[76:77], v96 offset0:168 offset1:172
	ds_read2_b32 v[38:39], v96 offset0:176 offset1:180
	ds_read2_b32 v[40:41], v96 offset0:184 offset1:188
	s_waitcnt vmcnt(7) lgkmcnt(7)
	v_pk_fma_f32 v[70:71], v[30:31], v[34:35], 0 op_sel_hi:[1,0,0]
	v_add_co_u32_e32 v30, vcc, s55, v54
	v_pk_fma_f32 v[72:73], v[32:33], v[34:35], 0 op_sel_hi:[1,0,0]
	s_nop 0
	v_addc_co_u32_e32 v31, vcc, 0, v55, vcc
	v_add_co_u32_e32 v34, vcc, s83, v54
	v_mov_b32_e32 v64, v35
	s_nop 0
	v_addc_co_u32_e32 v35, vcc, 0, v55, vcc
	v_add_co_u32_e32 v46, vcc, s86, v54
	s_waitcnt vmcnt(6)
	v_pk_fma_f32 v[2:3], v[2:3], v[64:65], v[70:71] op_sel_hi:[1,0,1]
	v_addc_co_u32_e32 v47, vcc, 0, v55, vcc
	v_add_co_u32_e32 v50, vcc, s87, v54
	global_load_dwordx4 v[46:49], v[46:47], off
	s_nop 0
	v_addc_co_u32_e32 v51, vcc, 0, v55, vcc
	v_add_co_u32_e32 v56, vcc, s88, v54
	global_load_dwordx4 v[50:53], v[50:51], off offset:2048
	s_nop 0
	v_addc_co_u32_e32 v57, vcc, 0, v55, vcc
	v_add_co_u32_e32 v60, vcc, s89, v54
	global_load_dwordx4 v[56:59], v[56:57], off
	s_nop 0
	v_addc_co_u32_e32 v61, vcc, 0, v55, vcc
	global_load_dwordx4 v[60:63], v[60:61], off offset:2048
	s_waitcnt lgkmcnt(6)
	v_mov_b32_e32 v78, v43
	s_waitcnt vmcnt(9)
	v_pk_fma_f32 v[2:3], v[6:7], v[42:43], v[2:3] op_sel_hi:[1,0,1]
	s_waitcnt lgkmcnt(5)
	v_mov_b32_e32 v80, v67
	s_waitcnt vmcnt(7)
	v_pk_fma_f32 v[2:3], v[14:15], v[78:79], v[2:3] op_sel_hi:[1,0,1]
	s_waitcnt lgkmcnt(4)
	v_mov_b32_e32 v92, v69
	v_pk_fma_f32 v[2:3], v[10:11], v[66:67], v[2:3] op_sel_hi:[1,0,1]
	s_waitcnt lgkmcnt(3)
	v_mov_b32_e32 v10, v75
	s_waitcnt vmcnt(6)
	v_pk_fma_f32 v[2:3], v[18:19], v[80:81], v[2:3] op_sel_hi:[1,0,1]
	s_waitcnt lgkmcnt(2)
	v_mov_b32_e32 v14, v77
	s_waitcnt vmcnt(5)
	v_pk_fma_f32 v[2:3], v[22:23], v[68:69], v[2:3] op_sel_hi:[1,0,1]
	global_load_dwordx4 v[30:33], v[30:31], off
	s_waitcnt vmcnt(5)
	v_pk_fma_f32 v[2:3], v[26:27], v[92:93], v[2:3] op_sel_hi:[1,0,1]
	global_load_dwordx4 v[34:37], v[34:35], off offset:2048
	s_waitcnt vmcnt(5)
; template <int NB>
; __device__ __forceinline__ void sb_decode_task(const Params& P, float* lds, int task) {
;     ...
;     for (int vb = 0; vb < NBT; ++vb) {
;         if (vb + 1 < NBT) {
; #pragma unroll
;             for (int i = 0; i < NB; ++i) nx[i] = *(const float4*)(Vp + (size_t)(4 * NB * (vb + 1) + 4 * i + g) * (SH * HD)); }
; #pragma unroll
;         for (int i = 0; i < NB; ++i) { const float w = wl[4 * NB * vb + 4 * i + g]; o4.x += w * cur[i].x; o4.y += w * cur[i].y; o4.z += w * cur[i].z; o4.w += w * cur[i].w; }
; #pragma unroll
;         for (int i = 0; i < NB; ++i) cur[i] = nx[i];
;     }
	v_pk_fma_f32 v[2:3], v[46:47], v[74:75], v[2:3] op_sel_hi:[1,0,1]
	s_waitcnt vmcnt(4)
	v_pk_fma_f32 v[2:3], v[50:51], v[10:11], v[2:3] op_sel_hi:[1,0,1]
	s_waitcnt vmcnt(3)
	v_pk_fma_f32 v[2:3], v[56:57], v[76:77], v[2:3] op_sel_hi:[1,0,1]
	s_waitcnt vmcnt(2)
	v_pk_fma_f32 v[6:7], v[60:61], v[14:15], v[2:3] op_sel_hi:[1,0,1]
	v_pk_fma_f32 v[2:3], v[4:5], v[64:65], v[72:73] op_sel_hi:[1,0,1]
	v_add_co_u32_e32 v4, vcc, s90, v54
	v_pk_fma_f32 v[2:3], v[8:9], v[42:43], v[2:3] op_sel_hi:[1,0,1]
	s_nop 0
	v_addc_co_u32_e32 v5, vcc, 0, v55, vcc
	v_pk_fma_f32 v[2:3], v[16:17], v[78:79], v[2:3] op_sel_hi:[1,0,1]
	s_waitcnt lgkmcnt(0)
	v_mov_b32_e32 v42, v41
	v_pk_fma_f32 v[2:3], v[12:13], v[66:67], v[2:3] op_sel_hi:[1,0,1]
	s_waitcnt vmcnt(1)
	v_pk_fma_f32 v[6:7], v[30:31], v[38:39], v[6:7] op_sel_hi:[1,0,1]
	v_pk_fma_f32 v[2:3], v[20:21], v[80:81], v[2:3] op_sel_hi:[1,0,1]
	s_nop 0
	v_pk_fma_f32 v[2:3], v[24:25], v[68:69], v[2:3] op_sel_hi:[1,0,1]
	s_nop 0
	v_pk_fma_f32 v[2:3], v[28:29], v[92:93], v[2:3] op_sel_hi:[1,0,1]
	v_mov_b32_e32 v28, v39
	v_pk_fma_f32 v[2:3], v[48:49], v[74:75], v[2:3] op_sel_hi:[1,0,1]
	s_waitcnt vmcnt(0)
	v_pk_fma_f32 v[6:7], v[34:35], v[28:29], v[6:7] op_sel_hi:[1,0,1]
	v_pk_fma_f32 v[2:3], v[52:53], v[10:11], v[2:3] op_sel_hi:[1,0,1]
	s_nop 0
	v_pk_fma_f32 v[2:3], v[58:59], v[76:77], v[2:3] op_sel_hi:[1,0,1]
	s_nop 0
	v_pk_fma_f32 v[2:3], v[62:63], v[14:15], v[2:3] op_sel_hi:[1,0,1]
	ds_read2_b32 v[14:15], v96 offset0:192 offset1:196
	ds_read2_b32 v[12:13], v96 offset0:200 offset1:204
	ds_read2_b32 v[10:11], v96 offset0:208 offset1:212
	ds_read2_b32 v[8:9], v96 offset0:216 offset1:220
	global_load_dwordx4 v[16:19], v[4:5], off
	v_add_co_u32_e32 v4, vcc, s91, v54
	v_pk_fma_f32 v[2:3], v[32:33], v[38:39], v[2:3] op_sel_hi:[1,0,1]
	s_nop 0
	v_addc_co_u32_e32 v5, vcc, 0, v55, vcc
	global_load_dwordx4 v[20:23], v[4:5], off offset:2048
	v_add_co_u32_e32 v4, vcc, s92, v54
	v_pk_fma_f32 v[2:3], v[36:37], v[28:29], v[2:3] op_sel_hi:[1,0,1]
	s_nop 0
	v_addc_co_u32_e32 v5, vcc, 0, v55, vcc
	global_load_dwordx4 v[24:27], v[4:5], off
	v_add_co_u32_e32 v4, vcc, s93, v54
	s_waitcnt lgkmcnt(0)
	v_mov_b32_e32 v36, v9
	v_addc_co_u32_e32 v5, vcc, 0, v55, vcc
	global_load_dwordx4 v[46:49], v[4:5], off offset:2048
	v_add_co_u32_e32 v4, vcc, s94, v54
	ds_read2_b32 v[30:31], v96 offset0:224 offset1:228
	s_nop 0
	v_addc_co_u32_e32 v5, vcc, 0, v55, vcc
	global_load_dwordx4 v[50:53], v[4:5], off
	v_add_co_u32_e32 v4, vcc, s95, v54
	s_waitcnt vmcnt(4)
	v_pk_fma_f32 v[2:3], v[18:19], v[40:41], v[2:3] op_sel_hi:[1,0,1]
	v_addc_co_u32_e32 v5, vcc, 0, v55, vcc
	global_load_dwordx4 v[56:59], v[4:5], off offset:2048
	v_add_co_u32_e32 v4, vcc, s96, v54
	s_waitcnt vmcnt(4)
	v_pk_fma_f32 v[2:3], v[22:23], v[42:43], v[2:3] op_sel_hi:[1,0,1]
	v_addc_co_u32_e32 v5, vcc, 0, v55, vcc
	global_load_dwordx4 v[60:63], v[4:5], off
	v_add_co_u32_e32 v4, vcc, s97, v54
	s_waitcnt vmcnt(4)
	v_pk_fma_f32 v[2:3], v[26:27], v[14:15], v[2:3] op_sel_hi:[1,0,1]
	v_addc_co_u32_e32 v5, vcc, 0, v55, vcc
	global_load_dwordx4 v[64:67], v[4:5], off offset:2048
	v_add_co_u32_e32 v4, vcc, s22, v54
	v_mov_b32_e32 v18, v15
	s_nop 0
	v_addc_co_u32_e32 v5, vcc, 0, v55, vcc
	global_load_dwordx4 v[68:71], v[4:5], off
	v_pk_fma_f32 v[6:7], v[16:17], v[40:41], v[6:7] op_sel_hi:[1,0,1]
	s_waitcnt vmcnt(5)
	v_pk_fma_f32 v[2:3], v[48:49], v[18:19], v[2:3] op_sel_hi:[1,0,1]
	v_pk_fma_f32 v[6:7], v[20:21], v[42:43], v[6:7] op_sel_hi:[1,0,1]
	s_waitcnt vmcnt(4)
	v_pk_fma_f32 v[2:3], v[52:53], v[12:13], v[2:3] op_sel_hi:[1,0,1]
	v_mov_b32_e32 v22, v13
	v_pk_fma_f32 v[6:7], v[24:25], v[14:15], v[6:7] op_sel_hi:[1,0,1]
	v_mov_b32_e32 v26, v11
	v_pk_fma_f32 v[6:7], v[46:47], v[18:19], v[6:7] op_sel_hi:[1,0,1]
	s_waitcnt vmcnt(3)
	v_pk_fma_f32 v[2:3], v[58:59], v[22:23], v[2:3] op_sel_hi:[1,0,1]
	v_pk_fma_f32 v[6:7], v[50:51], v[12:13], v[6:7] op_sel_hi:[1,0,1]
	s_waitcnt vmcnt(2)
	v_pk_fma_f32 v[2:3], v[62:63], v[10:11], v[2:3] op_sel_hi:[1,0,1]
	v_pk_fma_f32 v[6:7], v[56:57], v[22:23], v[6:7] op_sel_hi:[1,0,1]
	s_waitcnt vmcnt(1)
; template <int NB>
; __device__ __forceinline__ void sb_decode_task(const Params& P, float* lds, int task) {
;     ...
;     for (int vb = 0; vb < NBT; ++vb) {
;         if (vb + 1 < NBT) {
; #pragma unroll
;             for (int i = 0; i < NB; ++i) nx[i] = *(const float4*)(Vp + (size_t)(4 * NB * (vb + 1) + 4 * i + g) * (SH * HD)); }
; #pragma unroll
;         for (int i = 0; i < NB; ++i) { const float w = wl[4 * NB * vb + 4 * i + g]; o4.x += w * cur[i].x; o4.y += w * cur[i].y; o4.z += w * cur[i].z; o4.w += w * cur[i].w; }
; #pragma unroll
;         for (int i = 0; i < NB; ++i) cur[i] = nx[i];
;     }
; #pragma unroll
;     for (int off = 16; off < 64; off <<= 1) { o4.x += __shfl_xor(o4.x, off); o4.y += __shfl_xor(o4.y, off); o4.z += __shfl_xor(o4.z, off); o4.w += __shfl_xor(o4.w, off); }
;     if (g == 0) *(float4*)(dpart + (size_t)task * HD + 4 * c) = o4;
;     if (lane == 0) dl[task] = Ltot;
;     __builtin_amdgcn_wave_barrier();
	v_pk_fma_f32 v[2:3], v[66:67], v[26:27], v[2:3] op_sel_hi:[1,0,1]
	v_pk_fma_f32 v[6:7], v[60:61], v[10:11], v[6:7] op_sel_hi:[1,0,1]
	v_and_b32_e32 v10, 64, v103
	v_pk_fma_f32 v[6:7], v[64:65], v[26:27], v[6:7] op_sel_hi:[1,0,1]
	v_add_u32_e32 v37, 64, v10
	v_xor_b32_e32 v10, 16, v103
	s_waitcnt vmcnt(0)
	v_pk_fma_f32 v[32:33], v[70:71], v[8:9], v[2:3] op_sel_hi:[1,0,1]
	v_add_co_u32_e32 v2, vcc, s23, v54
	v_pk_fma_f32 v[34:35], v[68:69], v[8:9], v[6:7] op_sel_hi:[1,0,1]
	s_nop 0
	v_addc_co_u32_e32 v3, vcc, 0, v55, vcc
	v_add_co_u32_e32 v6, vcc, s24, v54
	global_load_dwordx4 v[2:5], v[2:3], off offset:2048
	s_nop 0
	v_addc_co_u32_e32 v7, vcc, 0, v55, vcc
	v_cmp_lt_i32_e32 vcc, v10, v37
	global_load_dwordx4 v[6:9], v[6:7], off
	ds_read2_b32 v[42:43], v96 offset0:232 offset1:236
	ds_read2_b32 v[40:41], v96 offset0:240 offset1:244
	ds_read2_b32 v[38:39], v96 offset0:248 offset1:252
	v_cndmask_b32_e32 v10, v103, v10, vcc
	v_lshlrev_b32_e32 v105, 2, v10
	v_add_co_u32_e32 v10, vcc, s72, v54
	s_waitcnt lgkmcnt(1)
	v_mov_b32_e32 v56, v41
	v_addc_co_u32_e32 v11, vcc, 0, v55, vcc
	v_add_co_u32_e32 v14, vcc, s73, v54
	global_load_dwordx4 v[10:13], v[10:11], off offset:2048
	s_nop 0
	v_addc_co_u32_e32 v15, vcc, 0, v55, vcc
	v_add_co_u32_e32 v18, vcc, s74, v54
	global_load_dwordx4 v[14:17], v[14:15], off
	s_nop 0
	v_addc_co_u32_e32 v19, vcc, 0, v55, vcc
	v_add_co_u32_e32 v22, vcc, s75, v54
	global_load_dwordx4 v[18:21], v[18:19], off offset:2048
	s_nop 0
	v_addc_co_u32_e32 v23, vcc, 0, v55, vcc
	v_add_co_u32_e32 v26, vcc, s80, v54
	global_load_dwordx4 v[22:25], v[22:23], off
	s_nop 0
	v_addc_co_u32_e32 v27, vcc, 0, v55, vcc
	v_add_co_u32_e32 v46, vcc, s81, v54
	global_load_dwordx4 v[26:29], v[26:27], off offset:2048
	s_nop 0
	v_addc_co_u32_e32 v47, vcc, 0, v55, vcc
	v_add_co_u32_e32 v50, vcc, s82, v54
	global_load_dwordx4 v[46:49], v[46:47], off
	s_nop 0
	v_addc_co_u32_e32 v51, vcc, 0, v55, vcc
	global_load_dwordx4 v[50:53], v[50:51], off offset:2048
	v_mov_b32_e32 v54, v43
	s_waitcnt lgkmcnt(0)
	v_mov_b32_e32 v58, v39
	s_waitcnt vmcnt(8)
	v_pk_fma_f32 v[2:3], v[2:3], v[36:37], v[34:35] op_sel_hi:[1,0,1]
	v_mov_b32_e32 v34, v31
	v_pk_fma_f32 v[4:5], v[4:5], v[36:37], v[32:33] op_sel_hi:[1,0,1]
	s_waitcnt vmcnt(7)
	v_pk_fma_f32 v[2:3], v[6:7], v[30:31], v[2:3] op_sel_hi:[1,0,1]
	v_pk_fma_f32 v[4:5], v[8:9], v[30:31], v[4:5] op_sel_hi:[1,0,1]
	s_waitcnt vmcnt(6)
	v_pk_fma_f32 v[2:3], v[10:11], v[34:35], v[2:3] op_sel_hi:[1,0,1]
	v_pk_fma_f32 v[4:5], v[12:13], v[34:35], v[4:5] op_sel_hi:[1,0,1]
	ds_bpermute_b32 v10, v104, v44
	s_waitcnt vmcnt(5)
	v_pk_fma_f32 v[2:3], v[14:15], v[42:43], v[2:3] op_sel_hi:[1,0,1]
	v_pk_fma_f32 v[4:5], v[16:17], v[42:43], v[4:5] op_sel_hi:[1,0,1]
	s_waitcnt vmcnt(4)
	v_pk_fma_f32 v[2:3], v[18:19], v[54:55], v[2:3] op_sel_hi:[1,0,1]
	v_pk_fma_f32 v[4:5], v[20:21], v[54:55], v[4:5] op_sel_hi:[1,0,1]
	s_waitcnt vmcnt(3)
	v_pk_fma_f32 v[2:3], v[22:23], v[40:41], v[2:3] op_sel_hi:[1,0,1]
	v_pk_fma_f32 v[4:5], v[24:25], v[40:41], v[4:5] op_sel_hi:[1,0,1]
	s_waitcnt vmcnt(2)
	v_pk_fma_f32 v[2:3], v[26:27], v[56:57], v[2:3] op_sel_hi:[1,0,1]
	v_pk_fma_f32 v[4:5], v[28:29], v[56:57], v[4:5] op_sel_hi:[1,0,1]
	s_waitcnt vmcnt(1)
	v_pk_fma_f32 v[2:3], v[46:47], v[38:39], v[2:3] op_sel_hi:[1,0,1]
	v_pk_fma_f32 v[4:5], v[48:49], v[38:39], v[4:5] op_sel_hi:[1,0,1]
	s_waitcnt vmcnt(0)
	v_pk_fma_f32 v[2:3], v[50:51], v[58:59], v[2:3] op_sel_hi:[1,0,1]
	ds_bpermute_b32 v6, v105, v2
	ds_bpermute_b32 v7, v105, v3
	v_pk_fma_f32 v[4:5], v[52:53], v[58:59], v[4:5] op_sel_hi:[1,0,1]
	s_waitcnt lgkmcnt(0)
	v_pk_add_f32 v[2:3], v[2:3], v[6:7]
	ds_bpermute_b32 v6, v105, v4
	ds_bpermute_b32 v7, v105, v5
	s_waitcnt lgkmcnt(0)
	v_pk_add_f32 v[4:5], v[4:5], v[6:7]
	v_xor_b32_e32 v6, 32, v103
	v_cmp_lt_i32_e32 vcc, v6, v37
	s_nop 1
	v_cndmask_b32_e32 v6, v103, v6, vcc
	v_lshlrev_b32_e32 v112, 2, v6
	ds_bpermute_b32 v6, v112, v2
	ds_bpermute_b32 v7, v112, v3
	ds_bpermute_b32 v8, v112, v4
	ds_bpermute_b32 v9, v112, v5
	s_and_saveexec_b64 s[0:1], s[20:21]
	s_cbranch_execz .LBB0_1022
	s_ashr_i32 s35, s34, 31
	s_lshl_b64 s[2:3], s[34:35], 8
	v_lshl_add_u64 v[12:13], v[88:89], 0, s[2:3]
	s_waitcnt lgkmcnt(2)
	v_pk_add_f32 v[2:3], v[2:3], v[6:7]
	s_waitcnt lgkmcnt(0)
	v_pk_add_f32 v[4:5], v[4:5], v[8:9]
	global_store_dwordx4 v[12:13], v[2:5], off

; __device__ __forceinline__ float bf2f(bf16_t b) { return __uint_as_float(((unsigned)b) << 16); }
; template <int NB>
; __device__ __forceinline__ void sb_decode_task(const Params& P, float* lds, int task) {
;     const int tid = threadIdx.x, lane = tid & 63, wave = tid >> 6;
;     const bf16_t* qb = (const bf16_t*)(P.ws + WS_QB);
;     float* dpart = (float*)(P.ws + WS_DPART); float* dl = (float*)(P.ws + WS_DL);
;     float* zl = lds + DEC_LDS_OFF / 4 + wave * 256; float* wl = zl + 128;
;     const int c = lane & 15, g = lane >> 4;
;     constexpr int NBT = 32 / NB;
;     const int h = task % SH, bj = task / SH, b = bj / NPAGES;
;     const int page = P.page_table[bj];
;     const float* Kp = P.cache_k + ((size_t)page * PAGE * SH + h) * HD + 4 * c;
;     const float* Vp = P.cache_v + ((size_t)page * PAGE * SH + h) * HD + 4 * c;
;     const bf16_t* qp = qb + (size_t)(NTOK + b) * SBW + h * 64 + 4 * c;
;     const float q0 = bf2f(qp[0]), q1 = bf2f(qp[1]), q2 = bf2f(qp[2]), q3 = bf2f(qp[3]);
;     const float bias = P.sb_bias[h] * LOG2E;
;     float4 cur[NB], nx[NB];
; #pragma unroll
;     for (int i = 0; i < NB; ++i) cur[i] = *(const float4*)(Kp + (size_t)(4 * i + g) * (SH * HD));
; #pragma unroll
;     for (int kb = 0; kb < NBT; ++kb) {
;         const float* np = (kb + 1 < NBT) ? Kp + (size_t)(4 * NB * (kb + 1)) * (SH * HD) : Vp;
; #pragma unroll
;         for (int i = 0; i < NB; ++i) nx[i] = *(const float4*)(np + (size_t)(4 * i + g) * (SH * HD));
; #pragma unroll
;         for (int i = 0; i < NB; ++i) { const int s = 4 * NB * kb + 4 * i + g;
;             float part = q0 * cur[i].x + q1 * cur[i].y + q2 * cur[i].z + q3 * cur[i].w; part = sum16(part);
;             if (c == 0) zl[s] = part + bias; }
; __device__ __forceinline__ void sb_decode_wave_loop(const Params& P, float* lds) {
;     ...
;         if (blockIdx.x < 96 && scan_running) { sb_decode_task<4>(P, lds, t); sb_decode_task<4>(P, lds, t + 1); }
;         else if (thin) { sb_decode_task<8>(P, lds, t); sb_decode_task<8>(P, lds, t + 1); }
.LBB0_1024:
	s_or_b64 exec, exec, s[0:1]
	v_readlane_b32 s36, v252, 48
	s_add_i32 s34, s34, 1
	v_readlane_b32 s37, v252, 49
	s_mul_hi_i32 s1, s34, 0x2aaaaaab
	s_load_dwordx16 s[56:71], s[36:37], 0x0
	s_lshr_b32 s3, s1, 31
	s_add_i32 s0, s1, s3
	s_ashr_i32 s1, s1, 7
	s_mul_i32 s2, s0, 6
	s_add_i32 s33, s1, s3
	s_ashr_i32 s1, s0, 31
	s_sub_i32 s2, s34, s2
	s_lshl_b64 s[0:1], s[0:1], 2
	s_waitcnt lgkmcnt(0)
	s_add_u32 s0, s66, s0
	s_addc_u32 s1, s67, s1
	v_mov_b32_e32 v2, v253
	s_add_i32 s0, s33, 0x4000
	s_ashr_i32 s3, s2, 31
	s_mul_hi_i32 s1, s0, 0x300
	s_mulk_i32 s0, 0x300
	s_add_u32 s33, s38, s0
	s_addc_u32 s35, s39, s1
	s_lshl_b32 s0, s2, 6
	s_ashr_i32 s1, s0, 31
	s_lshl_b64 s[0:1], s[0:1], 1
	s_add_u32 s0, s33, s0
	s_addc_u32 s1, s35, s1
	v_readlane_b32 s56, v252, 16
	v_readlane_b32 s57, v252, 17
	v_readlane_b32 s64, v252, 24
	v_readlane_b32 s65, v252, 25
	s_mov_b64 s[56:57], s[64:65]
	v_mov_b32_e32 v91, v83
	v_readlane_b32 s58, v252, 18
	v_readlane_b32 s59, v252, 19
	v_readlane_b32 s60, v252, 20
	v_readlane_b32 s61, v252, 21
	v_readlane_b32 s62, v252, 22
	v_readlane_b32 s63, v252, 23
	v_readlane_b32 s66, v252, 26
	v_readlane_b32 s67, v252, 27
	v_readlane_b32 s68, v252, 28
	v_readlane_b32 s69, v252, 29
	v_readlane_b32 s70, v252, 30
	v_readlane_b32 s71, v252, 31
	v_mul_hi_i32 v3, v2, s42
	v_mul_lo_u32 v2, v2, s42
	v_lshl_add_u64 v[92:93], v[2:3], 0, s[2:3]
	v_lshlrev_b64 v[2:3], 8, v[92:93]
	v_lshl_add_u64 v[66:67], v[84:85], 0, v[2:3]
	global_load_dwordx2 v[2:3], v99, s[0:1]
	s_lshl_b64 s[0:1], s[2:3], 2
	s_add_u32 s0, s56, s0
	s_addc_u32 s1, s57, s1
	global_load_dword v22, v83, s[0:1]
	v_lshl_add_u64 v[18:19], v[66:67], 0, v[82:83]
	v_lshl_add_u64 v[20:21], v[66:67], 0, v[90:91]
	global_load_dwordx4 v[14:17], v[18:19], off
	global_load_dwordx4 v[62:65], v[20:21], off
	s_waitcnt vmcnt(3)
	v_lshlrev_b32_e32 v114, 16, v2
	v_and_b32_e32 v116, 0xffff0000, v2
	v_add_co_u32_e32 v2, vcc, s44, v18
	v_lshlrev_b32_e32 v115, 16, v3
	v_and_b32_e32 v113, 0xffff0000, v3
	v_addc_co_u32_e32 v3, vcc, 0, v19, vcc
	global_load_dwordx4 v[10:13], v[2:3], off offset:2048
	v_add_co_u32_e32 v2, vcc, s45, v18
	s_waitcnt vmcnt(3)
	v_mul_f32_e32 v117, 0x3fb8aa3b, v22
	v_addc_co_u32_e32 v3, vcc, 0, v19, vcc
	global_load_dwordx4 v[6:9], v[2:3], off
	v_add_co_u32_e32 v2, vcc, s43, v18
	v_lshl_add_u64 v[22:23], v[66:67], 0, s[26:27]
	s_nop 0
	v_addc_co_u32_e32 v3, vcc, 0, v19, vcc
	v_add_co_u32_e32 v20, vcc, s46, v18
	v_lshl_add_u64 v[30:31], v[22:23], 0, v[82:83]
	s_nop 0
	v_addc_co_u32_e32 v21, vcc, 0, v19, vcc
	global_load_dwordx4 v[58:61], v[20:21], off offset:2048
	v_add_co_u32_e32 v20, vcc, s47, v18
	v_lshl_add_u64 v[22:23], v[22:23], 0, v[90:91]
	s_nop 0
	v_addc_co_u32_e32 v21, vcc, 0, v19, vcc
	v_add_co_u32_e32 v18, vcc, s48, v18
	global_load_dwordx4 v[54:57], v[20:21], off
	s_nop 0
	v_addc_co_u32_e32 v19, vcc, 0, v19, vcc
	global_load_dwordx4 v[50:53], v[18:19], off offset:2048
	v_add_co_u32_e32 v18, vcc, s44, v30
	global_load_dwordx4 v[22:25], v[22:23], off
	s_nop 0
	v_addc_co_u32_e32 v19, vcc, 0, v31, vcc
	global_load_dwordx4 v[34:37], v[18:19], off offset:2048
	v_add_co_u32_e32 v18, vcc, s45, v30
	global_load_dwordx4 v[2:5], v[2:3], off offset:2048
	s_nop 0
	v_addc_co_u32_e32 v19, vcc, 0, v31, vcc
	global_load_dwordx4 v[26:29], v[18:19], off
	v_add_co_u32_e32 v18, vcc, s43, v30
	global_load_dwordx4 v[46:49], v[30:31], off
	s_nop 0
	v_addc_co_u32_e32 v19, vcc, 0, v31, vcc
	v_add_co_u32_e32 v32, vcc, s46, v30
	global_load_dwordx4 v[18:21], v[18:19], off offset:2048
	s_nop 0
	v_addc_co_u32_e32 v33, vcc, 0, v31, vcc
	global_load_dwordx4 v[38:41], v[32:33], off offset:2048
	v_add_co_u32_e32 v32, vcc, s47, v30
	s_waitcnt vmcnt(13)
	v_mul_f32_e32 v15, v15, v116
	v_addc_co_u32_e32 v33, vcc, 0, v31, vcc
	v_add_co_u32_e32 v30, vcc, s48, v30
	global_load_dwordx4 v[42:45], v[32:33], off
	s_nop 0
	v_addc_co_u32_e32 v31, vcc, 0, v31, vcc
	global_load_dwordx4 v[30:33], v[30:31], off offset:2048
	v_fmac_f32_e32 v15, v14, v114
	v_fmac_f32_e32 v15, v16, v115
	v_fmac_f32_e32 v15, v17, v113
	s_nop 1
	v_add_f32_dpp v14, v15, v15 quad_perm:[1,0,3,2] row_mask:0xf bank_mask:0xf bound_ctrl:1
	s_nop 1
	v_add_f32_dpp v14, v14, v14 quad_perm:[2,3,0,1] row_mask:0xf bank_mask:0xf bound_ctrl:1
	s_nop 1
	v_add_f32_dpp v14, v14, v14 row_ror:4 row_mask:0xf bank_mask:0xf bound_ctrl:1
	s_nop 1
	v_mov_b32_dpp v15, v14 row_ror:8 row_mask:0xf bank_mask:0xf bound_ctrl:1
	s_and_saveexec_b64 s[0:1], s[6:7]
	v_add_f32_e32 v14, v14, v15
	v_add_f32_e32 v14, v117, v14
	ds_write_b32 v96, v14
	s_or_b64 exec, exec, s[0:1]
	s_waitcnt vmcnt(13)
	v_mul_f32_e32 v11, v11, v116
	v_fmac_f32_e32 v11, v10, v114
	v_fmac_f32_e32 v11, v12, v115
	v_fmac_f32_e32 v11, v13, v113
	s_nop 1
	v_add_f32_dpp v10, v11, v11 quad_perm:[1,0,3,2] row_mask:0xf bank_mask:0xf bound_ctrl:1
	s_nop 1
	v_add_f32_dpp v10, v10, v10 quad_perm:[2,3,0,1] row_mask:0xf bank_mask:0xf bound_ctrl:1
	s_nop 1
	v_add_f32_dpp v10, v10, v10 row_ror:4 row_mask:0xf bank_mask:0xf bound_ctrl:1
	s_nop 1
	v_mov_b32_dpp v11, v10 row_ror:8 row_mask:0xf bank_mask:0xf bound_ctrl:1
	s_and_saveexec_b64 s[0:1], s[6:7]
	v_add_f32_e32 v10, v10, v11
	v_add_f32_e32 v10, v117, v10
	ds_write_b32 v96, v10 offset:16
	s_or_b64 exec, exec, s[0:1]
	s_waitcnt vmcnt(12)
	v_mul_f32_e32 v7, v7, v116
	v_fmac_f32_e32 v7, v6, v114
	v_fmac_f32_e32 v7, v8, v115
	v_fmac_f32_e32 v7, v9, v113
	s_nop 1
	v_add_f32_dpp v6, v7, v7 quad_perm:[1,0,3,2] row_mask:0xf bank_mask:0xf bound_ctrl:1
	s_nop 1
	v_add_f32_dpp v6, v6, v6 quad_perm:[2,3,0,1] row_mask:0xf bank_mask:0xf bound_ctrl:1
	s_nop 1
	v_add_f32_dpp v6, v6, v6 row_ror:4 row_mask:0xf bank_mask:0xf bound_ctrl:1
	s_nop 1
	v_mov_b32_dpp v7, v6 row_ror:8 row_mask:0xf bank_mask:0xf bound_ctrl:1
	s_and_saveexec_b64 s[0:1], s[6:7]
	v_add_f32_e32 v6, v6, v7
	v_add_f32_e32 v6, v117, v6
	ds_write_b32 v96, v6 offset:32
	s_or_b64 exec, exec, s[0:1]
	s_waitcnt vmcnt(6)
; template <int NB>
; __device__ __forceinline__ void sb_decode_task(const Params& P, float* lds, int task) {
;     ...
;     for (int i = 0; i < NB; ++i) cur[i] = *(const float4*)(Kp + (size_t)(4 * i + g) * (SH * HD));
; #pragma unroll
;     for (int kb = 0; kb < NBT; ++kb) {
;         const float* np = (kb + 1 < NBT) ? Kp + (size_t)(4 * NB * (kb + 1)) * (SH * HD) : Vp;
; #pragma unroll
;         for (int i = 0; i < NB; ++i) nx[i] = *(const float4*)(np + (size_t)(4 * i + g) * (SH * HD));
; #pragma unroll
;         for (int i = 0; i < NB; ++i) { const int s = 4 * NB * kb + 4 * i + g;
;             float part = q0 * cur[i].x + q1 * cur[i].y + q2 * cur[i].z + q3 * cur[i].w; part = sum16(part);
;             if (c == 0) zl[s] = part + bias; }
	v_mul_f32_e32 v3, v3, v116
	v_fmac_f32_e32 v3, v2, v114
	v_fmac_f32_e32 v3, v4, v115
	v_fmac_f32_e32 v3, v5, v113
	s_nop 1
	v_add_f32_dpp v2, v3, v3 quad_perm:[1,0,3,2] row_mask:0xf bank_mask:0xf bound_ctrl:1
	s_nop 1
	v_add_f32_dpp v2, v2, v2 quad_perm:[2,3,0,1] row_mask:0xf bank_mask:0xf bound_ctrl:1
	s_nop 1
	v_add_f32_dpp v2, v2, v2 row_ror:4 row_mask:0xf bank_mask:0xf bound_ctrl:1
	s_nop 1
	v_mov_b32_dpp v3, v2 row_ror:8 row_mask:0xf bank_mask:0xf bound_ctrl:1
	s_and_saveexec_b64 s[0:1], s[6:7]
	v_add_f32_e32 v2, v2, v3
	v_add_f32_e32 v2, v117, v2
	ds_write_b32 v96, v2 offset:48
	s_or_b64 exec, exec, s[0:1]
	v_mul_f32_e32 v2, v63, v116
	v_fmac_f32_e32 v2, v62, v114
	v_fmac_f32_e32 v2, v64, v115
	v_fmac_f32_e32 v2, v65, v113
	s_nop 1
	v_add_f32_dpp v2, v2, v2 quad_perm:[1,0,3,2] row_mask:0xf bank_mask:0xf bound_ctrl:1
	s_nop 1
	v_add_f32_dpp v2, v2, v2 quad_perm:[2,3,0,1] row_mask:0xf bank_mask:0xf bound_ctrl:1
	s_nop 1
	v_add_f32_dpp v2, v2, v2 row_ror:4 row_mask:0xf bank_mask:0xf bound_ctrl:1
	s_nop 1
	v_mov_b32_dpp v3, v2 row_ror:8 row_mask:0xf bank_mask:0xf bound_ctrl:1
	s_and_saveexec_b64 s[0:1], s[6:7]
	v_add_f32_e32 v2, v2, v3
	v_add_f32_e32 v2, v117, v2
	ds_write_b32 v96, v2 offset:64
	s_or_b64 exec, exec, s[0:1]
	v_mul_f32_e32 v2, v59, v116
	v_fmac_f32_e32 v2, v58, v114
	v_fmac_f32_e32 v2, v60, v115
	v_fmac_f32_e32 v2, v61, v113
	s_nop 1
	v_add_f32_dpp v2, v2, v2 quad_perm:[1,0,3,2] row_mask:0xf bank_mask:0xf bound_ctrl:1
	s_nop 1
	v_add_f32_dpp v2, v2, v2 quad_perm:[2,3,0,1] row_mask:0xf bank_mask:0xf bound_ctrl:1
	s_nop 1
	v_add_f32_dpp v2, v2, v2 row_ror:4 row_mask:0xf bank_mask:0xf bound_ctrl:1
	s_nop 1
	v_mov_b32_dpp v3, v2 row_ror:8 row_mask:0xf bank_mask:0xf bound_ctrl:1
	s_and_saveexec_b64 s[0:1], s[6:7]
	v_add_f32_e32 v2, v2, v3
	v_add_f32_e32 v2, v117, v2
	ds_write_b32 v96, v2 offset:80
	s_or_b64 exec, exec, s[0:1]
	v_mul_f32_e32 v2, v55, v116
	v_fmac_f32_e32 v2, v54, v114
	v_fmac_f32_e32 v2, v56, v115
	v_fmac_f32_e32 v2, v57, v113
	s_nop 1
	v_add_f32_dpp v2, v2, v2 quad_perm:[1,0,3,2] row_mask:0xf bank_mask:0xf bound_ctrl:1
	s_nop 1
	v_add_f32_dpp v2, v2, v2 quad_perm:[2,3,0,1] row_mask:0xf bank_mask:0xf bound_ctrl:1
	s_nop 1
	v_add_f32_dpp v2, v2, v2 row_ror:4 row_mask:0xf bank_mask:0xf bound_ctrl:1
	s_nop 1
	v_mov_b32_dpp v3, v2 row_ror:8 row_mask:0xf bank_mask:0xf bound_ctrl:1
	s_and_saveexec_b64 s[0:1], s[6:7]
	v_add_f32_e32 v2, v2, v3
	v_add_f32_e32 v2, v117, v2
	ds_write_b32 v96, v2 offset:96
	s_or_b64 exec, exec, s[0:1]
	v_mul_f32_e32 v2, v51, v116
	v_fmac_f32_e32 v2, v50, v114
	v_fmac_f32_e32 v2, v52, v115
	v_fmac_f32_e32 v2, v53, v113
	s_nop 1
	v_add_f32_dpp v2, v2, v2 quad_perm:[1,0,3,2] row_mask:0xf bank_mask:0xf bound_ctrl:1
	s_nop 1
	v_add_f32_dpp v2, v2, v2 quad_perm:[2,3,0,1] row_mask:0xf bank_mask:0xf bound_ctrl:1
	s_nop 1
	v_add_f32_dpp v2, v2, v2 row_ror:4 row_mask:0xf bank_mask:0xf bound_ctrl:1
	s_nop 1
	v_mov_b32_dpp v3, v2 row_ror:8 row_mask:0xf bank_mask:0xf bound_ctrl:1
	s_and_saveexec_b64 s[0:1], s[6:7]
	v_add_f32_e32 v2, v2, v3
	v_add_f32_e32 v2, v117, v2
	ds_write_b32 v96, v2 offset:112
	s_or_b64 exec, exec, s[0:1]
	v_lshl_add_u64 v[2:3], v[66:67], 0, s[28:29]
	v_lshl_add_u64 v[4:5], v[2:3], 0, v[82:83]
	v_add_co_u32_e32 v6, vcc, 0x1000, v4
	v_mov_b32_e32 v91, v83
	s_nop 0
	v_addc_co_u32_e32 v7, vcc, 0, v5, vcc
	global_load_dwordx4 v[78:81], v[4:5], off
	global_load_dwordx4 v[70:73], v[6:7], off offset:2048
	v_add_co_u32_e32 v6, vcc, 0x3000, v4
	v_lshl_add_u64 v[2:3], v[2:3], 0, v[90:91]
	s_nop 0
	v_addc_co_u32_e32 v7, vcc, 0, v5, vcc
	v_add_co_u32_e32 v8, vcc, s43, v4
	s_waitcnt vmcnt(6)
	v_mul_f32_e32 v47, v47, v116
	v_addc_co_u32_e32 v9, vcc, 0, v5, vcc
	global_load_dwordx4 v[62:65], v[6:7], off
	global_load_dwordx4 v[54:57], v[8:9], off offset:2048
	v_add_co_u32_e32 v6, vcc, 0x7000, v4
	v_fmac_f32_e32 v47, v46, v114
	s_nop 0
	v_addc_co_u32_e32 v7, vcc, 0, v5, vcc
	global_load_dwordx4 v[14:17], v[2:3], off
	global_load_dwordx4 v[10:13], v[6:7], off offset:2048
	v_add_co_u32_e32 v2, vcc, 0x9000, v4
	v_fmac_f32_e32 v47, v48, v115
	s_nop 0
	v_addc_co_u32_e32 v3, vcc, 0, v5, vcc
	v_add_co_u32_e32 v4, vcc, 0xa000, v4
	v_fmac_f32_e32 v47, v49, v113
	s_nop 0
	v_addc_co_u32_e32 v5, vcc, 0, v5, vcc
	global_load_dwordx4 v[6:9], v[2:3], off
	s_nop 0
	global_load_dwordx4 v[2:5], v[4:5], off offset:2048
	v_add_f32_dpp v46, v47, v47 quad_perm:[1,0,3,2] row_mask:0xf bank_mask:0xf bound_ctrl:1
	s_nop 1
	v_add_f32_dpp v46, v46, v46 quad_perm:[2,3,0,1] row_mask:0xf bank_mask:0xf bound_ctrl:1
	s_nop 1
	v_add_f32_dpp v46, v46, v46 row_ror:4 row_mask:0xf bank_mask:0xf bound_ctrl:1
	s_nop 1
	v_mov_b32_dpp v47, v46 row_ror:8 row_mask:0xf bank_mask:0xf bound_ctrl:1
	s_and_saveexec_b64 s[0:1], s[6:7]
	v_add_f32_e32 v46, v46, v47
	v_add_f32_e32 v46, v117, v46
	ds_write_b32 v96, v46 offset:128
	s_or_b64 exec, exec, s[0:1]
	v_mul_f32_e32 v35, v35, v116
	v_fmac_f32_e32 v35, v34, v114
	v_fmac_f32_e32 v35, v36, v115
	v_fmac_f32_e32 v35, v37, v113
	s_nop 1
	v_add_f32_dpp v34, v35, v35 quad_perm:[1,0,3,2] row_mask:0xf bank_mask:0xf bound_ctrl:1
	s_nop 1
	v_add_f32_dpp v34, v34, v34 quad_perm:[2,3,0,1] row_mask:0xf bank_mask:0xf bound_ctrl:1
	s_nop 1
	v_add_f32_dpp v34, v34, v34 row_ror:4 row_mask:0xf bank_mask:0xf bound_ctrl:1
	s_nop 1
	v_mov_b32_dpp v35, v34 row_ror:8 row_mask:0xf bank_mask:0xf bound_ctrl:1
	s_and_saveexec_b64 s[0:1], s[6:7]
	v_add_f32_e32 v34, v34, v35
	v_add_f32_e32 v34, v117, v34
	ds_write_b32 v96, v34 offset:144
	s_or_b64 exec, exec, s[0:1]
	v_mul_f32_e32 v27, v27, v116
	v_fmac_f32_e32 v27, v26, v114
	v_fmac_f32_e32 v27, v28, v115
	v_fmac_f32_e32 v27, v29, v113
	s_nop 1
	v_add_f32_dpp v26, v27, v27 quad_perm:[1,0,3,2] row_mask:0xf bank_mask:0xf bound_ctrl:1
	s_nop 1
	v_add_f32_dpp v26, v26, v26 quad_perm:[2,3,0,1] row_mask:0xf bank_mask:0xf bound_ctrl:1
	s_nop 1
	v_add_f32_dpp v26, v26, v26 row_ror:4 row_mask:0xf bank_mask:0xf bound_ctrl:1
	s_nop 1
	v_mov_b32_dpp v27, v26 row_ror:8 row_mask:0xf bank_mask:0xf bound_ctrl:1
	s_and_saveexec_b64 s[0:1], s[6:7]
	v_add_f32_e32 v26, v26, v27
	v_add_f32_e32 v26, v117, v26
	ds_write_b32 v96, v26 offset:160
	s_or_b64 exec, exec, s[0:1]
	s_waitcnt vmcnt(11)
; template <int NB>
; __device__ __forceinline__ void sb_decode_task(const Params& P, float* lds, int task) {
;     ...
;     for (int i = 0; i < NB; ++i) cur[i] = *(const float4*)(Kp + (size_t)(4 * i + g) * (SH * HD));
; #pragma unroll
;     for (int kb = 0; kb < NBT; ++kb) {
;         const float* np = (kb + 1 < NBT) ? Kp + (size_t)(4 * NB * (kb + 1)) * (SH * HD) : Vp;
; #pragma unroll
;         for (int i = 0; i < NB; ++i) nx[i] = *(const float4*)(np + (size_t)(4 * i + g) * (SH * HD));
; #pragma unroll
;         for (int i = 0; i < NB; ++i) { const int s = 4 * NB * kb + 4 * i + g;
;             float part = q0 * cur[i].x + q1 * cur[i].y + q2 * cur[i].z + q3 * cur[i].w; part = sum16(part);
;             if (c == 0) zl[s] = part + bias; }
	v_mul_f32_e32 v19, v19, v116
	v_fmac_f32_e32 v19, v18, v114
	v_fmac_f32_e32 v19, v20, v115
	v_fmac_f32_e32 v19, v21, v113
	s_nop 1
	v_add_f32_dpp v18, v19, v19 quad_perm:[1,0,3,2] row_mask:0xf bank_mask:0xf bound_ctrl:1
	s_nop 1
	v_add_f32_dpp v18, v18, v18 quad_perm:[2,3,0,1] row_mask:0xf bank_mask:0xf bound_ctrl:1
	s_nop 1
	v_add_f32_dpp v18, v18, v18 row_ror:4 row_mask:0xf bank_mask:0xf bound_ctrl:1
	s_nop 1
	v_mov_b32_dpp v19, v18 row_ror:8 row_mask:0xf bank_mask:0xf bound_ctrl:1
	s_and_saveexec_b64 s[0:1], s[6:7]
	v_add_f32_e32 v18, v18, v19
	v_add_f32_e32 v18, v117, v18
	ds_write_b32 v96, v18 offset:176
	s_or_b64 exec, exec, s[0:1]
	v_mul_f32_e32 v18, v23, v116
	v_fmac_f32_e32 v18, v22, v114
	v_fmac_f32_e32 v18, v24, v115
	v_fmac_f32_e32 v18, v25, v113
	s_nop 1
	v_add_f32_dpp v18, v18, v18 quad_perm:[1,0,3,2] row_mask:0xf bank_mask:0xf bound_ctrl:1
	s_nop 1
	v_add_f32_dpp v18, v18, v18 quad_perm:[2,3,0,1] row_mask:0xf bank_mask:0xf bound_ctrl:1
	s_nop 1
	v_add_f32_dpp v18, v18, v18 row_ror:4 row_mask:0xf bank_mask:0xf bound_ctrl:1
	s_nop 1
	v_mov_b32_dpp v19, v18 row_ror:8 row_mask:0xf bank_mask:0xf bound_ctrl:1
	s_and_saveexec_b64 s[0:1], s[6:7]
	v_add_f32_e32 v18, v18, v19
	v_add_f32_e32 v18, v117, v18
	ds_write_b32 v96, v18 offset:192
	s_or_b64 exec, exec, s[0:1]
	s_waitcnt vmcnt(10)
	v_mul_f32_e32 v18, v39, v116
	v_fmac_f32_e32 v18, v38, v114
	v_fmac_f32_e32 v18, v40, v115
	v_fmac_f32_e32 v18, v41, v113
	s_nop 1
	v_add_f32_dpp v18, v18, v18 quad_perm:[1,0,3,2] row_mask:0xf bank_mask:0xf bound_ctrl:1
	s_nop 1
	v_add_f32_dpp v18, v18, v18 quad_perm:[2,3,0,1] row_mask:0xf bank_mask:0xf bound_ctrl:1
	s_nop 1
	v_add_f32_dpp v18, v18, v18 row_ror:4 row_mask:0xf bank_mask:0xf bound_ctrl:1
	s_nop 1
	v_mov_b32_dpp v19, v18 row_ror:8 row_mask:0xf bank_mask:0xf bound_ctrl:1
	s_and_saveexec_b64 s[0:1], s[6:7]
	v_add_f32_e32 v18, v18, v19
	v_add_f32_e32 v18, v117, v18
	ds_write_b32 v96, v18 offset:208
	s_or_b64 exec, exec, s[0:1]
	s_waitcnt vmcnt(9)
	v_mul_f32_e32 v18, v43, v116
	v_fmac_f32_e32 v18, v42, v114
	v_fmac_f32_e32 v18, v44, v115
	v_fmac_f32_e32 v18, v45, v113
	s_nop 1
	v_add_f32_dpp v18, v18, v18 quad_perm:[1,0,3,2] row_mask:0xf bank_mask:0xf bound_ctrl:1
	s_nop 1
	v_add_f32_dpp v18, v18, v18 quad_perm:[2,3,0,1] row_mask:0xf bank_mask:0xf bound_ctrl:1
	s_nop 1
	v_add_f32_dpp v18, v18, v18 row_ror:4 row_mask:0xf bank_mask:0xf bound_ctrl:1
	s_nop 1
	v_mov_b32_dpp v19, v18 row_ror:8 row_mask:0xf bank_mask:0xf bound_ctrl:1
	s_and_saveexec_b64 s[0:1], s[6:7]
	v_add_f32_e32 v18, v18, v19
	v_add_f32_e32 v18, v117, v18
	ds_write_b32 v96, v18 offset:224
	s_or_b64 exec, exec, s[0:1]
	s_waitcnt vmcnt(8)
	v_mul_f32_e32 v18, v31, v116
	v_fmac_f32_e32 v18, v30, v114
	v_fmac_f32_e32 v18, v32, v115
	v_fmac_f32_e32 v18, v33, v113
	s_nop 1
	v_add_f32_dpp v18, v18, v18 quad_perm:[1,0,3,2] row_mask:0xf bank_mask:0xf bound_ctrl:1
	s_nop 1
	v_add_f32_dpp v18, v18, v18 quad_perm:[2,3,0,1] row_mask:0xf bank_mask:0xf bound_ctrl:1
	s_nop 1
	v_add_f32_dpp v18, v18, v18 row_ror:4 row_mask:0xf bank_mask:0xf bound_ctrl:1
	s_nop 1
	v_mov_b32_dpp v19, v18 row_ror:8 row_mask:0xf bank_mask:0xf bound_ctrl:1
	s_and_saveexec_b64 s[0:1], s[6:7]
	v_add_f32_e32 v18, v18, v19
	v_add_f32_e32 v18, v117, v18
	ds_write_b32 v96, v18 offset:240
	s_or_b64 exec, exec, s[0:1]
	v_lshl_add_u64 v[18:19], v[66:67], 0, s[30:31]
	v_lshl_add_u64 v[20:21], v[18:19], 0, v[82:83]
	v_add_co_u32_e32 v22, vcc, 0x1000, v20
	v_mov_b32_e32 v91, v83
	s_nop 0
	v_addc_co_u32_e32 v23, vcc, 0, v21, vcc
	global_load_dwordx4 v[74:77], v[20:21], off
	global_load_dwordx4 v[66:69], v[22:23], off offset:2048
	v_add_co_u32_e32 v22, vcc, 0x3000, v20
	v_lshl_add_u64 v[18:19], v[18:19], 0, v[90:91]
	s_nop 0
	v_addc_co_u32_e32 v23, vcc, 0, v21, vcc
	v_add_co_u32_e32 v24, vcc, s43, v20
	s_nop 1
	v_addc_co_u32_e32 v25, vcc, 0, v21, vcc
	global_load_dwordx4 v[58:61], v[22:23], off
	global_load_dwordx4 v[50:53], v[24:25], off offset:2048
	v_add_co_u32_e32 v22, vcc, 0x7000, v20
	s_nop 1
	v_addc_co_u32_e32 v23, vcc, 0, v21, vcc
	global_load_dwordx4 v[46:49], v[18:19], off
	global_load_dwordx4 v[42:45], v[22:23], off offset:2048
	v_add_co_u32_e32 v18, vcc, 0x9000, v20
	s_nop 1
	v_addc_co_u32_e32 v19, vcc, 0, v21, vcc
	v_add_co_u32_e32 v20, vcc, 0xa000, v20
	s_nop 1
	v_addc_co_u32_e32 v21, vcc, 0, v21, vcc
	global_load_dwordx4 v[38:41], v[18:19], off
	global_load_dwordx4 v[34:37], v[20:21], off offset:2048
	s_waitcnt vmcnt(15)
	v_mul_f32_e32 v18, v79, v116
	v_fmac_f32_e32 v18, v78, v114
	v_fmac_f32_e32 v18, v80, v115
	v_fmac_f32_e32 v18, v81, v113
	s_nop 1
	v_add_f32_dpp v18, v18, v18 quad_perm:[1,0,3,2] row_mask:0xf bank_mask:0xf bound_ctrl:1
	s_nop 1
	v_add_f32_dpp v18, v18, v18 quad_perm:[2,3,0,1] row_mask:0xf bank_mask:0xf bound_ctrl:1
	s_nop 1
	v_add_f32_dpp v18, v18, v18 row_ror:4 row_mask:0xf bank_mask:0xf bound_ctrl:1
	s_nop 1
	v_mov_b32_dpp v19, v18 row_ror:8 row_mask:0xf bank_mask:0xf bound_ctrl:1
	s_and_saveexec_b64 s[0:1], s[6:7]
	v_add_f32_e32 v18, v18, v19
	v_add_f32_e32 v18, v117, v18
	ds_write_b32 v96, v18 offset:256
	s_or_b64 exec, exec, s[0:1]
	s_waitcnt vmcnt(14)
	v_mul_f32_e32 v18, v71, v116
	v_fmac_f32_e32 v18, v70, v114
	v_fmac_f32_e32 v18, v72, v115
	v_fmac_f32_e32 v18, v73, v113
	s_nop 1
	v_add_f32_dpp v18, v18, v18 quad_perm:[1,0,3,2] row_mask:0xf bank_mask:0xf bound_ctrl:1
	s_nop 1
	v_add_f32_dpp v18, v18, v18 quad_perm:[2,3,0,1] row_mask:0xf bank_mask:0xf bound_ctrl:1
	s_nop 1
	v_add_f32_dpp v18, v18, v18 row_ror:4 row_mask:0xf bank_mask:0xf bound_ctrl:1
	s_nop 1
	v_mov_b32_dpp v19, v18 row_ror:8 row_mask:0xf bank_mask:0xf bound_ctrl:1
	s_and_saveexec_b64 s[0:1], s[6:7]
	v_add_f32_e32 v18, v18, v19
	v_add_f32_e32 v18, v117, v18
	ds_write_b32 v96, v18 offset:272
	s_or_b64 exec, exec, s[0:1]
	s_waitcnt vmcnt(13)
; template <int NB>
; __device__ __forceinline__ void sb_decode_task(const Params& P, float* lds, int task) {
;     ...
;     for (int i = 0; i < NB; ++i) cur[i] = *(const float4*)(Kp + (size_t)(4 * i + g) * (SH * HD));
; #pragma unroll
;     for (int kb = 0; kb < NBT; ++kb) {
;         const float* np = (kb + 1 < NBT) ? Kp + (size_t)(4 * NB * (kb + 1)) * (SH * HD) : Vp;
; #pragma unroll
;         for (int i = 0; i < NB; ++i) nx[i] = *(const float4*)(np + (size_t)(4 * i + g) * (SH * HD));
; #pragma unroll
;         for (int i = 0; i < NB; ++i) { const int s = 4 * NB * kb + 4 * i + g;
;             float part = q0 * cur[i].x + q1 * cur[i].y + q2 * cur[i].z + q3 * cur[i].w; part = sum16(part);
;             if (c == 0) zl[s] = part + bias; }
;     ...
;     for (int vb = 0; vb < NBT; ++vb) {
;         if (vb + 1 < NBT) {
; #pragma unroll
;             for (int i = 0; i < NB; ++i) nx[i] = *(const float4*)(Vp + (size_t)(4 * NB * (vb + 1) + 4 * i + g) * (SH * HD)); }
	v_mul_f32_e32 v18, v63, v116
	v_fmac_f32_e32 v18, v62, v114
	v_fmac_f32_e32 v18, v64, v115
	v_fmac_f32_e32 v18, v65, v113
	s_nop 1
	v_add_f32_dpp v18, v18, v18 quad_perm:[1,0,3,2] row_mask:0xf bank_mask:0xf bound_ctrl:1
	s_nop 1
	v_add_f32_dpp v18, v18, v18 quad_perm:[2,3,0,1] row_mask:0xf bank_mask:0xf bound_ctrl:1
	s_nop 1
	v_add_f32_dpp v18, v18, v18 row_ror:4 row_mask:0xf bank_mask:0xf bound_ctrl:1
	s_nop 1
	v_mov_b32_dpp v19, v18 row_ror:8 row_mask:0xf bank_mask:0xf bound_ctrl:1
	s_and_saveexec_b64 s[0:1], s[6:7]
	v_add_f32_e32 v18, v18, v19
	v_add_f32_e32 v18, v117, v18
	ds_write_b32 v96, v18 offset:288
	s_or_b64 exec, exec, s[0:1]
	s_waitcnt vmcnt(12)
	v_mul_f32_e32 v18, v55, v116
	v_fmac_f32_e32 v18, v54, v114
	v_fmac_f32_e32 v18, v56, v115
	v_fmac_f32_e32 v18, v57, v113
	s_nop 1
	v_add_f32_dpp v18, v18, v18 quad_perm:[1,0,3,2] row_mask:0xf bank_mask:0xf bound_ctrl:1
	s_nop 1
	v_add_f32_dpp v18, v18, v18 quad_perm:[2,3,0,1] row_mask:0xf bank_mask:0xf bound_ctrl:1
	s_nop 1
	v_add_f32_dpp v18, v18, v18 row_ror:4 row_mask:0xf bank_mask:0xf bound_ctrl:1
	s_nop 1
	v_mov_b32_dpp v19, v18 row_ror:8 row_mask:0xf bank_mask:0xf bound_ctrl:1
	s_and_saveexec_b64 s[0:1], s[6:7]
	v_add_f32_e32 v18, v18, v19
	v_add_f32_e32 v18, v117, v18
	ds_write_b32 v96, v18 offset:304
	s_or_b64 exec, exec, s[0:1]
	s_waitcnt vmcnt(11)
	v_mul_f32_e32 v15, v15, v116
	v_fmac_f32_e32 v15, v14, v114
	v_fmac_f32_e32 v15, v16, v115
	v_fmac_f32_e32 v15, v17, v113
	s_nop 1
	v_add_f32_dpp v14, v15, v15 quad_perm:[1,0,3,2] row_mask:0xf bank_mask:0xf bound_ctrl:1
	s_nop 1
	v_add_f32_dpp v14, v14, v14 quad_perm:[2,3,0,1] row_mask:0xf bank_mask:0xf bound_ctrl:1
	s_nop 1
	v_add_f32_dpp v14, v14, v14 row_ror:4 row_mask:0xf bank_mask:0xf bound_ctrl:1
	s_nop 1
	v_mov_b32_dpp v15, v14 row_ror:8 row_mask:0xf bank_mask:0xf bound_ctrl:1
	s_and_saveexec_b64 s[0:1], s[6:7]
	v_add_f32_e32 v14, v14, v15
	v_add_f32_e32 v14, v117, v14
	ds_write_b32 v96, v14 offset:320
	s_or_b64 exec, exec, s[0:1]
	s_waitcnt vmcnt(10)
	v_mul_f32_e32 v11, v11, v116
	v_fmac_f32_e32 v11, v10, v114
	v_fmac_f32_e32 v11, v12, v115
	v_fmac_f32_e32 v11, v13, v113
	s_nop 1
	v_add_f32_dpp v10, v11, v11 quad_perm:[1,0,3,2] row_mask:0xf bank_mask:0xf bound_ctrl:1
	s_nop 1
	v_add_f32_dpp v10, v10, v10 quad_perm:[2,3,0,1] row_mask:0xf bank_mask:0xf bound_ctrl:1
	s_nop 1
	v_add_f32_dpp v10, v10, v10 row_ror:4 row_mask:0xf bank_mask:0xf bound_ctrl:1
	s_nop 1
	v_mov_b32_dpp v11, v10 row_ror:8 row_mask:0xf bank_mask:0xf bound_ctrl:1
	s_and_saveexec_b64 s[0:1], s[6:7]
	v_add_f32_e32 v10, v10, v11
	v_add_f32_e32 v10, v117, v10
	ds_write_b32 v96, v10 offset:336
	s_or_b64 exec, exec, s[0:1]
	s_waitcnt vmcnt(9)
	v_mul_f32_e32 v7, v7, v116
	v_fmac_f32_e32 v7, v6, v114
	v_fmac_f32_e32 v7, v8, v115
	v_fmac_f32_e32 v7, v9, v113
	s_nop 1
	v_add_f32_dpp v6, v7, v7 quad_perm:[1,0,3,2] row_mask:0xf bank_mask:0xf bound_ctrl:1
	s_nop 1
	v_add_f32_dpp v6, v6, v6 quad_perm:[2,3,0,1] row_mask:0xf bank_mask:0xf bound_ctrl:1
	s_nop 1
	v_add_f32_dpp v6, v6, v6 row_ror:4 row_mask:0xf bank_mask:0xf bound_ctrl:1
	s_nop 1
	v_mov_b32_dpp v7, v6 row_ror:8 row_mask:0xf bank_mask:0xf bound_ctrl:1
	s_and_saveexec_b64 s[0:1], s[6:7]
	v_add_f32_e32 v6, v6, v7
	v_add_f32_e32 v6, v117, v6
	ds_write_b32 v96, v6 offset:352
	s_or_b64 exec, exec, s[0:1]
	s_waitcnt vmcnt(8)
	v_mul_f32_e32 v3, v3, v116
	v_fmac_f32_e32 v3, v2, v114
	v_fmac_f32_e32 v3, v4, v115
	v_fmac_f32_e32 v3, v5, v113
	s_nop 1
	v_add_f32_dpp v2, v3, v3 quad_perm:[1,0,3,2] row_mask:0xf bank_mask:0xf bound_ctrl:1
	s_nop 1
	v_add_f32_dpp v2, v2, v2 quad_perm:[2,3,0,1] row_mask:0xf bank_mask:0xf bound_ctrl:1
	s_nop 1
	v_add_f32_dpp v2, v2, v2 row_ror:4 row_mask:0xf bank_mask:0xf bound_ctrl:1
	s_nop 1
	v_mov_b32_dpp v3, v2 row_ror:8 row_mask:0xf bank_mask:0xf bound_ctrl:1
	s_and_saveexec_b64 s[0:1], s[6:7]
	v_add_f32_e32 v2, v2, v3
	v_add_f32_e32 v2, v117, v2
	ds_write_b32 v96, v2 offset:368
	s_or_b64 exec, exec, s[0:1]
	v_lshlrev_b64 v[2:3], 6, v[92:93]
	v_lshl_add_u64 v[6:7], v[2:3], 2, v[86:87]
	v_lshl_add_u64 v[54:55], v[6:7], 0, v[82:83]
	v_add_co_u32_e32 v2, vcc, 0x1000, v54
	v_mov_b32_e32 v91, v83
	s_nop 0
	v_addc_co_u32_e32 v3, vcc, 0, v55, vcc
	v_add_co_u32_e32 v8, vcc, 0x3000, v54
	v_lshl_add_u64 v[10:11], v[6:7], 0, v[90:91]
	s_nop 0
	v_addc_co_u32_e32 v9, vcc, 0, v55, vcc
	v_add_co_u32_e32 v14, vcc, s43, v54
	global_load_dwordx4 v[30:33], v[54:55], off
	s_nop 0
	global_load_dwordx4 v[2:5], v[2:3], off offset:2048
	v_addc_co_u32_e32 v15, vcc, 0, v55, vcc
	v_add_co_u32_e32 v18, vcc, 0x7000, v54
	global_load_dwordx4 v[6:9], v[8:9], off
	s_nop 0
	global_load_dwordx4 v[10:13], v[10:11], off
	v_addc_co_u32_e32 v19, vcc, 0, v55, vcc
	v_add_co_u32_e32 v22, vcc, 0x9000, v54
	global_load_dwordx4 v[14:17], v[14:15], off offset:2048
	s_nop 0
	global_load_dwordx4 v[18:21], v[18:19], off offset:2048
	v_addc_co_u32_e32 v23, vcc, 0, v55, vcc
	v_add_co_u32_e32 v26, vcc, 0xa000, v54
	s_waitcnt vmcnt(13)
	v_mul_f32_e32 v56, v75, v116
	v_addc_co_u32_e32 v27, vcc, 0, v55, vcc
	global_load_dwordx4 v[22:25], v[22:23], off
	s_nop 0
	global_load_dwordx4 v[26:29], v[26:27], off offset:2048
	v_fmac_f32_e32 v56, v74, v114
	v_fmac_f32_e32 v56, v76, v115
	v_fmac_f32_e32 v56, v77, v113
	s_nop 1
	v_add_f32_dpp v56, v56, v56 quad_perm:[1,0,3,2] row_mask:0xf bank_mask:0xf bound_ctrl:1
	s_nop 1
	v_add_f32_dpp v56, v56, v56 quad_perm:[2,3,0,1] row_mask:0xf bank_mask:0xf bound_ctrl:1
	s_nop 1
	v_add_f32_dpp v56, v56, v56 row_ror:4 row_mask:0xf bank_mask:0xf bound_ctrl:1
	s_nop 1
	v_mov_b32_dpp v57, v56 row_ror:8 row_mask:0xf bank_mask:0xf bound_ctrl:1
	s_and_saveexec_b64 s[0:1], s[6:7]
	v_add_f32_e32 v56, v56, v57
	v_add_f32_e32 v56, v117, v56
	ds_write_b32 v96, v56 offset:384
	s_or_b64 exec, exec, s[0:1]
	s_waitcnt vmcnt(14)
; template <int NB>
; __device__ __forceinline__ void sb_decode_task(const Params& P, float* lds, int task) {
;     ...
;         for (int i = 0; i < NB; ++i) { const int s = 4 * NB * kb + 4 * i + g;
;             float part = q0 * cur[i].x + q1 * cur[i].y + q2 * cur[i].z + q3 * cur[i].w; part = sum16(part);
;             if (c == 0) zl[s] = part + bias; }
; #pragma unroll
;         for (int i = 0; i < NB; ++i) cur[i] = nx[i];
;     }
;     asm volatile("s_waitcnt lgkmcnt(0)" ::: "memory");
;     __builtin_amdgcn_wave_barrier();
;     const float z0 = zl[2 * lane], z1 = zl[2 * lane + 1];
	v_mul_f32_e32 v56, v67, v116
	v_fmac_f32_e32 v56, v66, v114
	v_fmac_f32_e32 v56, v68, v115
	v_fmac_f32_e32 v56, v69, v113
	s_nop 1
	v_add_f32_dpp v56, v56, v56 quad_perm:[1,0,3,2] row_mask:0xf bank_mask:0xf bound_ctrl:1
	s_nop 1
	v_add_f32_dpp v56, v56, v56 quad_perm:[2,3,0,1] row_mask:0xf bank_mask:0xf bound_ctrl:1
	s_nop 1
	v_add_f32_dpp v56, v56, v56 row_ror:4 row_mask:0xf bank_mask:0xf bound_ctrl:1
	s_nop 1
	v_mov_b32_dpp v57, v56 row_ror:8 row_mask:0xf bank_mask:0xf bound_ctrl:1
	s_and_saveexec_b64 s[0:1], s[6:7]
	v_add_f32_e32 v56, v56, v57
	v_add_f32_e32 v56, v117, v56
	ds_write_b32 v96, v56 offset:400
	s_or_b64 exec, exec, s[0:1]
	s_waitcnt vmcnt(13)
	v_mul_f32_e32 v56, v59, v116
	v_fmac_f32_e32 v56, v58, v114
	v_fmac_f32_e32 v56, v60, v115
	v_fmac_f32_e32 v56, v61, v113
	s_nop 1
	v_add_f32_dpp v56, v56, v56 quad_perm:[1,0,3,2] row_mask:0xf bank_mask:0xf bound_ctrl:1
	s_nop 1
	v_add_f32_dpp v56, v56, v56 quad_perm:[2,3,0,1] row_mask:0xf bank_mask:0xf bound_ctrl:1
	s_nop 1
	v_add_f32_dpp v56, v56, v56 row_ror:4 row_mask:0xf bank_mask:0xf bound_ctrl:1
	s_nop 1
	v_mov_b32_dpp v57, v56 row_ror:8 row_mask:0xf bank_mask:0xf bound_ctrl:1
	s_and_saveexec_b64 s[0:1], s[6:7]
	v_add_f32_e32 v56, v56, v57
	v_add_f32_e32 v56, v117, v56
	ds_write_b32 v96, v56 offset:416
	s_or_b64 exec, exec, s[0:1]
	s_waitcnt vmcnt(12)
	v_mul_f32_e32 v51, v51, v116
	v_fmac_f32_e32 v51, v50, v114
	v_fmac_f32_e32 v51, v52, v115
	v_fmac_f32_e32 v51, v53, v113
	s_nop 1
	v_add_f32_dpp v50, v51, v51 quad_perm:[1,0,3,2] row_mask:0xf bank_mask:0xf bound_ctrl:1
	s_nop 1
	v_add_f32_dpp v50, v50, v50 quad_perm:[2,3,0,1] row_mask:0xf bank_mask:0xf bound_ctrl:1
	s_nop 1
	v_add_f32_dpp v50, v50, v50 row_ror:4 row_mask:0xf bank_mask:0xf bound_ctrl:1
	s_nop 1
	v_mov_b32_dpp v51, v50 row_ror:8 row_mask:0xf bank_mask:0xf bound_ctrl:1
	s_and_saveexec_b64 s[0:1], s[6:7]
	v_add_f32_e32 v50, v50, v51
	v_add_f32_e32 v50, v117, v50
	ds_write_b32 v96, v50 offset:432
	s_or_b64 exec, exec, s[0:1]
	s_waitcnt vmcnt(11)
	v_mul_f32_e32 v47, v47, v116
	v_fmac_f32_e32 v47, v46, v114
	v_fmac_f32_e32 v47, v48, v115
	v_fmac_f32_e32 v47, v49, v113
	s_nop 1
	v_add_f32_dpp v46, v47, v47 quad_perm:[1,0,3,2] row_mask:0xf bank_mask:0xf bound_ctrl:1
	s_nop 1
	v_add_f32_dpp v46, v46, v46 quad_perm:[2,3,0,1] row_mask:0xf bank_mask:0xf bound_ctrl:1
	s_nop 1
	v_add_f32_dpp v46, v46, v46 row_ror:4 row_mask:0xf bank_mask:0xf bound_ctrl:1
	s_nop 1
	v_mov_b32_dpp v47, v46 row_ror:8 row_mask:0xf bank_mask:0xf bound_ctrl:1
	s_and_saveexec_b64 s[0:1], s[6:7]
	v_add_f32_e32 v46, v46, v47
	v_add_f32_e32 v46, v117, v46
	ds_write_b32 v96, v46 offset:448
	s_or_b64 exec, exec, s[0:1]
	s_waitcnt vmcnt(10)
	v_mul_f32_e32 v43, v43, v116
	v_fmac_f32_e32 v43, v42, v114
	v_fmac_f32_e32 v43, v44, v115
	v_fmac_f32_e32 v43, v45, v113
	s_nop 1
	v_add_f32_dpp v42, v43, v43 quad_perm:[1,0,3,2] row_mask:0xf bank_mask:0xf bound_ctrl:1
	s_nop 1
	v_add_f32_dpp v42, v42, v42 quad_perm:[2,3,0,1] row_mask:0xf bank_mask:0xf bound_ctrl:1
	s_nop 1
	v_add_f32_dpp v42, v42, v42 row_ror:4 row_mask:0xf bank_mask:0xf bound_ctrl:1
	s_nop 1
	v_mov_b32_dpp v43, v42 row_ror:8 row_mask:0xf bank_mask:0xf bound_ctrl:1
	s_and_saveexec_b64 s[0:1], s[6:7]
	v_add_f32_e32 v42, v42, v43
	v_add_f32_e32 v42, v117, v42
	ds_write_b32 v96, v42 offset:464
	s_or_b64 exec, exec, s[0:1]
	s_waitcnt vmcnt(9)
	v_mul_f32_e32 v39, v39, v116
	v_fmac_f32_e32 v39, v38, v114
	v_fmac_f32_e32 v39, v40, v115
	v_fmac_f32_e32 v39, v41, v113
	s_nop 1
	v_add_f32_dpp v38, v39, v39 quad_perm:[1,0,3,2] row_mask:0xf bank_mask:0xf bound_ctrl:1
	s_nop 1
	v_add_f32_dpp v38, v38, v38 quad_perm:[2,3,0,1] row_mask:0xf bank_mask:0xf bound_ctrl:1
	s_nop 1
	v_add_f32_dpp v38, v38, v38 row_ror:4 row_mask:0xf bank_mask:0xf bound_ctrl:1
	s_nop 1
	v_mov_b32_dpp v39, v38 row_ror:8 row_mask:0xf bank_mask:0xf bound_ctrl:1
	s_and_saveexec_b64 s[0:1], s[6:7]
	v_add_f32_e32 v38, v38, v39
	v_add_f32_e32 v38, v117, v38
	ds_write_b32 v96, v38 offset:480
	s_or_b64 exec, exec, s[0:1]
	s_waitcnt vmcnt(8)
	v_mul_f32_e32 v35, v35, v116
	v_fmac_f32_e32 v35, v34, v114
	v_fmac_f32_e32 v35, v36, v115
	v_fmac_f32_e32 v35, v37, v113
	s_nop 1
	v_add_f32_dpp v34, v35, v35 quad_perm:[1,0,3,2] row_mask:0xf bank_mask:0xf bound_ctrl:1
	s_nop 1
	v_add_f32_dpp v34, v34, v34 quad_perm:[2,3,0,1] row_mask:0xf bank_mask:0xf bound_ctrl:1
	s_nop 1
	v_add_f32_dpp v34, v34, v34 row_ror:4 row_mask:0xf bank_mask:0xf bound_ctrl:1
	s_nop 1
	v_mov_b32_dpp v35, v34 row_ror:8 row_mask:0xf bank_mask:0xf bound_ctrl:1
	s_and_saveexec_b64 s[0:1], s[6:7]
	v_add_f32_e32 v34, v34, v35
	v_add_f32_e32 v34, v117, v34
	ds_write_b32 v96, v34 offset:496
	s_or_b64 exec, exec, s[0:1]
	s_waitcnt lgkmcnt(0)
	ds_read_b64 v[34:35], v97
	s_waitcnt lgkmcnt(0)
; __device__ __forceinline__ float softplus2_(float z2) { return fmaxf(z2, 0.f) + log1pf(exp2f(-fabsf(z2))) * LOG2E; }
; template <int NB>
; __device__ __forceinline__ void sb_decode_task(const Params& P, float* lds, int task) {
;     ...
;     const float sp0 = softplus2_(z0), sp1 = softplus2_(z1);
	v_cmp_gt_f32_e64 vcc, |v34|, s49
	s_nop 1
	v_cndmask_b32_e32 v37, 0, v101, vcc
	v_sub_f32_e64 v37, v37, |v34|
	v_exp_f32_e32 v37, v37
	v_max_f32_e32 v36, v34, v34
	v_max_f32_e32 v38, 0, v36
	v_cndmask_b32_e32 v36, 0, v100, vcc
	v_ldexp_f32 v39, v37, v36
	v_add_f32_e32 v40, 1.0, v39
	v_add_f32_e32 v36, -1.0, v40
	v_sub_f32_e32 v37, v36, v40
	v_add_f32_e32 v37, 1.0, v37
	v_sub_f32_e32 v36, v39, v36
	v_add_f32_e32 v41, v36, v37
	v_frexp_mant_f32_e32 v36, v40
	v_cmp_gt_f32_e32 vcc, s50, v36
	v_cvt_f64_f32_e32 v[36:37], v40
	v_frexp_exp_i32_f64_e32 v36, v[36:37]
	v_subbrev_co_u32_e32 v36, vcc, 0, v36, vcc
	v_sub_u32_e32 v37, 0, v36
	v_ldexp_f32 v40, v40, v37
	v_ldexp_f32 v37, v41, v37
	v_add_f32_e32 v41, -1.0, v40
	v_add_f32_e32 v42, 1.0, v41
	v_sub_f32_e32 v42, v40, v42
	v_add_f32_e32 v42, v37, v42
	v_add_f32_e32 v43, v41, v42
	v_sub_f32_e32 v41, v41, v43
	v_add_f32_e32 v41, v42, v41
	v_add_f32_e32 v42, 1.0, v40
	v_add_f32_e32 v44, -1.0, v42
	v_sub_f32_e32 v40, v40, v44
	v_add_f32_e32 v37, v37, v40
	v_add_f32_e32 v40, v42, v37
	v_sub_f32_e32 v42, v42, v40
	v_add_f32_e32 v37, v37, v42
	v_rcp_f32_e32 v42, v40
	v_cvt_f32_i32_e32 v36, v36
	v_cmp_neq_f32_e32 vcc, s52, v39
	v_mul_f32_e32 v44, v43, v42
	v_mul_f32_e32 v45, v40, v44
	v_fma_f32 v46, v44, v40, -v45
	v_fmac_f32_e32 v46, v44, v37
	v_add_f32_e32 v47, v45, v46
	v_sub_f32_e32 v48, v43, v47
	v_sub_f32_e32 v43, v43, v48
	v_sub_f32_e32 v45, v47, v45
	v_sub_f32_e32 v43, v43, v47
	v_add_f32_e32 v41, v41, v43
	v_sub_f32_e32 v43, v45, v46
	v_add_f32_e32 v41, v43, v41
	v_add_f32_e32 v43, v48, v41
	v_mul_f32_e32 v45, v42, v43
	v_mul_f32_e32 v46, v40, v45
	v_fma_f32 v40, v45, v40, -v46
	v_fmac_f32_e32 v40, v45, v37
	v_sub_f32_e32 v37, v48, v43
	v_add_f32_e32 v37, v41, v37
	v_add_f32_e32 v41, v46, v40
	v_sub_f32_e32 v47, v43, v41
	v_sub_f32_e32 v43, v43, v47
	v_sub_f32_e32 v46, v41, v46
	v_sub_f32_e32 v41, v43, v41
	v_add_f32_e32 v37, v37, v41
	v_sub_f32_e32 v40, v46, v40
	v_add_f32_e32 v37, v40, v37
	v_add_f32_e32 v40, v44, v45
	v_add_f32_e32 v37, v47, v37
	v_sub_f32_e32 v41, v40, v44
	v_mul_f32_e32 v37, v42, v37
	v_sub_f32_e32 v41, v45, v41
	v_add_f32_e32 v37, v41, v37
	v_mul_f32_e32 v44, 0x3f317218, v36
	v_add_f32_e32 v41, v40, v37
	v_fma_f32 v45, v36, s51, -v44
	v_mul_f32_e32 v42, v41, v41
	v_fmac_f32_e32 v45, 0xb102e308, v36
	v_sub_f32_e32 v36, v41, v40
	v_fmamk_f32 v43, v42, 0x3e9b6dac, v98
	v_sub_f32_e32 v36, v37, v36
	v_add_f32_e32 v37, v44, v45
	v_fmaak_f32 v43, v42, v43, 0x3f2aaada
	v_sub_f32_e32 v40, v37, v44
	v_ldexp_f32 v44, v41, 1
	v_mul_f32_e32 v41, v41, v42
	v_mul_f32_e32 v41, v41, v43
	v_add_f32_e32 v42, v44, v41
	v_sub_f32_e32 v43, v42, v44
	v_ldexp_f32 v36, v36, 1
	v_sub_f32_e32 v41, v41, v43
	v_add_f32_e32 v36, v36, v41
	v_add_f32_e32 v41, v42, v36
	v_sub_f32_e32 v42, v41, v42
	v_sub_f32_e32 v36, v36, v42
	v_add_f32_e32 v42, v37, v41
	v_sub_f32_e32 v43, v42, v37
	v_sub_f32_e32 v44, v42, v43
	v_sub_f32_e32 v40, v45, v40
	v_sub_f32_e32 v37, v37, v44
	v_sub_f32_e32 v41, v41, v43
	v_add_f32_e32 v37, v41, v37
	v_add_f32_e32 v41, v40, v36
	v_sub_f32_e32 v43, v41, v40
	v_sub_f32_e32 v44, v41, v43
	v_sub_f32_e32 v40, v40, v44
	v_sub_f32_e32 v36, v36, v43
	v_add_f32_e32 v37, v41, v37
	v_add_f32_e32 v36, v36, v40
	v_add_f32_e32 v40, v42, v37
	v_sub_f32_e32 v41, v40, v42
	v_sub_f32_e32 v37, v37, v41
	v_add_f32_e32 v36, v36, v37
	v_add_f32_e32 v36, v40, v36
	v_cndmask_b32_e32 v36, v102, v36, vcc
	v_cmp_lt_f32_e64 vcc, |v39|, s53
	s_nop 1
	v_cndmask_b32_e32 v36, v36, v39, vcc
	v_cmp_gt_f32_e64 vcc, |v35|, s49
	v_fmac_f32_e32 v38, 0x3fb8aa3b, v36
	v_max_f32_e32 v36, v35, v35
	v_cndmask_b32_e32 v37, 0, v101, vcc
	v_sub_f32_e64 v37, v37, |v35|
	v_exp_f32_e32 v37, v37
	v_max_f32_e32 v39, 0, v36
	v_cndmask_b32_e32 v36, 0, v100, vcc
	v_sub_f32_e32 v34, v34, v38
	v_ldexp_f32 v40, v37, v36
	v_add_f32_e32 v41, 1.0, v40
	v_add_f32_e32 v36, -1.0, v41
	v_sub_f32_e32 v37, v36, v41
	v_add_f32_e32 v37, 1.0, v37
	v_sub_f32_e32 v36, v40, v36
	v_add_f32_e32 v42, v36, v37
	v_frexp_mant_f32_e32 v36, v41
	v_cmp_gt_f32_e32 vcc, s50, v36
	v_cvt_f64_f32_e32 v[36:37], v41
	v_frexp_exp_i32_f64_e32 v36, v[36:37]
	v_subbrev_co_u32_e32 v36, vcc, 0, v36, vcc
	v_sub_u32_e32 v37, 0, v36
	v_ldexp_f32 v41, v41, v37
	v_ldexp_f32 v37, v42, v37
	v_add_f32_e32 v42, -1.0, v41
	v_add_f32_e32 v43, 1.0, v42
	v_sub_f32_e32 v43, v41, v43
	v_add_f32_e32 v43, v37, v43
	v_add_f32_e32 v44, v42, v43
	v_sub_f32_e32 v42, v42, v44
	v_add_f32_e32 v42, v43, v42
	v_add_f32_e32 v43, 1.0, v41
	v_add_f32_e32 v45, -1.0, v43
	v_sub_f32_e32 v41, v41, v45
	v_add_f32_e32 v37, v37, v41
	v_add_f32_e32 v41, v43, v37
	v_sub_f32_e32 v43, v43, v41
	v_add_f32_e32 v37, v37, v43
	v_rcp_f32_e32 v43, v41
	v_cvt_f32_i32_e32 v36, v36
	v_cmp_neq_f32_e32 vcc, s52, v40
	v_mul_f32_e32 v45, v44, v43
	v_mul_f32_e32 v46, v41, v45
	v_fma_f32 v47, v45, v41, -v46
	v_fmac_f32_e32 v47, v45, v37
	v_add_f32_e32 v48, v46, v47
	v_sub_f32_e32 v49, v44, v48
	v_sub_f32_e32 v44, v44, v49
	v_sub_f32_e32 v46, v48, v46
	v_sub_f32_e32 v44, v44, v48
	v_add_f32_e32 v42, v42, v44
	v_sub_f32_e32 v44, v46, v47
	v_add_f32_e32 v42, v44, v42
	v_add_f32_e32 v44, v49, v42
	v_mul_f32_e32 v46, v43, v44
	v_mul_f32_e32 v47, v41, v46
	v_fma_f32 v41, v46, v41, -v47
	v_fmac_f32_e32 v41, v46, v37
	v_sub_f32_e32 v37, v49, v44
	v_add_f32_e32 v37, v42, v37
	v_add_f32_e32 v42, v47, v41
	v_sub_f32_e32 v48, v44, v42
	v_sub_f32_e32 v44, v44, v48
	v_sub_f32_e32 v47, v42, v47
	v_sub_f32_e32 v42, v44, v42
	v_add_f32_e32 v37, v37, v42
	v_sub_f32_e32 v41, v47, v41
	v_add_f32_e32 v37, v41, v37
	v_add_f32_e32 v41, v45, v46
	v_add_f32_e32 v37, v48, v37
	v_sub_f32_e32 v42, v41, v45
	v_mul_f32_e32 v37, v43, v37
; __device__ __forceinline__ float softplus2_(float z2) { return fmaxf(z2, 0.f) + log1pf(exp2f(-fabsf(z2))) * LOG2E; }
; template <int NB>
; __device__ __forceinline__ void sb_decode_task(const Params& P, float* lds, int task) {
;     ...
;     const float sp0 = softplus2_(z0), sp1 = softplus2_(z1);
;     float incl = sp0 + sp1;
; #pragma unroll
;     for (int off = 1; off < 64; off <<= 1) { const float t = __shfl_down(incl, off); if (lane + off < 64) incl += t; }
;     const float excl = incl - (sp0 + sp1);
;     wl[2 * lane] = exp2f(z0 - sp0 - (excl + sp1));
;     wl[2 * lane + 1] = exp2f(z1 - sp1 - excl);
;     const float Ltot = __shfl(incl, 0);
;     asm volatile("s_waitcnt lgkmcnt(0)" ::: "memory");
;     __builtin_amdgcn_wave_barrier();
;     float4 o4 = make_float4(0.f, 0.f, 0.f, 0.f);
; #pragma unroll
;     for (int vb = 0; vb < NBT; ++vb) {
;         if (vb + 1 < NBT) {
; #pragma unroll
;             for (int i = 0; i < NB; ++i) nx[i] = *(const float4*)(Vp + (size_t)(4 * NB * (vb + 1) + 4 * i + g) * (SH * HD)); }
; #pragma unroll
;         for (int i = 0; i < NB; ++i) { const float w = wl[4 * NB * vb + 4 * i + g]; o4.x += w * cur[i].x; o4.y += w * cur[i].y; o4.z += w * cur[i].z; o4.w += w * cur[i].w; }
	v_sub_f32_e32 v42, v46, v42
	v_add_f32_e32 v37, v42, v37
	v_mul_f32_e32 v45, 0x3f317218, v36
	v_add_f32_e32 v42, v41, v37
	v_fma_f32 v46, v36, s51, -v45
	v_mul_f32_e32 v43, v42, v42
	v_fmac_f32_e32 v46, 0xb102e308, v36
	v_sub_f32_e32 v36, v42, v41
	v_fmamk_f32 v44, v43, 0x3e9b6dac, v98
	v_sub_f32_e32 v36, v37, v36
	v_add_f32_e32 v37, v45, v46
	v_fmaak_f32 v44, v43, v44, 0x3f2aaada
	v_sub_f32_e32 v41, v37, v45
	v_ldexp_f32 v45, v42, 1
	v_mul_f32_e32 v42, v42, v43
	v_mul_f32_e32 v42, v42, v44
	v_add_f32_e32 v43, v45, v42
	v_sub_f32_e32 v44, v43, v45
	v_ldexp_f32 v36, v36, 1
	v_sub_f32_e32 v42, v42, v44
	v_add_f32_e32 v36, v36, v42
	v_add_f32_e32 v42, v43, v36
	v_sub_f32_e32 v43, v42, v43
	v_sub_f32_e32 v36, v36, v43
	v_add_f32_e32 v43, v37, v42
	v_sub_f32_e32 v44, v43, v37
	v_sub_f32_e32 v45, v43, v44
	v_sub_f32_e32 v41, v46, v41
	v_sub_f32_e32 v37, v37, v45
	v_sub_f32_e32 v42, v42, v44
	v_add_f32_e32 v37, v42, v37
	v_add_f32_e32 v42, v41, v36
	v_sub_f32_e32 v44, v42, v41
	v_sub_f32_e32 v45, v42, v44
	v_sub_f32_e32 v41, v41, v45
	v_sub_f32_e32 v36, v36, v44
	v_add_f32_e32 v37, v42, v37
	v_add_f32_e32 v36, v36, v41
	v_add_f32_e32 v41, v43, v37
	v_sub_f32_e32 v42, v41, v43
	v_sub_f32_e32 v37, v37, v42
	v_add_f32_e32 v36, v36, v37
	v_add_f32_e32 v36, v41, v36
	v_cndmask_b32_e32 v36, v102, v36, vcc
	v_cmp_lt_f32_e64 vcc, |v40|, s53
	s_nop 1
	v_cndmask_b32_e32 v36, v36, v40, vcc
	v_fmac_f32_e32 v39, 0x3fb8aa3b, v36
	v_add_f32_e32 v36, v38, v39
	ds_bpermute_b32 v37, v106, v36
	v_sub_f32_e32 v35, v35, v39
	s_waitcnt lgkmcnt(0)
	v_add_f32_e32 v37, v36, v37
	v_cndmask_b32_e64 v37, v37, v36, s[8:9]
	ds_bpermute_b32 v40, v107, v37
	s_waitcnt lgkmcnt(0)
	v_add_f32_e32 v40, v37, v40
	v_cndmask_b32_e64 v37, v37, v40, s[10:11]
	ds_bpermute_b32 v40, v108, v37
	s_waitcnt lgkmcnt(0)
	v_add_f32_e32 v40, v37, v40
	v_cndmask_b32_e64 v37, v37, v40, s[12:13]
	ds_bpermute_b32 v40, v109, v37
	s_waitcnt lgkmcnt(0)
	v_add_f32_e32 v40, v37, v40
	v_cndmask_b32_e64 v37, v37, v40, s[14:15]
	ds_bpermute_b32 v40, v110, v37
	s_waitcnt lgkmcnt(0)
	v_add_f32_e32 v40, v37, v40
	v_cndmask_b32_e64 v37, v37, v40, s[16:17]
	ds_bpermute_b32 v40, v111, v37
	s_waitcnt lgkmcnt(0)
	v_add_f32_e32 v40, v37, v40
	v_cndmask_b32_e64 v44, v37, v40, s[18:19]
	v_sub_f32_e32 v36, v44, v36
	v_add_f32_e32 v37, v39, v36
	v_sub_f32_e32 v34, v34, v37
	v_cmp_gt_f32_e32 vcc, s54, v34
	v_sub_f32_e32 v35, v35, v36
	s_nop 0
	v_cndmask_b32_e32 v37, 0, v101, vcc
	v_add_f32_e32 v34, v34, v37
	v_cndmask_b32_e32 v37, 0, v100, vcc
	v_cmp_gt_f32_e32 vcc, s54, v35
	v_exp_f32_e32 v34, v34
	s_nop 0
	v_cndmask_b32_e32 v36, 0, v101, vcc
	v_add_f32_e32 v35, v35, v36
	v_exp_f32_e32 v35, v35
	v_cndmask_b32_e32 v36, 0, v100, vcc
	v_ldexp_f32 v34, v34, v37
	v_ldexp_f32 v35, v35, v36
	ds_write_b64 v97, v[34:35] offset:512
	s_waitcnt lgkmcnt(0)
	ds_read2_b32 v[34:35], v96 offset0:128 offset1:132
	ds_read2_b32 v[42:43], v96 offset0:136 offset1:140
	ds_read2_b32 v[66:67], v96 offset0:144 offset1:148
	ds_read2_b32 v[68:69], v96 offset0:152 offset1:156
	ds_read2_b32 v[74:75], v96 offset0:160 offset1:164
	ds_read2_b32 v[76:77], v96 offset0:168 offset1:172
	ds_read2_b32 v[38:39], v96 offset0:176 offset1:180
	ds_read2_b32 v[40:41], v96 offset0:184 offset1:188
	s_waitcnt vmcnt(7) lgkmcnt(7)
	v_pk_fma_f32 v[70:71], v[30:31], v[34:35], 0 op_sel_hi:[1,0,0]
	v_add_co_u32_e32 v30, vcc, s55, v54
	v_pk_fma_f32 v[72:73], v[32:33], v[34:35], 0 op_sel_hi:[1,0,0]
	s_nop 0
	v_addc_co_u32_e32 v31, vcc, 0, v55, vcc
	v_add_co_u32_e32 v34, vcc, s83, v54
	v_mov_b32_e32 v64, v35
	s_nop 0
	v_addc_co_u32_e32 v35, vcc, 0, v55, vcc
	v_add_co_u32_e32 v46, vcc, s86, v54
	s_waitcnt vmcnt(6)
	v_pk_fma_f32 v[2:3], v[2:3], v[64:65], v[70:71] op_sel_hi:[1,0,1]
	v_addc_co_u32_e32 v47, vcc, 0, v55, vcc
	v_add_co_u32_e32 v50, vcc, s87, v54
	global_load_dwordx4 v[46:49], v[46:47], off
	s_nop 0
	v_addc_co_u32_e32 v51, vcc, 0, v55, vcc
	v_add_co_u32_e32 v56, vcc, s88, v54
	global_load_dwordx4 v[50:53], v[50:51], off offset:2048
	s_nop 0
	v_addc_co_u32_e32 v57, vcc, 0, v55, vcc
	v_add_co_u32_e32 v60, vcc, s89, v54
	global_load_dwordx4 v[56:59], v[56:57], off
	s_nop 0
	v_addc_co_u32_e32 v61, vcc, 0, v55, vcc
	global_load_dwordx4 v[60:63], v[60:61], off offset:2048
	s_waitcnt lgkmcnt(6)
	v_mov_b32_e32 v78, v43
	s_waitcnt vmcnt(9)
	v_pk_fma_f32 v[2:3], v[6:7], v[42:43], v[2:3] op_sel_hi:[1,0,1]
	s_waitcnt lgkmcnt(5)
	v_mov_b32_e32 v80, v67
	s_waitcnt vmcnt(7)
	v_pk_fma_f32 v[2:3], v[14:15], v[78:79], v[2:3] op_sel_hi:[1,0,1]
	s_waitcnt lgkmcnt(4)
	v_mov_b32_e32 v92, v69
	v_pk_fma_f32 v[2:3], v[10:11], v[66:67], v[2:3] op_sel_hi:[1,0,1]
	s_waitcnt lgkmcnt(3)
	v_mov_b32_e32 v10, v75
	s_waitcnt vmcnt(6)
	v_pk_fma_f32 v[2:3], v[18:19], v[80:81], v[2:3] op_sel_hi:[1,0,1]
	s_waitcnt lgkmcnt(2)
	v_mov_b32_e32 v14, v77
	s_waitcnt vmcnt(5)
	v_pk_fma_f32 v[2:3], v[22:23], v[68:69], v[2:3] op_sel_hi:[1,0,1]
	global_load_dwordx4 v[30:33], v[30:31], off
	s_waitcnt vmcnt(5)
	v_pk_fma_f32 v[2:3], v[26:27], v[92:93], v[2:3] op_sel_hi:[1,0,1]
	global_load_dwordx4 v[34:37], v[34:35], off offset:2048
	s_waitcnt vmcnt(5)
	v_pk_fma_f32 v[2:3], v[46:47], v[74:75], v[2:3] op_sel_hi:[1,0,1]
	s_waitcnt vmcnt(4)
	v_pk_fma_f32 v[2:3], v[50:51], v[10:11], v[2:3] op_sel_hi:[1,0,1]
	s_waitcnt vmcnt(3)
	v_pk_fma_f32 v[2:3], v[56:57], v[76:77], v[2:3] op_sel_hi:[1,0,1]
	s_waitcnt vmcnt(2)
	v_pk_fma_f32 v[6:7], v[60:61], v[14:15], v[2:3] op_sel_hi:[1,0,1]
	v_pk_fma_f32 v[2:3], v[4:5], v[64:65], v[72:73] op_sel_hi:[1,0,1]
	v_add_co_u32_e32 v4, vcc, s90, v54
	v_pk_fma_f32 v[2:3], v[8:9], v[42:43], v[2:3] op_sel_hi:[1,0,1]
	s_nop 0
	v_addc_co_u32_e32 v5, vcc, 0, v55, vcc
	v_pk_fma_f32 v[2:3], v[16:17], v[78:79], v[2:3] op_sel_hi:[1,0,1]
	s_waitcnt lgkmcnt(0)
; template <int NB>
; __device__ __forceinline__ void sb_decode_task(const Params& P, float* lds, int task) {
;     ...
;     for (int vb = 0; vb < NBT; ++vb) {
;         if (vb + 1 < NBT) {
; #pragma unroll
;             for (int i = 0; i < NB; ++i) nx[i] = *(const float4*)(Vp + (size_t)(4 * NB * (vb + 1) + 4 * i + g) * (SH * HD)); }
; #pragma unroll
;         for (int i = 0; i < NB; ++i) { const float w = wl[4 * NB * vb + 4 * i + g]; o4.x += w * cur[i].x; o4.y += w * cur[i].y; o4.z += w * cur[i].z; o4.w += w * cur[i].w; }
; #pragma unroll
;         for (int i = 0; i < NB; ++i) cur[i] = nx[i];
;     }
	v_mov_b32_e32 v42, v41
	v_pk_fma_f32 v[2:3], v[12:13], v[66:67], v[2:3] op_sel_hi:[1,0,1]
	s_waitcnt vmcnt(1)
	v_pk_fma_f32 v[6:7], v[30:31], v[38:39], v[6:7] op_sel_hi:[1,0,1]
	v_pk_fma_f32 v[2:3], v[20:21], v[80:81], v[2:3] op_sel_hi:[1,0,1]
	s_nop 0
	v_pk_fma_f32 v[2:3], v[24:25], v[68:69], v[2:3] op_sel_hi:[1,0,1]
	s_nop 0
	v_pk_fma_f32 v[2:3], v[28:29], v[92:93], v[2:3] op_sel_hi:[1,0,1]
	v_mov_b32_e32 v28, v39
	v_pk_fma_f32 v[2:3], v[48:49], v[74:75], v[2:3] op_sel_hi:[1,0,1]
	s_waitcnt vmcnt(0)
	v_pk_fma_f32 v[6:7], v[34:35], v[28:29], v[6:7] op_sel_hi:[1,0,1]
	v_pk_fma_f32 v[2:3], v[52:53], v[10:11], v[2:3] op_sel_hi:[1,0,1]
	s_nop 0
	v_pk_fma_f32 v[2:3], v[58:59], v[76:77], v[2:3] op_sel_hi:[1,0,1]
	s_nop 0
	v_pk_fma_f32 v[2:3], v[62:63], v[14:15], v[2:3] op_sel_hi:[1,0,1]
	ds_read2_b32 v[14:15], v96 offset0:192 offset1:196
	ds_read2_b32 v[12:13], v96 offset0:200 offset1:204
	ds_read2_b32 v[10:11], v96 offset0:208 offset1:212
	ds_read2_b32 v[8:9], v96 offset0:216 offset1:220
	global_load_dwordx4 v[16:19], v[4:5], off
	v_add_co_u32_e32 v4, vcc, s91, v54
	v_pk_fma_f32 v[2:3], v[32:33], v[38:39], v[2:3] op_sel_hi:[1,0,1]
	s_nop 0
	v_addc_co_u32_e32 v5, vcc, 0, v55, vcc
	global_load_dwordx4 v[20:23], v[4:5], off offset:2048
	v_add_co_u32_e32 v4, vcc, s92, v54
	v_pk_fma_f32 v[2:3], v[36:37], v[28:29], v[2:3] op_sel_hi:[1,0,1]
	s_nop 0
	v_addc_co_u32_e32 v5, vcc, 0, v55, vcc
	global_load_dwordx4 v[24:27], v[4:5], off
	v_add_co_u32_e32 v4, vcc, s93, v54
	s_waitcnt lgkmcnt(0)
	v_mov_b32_e32 v36, v9
	v_addc_co_u32_e32 v5, vcc, 0, v55, vcc
	global_load_dwordx4 v[46:49], v[4:5], off offset:2048
	v_add_co_u32_e32 v4, vcc, s94, v54
	ds_read2_b32 v[30:31], v96 offset0:224 offset1:228
	s_nop 0
	v_addc_co_u32_e32 v5, vcc, 0, v55, vcc
	global_load_dwordx4 v[50:53], v[4:5], off
	v_add_co_u32_e32 v4, vcc, s95, v54
	s_waitcnt vmcnt(4)
	v_pk_fma_f32 v[2:3], v[18:19], v[40:41], v[2:3] op_sel_hi:[1,0,1]
	v_addc_co_u32_e32 v5, vcc, 0, v55, vcc
	global_load_dwordx4 v[56:59], v[4:5], off offset:2048
	v_add_co_u32_e32 v4, vcc, s96, v54
	s_waitcnt vmcnt(4)
	v_pk_fma_f32 v[2:3], v[22:23], v[42:43], v[2:3] op_sel_hi:[1,0,1]
	v_addc_co_u32_e32 v5, vcc, 0, v55, vcc
	global_load_dwordx4 v[60:63], v[4:5], off
	v_add_co_u32_e32 v4, vcc, s97, v54
	s_waitcnt vmcnt(4)
	v_pk_fma_f32 v[2:3], v[26:27], v[14:15], v[2:3] op_sel_hi:[1,0,1]
	v_addc_co_u32_e32 v5, vcc, 0, v55, vcc
	global_load_dwordx4 v[64:67], v[4:5], off offset:2048
	v_add_co_u32_e32 v4, vcc, s22, v54
	v_mov_b32_e32 v18, v15
	s_nop 0
	v_addc_co_u32_e32 v5, vcc, 0, v55, vcc
	global_load_dwordx4 v[68:71], v[4:5], off
	v_pk_fma_f32 v[6:7], v[16:17], v[40:41], v[6:7] op_sel_hi:[1,0,1]
	s_waitcnt vmcnt(5)
	v_pk_fma_f32 v[2:3], v[48:49], v[18:19], v[2:3] op_sel_hi:[1,0,1]
	v_pk_fma_f32 v[6:7], v[20:21], v[42:43], v[6:7] op_sel_hi:[1,0,1]
	s_waitcnt vmcnt(4)
	v_pk_fma_f32 v[2:3], v[52:53], v[12:13], v[2:3] op_sel_hi:[1,0,1]
	v_mov_b32_e32 v22, v13
	v_pk_fma_f32 v[6:7], v[24:25], v[14:15], v[6:7] op_sel_hi:[1,0,1]
	v_mov_b32_e32 v26, v11
	v_pk_fma_f32 v[6:7], v[46:47], v[18:19], v[6:7] op_sel_hi:[1,0,1]
	s_waitcnt vmcnt(3)
	v_pk_fma_f32 v[2:3], v[58:59], v[22:23], v[2:3] op_sel_hi:[1,0,1]
	v_pk_fma_f32 v[6:7], v[50:51], v[12:13], v[6:7] op_sel_hi:[1,0,1]
	s_waitcnt vmcnt(2)
	v_pk_fma_f32 v[2:3], v[62:63], v[10:11], v[2:3] op_sel_hi:[1,0,1]
	v_pk_fma_f32 v[6:7], v[56:57], v[22:23], v[6:7] op_sel_hi:[1,0,1]
	s_waitcnt vmcnt(1)
	v_pk_fma_f32 v[2:3], v[66:67], v[26:27], v[2:3] op_sel_hi:[1,0,1]
	v_pk_fma_f32 v[6:7], v[60:61], v[10:11], v[6:7] op_sel_hi:[1,0,1]
	s_waitcnt vmcnt(0)
; template <int NB>
; __device__ __forceinline__ void sb_decode_task(const Params& P, float* lds, int task) {
;     ...
;     for (int vb = 0; vb < NBT; ++vb) {
;         if (vb + 1 < NBT) {
; #pragma unroll
;             for (int i = 0; i < NB; ++i) nx[i] = *(const float4*)(Vp + (size_t)(4 * NB * (vb + 1) + 4 * i + g) * (SH * HD)); }
; #pragma unroll
;         for (int i = 0; i < NB; ++i) { const float w = wl[4 * NB * vb + 4 * i + g]; o4.x += w * cur[i].x; o4.y += w * cur[i].y; o4.z += w * cur[i].z; o4.w += w * cur[i].w; }
; #pragma unroll
;         for (int i = 0; i < NB; ++i) cur[i] = nx[i];
;     }
; #pragma unroll
;     for (int off = 16; off < 64; off <<= 1) { o4.x += __shfl_xor(o4.x, off); o4.y += __shfl_xor(o4.y, off); o4.z += __shfl_xor(o4.z, off); o4.w += __shfl_xor(o4.w, off); }
;     if (g == 0) *(float4*)(dpart + (size_t)task * HD + 4 * c) = o4;
;     if (lane == 0) dl[task] = Ltot;
	v_pk_fma_f32 v[32:33], v[70:71], v[8:9], v[2:3] op_sel_hi:[1,0,1]
	v_add_co_u32_e32 v2, vcc, s23, v54
	v_pk_fma_f32 v[6:7], v[64:65], v[26:27], v[6:7] op_sel_hi:[1,0,1]
	s_nop 0
	v_addc_co_u32_e32 v3, vcc, 0, v55, vcc
	v_pk_fma_f32 v[34:35], v[68:69], v[8:9], v[6:7] op_sel_hi:[1,0,1]
	v_add_co_u32_e32 v6, vcc, s24, v54
	global_load_dwordx4 v[2:5], v[2:3], off offset:2048
	s_nop 0
	v_addc_co_u32_e32 v7, vcc, 0, v55, vcc
	v_add_co_u32_e32 v10, vcc, s72, v54
	global_load_dwordx4 v[6:9], v[6:7], off
	s_nop 0
	v_addc_co_u32_e32 v11, vcc, 0, v55, vcc
	v_add_co_u32_e32 v14, vcc, s73, v54
	ds_read2_b32 v[42:43], v96 offset0:232 offset1:236
	ds_read2_b32 v[40:41], v96 offset0:240 offset1:244
	ds_read2_b32 v[38:39], v96 offset0:248 offset1:252
	v_addc_co_u32_e32 v15, vcc, 0, v55, vcc
	v_add_co_u32_e32 v18, vcc, s74, v54
	global_load_dwordx4 v[10:13], v[10:11], off offset:2048
	s_nop 0
	v_addc_co_u32_e32 v19, vcc, 0, v55, vcc
	v_add_co_u32_e32 v22, vcc, s75, v54
	global_load_dwordx4 v[14:17], v[14:15], off
	s_nop 0
	v_addc_co_u32_e32 v23, vcc, 0, v55, vcc
	v_add_co_u32_e32 v26, vcc, s80, v54
	global_load_dwordx4 v[18:21], v[18:19], off offset:2048
	s_nop 0
	v_addc_co_u32_e32 v27, vcc, 0, v55, vcc
	v_add_co_u32_e32 v46, vcc, s81, v54
	global_load_dwordx4 v[22:25], v[22:23], off
	s_nop 0
	v_addc_co_u32_e32 v47, vcc, 0, v55, vcc
	global_load_dwordx4 v[26:29], v[26:27], off offset:2048
	v_add_co_u32_e32 v50, vcc, s82, v54
	global_load_dwordx4 v[46:49], v[46:47], off
	s_nop 0
	v_addc_co_u32_e32 v51, vcc, 0, v55, vcc
	global_load_dwordx4 v[50:53], v[50:51], off offset:2048
	s_waitcnt lgkmcnt(2)
	v_mov_b32_e32 v54, v43
	s_waitcnt lgkmcnt(1)
	v_mov_b32_e32 v56, v41
	s_waitcnt lgkmcnt(0)
	v_mov_b32_e32 v58, v39
	s_waitcnt vmcnt(8)
	v_pk_fma_f32 v[2:3], v[2:3], v[36:37], v[34:35] op_sel_hi:[1,0,1]
	v_mov_b32_e32 v34, v31
	v_pk_fma_f32 v[4:5], v[4:5], v[36:37], v[32:33] op_sel_hi:[1,0,1]
	s_waitcnt vmcnt(7)
	v_pk_fma_f32 v[2:3], v[6:7], v[30:31], v[2:3] op_sel_hi:[1,0,1]
	v_pk_fma_f32 v[4:5], v[8:9], v[30:31], v[4:5] op_sel_hi:[1,0,1]
	s_waitcnt vmcnt(6)
	v_pk_fma_f32 v[2:3], v[10:11], v[34:35], v[2:3] op_sel_hi:[1,0,1]
	v_pk_fma_f32 v[4:5], v[12:13], v[34:35], v[4:5] op_sel_hi:[1,0,1]
	ds_bpermute_b32 v10, v104, v44
	s_waitcnt vmcnt(5)
	v_pk_fma_f32 v[2:3], v[14:15], v[42:43], v[2:3] op_sel_hi:[1,0,1]
	v_pk_fma_f32 v[4:5], v[16:17], v[42:43], v[4:5] op_sel_hi:[1,0,1]
	s_waitcnt vmcnt(4)
	v_pk_fma_f32 v[2:3], v[18:19], v[54:55], v[2:3] op_sel_hi:[1,0,1]
	v_pk_fma_f32 v[4:5], v[20:21], v[54:55], v[4:5] op_sel_hi:[1,0,1]
	s_waitcnt vmcnt(3)
	v_pk_fma_f32 v[2:3], v[22:23], v[40:41], v[2:3] op_sel_hi:[1,0,1]
	v_pk_fma_f32 v[4:5], v[24:25], v[40:41], v[4:5] op_sel_hi:[1,0,1]
	s_waitcnt vmcnt(2)
	v_pk_fma_f32 v[2:3], v[26:27], v[56:57], v[2:3] op_sel_hi:[1,0,1]
	v_pk_fma_f32 v[4:5], v[28:29], v[56:57], v[4:5] op_sel_hi:[1,0,1]
	s_waitcnt vmcnt(1)
	v_pk_fma_f32 v[2:3], v[46:47], v[38:39], v[2:3] op_sel_hi:[1,0,1]
	v_pk_fma_f32 v[4:5], v[48:49], v[38:39], v[4:5] op_sel_hi:[1,0,1]
	s_waitcnt vmcnt(0)
	v_pk_fma_f32 v[2:3], v[50:51], v[58:59], v[2:3] op_sel_hi:[1,0,1]
	ds_bpermute_b32 v6, v105, v2
	ds_bpermute_b32 v7, v105, v3
	v_pk_fma_f32 v[4:5], v[52:53], v[58:59], v[4:5] op_sel_hi:[1,0,1]
	s_waitcnt lgkmcnt(0)
	v_pk_add_f32 v[2:3], v[2:3], v[6:7]
	ds_bpermute_b32 v6, v105, v4
	ds_bpermute_b32 v7, v105, v5
	s_waitcnt lgkmcnt(0)
	v_pk_add_f32 v[4:5], v[4:5], v[6:7]
	ds_bpermute_b32 v6, v112, v2
	ds_bpermute_b32 v7, v112, v3
	ds_bpermute_b32 v8, v112, v4
	ds_bpermute_b32 v9, v112, v5
	s_and_saveexec_b64 s[0:1], s[20:21]
	s_cbranch_execz .LBB0_1090
	s_ashr_i32 s35, s34, 31
	s_lshl_b64 s[2:3], s[34:35], 8
	v_lshl_add_u64 v[12:13], v[88:89], 0, s[2:3]
	s_waitcnt lgkmcnt(2)
	v_pk_add_f32 v[2:3], v[2:3], v[6:7]
	s_waitcnt lgkmcnt(0)
	v_pk_add_f32 v[4:5], v[4:5], v[8:9]
	global_store_dwordx4 v[12:13], v[2:5], off

; __device__ __forceinline__ float bf2f(bf16_t b) { return __uint_as_float(((unsigned)b) << 16); }
; template <int NB>
; __device__ __forceinline__ void sb_decode_task(const Params& P, float* lds, int task) {
;     ...
;     const int h = task % SH, bj = task / SH, b = bj / NPAGES;
;     const int page = P.page_table[bj];
;     const float* Kp = P.cache_k + ((size_t)page * PAGE * SH + h) * HD + 4 * c;
;     const float* Vp = P.cache_v + ((size_t)page * PAGE * SH + h) * HD + 4 * c;
;     const bf16_t* qp = qb + (size_t)(NTOK + b) * SBW + h * 64 + 4 * c;
;     const float q0 = bf2f(qp[0]), q1 = bf2f(qp[1]), q2 = bf2f(qp[2]), q3 = bf2f(qp[3]);
;     const float bias = P.sb_bias[h] * LOG2E;
;     float4 cur[NB], nx[NB];
; #pragma unroll
;     for (int i = 0; i < NB; ++i) cur[i] = *(const float4*)(Kp + (size_t)(4 * i + g) * (SH * HD));
; #pragma unroll
;     for (int kb = 0; kb < NBT; ++kb) {
;         const float* np = (kb + 1 < NBT) ? Kp + (size_t)(4 * NB * (kb + 1)) * (SH * HD) : Vp;
; #pragma unroll
;         for (int i = 0; i < NB; ++i) nx[i] = *(const float4*)(np + (size_t)(4 * i + g) * (SH * HD));
; #pragma unroll
;         for (int i = 0; i < NB; ++i) { const int s = 4 * NB * kb + 4 * i + g;
;             float part = q0 * cur[i].x + q1 * cur[i].y + q2 * cur[i].z + q3 * cur[i].w; part = sum16(part);
;             if (c == 0) zl[s] = part + bias; }
.LBB0_1281:
	v_readlane_b32 s90, v252, 48
	s_lshr_b32 s1, s2, 31
	v_readlane_b32 s91, v252, 49
	s_add_i32 s0, s2, s1
	s_load_dwordx16 s[52:67], s[90:91], 0x0
	s_mul_i32 s3, s0, 6
	s_sub_i32 s36, s34, s3
	s_ashr_i32 s3, s2, 7
	s_add_i32 s3, s3, s1
	s_ashr_i32 s1, s0, 31
	s_lshl_b64 s[0:1], s[0:1], 2
	s_waitcnt lgkmcnt(0)
	s_add_u32 s0, s62, s0
	s_addc_u32 s1, s63, s1
	global_load_dword v2, v83, s[0:1]
	s_add_i32 s0, s3, 0x4000
	s_ashr_i32 s37, s36, 31
	s_mul_hi_i32 s1, s0, 0x300
	s_mulk_i32 s0, 0x300
	s_add_u32 s3, s38, s0
	s_addc_u32 s33, s39, s1
	s_lshl_b32 s0, s36, 6
	s_ashr_i32 s1, s0, 31
	s_lshl_b64 s[0:1], s[0:1], 1
	s_add_u32 s0, s3, s0
	s_addc_u32 s1, s33, s1
	v_readlane_b32 s52, v252, 16
	v_readlane_b32 s53, v252, 17
	v_readlane_b32 s60, v252, 24
	v_readlane_b32 s61, v252, 25
	s_mov_b64 s[52:53], s[60:61]
	v_mov_b32_e32 v93, v83
	v_readlane_b32 s54, v252, 18
	v_readlane_b32 s55, v252, 19
	v_readlane_b32 s56, v252, 20
	v_readlane_b32 s57, v252, 21
	v_readlane_b32 s58, v252, 22
	v_readlane_b32 s59, v252, 23
	v_readlane_b32 s62, v252, 26
	v_readlane_b32 s63, v252, 27
	v_readlane_b32 s64, v252, 28
	v_readlane_b32 s65, v252, 29
	v_readlane_b32 s66, v252, 30
	v_readlane_b32 s67, v252, 31
	s_waitcnt vmcnt(0)
	v_mov_b32_e32 v253, v2
	v_mul_hi_i32 v3, v2, s48
	v_mul_lo_u32 v2, v2, s48
	v_lshl_add_u64 v[94:95], v[2:3], 0, s[36:37]
	v_lshlrev_b64 v[2:3], 8, v[94:95]
	v_lshl_add_u64 v[70:71], v[84:85], 0, v[2:3]
	global_load_dwordx2 v[2:3], v101, s[0:1]
	s_lshl_b64 s[0:1], s[36:37], 2
	s_add_u32 s0, s52, s0
	s_addc_u32 s1, s53, s1
	global_load_dword v22, v83, s[0:1]
	v_lshl_add_u64 v[14:15], v[70:71], 0, v[82:83]
	v_lshl_add_u64 v[16:17], v[70:71], 0, v[92:93]
	global_load_dwordx4 v[18:21], v[14:15], off
	s_mov_b64 s[0:1], 0xc000
	global_load_dwordx4 v[62:65], v[16:17], off
	s_waitcnt vmcnt(3)
	v_lshlrev_b32_e32 v107, 16, v2
	v_and_b32_e32 v109, 0xffff0000, v2
	v_add_co_u32_e32 v2, vcc, s50, v14
	v_lshlrev_b32_e32 v108, 16, v3
	v_and_b32_e32 v106, 0xffff0000, v3
	v_addc_co_u32_e32 v3, vcc, 0, v15, vcc
	global_load_dwordx4 v[10:13], v[2:3], off offset:2048
	v_add_co_u32_e32 v2, vcc, s51, v14
	s_waitcnt vmcnt(3)
	v_mul_f32_e32 v110, 0x3fb8aa3b, v22
	v_addc_co_u32_e32 v3, vcc, 0, v15, vcc
	global_load_dwordx4 v[6:9], v[2:3], off
	v_add_co_u32_e32 v2, vcc, s49, v14
	v_lshl_add_u64 v[22:23], v[70:71], 0, s[0:1]
	s_nop 0
	v_addc_co_u32_e32 v3, vcc, 0, v15, vcc
	v_add_co_u32_e32 v16, vcc, s92, v14
	v_lshl_add_u64 v[30:31], v[22:23], 0, v[82:83]
	s_nop 0
	v_addc_co_u32_e32 v17, vcc, 0, v15, vcc
	global_load_dwordx4 v[58:61], v[16:17], off offset:2048
	v_add_co_u32_e32 v16, vcc, s93, v14
	v_lshl_add_u64 v[22:23], v[22:23], 0, v[92:93]
	s_nop 0
	v_addc_co_u32_e32 v17, vcc, 0, v15, vcc
	v_add_co_u32_e32 v14, vcc, s96, v14
	global_load_dwordx4 v[54:57], v[16:17], off
	s_nop 0
	v_addc_co_u32_e32 v15, vcc, 0, v15, vcc
	global_load_dwordx4 v[50:53], v[14:15], off offset:2048
	v_add_co_u32_e32 v14, vcc, s50, v30
	global_load_dwordx4 v[22:25], v[22:23], off
	s_nop 0
	v_addc_co_u32_e32 v15, vcc, 0, v31, vcc
	global_load_dwordx4 v[34:37], v[14:15], off offset:2048
	v_add_co_u32_e32 v14, vcc, s51, v30
	global_load_dwordx4 v[2:5], v[2:3], off offset:2048
	s_nop 0
	v_addc_co_u32_e32 v15, vcc, 0, v31, vcc
	global_load_dwordx4 v[26:29], v[14:15], off
	v_add_co_u32_e32 v14, vcc, s49, v30
	global_load_dwordx4 v[46:49], v[30:31], off
	s_nop 0
	v_addc_co_u32_e32 v15, vcc, 0, v31, vcc
	v_add_co_u32_e32 v32, vcc, s92, v30
	global_load_dwordx4 v[14:17], v[14:15], off offset:2048
	s_nop 0
	v_addc_co_u32_e32 v33, vcc, 0, v31, vcc
	global_load_dwordx4 v[38:41], v[32:33], off offset:2048
	v_add_co_u32_e32 v32, vcc, s93, v30
	s_waitcnt vmcnt(13)
	v_mul_f32_e32 v19, v19, v109
	v_addc_co_u32_e32 v33, vcc, 0, v31, vcc
	v_add_co_u32_e32 v30, vcc, s96, v30
	global_load_dwordx4 v[42:45], v[32:33], off
	s_nop 0
	v_addc_co_u32_e32 v31, vcc, 0, v31, vcc
	global_load_dwordx4 v[30:33], v[30:31], off offset:2048
	v_fmac_f32_e32 v19, v18, v107
	v_fmac_f32_e32 v19, v20, v108
	v_fmac_f32_e32 v19, v21, v106
	s_nop 1
	v_add_f32_dpp v18, v19, v19 quad_perm:[1,0,3,2] row_mask:0xf bank_mask:0xf bound_ctrl:1
	s_nop 1
	v_add_f32_dpp v18, v18, v18 quad_perm:[2,3,0,1] row_mask:0xf bank_mask:0xf bound_ctrl:1
	s_nop 1
	v_add_f32_dpp v18, v18, v18 row_ror:4 row_mask:0xf bank_mask:0xf bound_ctrl:1
	s_nop 1
	v_mov_b32_dpp v19, v18 row_ror:8 row_mask:0xf bank_mask:0xf bound_ctrl:1
	s_and_saveexec_b64 s[0:1], s[6:7]
	v_add_f32_e32 v18, v18, v19
	v_add_f32_e32 v18, v110, v18
	ds_write_b32 v99, v18
	s_or_b64 exec, exec, s[0:1]
	s_waitcnt vmcnt(13)
	v_mul_f32_e32 v11, v11, v109
	v_fmac_f32_e32 v11, v10, v107
	v_fmac_f32_e32 v11, v12, v108
	v_fmac_f32_e32 v11, v13, v106
	s_nop 1
	v_add_f32_dpp v10, v11, v11 quad_perm:[1,0,3,2] row_mask:0xf bank_mask:0xf bound_ctrl:1
	s_nop 1
	v_add_f32_dpp v10, v10, v10 quad_perm:[2,3,0,1] row_mask:0xf bank_mask:0xf bound_ctrl:1
	s_nop 1
	v_add_f32_dpp v10, v10, v10 row_ror:4 row_mask:0xf bank_mask:0xf bound_ctrl:1
	s_nop 1
	v_mov_b32_dpp v11, v10 row_ror:8 row_mask:0xf bank_mask:0xf bound_ctrl:1
	s_and_saveexec_b64 s[0:1], s[6:7]
	v_add_f32_e32 v10, v10, v11
	v_add_f32_e32 v10, v110, v10
	ds_write_b32 v99, v10 offset:16
	s_or_b64 exec, exec, s[0:1]
	s_waitcnt vmcnt(12)
	v_mul_f32_e32 v7, v7, v109
	v_fmac_f32_e32 v7, v6, v107
	v_fmac_f32_e32 v7, v8, v108
	v_fmac_f32_e32 v7, v9, v106
	s_nop 1
	v_add_f32_dpp v6, v7, v7 quad_perm:[1,0,3,2] row_mask:0xf bank_mask:0xf bound_ctrl:1
	s_nop 1
	v_add_f32_dpp v6, v6, v6 quad_perm:[2,3,0,1] row_mask:0xf bank_mask:0xf bound_ctrl:1
	s_nop 1
	v_add_f32_dpp v6, v6, v6 row_ror:4 row_mask:0xf bank_mask:0xf bound_ctrl:1
	s_nop 1
	v_mov_b32_dpp v7, v6 row_ror:8 row_mask:0xf bank_mask:0xf bound_ctrl:1
	s_and_saveexec_b64 s[0:1], s[6:7]
	v_add_f32_e32 v6, v6, v7
	v_add_f32_e32 v6, v110, v6
	ds_write_b32 v99, v6 offset:32
	s_or_b64 exec, exec, s[0:1]
	s_waitcnt vmcnt(6)
; template <int NB>
; __device__ __forceinline__ void sb_decode_task(const Params& P, float* lds, int task) {
;     ...
;     for (int kb = 0; kb < NBT; ++kb) {
;         const float* np = (kb + 1 < NBT) ? Kp + (size_t)(4 * NB * (kb + 1)) * (SH * HD) : Vp;
; #pragma unroll
;         for (int i = 0; i < NB; ++i) nx[i] = *(const float4*)(np + (size_t)(4 * i + g) * (SH * HD));
; #pragma unroll
;         for (int i = 0; i < NB; ++i) { const int s = 4 * NB * kb + 4 * i + g;
;             float part = q0 * cur[i].x + q1 * cur[i].y + q2 * cur[i].z + q3 * cur[i].w; part = sum16(part);
;             if (c == 0) zl[s] = part + bias; }
	v_mul_f32_e32 v3, v3, v109
	v_fmac_f32_e32 v3, v2, v107
	v_fmac_f32_e32 v3, v4, v108
	v_fmac_f32_e32 v3, v5, v106
	s_nop 1
	v_add_f32_dpp v2, v3, v3 quad_perm:[1,0,3,2] row_mask:0xf bank_mask:0xf bound_ctrl:1
	s_nop 1
	v_add_f32_dpp v2, v2, v2 quad_perm:[2,3,0,1] row_mask:0xf bank_mask:0xf bound_ctrl:1
	s_nop 1
	v_add_f32_dpp v2, v2, v2 row_ror:4 row_mask:0xf bank_mask:0xf bound_ctrl:1
	s_nop 1
	v_mov_b32_dpp v3, v2 row_ror:8 row_mask:0xf bank_mask:0xf bound_ctrl:1
	s_and_saveexec_b64 s[0:1], s[6:7]
	v_add_f32_e32 v2, v2, v3
	v_add_f32_e32 v2, v110, v2
	ds_write_b32 v99, v2 offset:48
	s_or_b64 exec, exec, s[0:1]
	v_mul_f32_e32 v2, v63, v109
	v_fmac_f32_e32 v2, v62, v107
	v_fmac_f32_e32 v2, v64, v108
	v_fmac_f32_e32 v2, v65, v106
	s_nop 1
	v_add_f32_dpp v2, v2, v2 quad_perm:[1,0,3,2] row_mask:0xf bank_mask:0xf bound_ctrl:1
	s_nop 1
	v_add_f32_dpp v2, v2, v2 quad_perm:[2,3,0,1] row_mask:0xf bank_mask:0xf bound_ctrl:1
	s_nop 1
	v_add_f32_dpp v2, v2, v2 row_ror:4 row_mask:0xf bank_mask:0xf bound_ctrl:1
	s_nop 1
	v_mov_b32_dpp v3, v2 row_ror:8 row_mask:0xf bank_mask:0xf bound_ctrl:1
	s_and_saveexec_b64 s[0:1], s[6:7]
	v_add_f32_e32 v2, v2, v3
	v_add_f32_e32 v2, v110, v2
	ds_write_b32 v99, v2 offset:64
	s_or_b64 exec, exec, s[0:1]
	v_mul_f32_e32 v2, v59, v109
	v_fmac_f32_e32 v2, v58, v107
	v_fmac_f32_e32 v2, v60, v108
	v_fmac_f32_e32 v2, v61, v106
	s_nop 1
	v_add_f32_dpp v2, v2, v2 quad_perm:[1,0,3,2] row_mask:0xf bank_mask:0xf bound_ctrl:1
	s_nop 1
	v_add_f32_dpp v2, v2, v2 quad_perm:[2,3,0,1] row_mask:0xf bank_mask:0xf bound_ctrl:1
	s_nop 1
	v_add_f32_dpp v2, v2, v2 row_ror:4 row_mask:0xf bank_mask:0xf bound_ctrl:1
	s_nop 1
	v_mov_b32_dpp v3, v2 row_ror:8 row_mask:0xf bank_mask:0xf bound_ctrl:1
	s_and_saveexec_b64 s[0:1], s[6:7]
	v_add_f32_e32 v2, v2, v3
	v_add_f32_e32 v2, v110, v2
	ds_write_b32 v99, v2 offset:80
	s_or_b64 exec, exec, s[0:1]
	v_mul_f32_e32 v2, v55, v109
	v_fmac_f32_e32 v2, v54, v107
	v_fmac_f32_e32 v2, v56, v108
	v_fmac_f32_e32 v2, v57, v106
	s_nop 1
	v_add_f32_dpp v2, v2, v2 quad_perm:[1,0,3,2] row_mask:0xf bank_mask:0xf bound_ctrl:1
	s_nop 1
	v_add_f32_dpp v2, v2, v2 quad_perm:[2,3,0,1] row_mask:0xf bank_mask:0xf bound_ctrl:1
	s_nop 1
	v_add_f32_dpp v2, v2, v2 row_ror:4 row_mask:0xf bank_mask:0xf bound_ctrl:1
	s_nop 1
	v_mov_b32_dpp v3, v2 row_ror:8 row_mask:0xf bank_mask:0xf bound_ctrl:1
	s_and_saveexec_b64 s[0:1], s[6:7]
	v_add_f32_e32 v2, v2, v3
	v_add_f32_e32 v2, v110, v2
	ds_write_b32 v99, v2 offset:96
	s_or_b64 exec, exec, s[0:1]
	v_mul_f32_e32 v2, v51, v109
	v_fmac_f32_e32 v2, v50, v107
	v_fmac_f32_e32 v2, v52, v108
	v_fmac_f32_e32 v2, v53, v106
	s_nop 1
	v_add_f32_dpp v2, v2, v2 quad_perm:[1,0,3,2] row_mask:0xf bank_mask:0xf bound_ctrl:1
	s_nop 1
	v_add_f32_dpp v2, v2, v2 quad_perm:[2,3,0,1] row_mask:0xf bank_mask:0xf bound_ctrl:1
	s_nop 1
	v_add_f32_dpp v2, v2, v2 row_ror:4 row_mask:0xf bank_mask:0xf bound_ctrl:1
	s_nop 1
	v_mov_b32_dpp v3, v2 row_ror:8 row_mask:0xf bank_mask:0xf bound_ctrl:1
	s_and_saveexec_b64 s[0:1], s[6:7]
	v_add_f32_e32 v2, v2, v3
	v_add_f32_e32 v2, v110, v2
	ds_write_b32 v99, v2 offset:112
	s_or_b64 exec, exec, s[0:1]
	s_mov_b64 s[0:1], 0x18000
	v_lshl_add_u64 v[2:3], v[70:71], 0, s[0:1]
	v_lshl_add_u64 v[4:5], v[2:3], 0, v[82:83]
	v_add_co_u32_e32 v6, vcc, 0x1000, v4
	v_mov_b32_e32 v93, v83
	s_nop 0
	v_addc_co_u32_e32 v7, vcc, 0, v5, vcc
	global_load_dwordx4 v[74:77], v[4:5], off
	global_load_dwordx4 v[66:69], v[6:7], off offset:2048
	v_add_co_u32_e32 v6, vcc, 0x3000, v4
	v_lshl_add_u64 v[2:3], v[2:3], 0, v[92:93]
	s_nop 0
	v_addc_co_u32_e32 v7, vcc, 0, v5, vcc
	v_add_co_u32_e32 v8, vcc, s49, v4
	s_waitcnt vmcnt(6)
	v_mul_f32_e32 v47, v47, v109
	v_addc_co_u32_e32 v9, vcc, 0, v5, vcc
	global_load_dwordx4 v[58:61], v[6:7], off
	global_load_dwordx4 v[50:53], v[8:9], off offset:2048
	v_add_co_u32_e32 v6, vcc, 0x7000, v4
	v_fmac_f32_e32 v47, v46, v107
	s_nop 0
	v_addc_co_u32_e32 v7, vcc, 0, v5, vcc
	global_load_dwordx4 v[18:21], v[2:3], off
	global_load_dwordx4 v[10:13], v[6:7], off offset:2048
	v_add_co_u32_e32 v2, vcc, 0x9000, v4
	v_fmac_f32_e32 v47, v48, v108
	s_nop 0
	v_addc_co_u32_e32 v3, vcc, 0, v5, vcc
	v_add_co_u32_e32 v4, vcc, 0xa000, v4
	v_fmac_f32_e32 v47, v49, v106
	s_nop 0
	v_addc_co_u32_e32 v5, vcc, 0, v5, vcc
	global_load_dwordx4 v[6:9], v[2:3], off
	s_nop 0
	global_load_dwordx4 v[2:5], v[4:5], off offset:2048
	v_add_f32_dpp v46, v47, v47 quad_perm:[1,0,3,2] row_mask:0xf bank_mask:0xf bound_ctrl:1
	s_nop 1
	v_add_f32_dpp v46, v46, v46 quad_perm:[2,3,0,1] row_mask:0xf bank_mask:0xf bound_ctrl:1
	s_nop 1
	v_add_f32_dpp v46, v46, v46 row_ror:4 row_mask:0xf bank_mask:0xf bound_ctrl:1
	s_nop 1
	v_mov_b32_dpp v47, v46 row_ror:8 row_mask:0xf bank_mask:0xf bound_ctrl:1
	s_and_saveexec_b64 s[0:1], s[6:7]
	v_add_f32_e32 v46, v46, v47
	v_add_f32_e32 v46, v110, v46
	ds_write_b32 v99, v46 offset:128
	s_or_b64 exec, exec, s[0:1]
	v_mul_f32_e32 v35, v35, v109
	v_fmac_f32_e32 v35, v34, v107
	v_fmac_f32_e32 v35, v36, v108
	v_fmac_f32_e32 v35, v37, v106
	s_nop 1
	v_add_f32_dpp v34, v35, v35 quad_perm:[1,0,3,2] row_mask:0xf bank_mask:0xf bound_ctrl:1
	s_nop 1
	v_add_f32_dpp v34, v34, v34 quad_perm:[2,3,0,1] row_mask:0xf bank_mask:0xf bound_ctrl:1
	s_nop 1
	v_add_f32_dpp v34, v34, v34 row_ror:4 row_mask:0xf bank_mask:0xf bound_ctrl:1
	s_nop 1
	v_mov_b32_dpp v35, v34 row_ror:8 row_mask:0xf bank_mask:0xf bound_ctrl:1
	s_and_saveexec_b64 s[0:1], s[6:7]
	v_add_f32_e32 v34, v34, v35
	v_add_f32_e32 v34, v110, v34
	ds_write_b32 v99, v34 offset:144
	s_or_b64 exec, exec, s[0:1]
	v_mul_f32_e32 v27, v27, v109
	v_fmac_f32_e32 v27, v26, v107
	v_fmac_f32_e32 v27, v28, v108
	v_fmac_f32_e32 v27, v29, v106
	s_nop 1
	v_add_f32_dpp v26, v27, v27 quad_perm:[1,0,3,2] row_mask:0xf bank_mask:0xf bound_ctrl:1
	s_nop 1
	v_add_f32_dpp v26, v26, v26 quad_perm:[2,3,0,1] row_mask:0xf bank_mask:0xf bound_ctrl:1
	s_nop 1
	v_add_f32_dpp v26, v26, v26 row_ror:4 row_mask:0xf bank_mask:0xf bound_ctrl:1
	s_nop 1
	v_mov_b32_dpp v27, v26 row_ror:8 row_mask:0xf bank_mask:0xf bound_ctrl:1
	s_and_saveexec_b64 s[0:1], s[6:7]
	v_add_f32_e32 v26, v26, v27
	v_add_f32_e32 v26, v110, v26
	ds_write_b32 v99, v26 offset:160
	s_or_b64 exec, exec, s[0:1]
	s_waitcnt vmcnt(11)
; template <int NB>
; __device__ __forceinline__ void sb_decode_task(const Params& P, float* lds, int task) {
;     ...
;     for (int kb = 0; kb < NBT; ++kb) {
;         const float* np = (kb + 1 < NBT) ? Kp + (size_t)(4 * NB * (kb + 1)) * (SH * HD) : Vp;
; #pragma unroll
;         for (int i = 0; i < NB; ++i) nx[i] = *(const float4*)(np + (size_t)(4 * i + g) * (SH * HD));
; #pragma unroll
;         for (int i = 0; i < NB; ++i) { const int s = 4 * NB * kb + 4 * i + g;
;             float part = q0 * cur[i].x + q1 * cur[i].y + q2 * cur[i].z + q3 * cur[i].w; part = sum16(part);
;             if (c == 0) zl[s] = part + bias; }
	v_mul_f32_e32 v15, v15, v109
	v_fmac_f32_e32 v15, v14, v107
	v_fmac_f32_e32 v15, v16, v108
	v_fmac_f32_e32 v15, v17, v106
	s_nop 1
	v_add_f32_dpp v14, v15, v15 quad_perm:[1,0,3,2] row_mask:0xf bank_mask:0xf bound_ctrl:1
	s_nop 1
	v_add_f32_dpp v14, v14, v14 quad_perm:[2,3,0,1] row_mask:0xf bank_mask:0xf bound_ctrl:1
	s_nop 1
	v_add_f32_dpp v14, v14, v14 row_ror:4 row_mask:0xf bank_mask:0xf bound_ctrl:1
	s_nop 1
	v_mov_b32_dpp v15, v14 row_ror:8 row_mask:0xf bank_mask:0xf bound_ctrl:1
	s_and_saveexec_b64 s[0:1], s[6:7]
	v_add_f32_e32 v14, v14, v15
	v_add_f32_e32 v14, v110, v14
	ds_write_b32 v99, v14 offset:176
	s_or_b64 exec, exec, s[0:1]
	v_mul_f32_e32 v14, v23, v109
	v_fmac_f32_e32 v14, v22, v107
	v_fmac_f32_e32 v14, v24, v108
	v_fmac_f32_e32 v14, v25, v106
	s_nop 1
	v_add_f32_dpp v14, v14, v14 quad_perm:[1,0,3,2] row_mask:0xf bank_mask:0xf bound_ctrl:1
	s_nop 1
	v_add_f32_dpp v14, v14, v14 quad_perm:[2,3,0,1] row_mask:0xf bank_mask:0xf bound_ctrl:1
	s_nop 1
	v_add_f32_dpp v14, v14, v14 row_ror:4 row_mask:0xf bank_mask:0xf bound_ctrl:1
	s_nop 1
	v_mov_b32_dpp v15, v14 row_ror:8 row_mask:0xf bank_mask:0xf bound_ctrl:1
	s_and_saveexec_b64 s[0:1], s[6:7]
	v_add_f32_e32 v14, v14, v15
	v_add_f32_e32 v14, v110, v14
	ds_write_b32 v99, v14 offset:192
	s_or_b64 exec, exec, s[0:1]
	s_waitcnt vmcnt(10)
	v_mul_f32_e32 v14, v39, v109
	v_fmac_f32_e32 v14, v38, v107
	v_fmac_f32_e32 v14, v40, v108
	v_fmac_f32_e32 v14, v41, v106
	s_nop 1
	v_add_f32_dpp v14, v14, v14 quad_perm:[1,0,3,2] row_mask:0xf bank_mask:0xf bound_ctrl:1
	s_nop 1
	v_add_f32_dpp v14, v14, v14 quad_perm:[2,3,0,1] row_mask:0xf bank_mask:0xf bound_ctrl:1
	s_nop 1
	v_add_f32_dpp v14, v14, v14 row_ror:4 row_mask:0xf bank_mask:0xf bound_ctrl:1
	s_nop 1
	v_mov_b32_dpp v15, v14 row_ror:8 row_mask:0xf bank_mask:0xf bound_ctrl:1
	s_and_saveexec_b64 s[0:1], s[6:7]
	v_add_f32_e32 v14, v14, v15
	v_add_f32_e32 v14, v110, v14
	ds_write_b32 v99, v14 offset:208
	s_or_b64 exec, exec, s[0:1]
	s_waitcnt vmcnt(9)
	v_mul_f32_e32 v14, v43, v109
	v_fmac_f32_e32 v14, v42, v107
	v_fmac_f32_e32 v14, v44, v108
	v_fmac_f32_e32 v14, v45, v106
	s_nop 1
	v_add_f32_dpp v14, v14, v14 quad_perm:[1,0,3,2] row_mask:0xf bank_mask:0xf bound_ctrl:1
	s_nop 1
	v_add_f32_dpp v14, v14, v14 quad_perm:[2,3,0,1] row_mask:0xf bank_mask:0xf bound_ctrl:1
	s_nop 1
	v_add_f32_dpp v14, v14, v14 row_ror:4 row_mask:0xf bank_mask:0xf bound_ctrl:1
	s_nop 1
	v_mov_b32_dpp v15, v14 row_ror:8 row_mask:0xf bank_mask:0xf bound_ctrl:1
	s_and_saveexec_b64 s[0:1], s[6:7]
	v_add_f32_e32 v14, v14, v15
	v_add_f32_e32 v14, v110, v14
	ds_write_b32 v99, v14 offset:224
	s_or_b64 exec, exec, s[0:1]
	s_waitcnt vmcnt(8)
	v_mul_f32_e32 v14, v31, v109
	v_fmac_f32_e32 v14, v30, v107
	v_fmac_f32_e32 v14, v32, v108
	v_fmac_f32_e32 v14, v33, v106
	s_nop 1
	v_add_f32_dpp v14, v14, v14 quad_perm:[1,0,3,2] row_mask:0xf bank_mask:0xf bound_ctrl:1
	s_nop 1
	v_add_f32_dpp v14, v14, v14 quad_perm:[2,3,0,1] row_mask:0xf bank_mask:0xf bound_ctrl:1
	s_nop 1
	v_add_f32_dpp v14, v14, v14 row_ror:4 row_mask:0xf bank_mask:0xf bound_ctrl:1
	s_nop 1
	v_mov_b32_dpp v15, v14 row_ror:8 row_mask:0xf bank_mask:0xf bound_ctrl:1
	s_and_saveexec_b64 s[0:1], s[6:7]
	v_add_f32_e32 v14, v14, v15
	v_add_f32_e32 v14, v110, v14
	ds_write_b32 v99, v14 offset:240
	s_or_b64 exec, exec, s[0:1]
	s_mov_b64 s[0:1], 0x24000
	v_lshl_add_u64 v[14:15], v[70:71], 0, s[0:1]
	v_lshl_add_u64 v[16:17], v[14:15], 0, v[82:83]
	v_add_co_u32_e32 v22, vcc, 0x1000, v16
	v_mov_b32_e32 v93, v83
	s_nop 0
	v_addc_co_u32_e32 v23, vcc, 0, v17, vcc
	global_load_dwordx4 v[78:81], v[16:17], off
	global_load_dwordx4 v[70:73], v[22:23], off offset:2048
	v_add_co_u32_e32 v22, vcc, 0x3000, v16
	v_lshl_add_u64 v[14:15], v[14:15], 0, v[92:93]
	s_nop 0
	v_addc_co_u32_e32 v23, vcc, 0, v17, vcc
	v_add_co_u32_e32 v24, vcc, s49, v16
	s_nop 1
	v_addc_co_u32_e32 v25, vcc, 0, v17, vcc
	global_load_dwordx4 v[62:65], v[22:23], off
	global_load_dwordx4 v[54:57], v[24:25], off offset:2048
	v_add_co_u32_e32 v22, vcc, 0x7000, v16
	s_nop 1
	v_addc_co_u32_e32 v23, vcc, 0, v17, vcc
	global_load_dwordx4 v[46:49], v[14:15], off
	global_load_dwordx4 v[42:45], v[22:23], off offset:2048
	v_add_co_u32_e32 v14, vcc, 0x9000, v16
	s_nop 1
	v_addc_co_u32_e32 v15, vcc, 0, v17, vcc
	v_add_co_u32_e32 v16, vcc, 0xa000, v16
	s_nop 1
	v_addc_co_u32_e32 v17, vcc, 0, v17, vcc
	global_load_dwordx4 v[38:41], v[14:15], off
	global_load_dwordx4 v[34:37], v[16:17], off offset:2048
	s_waitcnt vmcnt(15)
	v_mul_f32_e32 v14, v75, v109
	v_fmac_f32_e32 v14, v74, v107
	v_fmac_f32_e32 v14, v76, v108
	v_fmac_f32_e32 v14, v77, v106
	s_nop 1
	v_add_f32_dpp v14, v14, v14 quad_perm:[1,0,3,2] row_mask:0xf bank_mask:0xf bound_ctrl:1
	s_nop 1
	v_add_f32_dpp v14, v14, v14 quad_perm:[2,3,0,1] row_mask:0xf bank_mask:0xf bound_ctrl:1
	s_nop 1
	v_add_f32_dpp v14, v14, v14 row_ror:4 row_mask:0xf bank_mask:0xf bound_ctrl:1
	s_nop 1
	v_mov_b32_dpp v15, v14 row_ror:8 row_mask:0xf bank_mask:0xf bound_ctrl:1
	s_and_saveexec_b64 s[0:1], s[6:7]
	v_add_f32_e32 v14, v14, v15
	v_add_f32_e32 v14, v110, v14
	ds_write_b32 v99, v14 offset:256
	s_or_b64 exec, exec, s[0:1]
	s_waitcnt vmcnt(14)
	v_mul_f32_e32 v14, v67, v109
	v_fmac_f32_e32 v14, v66, v107
	v_fmac_f32_e32 v14, v68, v108
	v_fmac_f32_e32 v14, v69, v106
	s_nop 1
	v_add_f32_dpp v14, v14, v14 quad_perm:[1,0,3,2] row_mask:0xf bank_mask:0xf bound_ctrl:1
	s_nop 1
	v_add_f32_dpp v14, v14, v14 quad_perm:[2,3,0,1] row_mask:0xf bank_mask:0xf bound_ctrl:1
	s_nop 1
	v_add_f32_dpp v14, v14, v14 row_ror:4 row_mask:0xf bank_mask:0xf bound_ctrl:1
	s_nop 1
	v_mov_b32_dpp v15, v14 row_ror:8 row_mask:0xf bank_mask:0xf bound_ctrl:1
	s_and_saveexec_b64 s[0:1], s[6:7]
	v_add_f32_e32 v14, v14, v15
	v_add_f32_e32 v14, v110, v14
	ds_write_b32 v99, v14 offset:272
	s_or_b64 exec, exec, s[0:1]
	s_waitcnt vmcnt(13)
; template <int NB>
; __device__ __forceinline__ void sb_decode_task(const Params& P, float* lds, int task) {
;     ...
;     for (int kb = 0; kb < NBT; ++kb) {
;         const float* np = (kb + 1 < NBT) ? Kp + (size_t)(4 * NB * (kb + 1)) * (SH * HD) : Vp;
; #pragma unroll
;         for (int i = 0; i < NB; ++i) nx[i] = *(const float4*)(np + (size_t)(4 * i + g) * (SH * HD));
; #pragma unroll
;         for (int i = 0; i < NB; ++i) { const int s = 4 * NB * kb + 4 * i + g;
;             float part = q0 * cur[i].x + q1 * cur[i].y + q2 * cur[i].z + q3 * cur[i].w; part = sum16(part);
;             if (c == 0) zl[s] = part + bias; }
; #pragma unroll
;         for (int i = 0; i < NB; ++i) cur[i] = nx[i];
;     }
;     asm volatile("s_waitcnt lgkmcnt(0)" ::: "memory");
	v_mul_f32_e32 v14, v59, v109
	v_fmac_f32_e32 v14, v58, v107
	v_fmac_f32_e32 v14, v60, v108
	v_fmac_f32_e32 v14, v61, v106
	s_nop 1
	v_add_f32_dpp v14, v14, v14 quad_perm:[1,0,3,2] row_mask:0xf bank_mask:0xf bound_ctrl:1
	s_nop 1
	v_add_f32_dpp v14, v14, v14 quad_perm:[2,3,0,1] row_mask:0xf bank_mask:0xf bound_ctrl:1
	s_nop 1
	v_add_f32_dpp v14, v14, v14 row_ror:4 row_mask:0xf bank_mask:0xf bound_ctrl:1
	s_nop 1
	v_mov_b32_dpp v15, v14 row_ror:8 row_mask:0xf bank_mask:0xf bound_ctrl:1
	s_and_saveexec_b64 s[0:1], s[6:7]
	v_add_f32_e32 v14, v14, v15
	v_add_f32_e32 v14, v110, v14
	ds_write_b32 v99, v14 offset:288
	s_or_b64 exec, exec, s[0:1]
	s_waitcnt vmcnt(12)
	v_mul_f32_e32 v14, v51, v109
	v_fmac_f32_e32 v14, v50, v107
	v_fmac_f32_e32 v14, v52, v108
	v_fmac_f32_e32 v14, v53, v106
	s_nop 1
	v_add_f32_dpp v14, v14, v14 quad_perm:[1,0,3,2] row_mask:0xf bank_mask:0xf bound_ctrl:1
	s_nop 1
	v_add_f32_dpp v14, v14, v14 quad_perm:[2,3,0,1] row_mask:0xf bank_mask:0xf bound_ctrl:1
	s_nop 1
	v_add_f32_dpp v14, v14, v14 row_ror:4 row_mask:0xf bank_mask:0xf bound_ctrl:1
	s_nop 1
	v_mov_b32_dpp v15, v14 row_ror:8 row_mask:0xf bank_mask:0xf bound_ctrl:1
	s_and_saveexec_b64 s[0:1], s[6:7]
	v_add_f32_e32 v14, v14, v15
	v_add_f32_e32 v14, v110, v14
	ds_write_b32 v99, v14 offset:304
	s_or_b64 exec, exec, s[0:1]
	s_waitcnt vmcnt(11)
	v_mul_f32_e32 v14, v19, v109
	v_fmac_f32_e32 v14, v18, v107
	v_fmac_f32_e32 v14, v20, v108
	v_fmac_f32_e32 v14, v21, v106
	s_nop 1
	v_add_f32_dpp v14, v14, v14 quad_perm:[1,0,3,2] row_mask:0xf bank_mask:0xf bound_ctrl:1
	s_nop 1
	v_add_f32_dpp v14, v14, v14 quad_perm:[2,3,0,1] row_mask:0xf bank_mask:0xf bound_ctrl:1
	s_nop 1
	v_add_f32_dpp v14, v14, v14 row_ror:4 row_mask:0xf bank_mask:0xf bound_ctrl:1
	s_nop 1
	v_mov_b32_dpp v15, v14 row_ror:8 row_mask:0xf bank_mask:0xf bound_ctrl:1
	s_and_saveexec_b64 s[0:1], s[6:7]
	v_add_f32_e32 v14, v14, v15
	v_add_f32_e32 v14, v110, v14
	ds_write_b32 v99, v14 offset:320
	s_or_b64 exec, exec, s[0:1]
	s_waitcnt vmcnt(10)
	v_mul_f32_e32 v11, v11, v109
	v_fmac_f32_e32 v11, v10, v107
	v_fmac_f32_e32 v11, v12, v108
	v_fmac_f32_e32 v11, v13, v106
	s_nop 1
	v_add_f32_dpp v10, v11, v11 quad_perm:[1,0,3,2] row_mask:0xf bank_mask:0xf bound_ctrl:1
	s_nop 1
	v_add_f32_dpp v10, v10, v10 quad_perm:[2,3,0,1] row_mask:0xf bank_mask:0xf bound_ctrl:1
	s_nop 1
	v_add_f32_dpp v10, v10, v10 row_ror:4 row_mask:0xf bank_mask:0xf bound_ctrl:1
	s_nop 1
	v_mov_b32_dpp v11, v10 row_ror:8 row_mask:0xf bank_mask:0xf bound_ctrl:1
	s_and_saveexec_b64 s[0:1], s[6:7]
	v_add_f32_e32 v10, v10, v11
	v_add_f32_e32 v10, v110, v10
	ds_write_b32 v99, v10 offset:336
	s_or_b64 exec, exec, s[0:1]
	s_waitcnt vmcnt(9)
	v_mul_f32_e32 v7, v7, v109
	v_fmac_f32_e32 v7, v6, v107
	v_fmac_f32_e32 v7, v8, v108
	v_fmac_f32_e32 v7, v9, v106
	s_nop 1
	v_add_f32_dpp v6, v7, v7 quad_perm:[1,0,3,2] row_mask:0xf bank_mask:0xf bound_ctrl:1
	s_nop 1
	v_add_f32_dpp v6, v6, v6 quad_perm:[2,3,0,1] row_mask:0xf bank_mask:0xf bound_ctrl:1
	s_nop 1
	v_add_f32_dpp v6, v6, v6 row_ror:4 row_mask:0xf bank_mask:0xf bound_ctrl:1
	s_nop 1
	v_mov_b32_dpp v7, v6 row_ror:8 row_mask:0xf bank_mask:0xf bound_ctrl:1
	s_and_saveexec_b64 s[0:1], s[6:7]
	v_add_f32_e32 v6, v6, v7
	v_add_f32_e32 v6, v110, v6
	ds_write_b32 v99, v6 offset:352
	s_or_b64 exec, exec, s[0:1]
	s_waitcnt vmcnt(8)
	v_mul_f32_e32 v3, v3, v109
	v_fmac_f32_e32 v3, v2, v107
	v_fmac_f32_e32 v3, v4, v108
	v_fmac_f32_e32 v3, v5, v106
	s_nop 1
	v_add_f32_dpp v2, v3, v3 quad_perm:[1,0,3,2] row_mask:0xf bank_mask:0xf bound_ctrl:1
	s_nop 1
	v_add_f32_dpp v2, v2, v2 quad_perm:[2,3,0,1] row_mask:0xf bank_mask:0xf bound_ctrl:1
	s_nop 1
	v_add_f32_dpp v2, v2, v2 row_ror:4 row_mask:0xf bank_mask:0xf bound_ctrl:1
	s_nop 1
	v_mov_b32_dpp v3, v2 row_ror:8 row_mask:0xf bank_mask:0xf bound_ctrl:1
	s_and_saveexec_b64 s[0:1], s[6:7]
	v_add_f32_e32 v2, v2, v3
	v_add_f32_e32 v2, v110, v2
	ds_write_b32 v99, v2 offset:368
	s_or_b64 exec, exec, s[0:1]
	v_lshlrev_b64 v[2:3], 6, v[94:95]
	v_lshl_add_u64 v[6:7], v[2:3], 2, v[86:87]
	v_lshl_add_u64 v[50:51], v[6:7], 0, v[82:83]
	v_add_co_u32_e32 v2, vcc, 0x1000, v50
	v_mov_b32_e32 v93, v83
	s_nop 0
	v_addc_co_u32_e32 v3, vcc, 0, v51, vcc
	v_add_co_u32_e32 v8, vcc, 0x3000, v50
	v_lshl_add_u64 v[10:11], v[6:7], 0, v[92:93]
	s_nop 0
	v_addc_co_u32_e32 v9, vcc, 0, v51, vcc
	v_add_co_u32_e32 v14, vcc, s49, v50
	global_load_dwordx4 v[30:33], v[50:51], off
	s_nop 0
	global_load_dwordx4 v[2:5], v[2:3], off offset:2048
	v_addc_co_u32_e32 v15, vcc, 0, v51, vcc
	v_add_co_u32_e32 v18, vcc, 0x7000, v50
	global_load_dwordx4 v[6:9], v[8:9], off
	s_nop 0
	global_load_dwordx4 v[10:13], v[10:11], off
	v_addc_co_u32_e32 v19, vcc, 0, v51, vcc
	v_add_co_u32_e32 v22, vcc, 0x9000, v50
	global_load_dwordx4 v[14:17], v[14:15], off offset:2048
	s_nop 0
	global_load_dwordx4 v[18:21], v[18:19], off offset:2048
	v_addc_co_u32_e32 v23, vcc, 0, v51, vcc
	v_add_co_u32_e32 v26, vcc, 0xa000, v50
	s_waitcnt vmcnt(13)
	v_mul_f32_e32 v52, v79, v109
	v_addc_co_u32_e32 v27, vcc, 0, v51, vcc
	global_load_dwordx4 v[22:25], v[22:23], off
	s_nop 0
	global_load_dwordx4 v[26:29], v[26:27], off offset:2048
	v_fmac_f32_e32 v52, v78, v107
	v_fmac_f32_e32 v52, v80, v108
	v_fmac_f32_e32 v52, v81, v106
	s_nop 1
	v_add_f32_dpp v52, v52, v52 quad_perm:[1,0,3,2] row_mask:0xf bank_mask:0xf bound_ctrl:1
	s_nop 1
	v_add_f32_dpp v52, v52, v52 quad_perm:[2,3,0,1] row_mask:0xf bank_mask:0xf bound_ctrl:1
	s_nop 1
	v_add_f32_dpp v52, v52, v52 row_ror:4 row_mask:0xf bank_mask:0xf bound_ctrl:1
	s_nop 1
	v_mov_b32_dpp v53, v52 row_ror:8 row_mask:0xf bank_mask:0xf bound_ctrl:1
	s_and_saveexec_b64 s[0:1], s[6:7]
	v_add_f32_e32 v52, v52, v53
	v_add_f32_e32 v52, v110, v52
	ds_write_b32 v99, v52 offset:384
	s_or_b64 exec, exec, s[0:1]
	s_waitcnt vmcnt(14)
; template <int NB>
; __device__ __forceinline__ void sb_decode_task(const Params& P, float* lds, int task) {
;     ...
;     for (int kb = 0; kb < NBT; ++kb) {
;         const float* np = (kb + 1 < NBT) ? Kp + (size_t)(4 * NB * (kb + 1)) * (SH * HD) : Vp;
; #pragma unroll
;         for (int i = 0; i < NB; ++i) nx[i] = *(const float4*)(np + (size_t)(4 * i + g) * (SH * HD));
; #pragma unroll
;         for (int i = 0; i < NB; ++i) { const int s = 4 * NB * kb + 4 * i + g;
;             float part = q0 * cur[i].x + q1 * cur[i].y + q2 * cur[i].z + q3 * cur[i].w; part = sum16(part);
;             if (c == 0) zl[s] = part + bias; }
; #pragma unroll
;         for (int i = 0; i < NB; ++i) cur[i] = nx[i];
;     }
;     asm volatile("s_waitcnt lgkmcnt(0)" ::: "memory");
;     __builtin_amdgcn_wave_barrier();
;     const float z0 = zl[2 * lane], z1 = zl[2 * lane + 1];
	v_mul_f32_e32 v52, v71, v109
	v_fmac_f32_e32 v52, v70, v107
	v_fmac_f32_e32 v52, v72, v108
	v_fmac_f32_e32 v52, v73, v106
	s_nop 1
	v_add_f32_dpp v52, v52, v52 quad_perm:[1,0,3,2] row_mask:0xf bank_mask:0xf bound_ctrl:1
	s_nop 1
	v_add_f32_dpp v52, v52, v52 quad_perm:[2,3,0,1] row_mask:0xf bank_mask:0xf bound_ctrl:1
	s_nop 1
	v_add_f32_dpp v52, v52, v52 row_ror:4 row_mask:0xf bank_mask:0xf bound_ctrl:1
	s_nop 1
	v_mov_b32_dpp v53, v52 row_ror:8 row_mask:0xf bank_mask:0xf bound_ctrl:1
	s_and_saveexec_b64 s[0:1], s[6:7]
	v_add_f32_e32 v52, v52, v53
	v_add_f32_e32 v52, v110, v52
	ds_write_b32 v99, v52 offset:400
	s_or_b64 exec, exec, s[0:1]
	s_waitcnt vmcnt(13)
	v_mul_f32_e32 v52, v63, v109
	v_fmac_f32_e32 v52, v62, v107
	v_fmac_f32_e32 v52, v64, v108
	v_fmac_f32_e32 v52, v65, v106
	s_nop 1
	v_add_f32_dpp v52, v52, v52 quad_perm:[1,0,3,2] row_mask:0xf bank_mask:0xf bound_ctrl:1
	s_nop 1
	v_add_f32_dpp v52, v52, v52 quad_perm:[2,3,0,1] row_mask:0xf bank_mask:0xf bound_ctrl:1
	s_nop 1
	v_add_f32_dpp v52, v52, v52 row_ror:4 row_mask:0xf bank_mask:0xf bound_ctrl:1
	s_nop 1
	v_mov_b32_dpp v53, v52 row_ror:8 row_mask:0xf bank_mask:0xf bound_ctrl:1
	s_and_saveexec_b64 s[0:1], s[6:7]
	v_add_f32_e32 v52, v52, v53
	v_add_f32_e32 v52, v110, v52
	ds_write_b32 v99, v52 offset:416
	s_or_b64 exec, exec, s[0:1]
	s_waitcnt vmcnt(12)
	v_mul_f32_e32 v52, v55, v109
	v_fmac_f32_e32 v52, v54, v107
	v_fmac_f32_e32 v52, v56, v108
	v_fmac_f32_e32 v52, v57, v106
	s_nop 1
	v_add_f32_dpp v52, v52, v52 quad_perm:[1,0,3,2] row_mask:0xf bank_mask:0xf bound_ctrl:1
	s_nop 1
	v_add_f32_dpp v52, v52, v52 quad_perm:[2,3,0,1] row_mask:0xf bank_mask:0xf bound_ctrl:1
	s_nop 1
	v_add_f32_dpp v52, v52, v52 row_ror:4 row_mask:0xf bank_mask:0xf bound_ctrl:1
	s_nop 1
	v_mov_b32_dpp v53, v52 row_ror:8 row_mask:0xf bank_mask:0xf bound_ctrl:1
	s_and_saveexec_b64 s[0:1], s[6:7]
	v_add_f32_e32 v52, v52, v53
	v_add_f32_e32 v52, v110, v52
	ds_write_b32 v99, v52 offset:432
	s_or_b64 exec, exec, s[0:1]
	s_waitcnt vmcnt(11)
	v_mul_f32_e32 v47, v47, v109
	v_fmac_f32_e32 v47, v46, v107
	v_fmac_f32_e32 v47, v48, v108
	v_fmac_f32_e32 v47, v49, v106
	s_nop 1
	v_add_f32_dpp v46, v47, v47 quad_perm:[1,0,3,2] row_mask:0xf bank_mask:0xf bound_ctrl:1
	s_nop 1
	v_add_f32_dpp v46, v46, v46 quad_perm:[2,3,0,1] row_mask:0xf bank_mask:0xf bound_ctrl:1
	s_nop 1
	v_add_f32_dpp v46, v46, v46 row_ror:4 row_mask:0xf bank_mask:0xf bound_ctrl:1
	s_nop 1
	v_mov_b32_dpp v47, v46 row_ror:8 row_mask:0xf bank_mask:0xf bound_ctrl:1
	s_and_saveexec_b64 s[0:1], s[6:7]
	v_add_f32_e32 v46, v46, v47
	v_add_f32_e32 v46, v110, v46
	ds_write_b32 v99, v46 offset:448
	s_or_b64 exec, exec, s[0:1]
	s_waitcnt vmcnt(10)
	v_mul_f32_e32 v43, v43, v109
	v_fmac_f32_e32 v43, v42, v107
	v_fmac_f32_e32 v43, v44, v108
	v_fmac_f32_e32 v43, v45, v106
	s_nop 1
	v_add_f32_dpp v42, v43, v43 quad_perm:[1,0,3,2] row_mask:0xf bank_mask:0xf bound_ctrl:1
	s_nop 1
	v_add_f32_dpp v42, v42, v42 quad_perm:[2,3,0,1] row_mask:0xf bank_mask:0xf bound_ctrl:1
	s_nop 1
	v_add_f32_dpp v42, v42, v42 row_ror:4 row_mask:0xf bank_mask:0xf bound_ctrl:1
	s_nop 1
	v_mov_b32_dpp v43, v42 row_ror:8 row_mask:0xf bank_mask:0xf bound_ctrl:1
	s_and_saveexec_b64 s[0:1], s[6:7]
	v_add_f32_e32 v42, v42, v43
	v_add_f32_e32 v42, v110, v42
	ds_write_b32 v99, v42 offset:464
	s_or_b64 exec, exec, s[0:1]
	s_waitcnt vmcnt(9)
	v_mul_f32_e32 v39, v39, v109
	v_fmac_f32_e32 v39, v38, v107
	v_fmac_f32_e32 v39, v40, v108
	v_fmac_f32_e32 v39, v41, v106
	s_nop 1
	v_add_f32_dpp v38, v39, v39 quad_perm:[1,0,3,2] row_mask:0xf bank_mask:0xf bound_ctrl:1
	s_nop 1
	v_add_f32_dpp v38, v38, v38 quad_perm:[2,3,0,1] row_mask:0xf bank_mask:0xf bound_ctrl:1
	s_nop 1
	v_add_f32_dpp v38, v38, v38 row_ror:4 row_mask:0xf bank_mask:0xf bound_ctrl:1
	s_nop 1
	v_mov_b32_dpp v39, v38 row_ror:8 row_mask:0xf bank_mask:0xf bound_ctrl:1
	s_and_saveexec_b64 s[0:1], s[6:7]
	v_add_f32_e32 v38, v38, v39
	v_add_f32_e32 v38, v110, v38
	ds_write_b32 v99, v38 offset:480
	s_or_b64 exec, exec, s[0:1]
	s_waitcnt vmcnt(8)
	v_mul_f32_e32 v35, v35, v109
	v_fmac_f32_e32 v35, v34, v107
	v_fmac_f32_e32 v35, v36, v108
	v_fmac_f32_e32 v35, v37, v106
	s_nop 1
	v_add_f32_dpp v34, v35, v35 quad_perm:[1,0,3,2] row_mask:0xf bank_mask:0xf bound_ctrl:1
	s_nop 1
	v_add_f32_dpp v34, v34, v34 quad_perm:[2,3,0,1] row_mask:0xf bank_mask:0xf bound_ctrl:1
	s_nop 1
	v_add_f32_dpp v34, v34, v34 row_ror:4 row_mask:0xf bank_mask:0xf bound_ctrl:1
	s_nop 1
	v_mov_b32_dpp v35, v34 row_ror:8 row_mask:0xf bank_mask:0xf bound_ctrl:1
	s_and_saveexec_b64 s[0:1], s[6:7]
	v_add_f32_e32 v34, v34, v35
	v_add_f32_e32 v34, v110, v34
	ds_write_b32 v99, v34 offset:496
	s_or_b64 exec, exec, s[0:1]
	s_waitcnt lgkmcnt(0)
	ds_read_b64 v[34:35], v100
	s_waitcnt lgkmcnt(0)
; __device__ __forceinline__ float softplus2_(float z2) { return fmaxf(z2, 0.f) + log1pf(exp2f(-fabsf(z2))) * LOG2E; }
; template <int NB>
; __device__ __forceinline__ void sb_decode_task(const Params& P, float* lds, int task) {
;     ...
;     const float sp0 = softplus2_(z0), sp1 = softplus2_(z1);
	v_cmp_gt_f32_e64 vcc, |v34|, s97
	s_nop 1
	v_cndmask_b32_e32 v37, 0, v103, vcc
	v_sub_f32_e64 v37, v37, |v34|
	v_exp_f32_e32 v37, v37
	v_max_f32_e32 v36, v34, v34
	v_max_f32_e32 v38, 0, v36
	v_cndmask_b32_e32 v36, 0, v102, vcc
	v_ldexp_f32 v39, v37, v36
	v_add_f32_e32 v40, 1.0, v39
	v_add_f32_e32 v36, -1.0, v40
	v_sub_f32_e32 v37, v36, v40
	v_add_f32_e32 v37, 1.0, v37
	v_sub_f32_e32 v36, v39, v36
	v_add_f32_e32 v41, v36, v37
	v_frexp_mant_f32_e32 v36, v40
	v_cmp_gt_f32_e32 vcc, s47, v36
	v_cvt_f64_f32_e32 v[36:37], v40
	v_frexp_exp_i32_f64_e32 v36, v[36:37]
	v_subbrev_co_u32_e32 v36, vcc, 0, v36, vcc
	v_sub_u32_e32 v37, 0, v36
	v_ldexp_f32 v40, v40, v37
	v_ldexp_f32 v37, v41, v37
	v_add_f32_e32 v41, -1.0, v40
	v_add_f32_e32 v42, 1.0, v41
	v_sub_f32_e32 v42, v40, v42
	v_add_f32_e32 v42, v37, v42
	v_add_f32_e32 v43, v41, v42
	v_sub_f32_e32 v41, v41, v43
	v_add_f32_e32 v41, v42, v41
	v_add_f32_e32 v42, 1.0, v40
	v_add_f32_e32 v44, -1.0, v42
	v_sub_f32_e32 v40, v40, v44
	v_add_f32_e32 v37, v37, v40
	v_add_f32_e32 v40, v42, v37
	v_sub_f32_e32 v42, v42, v40
	v_add_f32_e32 v37, v37, v42
	v_rcp_f32_e32 v42, v40
	v_cvt_f32_i32_e32 v36, v36
	v_cmp_neq_f32_e32 vcc, s46, v39
	v_mul_f32_e32 v44, v43, v42
	v_mul_f32_e32 v45, v40, v44
	v_fma_f32 v46, v44, v40, -v45
	v_fmac_f32_e32 v46, v44, v37
	v_add_f32_e32 v47, v45, v46
	v_sub_f32_e32 v48, v43, v47
	v_sub_f32_e32 v43, v43, v48
	v_sub_f32_e32 v45, v47, v45
	v_sub_f32_e32 v43, v43, v47
	v_add_f32_e32 v41, v41, v43
	v_sub_f32_e32 v43, v45, v46
	v_add_f32_e32 v41, v43, v41
	v_add_f32_e32 v43, v48, v41
	v_mul_f32_e32 v45, v42, v43
	v_mul_f32_e32 v46, v40, v45
	v_fma_f32 v40, v45, v40, -v46
	v_fmac_f32_e32 v40, v45, v37
	v_sub_f32_e32 v37, v48, v43
	v_add_f32_e32 v37, v41, v37
	v_add_f32_e32 v41, v46, v40
	v_sub_f32_e32 v47, v43, v41
	v_sub_f32_e32 v43, v43, v47
	v_sub_f32_e32 v46, v41, v46
	v_sub_f32_e32 v41, v43, v41
	v_add_f32_e32 v37, v37, v41
	v_sub_f32_e32 v40, v46, v40
	v_add_f32_e32 v37, v40, v37
	v_add_f32_e32 v40, v44, v45
	v_add_f32_e32 v37, v47, v37
	v_sub_f32_e32 v41, v40, v44
	v_mul_f32_e32 v37, v42, v37
	v_sub_f32_e32 v41, v45, v41
	v_add_f32_e32 v37, v41, v37
	v_mul_f32_e32 v44, 0x3f317218, v36
	v_add_f32_e32 v41, v40, v37
	v_fma_f32 v45, v36, s95, -v44
	v_mul_f32_e32 v42, v41, v41
	v_fmac_f32_e32 v45, 0xb102e308, v36
	v_sub_f32_e32 v36, v41, v40
	v_fmamk_f32 v43, v42, 0x3e9b6dac, v1
	v_sub_f32_e32 v36, v37, v36
	v_add_f32_e32 v37, v44, v45
	v_fmaak_f32 v43, v42, v43, 0x3f2aaada
	v_sub_f32_e32 v40, v37, v44
	v_ldexp_f32 v44, v41, 1
	v_mul_f32_e32 v41, v41, v42
	v_mul_f32_e32 v41, v41, v43
	v_add_f32_e32 v42, v44, v41
	v_sub_f32_e32 v43, v42, v44
	v_ldexp_f32 v36, v36, 1
	v_sub_f32_e32 v41, v41, v43
	v_add_f32_e32 v36, v36, v41
	v_add_f32_e32 v41, v42, v36
	v_sub_f32_e32 v42, v41, v42
	v_sub_f32_e32 v36, v36, v42
	v_add_f32_e32 v42, v37, v41
	v_sub_f32_e32 v43, v42, v37
	v_sub_f32_e32 v44, v42, v43
	v_sub_f32_e32 v40, v45, v40
	v_sub_f32_e32 v37, v37, v44
	v_sub_f32_e32 v41, v41, v43
	v_add_f32_e32 v37, v41, v37
	v_add_f32_e32 v41, v40, v36
	v_sub_f32_e32 v43, v41, v40
	v_sub_f32_e32 v44, v41, v43
	v_sub_f32_e32 v40, v40, v44
	v_sub_f32_e32 v36, v36, v43
	v_add_f32_e32 v37, v41, v37
	v_add_f32_e32 v36, v36, v40
	v_add_f32_e32 v40, v42, v37
	v_sub_f32_e32 v41, v40, v42
	v_sub_f32_e32 v37, v37, v41
	v_add_f32_e32 v36, v36, v37
	v_add_f32_e32 v36, v40, v36
	v_cndmask_b32_e32 v36, v104, v36, vcc
	v_cmp_lt_f32_e64 vcc, |v39|, s45
	s_nop 1
	v_cndmask_b32_e32 v36, v36, v39, vcc
	v_cmp_gt_f32_e64 vcc, |v35|, s97
	v_fmac_f32_e32 v38, 0x3fb8aa3b, v36
	v_max_f32_e32 v36, v35, v35
	v_cndmask_b32_e32 v37, 0, v103, vcc
	v_sub_f32_e64 v37, v37, |v35|
	v_exp_f32_e32 v37, v37
	v_max_f32_e32 v39, 0, v36
	v_cndmask_b32_e32 v36, 0, v102, vcc
	v_sub_f32_e32 v34, v34, v38
	v_ldexp_f32 v40, v37, v36
	v_add_f32_e32 v41, 1.0, v40
	v_add_f32_e32 v36, -1.0, v41
	v_sub_f32_e32 v37, v36, v41
	v_add_f32_e32 v37, 1.0, v37
	v_sub_f32_e32 v36, v40, v36
	v_add_f32_e32 v42, v36, v37
	v_frexp_mant_f32_e32 v36, v41
	v_cmp_gt_f32_e32 vcc, s47, v36
	v_cvt_f64_f32_e32 v[36:37], v41
	v_frexp_exp_i32_f64_e32 v36, v[36:37]
	v_subbrev_co_u32_e32 v36, vcc, 0, v36, vcc
	v_sub_u32_e32 v37, 0, v36
	v_ldexp_f32 v41, v41, v37
	v_ldexp_f32 v37, v42, v37
	v_add_f32_e32 v42, -1.0, v41
	v_add_f32_e32 v43, 1.0, v42
	v_sub_f32_e32 v43, v41, v43
	v_add_f32_e32 v43, v37, v43
	v_add_f32_e32 v44, v42, v43
	v_sub_f32_e32 v42, v42, v44
	v_add_f32_e32 v42, v43, v42
	v_add_f32_e32 v43, 1.0, v41
	v_add_f32_e32 v45, -1.0, v43
	v_sub_f32_e32 v41, v41, v45
	v_add_f32_e32 v37, v37, v41
	v_add_f32_e32 v41, v43, v37
	v_sub_f32_e32 v43, v43, v41
	v_add_f32_e32 v37, v37, v43
	v_rcp_f32_e32 v43, v41
	v_cvt_f32_i32_e32 v36, v36
	v_cmp_neq_f32_e32 vcc, s46, v40
	v_mul_f32_e32 v45, v44, v43
	v_mul_f32_e32 v46, v41, v45
	v_fma_f32 v47, v45, v41, -v46
	v_fmac_f32_e32 v47, v45, v37
	v_add_f32_e32 v48, v46, v47
	v_sub_f32_e32 v49, v44, v48
	v_sub_f32_e32 v44, v44, v49
	v_sub_f32_e32 v46, v48, v46
	v_sub_f32_e32 v44, v44, v48
	v_add_f32_e32 v42, v42, v44
	v_sub_f32_e32 v44, v46, v47
	v_add_f32_e32 v42, v44, v42
	v_add_f32_e32 v44, v49, v42
	v_mul_f32_e32 v46, v43, v44
	v_mul_f32_e32 v47, v41, v46
	v_fma_f32 v41, v46, v41, -v47
	v_fmac_f32_e32 v41, v46, v37
	v_sub_f32_e32 v37, v49, v44
	v_add_f32_e32 v37, v42, v37
	v_add_f32_e32 v42, v47, v41
	v_sub_f32_e32 v48, v44, v42
	v_sub_f32_e32 v44, v44, v48
	v_sub_f32_e32 v47, v42, v47
	v_sub_f32_e32 v42, v44, v42
	v_add_f32_e32 v37, v37, v42
	v_sub_f32_e32 v41, v47, v41
	v_add_f32_e32 v37, v41, v37
	v_add_f32_e32 v41, v45, v46
	v_add_f32_e32 v37, v48, v37
	v_sub_f32_e32 v42, v41, v45
	v_mul_f32_e32 v37, v43, v37
; __device__ __forceinline__ float softplus2_(float z2) { return fmaxf(z2, 0.f) + log1pf(exp2f(-fabsf(z2))) * LOG2E; }
; template <int NB>
; __device__ __forceinline__ void sb_decode_task(const Params& P, float* lds, int task) {
;     ...
;     const float sp0 = softplus2_(z0), sp1 = softplus2_(z1);
;     float incl = sp0 + sp1;
; #pragma unroll
;     for (int off = 1; off < 64; off <<= 1) { const float t = __shfl_down(incl, off); if (lane + off < 64) incl += t; }
;     const float excl = incl - (sp0 + sp1);
;     wl[2 * lane] = exp2f(z0 - sp0 - (excl + sp1));
;     wl[2 * lane + 1] = exp2f(z1 - sp1 - excl);
;     const float Ltot = __shfl(incl, 0);
;     asm volatile("s_waitcnt lgkmcnt(0)" ::: "memory");
;     __builtin_amdgcn_wave_barrier();
;     float4 o4 = make_float4(0.f, 0.f, 0.f, 0.f);
; #pragma unroll
;     for (int vb = 0; vb < NBT; ++vb) {
;         if (vb + 1 < NBT) {
; #pragma unroll
;             for (int i = 0; i < NB; ++i) nx[i] = *(const float4*)(Vp + (size_t)(4 * NB * (vb + 1) + 4 * i + g) * (SH * HD)); }
; #pragma unroll
;         for (int i = 0; i < NB; ++i) { const float w = wl[4 * NB * vb + 4 * i + g]; o4.x += w * cur[i].x; o4.y += w * cur[i].y; o4.z += w * cur[i].z; o4.w += w * cur[i].w; }
; #pragma unroll
;         for (int i = 0; i < NB; ++i) cur[i] = nx[i];
;     }
	v_sub_f32_e32 v42, v46, v42
	v_add_f32_e32 v37, v42, v37
	v_mul_f32_e32 v45, 0x3f317218, v36
	v_add_f32_e32 v42, v41, v37
	v_fma_f32 v46, v36, s95, -v45
	v_mul_f32_e32 v43, v42, v42
	v_fmac_f32_e32 v46, 0xb102e308, v36
	v_sub_f32_e32 v36, v42, v41
	v_fmamk_f32 v44, v43, 0x3e9b6dac, v1
	v_sub_f32_e32 v36, v37, v36
	v_add_f32_e32 v37, v45, v46
	v_fmaak_f32 v44, v43, v44, 0x3f2aaada
	v_sub_f32_e32 v41, v37, v45
	v_ldexp_f32 v45, v42, 1
	v_mul_f32_e32 v42, v42, v43
	v_mul_f32_e32 v42, v42, v44
	v_add_f32_e32 v43, v45, v42
	v_sub_f32_e32 v44, v43, v45
	v_ldexp_f32 v36, v36, 1
	v_sub_f32_e32 v42, v42, v44
	v_add_f32_e32 v36, v36, v42
	v_add_f32_e32 v42, v43, v36
	v_sub_f32_e32 v43, v42, v43
	v_sub_f32_e32 v36, v36, v43
	v_add_f32_e32 v43, v37, v42
	v_sub_f32_e32 v44, v43, v37
	v_sub_f32_e32 v45, v43, v44
	v_sub_f32_e32 v41, v46, v41
	v_sub_f32_e32 v37, v37, v45
	v_sub_f32_e32 v42, v42, v44
	v_add_f32_e32 v37, v42, v37
	v_add_f32_e32 v42, v41, v36
	v_sub_f32_e32 v44, v42, v41
	v_sub_f32_e32 v45, v42, v44
	v_sub_f32_e32 v41, v41, v45
	v_sub_f32_e32 v36, v36, v44
	v_add_f32_e32 v37, v42, v37
	v_add_f32_e32 v36, v36, v41
	v_add_f32_e32 v41, v43, v37
	v_sub_f32_e32 v42, v41, v43
	v_sub_f32_e32 v37, v37, v42
	v_add_f32_e32 v36, v36, v37
	v_add_f32_e32 v36, v41, v36
	v_cndmask_b32_e32 v36, v104, v36, vcc
	v_cmp_lt_f32_e64 vcc, |v40|, s45
	v_and_b32_e32 v37, 63, v105
	s_nop 0
	v_cndmask_b32_e32 v36, v36, v40, vcc
	v_cmp_ne_u32_e32 vcc, 63, v37
	v_fmac_f32_e32 v39, 0x3fb8aa3b, v36
	v_add_f32_e32 v36, v38, v39
	v_addc_co_u32_e32 v40, vcc, 0, v105, vcc
	v_lshlrev_b32_e32 v108, 2, v40
	ds_bpermute_b32 v40, v108, v36
	v_cmp_gt_u32_e32 vcc, 62, v37
	v_sub_f32_e32 v35, v35, v39
	s_waitcnt lgkmcnt(0)
	v_add_f32_e32 v40, v36, v40
	v_cndmask_b32_e64 v41, 0, 2, vcc
	v_cndmask_b32_e64 v40, v40, v36, s[8:9]
	v_add_lshl_u32 v109, v41, v105, 2
	ds_bpermute_b32 v41, v109, v40
	v_cmp_gt_u32_e32 vcc, 60, v37
	s_waitcnt lgkmcnt(0)
	v_add_f32_e32 v41, v40, v41
	v_cndmask_b32_e64 v40, v40, v41, s[10:11]
	v_cndmask_b32_e64 v41, 0, 4, vcc
	v_add_lshl_u32 v110, v41, v105, 2
	ds_bpermute_b32 v41, v110, v40
	v_cmp_gt_u32_e32 vcc, 56, v37
	s_waitcnt lgkmcnt(0)
	v_add_f32_e32 v41, v40, v41
	v_cndmask_b32_e64 v40, v40, v41, s[12:13]
	v_cndmask_b32_e64 v41, 0, 8, vcc
	v_add_lshl_u32 v111, v41, v105, 2
	ds_bpermute_b32 v41, v111, v40
	v_cmp_gt_u32_e32 vcc, 48, v37
	s_waitcnt lgkmcnt(0)
	v_add_f32_e32 v41, v40, v41
	v_cndmask_b32_e64 v37, 0, 16, vcc
	v_cndmask_b32_e64 v40, v40, v41, s[14:15]
	v_add_lshl_u32 v112, v37, v105, 2
	ds_bpermute_b32 v37, v112, v40
	s_waitcnt lgkmcnt(0)
	v_add_f32_e32 v37, v40, v37
	v_cndmask_b32_e64 v37, v40, v37, s[16:17]
	v_lshlrev_b32_e32 v40, 2, v105
	v_or_b32_e32 v113, 0x80, v40
	ds_bpermute_b32 v41, v113, v37
	v_and_b32_e32 v106, 0x100, v40
	s_waitcnt lgkmcnt(0)
	v_add_f32_e32 v41, v37, v41
	v_cndmask_b32_e64 v44, v37, v41, s[18:19]
	v_sub_f32_e32 v36, v44, v36
	v_add_f32_e32 v37, v39, v36
	v_sub_f32_e32 v34, v34, v37
	v_cmp_gt_f32_e32 vcc, s24, v34
	v_sub_f32_e32 v35, v35, v36
	s_nop 0
	v_cndmask_b32_e32 v37, 0, v103, vcc
	v_add_f32_e32 v34, v34, v37
	v_cndmask_b32_e32 v37, 0, v102, vcc
	v_cmp_gt_f32_e32 vcc, s24, v35
	v_exp_f32_e32 v34, v34
	s_nop 0
	v_cndmask_b32_e32 v36, 0, v103, vcc
	v_add_f32_e32 v35, v35, v36
	v_exp_f32_e32 v35, v35
	v_cndmask_b32_e32 v36, 0, v102, vcc
	v_ldexp_f32 v34, v34, v37
	v_ldexp_f32 v35, v35, v36
	ds_write_b64 v100, v[34:35] offset:512
	s_waitcnt lgkmcnt(0)
	ds_read2_b32 v[34:35], v99 offset0:128 offset1:132
	ds_read2_b32 v[42:43], v99 offset0:136 offset1:140
	ds_read2_b32 v[66:67], v99 offset0:144 offset1:148
	ds_read2_b32 v[68:69], v99 offset0:152 offset1:156
	ds_read2_b32 v[74:75], v99 offset0:160 offset1:164
	ds_read2_b32 v[76:77], v99 offset0:168 offset1:172
	ds_read2_b32 v[38:39], v99 offset0:176 offset1:180
	ds_read2_b32 v[40:41], v99 offset0:184 offset1:188
	s_waitcnt vmcnt(7) lgkmcnt(7)
	v_pk_fma_f32 v[70:71], v[30:31], v[34:35], 0 op_sel_hi:[1,0,0]
	v_add_co_u32_e32 v30, vcc, s25, v50
	v_pk_fma_f32 v[72:73], v[32:33], v[34:35], 0 op_sel_hi:[1,0,0]
	s_nop 0
	v_addc_co_u32_e32 v31, vcc, 0, v51, vcc
	v_add_co_u32_e32 v34, vcc, s43, v50
	v_mov_b32_e32 v64, v35
	s_nop 0
	v_addc_co_u32_e32 v35, vcc, 0, v51, vcc
	v_add_co_u32_e32 v46, vcc, s44, v50
	s_waitcnt vmcnt(6)
	v_pk_fma_f32 v[2:3], v[2:3], v[64:65], v[70:71] op_sel_hi:[1,0,1]
	v_addc_co_u32_e32 v47, vcc, 0, v51, vcc
	v_add_co_u32_e32 v52, vcc, s26, v50
	global_load_dwordx4 v[46:49], v[46:47], off
	s_nop 0
	v_addc_co_u32_e32 v53, vcc, 0, v51, vcc
	v_add_co_u32_e32 v56, vcc, s27, v50
	global_load_dwordx4 v[52:55], v[52:53], off offset:2048
	s_nop 0
	v_addc_co_u32_e32 v57, vcc, 0, v51, vcc
	v_add_co_u32_e32 v60, vcc, s28, v50
	global_load_dwordx4 v[56:59], v[56:57], off
	s_nop 0
	v_addc_co_u32_e32 v61, vcc, 0, v51, vcc
	global_load_dwordx4 v[60:63], v[60:61], off offset:2048
	s_waitcnt lgkmcnt(6)
	v_mov_b32_e32 v78, v43
	s_waitcnt vmcnt(9)
	v_pk_fma_f32 v[2:3], v[6:7], v[42:43], v[2:3] op_sel_hi:[1,0,1]
	s_waitcnt lgkmcnt(5)
	v_mov_b32_e32 v80, v67
	s_waitcnt vmcnt(7)
	v_pk_fma_f32 v[2:3], v[14:15], v[78:79], v[2:3] op_sel_hi:[1,0,1]
	s_waitcnt lgkmcnt(4)
	v_mov_b32_e32 v94, v69
	v_pk_fma_f32 v[2:3], v[10:11], v[66:67], v[2:3] op_sel_hi:[1,0,1]
	s_waitcnt lgkmcnt(3)
	v_mov_b32_e32 v10, v75
	s_waitcnt vmcnt(6)
	v_pk_fma_f32 v[2:3], v[18:19], v[80:81], v[2:3] op_sel_hi:[1,0,1]
	s_waitcnt lgkmcnt(2)
	v_mov_b32_e32 v14, v77
	s_waitcnt vmcnt(5)
	v_pk_fma_f32 v[2:3], v[22:23], v[68:69], v[2:3] op_sel_hi:[1,0,1]
	global_load_dwordx4 v[30:33], v[30:31], off
	s_waitcnt vmcnt(5)
	v_pk_fma_f32 v[2:3], v[26:27], v[94:95], v[2:3] op_sel_hi:[1,0,1]
	global_load_dwordx4 v[34:37], v[34:35], off offset:2048
	s_waitcnt vmcnt(5)
; template <int NB>
; __device__ __forceinline__ void sb_decode_task(const Params& P, float* lds, int task) {
;     ...
;     for (int vb = 0; vb < NBT; ++vb) {
;         if (vb + 1 < NBT) {
; #pragma unroll
;             for (int i = 0; i < NB; ++i) nx[i] = *(const float4*)(Vp + (size_t)(4 * NB * (vb + 1) + 4 * i + g) * (SH * HD)); }
; #pragma unroll
;         for (int i = 0; i < NB; ++i) { const float w = wl[4 * NB * vb + 4 * i + g]; o4.x += w * cur[i].x; o4.y += w * cur[i].y; o4.z += w * cur[i].z; o4.w += w * cur[i].w; }
; #pragma unroll
;         for (int i = 0; i < NB; ++i) cur[i] = nx[i];
;     }
	v_pk_fma_f32 v[2:3], v[46:47], v[74:75], v[2:3] op_sel_hi:[1,0,1]
	s_waitcnt vmcnt(4)
	v_pk_fma_f32 v[2:3], v[52:53], v[10:11], v[2:3] op_sel_hi:[1,0,1]
	s_waitcnt vmcnt(3)
	v_pk_fma_f32 v[2:3], v[56:57], v[76:77], v[2:3] op_sel_hi:[1,0,1]
	s_waitcnt vmcnt(2)
	v_pk_fma_f32 v[6:7], v[60:61], v[14:15], v[2:3] op_sel_hi:[1,0,1]
	v_pk_fma_f32 v[2:3], v[4:5], v[64:65], v[72:73] op_sel_hi:[1,0,1]
	v_add_co_u32_e32 v4, vcc, s29, v50
	v_pk_fma_f32 v[2:3], v[8:9], v[42:43], v[2:3] op_sel_hi:[1,0,1]
	s_nop 0
	v_addc_co_u32_e32 v5, vcc, 0, v51, vcc
	v_pk_fma_f32 v[2:3], v[16:17], v[78:79], v[2:3] op_sel_hi:[1,0,1]
	s_waitcnt lgkmcnt(0)
	v_mov_b32_e32 v42, v41
	v_pk_fma_f32 v[2:3], v[12:13], v[66:67], v[2:3] op_sel_hi:[1,0,1]
	s_waitcnt vmcnt(1)
	v_pk_fma_f32 v[6:7], v[30:31], v[38:39], v[6:7] op_sel_hi:[1,0,1]
	v_pk_fma_f32 v[2:3], v[20:21], v[80:81], v[2:3] op_sel_hi:[1,0,1]
	s_nop 0
	v_pk_fma_f32 v[2:3], v[24:25], v[68:69], v[2:3] op_sel_hi:[1,0,1]
	s_nop 0
	v_pk_fma_f32 v[2:3], v[28:29], v[94:95], v[2:3] op_sel_hi:[1,0,1]
	v_mov_b32_e32 v28, v39
	v_pk_fma_f32 v[2:3], v[48:49], v[74:75], v[2:3] op_sel_hi:[1,0,1]
	s_waitcnt vmcnt(0)
	v_pk_fma_f32 v[6:7], v[34:35], v[28:29], v[6:7] op_sel_hi:[1,0,1]
	v_pk_fma_f32 v[2:3], v[54:55], v[10:11], v[2:3] op_sel_hi:[1,0,1]
	s_nop 0
	v_pk_fma_f32 v[2:3], v[58:59], v[76:77], v[2:3] op_sel_hi:[1,0,1]
	s_nop 0
	v_pk_fma_f32 v[2:3], v[62:63], v[14:15], v[2:3] op_sel_hi:[1,0,1]
	ds_read2_b32 v[14:15], v99 offset0:192 offset1:196
	ds_read2_b32 v[12:13], v99 offset0:200 offset1:204
	ds_read2_b32 v[10:11], v99 offset0:208 offset1:212
	ds_read2_b32 v[8:9], v99 offset0:216 offset1:220
	global_load_dwordx4 v[16:19], v[4:5], off
	v_add_co_u32_e32 v4, vcc, s68, v50
	v_pk_fma_f32 v[2:3], v[32:33], v[38:39], v[2:3] op_sel_hi:[1,0,1]
	s_nop 0
	v_addc_co_u32_e32 v5, vcc, 0, v51, vcc
	global_load_dwordx4 v[20:23], v[4:5], off offset:2048
	v_add_co_u32_e32 v4, vcc, s69, v50
	v_pk_fma_f32 v[2:3], v[36:37], v[28:29], v[2:3] op_sel_hi:[1,0,1]
	s_nop 0
	v_addc_co_u32_e32 v5, vcc, 0, v51, vcc
	global_load_dwordx4 v[24:27], v[4:5], off
	v_add_co_u32_e32 v4, vcc, s70, v50
	s_waitcnt lgkmcnt(0)
	v_mov_b32_e32 v36, v9
	v_addc_co_u32_e32 v5, vcc, 0, v51, vcc
	global_load_dwordx4 v[46:49], v[4:5], off offset:2048
	v_add_co_u32_e32 v4, vcc, s71, v50
	ds_read2_b32 v[30:31], v99 offset0:224 offset1:228
	s_nop 0
	v_addc_co_u32_e32 v5, vcc, 0, v51, vcc
	global_load_dwordx4 v[52:55], v[4:5], off
	v_add_co_u32_e32 v4, vcc, s72, v50
	s_waitcnt vmcnt(4)
	v_pk_fma_f32 v[2:3], v[18:19], v[40:41], v[2:3] op_sel_hi:[1,0,1]
	v_addc_co_u32_e32 v5, vcc, 0, v51, vcc
	global_load_dwordx4 v[56:59], v[4:5], off offset:2048
	v_add_co_u32_e32 v4, vcc, s73, v50
	s_waitcnt vmcnt(4)
	v_pk_fma_f32 v[2:3], v[22:23], v[42:43], v[2:3] op_sel_hi:[1,0,1]
	v_addc_co_u32_e32 v5, vcc, 0, v51, vcc
	global_load_dwordx4 v[60:63], v[4:5], off
	v_add_co_u32_e32 v4, vcc, s74, v50
	s_waitcnt vmcnt(4)
	v_pk_fma_f32 v[2:3], v[26:27], v[14:15], v[2:3] op_sel_hi:[1,0,1]
	v_addc_co_u32_e32 v5, vcc, 0, v51, vcc
	global_load_dwordx4 v[64:67], v[4:5], off offset:2048
	v_add_co_u32_e32 v4, vcc, s75, v50
	v_mov_b32_e32 v18, v15
	s_nop 0
	v_addc_co_u32_e32 v5, vcc, 0, v51, vcc
	global_load_dwordx4 v[68:71], v[4:5], off
	v_pk_fma_f32 v[6:7], v[16:17], v[40:41], v[6:7] op_sel_hi:[1,0,1]
	s_waitcnt vmcnt(5)
	v_pk_fma_f32 v[2:3], v[48:49], v[18:19], v[2:3] op_sel_hi:[1,0,1]
	v_pk_fma_f32 v[6:7], v[20:21], v[42:43], v[6:7] op_sel_hi:[1,0,1]
	s_waitcnt vmcnt(4)
	v_pk_fma_f32 v[2:3], v[54:55], v[12:13], v[2:3] op_sel_hi:[1,0,1]
	v_mov_b32_e32 v22, v13
	v_pk_fma_f32 v[6:7], v[24:25], v[14:15], v[6:7] op_sel_hi:[1,0,1]
	v_mov_b32_e32 v26, v11
	v_pk_fma_f32 v[6:7], v[46:47], v[18:19], v[6:7] op_sel_hi:[1,0,1]
	s_waitcnt vmcnt(3)
	v_pk_fma_f32 v[2:3], v[58:59], v[22:23], v[2:3] op_sel_hi:[1,0,1]
	v_pk_fma_f32 v[6:7], v[52:53], v[12:13], v[6:7] op_sel_hi:[1,0,1]
	s_waitcnt vmcnt(2)
	v_pk_fma_f32 v[2:3], v[62:63], v[10:11], v[2:3] op_sel_hi:[1,0,1]
	v_pk_fma_f32 v[6:7], v[56:57], v[22:23], v[6:7] op_sel_hi:[1,0,1]
	s_waitcnt vmcnt(1)
; template <int NB>
; __device__ __forceinline__ void sb_decode_task(const Params& P, float* lds, int task) {
;     ...
;     for (int vb = 0; vb < NBT; ++vb) {
;         if (vb + 1 < NBT) {
; #pragma unroll
;             for (int i = 0; i < NB; ++i) nx[i] = *(const float4*)(Vp + (size_t)(4 * NB * (vb + 1) + 4 * i + g) * (SH * HD)); }
; #pragma unroll
;         for (int i = 0; i < NB; ++i) { const float w = wl[4 * NB * vb + 4 * i + g]; o4.x += w * cur[i].x; o4.y += w * cur[i].y; o4.z += w * cur[i].z; o4.w += w * cur[i].w; }
; #pragma unroll
;         for (int i = 0; i < NB; ++i) cur[i] = nx[i];
;     }
; #pragma unroll
;     for (int off = 16; off < 64; off <<= 1) { o4.x += __shfl_xor(o4.x, off); o4.y += __shfl_xor(o4.y, off); o4.z += __shfl_xor(o4.z, off); o4.w += __shfl_xor(o4.w, off); }
;     if (g == 0) *(float4*)(dpart + (size_t)task * HD + 4 * c) = o4;
;     if (lane == 0) dl[task] = Ltot;
;     __builtin_amdgcn_wave_barrier();
	v_pk_fma_f32 v[2:3], v[66:67], v[26:27], v[2:3] op_sel_hi:[1,0,1]
	v_pk_fma_f32 v[6:7], v[60:61], v[10:11], v[6:7] op_sel_hi:[1,0,1]
	v_and_b32_e32 v10, 64, v105
	v_pk_fma_f32 v[6:7], v[64:65], v[26:27], v[6:7] op_sel_hi:[1,0,1]
	v_add_u32_e32 v37, 64, v10
	v_xor_b32_e32 v10, 16, v105
	s_waitcnt vmcnt(0)
	v_pk_fma_f32 v[32:33], v[70:71], v[8:9], v[2:3] op_sel_hi:[1,0,1]
	v_add_co_u32_e32 v2, vcc, s80, v50
	v_pk_fma_f32 v[34:35], v[68:69], v[8:9], v[6:7] op_sel_hi:[1,0,1]
	s_nop 0
	v_addc_co_u32_e32 v3, vcc, 0, v51, vcc
	v_add_co_u32_e32 v6, vcc, s81, v50
	global_load_dwordx4 v[2:5], v[2:3], off offset:2048
	s_nop 0
	v_addc_co_u32_e32 v7, vcc, 0, v51, vcc
	v_cmp_lt_i32_e32 vcc, v10, v37
	global_load_dwordx4 v[6:9], v[6:7], off
	ds_read2_b32 v[42:43], v99 offset0:232 offset1:236
	ds_read2_b32 v[40:41], v99 offset0:240 offset1:244
	ds_read2_b32 v[38:39], v99 offset0:248 offset1:252
	v_cndmask_b32_e32 v10, v105, v10, vcc
	v_lshlrev_b32_e32 v107, 2, v10
	v_add_co_u32_e32 v10, vcc, s82, v50
	s_waitcnt lgkmcnt(2)
	v_mov_b32_e32 v54, v43
	v_addc_co_u32_e32 v11, vcc, 0, v51, vcc
	v_add_co_u32_e32 v14, vcc, s83, v50
	global_load_dwordx4 v[10:13], v[10:11], off offset:2048
	s_nop 0
	v_addc_co_u32_e32 v15, vcc, 0, v51, vcc
	v_add_co_u32_e32 v18, vcc, s84, v50
	global_load_dwordx4 v[14:17], v[14:15], off
	s_nop 0
	v_addc_co_u32_e32 v19, vcc, 0, v51, vcc
	v_add_co_u32_e32 v22, vcc, s85, v50
	global_load_dwordx4 v[18:21], v[18:19], off offset:2048
	s_nop 0
	v_addc_co_u32_e32 v23, vcc, 0, v51, vcc
	v_add_co_u32_e32 v26, vcc, s86, v50
	global_load_dwordx4 v[22:25], v[22:23], off
	s_nop 0
	v_addc_co_u32_e32 v27, vcc, 0, v51, vcc
	v_add_co_u32_e32 v46, vcc, s87, v50
	global_load_dwordx4 v[26:29], v[26:27], off offset:2048
	s_nop 0
	v_addc_co_u32_e32 v47, vcc, 0, v51, vcc
	v_add_co_u32_e32 v50, vcc, s88, v50
	global_load_dwordx4 v[46:49], v[46:47], off
	s_nop 0
	v_addc_co_u32_e32 v51, vcc, 0, v51, vcc
	global_load_dwordx4 v[50:53], v[50:51], off offset:2048
	s_waitcnt lgkmcnt(1)
	v_mov_b32_e32 v56, v41
	s_waitcnt lgkmcnt(0)
	v_mov_b32_e32 v58, v39
	s_waitcnt vmcnt(8)
	v_pk_fma_f32 v[2:3], v[2:3], v[36:37], v[34:35] op_sel_hi:[1,0,1]
	v_mov_b32_e32 v34, v31
	v_pk_fma_f32 v[4:5], v[4:5], v[36:37], v[32:33] op_sel_hi:[1,0,1]
	s_waitcnt vmcnt(7)
	v_pk_fma_f32 v[2:3], v[6:7], v[30:31], v[2:3] op_sel_hi:[1,0,1]
	v_pk_fma_f32 v[4:5], v[8:9], v[30:31], v[4:5] op_sel_hi:[1,0,1]
	s_waitcnt vmcnt(6)
	v_pk_fma_f32 v[2:3], v[10:11], v[34:35], v[2:3] op_sel_hi:[1,0,1]
	v_pk_fma_f32 v[4:5], v[12:13], v[34:35], v[4:5] op_sel_hi:[1,0,1]
	ds_bpermute_b32 v10, v106, v44
	s_waitcnt vmcnt(5)
	v_pk_fma_f32 v[2:3], v[14:15], v[42:43], v[2:3] op_sel_hi:[1,0,1]
	v_pk_fma_f32 v[4:5], v[16:17], v[42:43], v[4:5] op_sel_hi:[1,0,1]
	s_waitcnt vmcnt(4)
	v_pk_fma_f32 v[2:3], v[18:19], v[54:55], v[2:3] op_sel_hi:[1,0,1]
	v_pk_fma_f32 v[4:5], v[20:21], v[54:55], v[4:5] op_sel_hi:[1,0,1]
	s_waitcnt vmcnt(3)
	v_pk_fma_f32 v[2:3], v[22:23], v[40:41], v[2:3] op_sel_hi:[1,0,1]
	v_pk_fma_f32 v[4:5], v[24:25], v[40:41], v[4:5] op_sel_hi:[1,0,1]
	s_waitcnt vmcnt(2)
	v_pk_fma_f32 v[2:3], v[26:27], v[56:57], v[2:3] op_sel_hi:[1,0,1]
	v_pk_fma_f32 v[4:5], v[28:29], v[56:57], v[4:5] op_sel_hi:[1,0,1]
	s_waitcnt vmcnt(1)
	v_pk_fma_f32 v[2:3], v[46:47], v[38:39], v[2:3] op_sel_hi:[1,0,1]
	v_pk_fma_f32 v[4:5], v[48:49], v[38:39], v[4:5] op_sel_hi:[1,0,1]
	s_waitcnt vmcnt(0)
	v_pk_fma_f32 v[2:3], v[50:51], v[58:59], v[2:3] op_sel_hi:[1,0,1]
	ds_bpermute_b32 v6, v107, v2
	ds_bpermute_b32 v7, v107, v3
	v_pk_fma_f32 v[4:5], v[52:53], v[58:59], v[4:5] op_sel_hi:[1,0,1]
	s_waitcnt lgkmcnt(0)
	v_pk_add_f32 v[2:3], v[2:3], v[6:7]
	ds_bpermute_b32 v6, v107, v4
	ds_bpermute_b32 v7, v107, v5
	s_waitcnt lgkmcnt(0)
	v_pk_add_f32 v[4:5], v[4:5], v[6:7]
	v_xor_b32_e32 v6, 32, v105
	v_cmp_lt_i32_e32 vcc, v6, v37
	s_nop 1
	v_cndmask_b32_e32 v6, v105, v6, vcc
	v_lshlrev_b32_e32 v114, 2, v6
	ds_bpermute_b32 v6, v114, v2
	ds_bpermute_b32 v7, v114, v3
	ds_bpermute_b32 v8, v114, v4
	ds_bpermute_b32 v9, v114, v5
	s_and_saveexec_b64 s[0:1], s[20:21]
	s_cbranch_execz .LBB0_1347
	s_ashr_i32 s35, s34, 31
	s_lshl_b64 s[36:37], s[34:35], 8
	v_lshl_add_u64 v[12:13], v[88:89], 0, s[36:37]
	s_waitcnt lgkmcnt(2)
	v_pk_add_f32 v[2:3], v[2:3], v[6:7]
	s_waitcnt lgkmcnt(0)
	v_pk_add_f32 v[4:5], v[4:5], v[8:9]
	global_store_dwordx4 v[12:13], v[2:5], off

; __device__ __forceinline__ float bf2f(bf16_t b) { return __uint_as_float(((unsigned)b) << 16); }
; template <int NB>
; __device__ __forceinline__ void sb_decode_task(const Params& P, float* lds, int task) {
;     ...
;     const int h = task % SH, bj = task / SH, b = bj / NPAGES;
;     const int page = P.page_table[bj];
;     const float* Kp = P.cache_k + ((size_t)page * PAGE * SH + h) * HD + 4 * c;
;     const float* Vp = P.cache_v + ((size_t)page * PAGE * SH + h) * HD + 4 * c;
;     const bf16_t* qp = qb + (size_t)(NTOK + b) * SBW + h * 64 + 4 * c;
;     const float q0 = bf2f(qp[0]), q1 = bf2f(qp[1]), q2 = bf2f(qp[2]), q3 = bf2f(qp[3]);
;     const float bias = P.sb_bias[h] * LOG2E;
;     float4 cur[NB], nx[NB];
; #pragma unroll
;     for (int i = 0; i < NB; ++i) cur[i] = *(const float4*)(Kp + (size_t)(4 * i + g) * (SH * HD));
; #pragma unroll
;     for (int kb = 0; kb < NBT; ++kb) {
;         const float* np = (kb + 1 < NBT) ? Kp + (size_t)(4 * NB * (kb + 1)) * (SH * HD) : Vp;
; #pragma unroll
;         for (int i = 0; i < NB; ++i) nx[i] = *(const float4*)(np + (size_t)(4 * i + g) * (SH * HD));
; #pragma unroll
;         for (int i = 0; i < NB; ++i) { const int s = 4 * NB * kb + 4 * i + g;
;             float part = q0 * cur[i].x + q1 * cur[i].y + q2 * cur[i].z + q3 * cur[i].w; part = sum16(part);
;             if (c == 0) zl[s] = part + bias; }
; __device__ __forceinline__ void sb_decode_wave_loop(const Params& P, float* lds) {
;     ...
;         if (blockIdx.x < 96 && scan_running) { sb_decode_task<4>(P, lds, t); sb_decode_task<4>(P, lds, t + 1); }
;         else if (thin) { sb_decode_task<8>(P, lds, t); sb_decode_task<8>(P, lds, t + 1); }
.LBB0_1349:
	s_or_b64 exec, exec, s[0:1]
	v_readlane_b32 s30, v252, 48
	s_add_i32 s36, s34, 1
	v_readlane_b32 s31, v252, 49
	s_mul_hi_i32 s1, s36, 0x2aaaaaab
	s_load_dwordx16 s[52:67], s[30:31], 0x0
	s_lshr_b32 s3, s1, 31
	s_add_i32 s0, s1, s3
	s_ashr_i32 s1, s1, 7
	s_mul_i32 s33, s0, 6
	s_add_i32 s3, s1, s3
	s_ashr_i32 s1, s0, 31
	s_sub_i32 s90, s36, s33
	s_lshl_b64 s[0:1], s[0:1], 2
	s_waitcnt lgkmcnt(0)
	s_add_u32 s0, s62, s0
	s_addc_u32 s1, s63, s1
	v_mov_b32_e32 v2, v253
	s_add_i32 s0, s3, 0x4000
	s_ashr_i32 s91, s90, 31
	s_mul_hi_i32 s1, s0, 0x300
	s_mulk_i32 s0, 0x300
	s_add_u32 s3, s38, s0
	s_addc_u32 s33, s39, s1
	s_lshl_b32 s0, s90, 6
	s_ashr_i32 s1, s0, 31
	s_lshl_b64 s[0:1], s[0:1], 1
	s_add_u32 s0, s3, s0
	s_addc_u32 s1, s33, s1
	v_readlane_b32 s52, v252, 16
	v_readlane_b32 s53, v252, 17
	v_readlane_b32 s60, v252, 24
	v_readlane_b32 s61, v252, 25
	s_mov_b64 s[52:53], s[60:61]
	v_mov_b32_e32 v93, v83
	v_readlane_b32 s54, v252, 18
	v_readlane_b32 s55, v252, 19
	v_readlane_b32 s56, v252, 20
	v_readlane_b32 s57, v252, 21
	v_readlane_b32 s58, v252, 22
	v_readlane_b32 s59, v252, 23
	v_readlane_b32 s62, v252, 26
	v_readlane_b32 s63, v252, 27
	v_readlane_b32 s64, v252, 28
	v_readlane_b32 s65, v252, 29
	v_readlane_b32 s66, v252, 30
	v_readlane_b32 s67, v252, 31
	v_mul_hi_i32 v3, v2, s48
	v_mul_lo_u32 v2, v2, s48
	v_lshl_add_u64 v[94:95], v[2:3], 0, s[90:91]
	v_lshlrev_b64 v[2:3], 8, v[94:95]
	v_lshl_add_u64 v[70:71], v[84:85], 0, v[2:3]
	global_load_dwordx2 v[2:3], v101, s[0:1]
	s_lshl_b64 s[0:1], s[90:91], 2
	s_add_u32 s0, s52, s0
	s_addc_u32 s1, s53, s1
	global_load_dword v22, v83, s[0:1]
	v_lshl_add_u64 v[18:19], v[70:71], 0, v[82:83]
	v_lshl_add_u64 v[20:21], v[70:71], 0, v[92:93]
	global_load_dwordx4 v[14:17], v[18:19], off
	s_mov_b64 s[0:1], 0xc000
	global_load_dwordx4 v[62:65], v[20:21], off
	s_waitcnt vmcnt(3)
	v_lshlrev_b32_e32 v116, 16, v2
	v_and_b32_e32 v118, 0xffff0000, v2
	v_add_co_u32_e32 v2, vcc, s50, v18
	v_lshlrev_b32_e32 v117, 16, v3
	v_and_b32_e32 v115, 0xffff0000, v3
	v_addc_co_u32_e32 v3, vcc, 0, v19, vcc
	global_load_dwordx4 v[10:13], v[2:3], off offset:2048
	v_add_co_u32_e32 v2, vcc, s51, v18
	s_waitcnt vmcnt(3)
	v_mul_f32_e32 v119, 0x3fb8aa3b, v22
	v_addc_co_u32_e32 v3, vcc, 0, v19, vcc
	global_load_dwordx4 v[6:9], v[2:3], off
	v_add_co_u32_e32 v2, vcc, s49, v18
	v_lshl_add_u64 v[22:23], v[70:71], 0, s[0:1]
	s_nop 0
	v_addc_co_u32_e32 v3, vcc, 0, v19, vcc
	v_add_co_u32_e32 v20, vcc, s92, v18
	v_lshl_add_u64 v[30:31], v[22:23], 0, v[82:83]
	s_nop 0
	v_addc_co_u32_e32 v21, vcc, 0, v19, vcc
	global_load_dwordx4 v[58:61], v[20:21], off offset:2048
	v_add_co_u32_e32 v20, vcc, s93, v18
	v_lshl_add_u64 v[22:23], v[22:23], 0, v[92:93]
	s_nop 0
	v_addc_co_u32_e32 v21, vcc, 0, v19, vcc
	v_add_co_u32_e32 v18, vcc, s96, v18
	global_load_dwordx4 v[54:57], v[20:21], off
	s_nop 0
	v_addc_co_u32_e32 v19, vcc, 0, v19, vcc
	global_load_dwordx4 v[50:53], v[18:19], off offset:2048
	v_add_co_u32_e32 v18, vcc, s50, v30
	global_load_dwordx4 v[22:25], v[22:23], off
	s_nop 0
	v_addc_co_u32_e32 v19, vcc, 0, v31, vcc
	global_load_dwordx4 v[34:37], v[18:19], off offset:2048
	v_add_co_u32_e32 v18, vcc, s51, v30
	global_load_dwordx4 v[2:5], v[2:3], off offset:2048
	s_nop 0
	v_addc_co_u32_e32 v19, vcc, 0, v31, vcc
	global_load_dwordx4 v[26:29], v[18:19], off
	v_add_co_u32_e32 v18, vcc, s49, v30
	global_load_dwordx4 v[46:49], v[30:31], off
	s_nop 0
	v_addc_co_u32_e32 v19, vcc, 0, v31, vcc
	v_add_co_u32_e32 v32, vcc, s92, v30
	global_load_dwordx4 v[18:21], v[18:19], off offset:2048
	s_nop 0
	v_addc_co_u32_e32 v33, vcc, 0, v31, vcc
	global_load_dwordx4 v[38:41], v[32:33], off offset:2048
	v_add_co_u32_e32 v32, vcc, s93, v30
	s_waitcnt vmcnt(13)
	v_mul_f32_e32 v15, v15, v118
	v_addc_co_u32_e32 v33, vcc, 0, v31, vcc
	v_add_co_u32_e32 v30, vcc, s96, v30
	global_load_dwordx4 v[42:45], v[32:33], off
	s_nop 0
	v_addc_co_u32_e32 v31, vcc, 0, v31, vcc
	global_load_dwordx4 v[30:33], v[30:31], off offset:2048
	v_fmac_f32_e32 v15, v14, v116
	v_fmac_f32_e32 v15, v16, v117
	v_fmac_f32_e32 v15, v17, v115
	s_nop 1
	v_add_f32_dpp v14, v15, v15 quad_perm:[1,0,3,2] row_mask:0xf bank_mask:0xf bound_ctrl:1
	s_nop 1
	v_add_f32_dpp v14, v14, v14 quad_perm:[2,3,0,1] row_mask:0xf bank_mask:0xf bound_ctrl:1
	s_nop 1
	v_add_f32_dpp v14, v14, v14 row_ror:4 row_mask:0xf bank_mask:0xf bound_ctrl:1
	s_nop 1
	v_mov_b32_dpp v15, v14 row_ror:8 row_mask:0xf bank_mask:0xf bound_ctrl:1
	s_and_saveexec_b64 s[0:1], s[6:7]
	v_add_f32_e32 v14, v14, v15
	v_add_f32_e32 v14, v119, v14
	ds_write_b32 v99, v14
	s_or_b64 exec, exec, s[0:1]
	s_waitcnt vmcnt(13)
	v_mul_f32_e32 v11, v11, v118
	v_fmac_f32_e32 v11, v10, v116
	v_fmac_f32_e32 v11, v12, v117
	v_fmac_f32_e32 v11, v13, v115
	s_nop 1
	v_add_f32_dpp v10, v11, v11 quad_perm:[1,0,3,2] row_mask:0xf bank_mask:0xf bound_ctrl:1
	s_nop 1
	v_add_f32_dpp v10, v10, v10 quad_perm:[2,3,0,1] row_mask:0xf bank_mask:0xf bound_ctrl:1
	s_nop 1
	v_add_f32_dpp v10, v10, v10 row_ror:4 row_mask:0xf bank_mask:0xf bound_ctrl:1
	s_nop 1
	v_mov_b32_dpp v11, v10 row_ror:8 row_mask:0xf bank_mask:0xf bound_ctrl:1
	s_and_saveexec_b64 s[0:1], s[6:7]
	v_add_f32_e32 v10, v10, v11
	v_add_f32_e32 v10, v119, v10
	ds_write_b32 v99, v10 offset:16
	s_or_b64 exec, exec, s[0:1]
	s_waitcnt vmcnt(12)
	v_mul_f32_e32 v7, v7, v118
	v_fmac_f32_e32 v7, v6, v116
	v_fmac_f32_e32 v7, v8, v117
	v_fmac_f32_e32 v7, v9, v115
	s_nop 1
	v_add_f32_dpp v6, v7, v7 quad_perm:[1,0,3,2] row_mask:0xf bank_mask:0xf bound_ctrl:1
	s_nop 1
	v_add_f32_dpp v6, v6, v6 quad_perm:[2,3,0,1] row_mask:0xf bank_mask:0xf bound_ctrl:1
	s_nop 1
	v_add_f32_dpp v6, v6, v6 row_ror:4 row_mask:0xf bank_mask:0xf bound_ctrl:1
	s_nop 1
	v_mov_b32_dpp v7, v6 row_ror:8 row_mask:0xf bank_mask:0xf bound_ctrl:1
	s_and_saveexec_b64 s[0:1], s[6:7]
	v_add_f32_e32 v6, v6, v7
	v_add_f32_e32 v6, v119, v6
	ds_write_b32 v99, v6 offset:32
	s_or_b64 exec, exec, s[0:1]
	s_waitcnt vmcnt(6)
; template <int NB>
; __device__ __forceinline__ void sb_decode_task(const Params& P, float* lds, int task) {
;     ...
;     for (int kb = 0; kb < NBT; ++kb) {
;         const float* np = (kb + 1 < NBT) ? Kp + (size_t)(4 * NB * (kb + 1)) * (SH * HD) : Vp;
; #pragma unroll
;         for (int i = 0; i < NB; ++i) nx[i] = *(const float4*)(np + (size_t)(4 * i + g) * (SH * HD));
; #pragma unroll
;         for (int i = 0; i < NB; ++i) { const int s = 4 * NB * kb + 4 * i + g;
;             float part = q0 * cur[i].x + q1 * cur[i].y + q2 * cur[i].z + q3 * cur[i].w; part = sum16(part);
;             if (c == 0) zl[s] = part + bias; }
	v_mul_f32_e32 v3, v3, v118
	v_fmac_f32_e32 v3, v2, v116
	v_fmac_f32_e32 v3, v4, v117
	v_fmac_f32_e32 v3, v5, v115
	s_nop 1
	v_add_f32_dpp v2, v3, v3 quad_perm:[1,0,3,2] row_mask:0xf bank_mask:0xf bound_ctrl:1
	s_nop 1
	v_add_f32_dpp v2, v2, v2 quad_perm:[2,3,0,1] row_mask:0xf bank_mask:0xf bound_ctrl:1
	s_nop 1
	v_add_f32_dpp v2, v2, v2 row_ror:4 row_mask:0xf bank_mask:0xf bound_ctrl:1
	s_nop 1
	v_mov_b32_dpp v3, v2 row_ror:8 row_mask:0xf bank_mask:0xf bound_ctrl:1
	s_and_saveexec_b64 s[0:1], s[6:7]
	v_add_f32_e32 v2, v2, v3
	v_add_f32_e32 v2, v119, v2
	ds_write_b32 v99, v2 offset:48
	s_or_b64 exec, exec, s[0:1]
	v_mul_f32_e32 v2, v63, v118
	v_fmac_f32_e32 v2, v62, v116
	v_fmac_f32_e32 v2, v64, v117
	v_fmac_f32_e32 v2, v65, v115
	s_nop 1
	v_add_f32_dpp v2, v2, v2 quad_perm:[1,0,3,2] row_mask:0xf bank_mask:0xf bound_ctrl:1
	s_nop 1
	v_add_f32_dpp v2, v2, v2 quad_perm:[2,3,0,1] row_mask:0xf bank_mask:0xf bound_ctrl:1
	s_nop 1
	v_add_f32_dpp v2, v2, v2 row_ror:4 row_mask:0xf bank_mask:0xf bound_ctrl:1
	s_nop 1
	v_mov_b32_dpp v3, v2 row_ror:8 row_mask:0xf bank_mask:0xf bound_ctrl:1
	s_and_saveexec_b64 s[0:1], s[6:7]
	v_add_f32_e32 v2, v2, v3
	v_add_f32_e32 v2, v119, v2
	ds_write_b32 v99, v2 offset:64
	s_or_b64 exec, exec, s[0:1]
	v_mul_f32_e32 v2, v59, v118
	v_fmac_f32_e32 v2, v58, v116
	v_fmac_f32_e32 v2, v60, v117
	v_fmac_f32_e32 v2, v61, v115
	s_nop 1
	v_add_f32_dpp v2, v2, v2 quad_perm:[1,0,3,2] row_mask:0xf bank_mask:0xf bound_ctrl:1
	s_nop 1
	v_add_f32_dpp v2, v2, v2 quad_perm:[2,3,0,1] row_mask:0xf bank_mask:0xf bound_ctrl:1
	s_nop 1
	v_add_f32_dpp v2, v2, v2 row_ror:4 row_mask:0xf bank_mask:0xf bound_ctrl:1
	s_nop 1
	v_mov_b32_dpp v3, v2 row_ror:8 row_mask:0xf bank_mask:0xf bound_ctrl:1
	s_and_saveexec_b64 s[0:1], s[6:7]
	v_add_f32_e32 v2, v2, v3
	v_add_f32_e32 v2, v119, v2
	ds_write_b32 v99, v2 offset:80
	s_or_b64 exec, exec, s[0:1]
	v_mul_f32_e32 v2, v55, v118
	v_fmac_f32_e32 v2, v54, v116
	v_fmac_f32_e32 v2, v56, v117
	v_fmac_f32_e32 v2, v57, v115
	s_nop 1
	v_add_f32_dpp v2, v2, v2 quad_perm:[1,0,3,2] row_mask:0xf bank_mask:0xf bound_ctrl:1
	s_nop 1
	v_add_f32_dpp v2, v2, v2 quad_perm:[2,3,0,1] row_mask:0xf bank_mask:0xf bound_ctrl:1
	s_nop 1
	v_add_f32_dpp v2, v2, v2 row_ror:4 row_mask:0xf bank_mask:0xf bound_ctrl:1
	s_nop 1
	v_mov_b32_dpp v3, v2 row_ror:8 row_mask:0xf bank_mask:0xf bound_ctrl:1
	s_and_saveexec_b64 s[0:1], s[6:7]
	v_add_f32_e32 v2, v2, v3
	v_add_f32_e32 v2, v119, v2
	ds_write_b32 v99, v2 offset:96
	s_or_b64 exec, exec, s[0:1]
	v_mul_f32_e32 v2, v51, v118
	v_fmac_f32_e32 v2, v50, v116
	v_fmac_f32_e32 v2, v52, v117
	v_fmac_f32_e32 v2, v53, v115
	s_nop 1
	v_add_f32_dpp v2, v2, v2 quad_perm:[1,0,3,2] row_mask:0xf bank_mask:0xf bound_ctrl:1
	s_nop 1
	v_add_f32_dpp v2, v2, v2 quad_perm:[2,3,0,1] row_mask:0xf bank_mask:0xf bound_ctrl:1
	s_nop 1
	v_add_f32_dpp v2, v2, v2 row_ror:4 row_mask:0xf bank_mask:0xf bound_ctrl:1
	s_nop 1
	v_mov_b32_dpp v3, v2 row_ror:8 row_mask:0xf bank_mask:0xf bound_ctrl:1
	s_and_saveexec_b64 s[0:1], s[6:7]
	v_add_f32_e32 v2, v2, v3
	v_add_f32_e32 v2, v119, v2
	ds_write_b32 v99, v2 offset:112
	s_or_b64 exec, exec, s[0:1]
	s_mov_b64 s[0:1], 0x18000
	v_lshl_add_u64 v[2:3], v[70:71], 0, s[0:1]
	v_lshl_add_u64 v[4:5], v[2:3], 0, v[82:83]
	v_add_co_u32_e32 v6, vcc, 0x1000, v4
	v_mov_b32_e32 v93, v83
	s_nop 0
	v_addc_co_u32_e32 v7, vcc, 0, v5, vcc
	global_load_dwordx4 v[74:77], v[4:5], off
	global_load_dwordx4 v[66:69], v[6:7], off offset:2048
	v_add_co_u32_e32 v6, vcc, 0x3000, v4
	v_lshl_add_u64 v[2:3], v[2:3], 0, v[92:93]
	s_nop 0
	v_addc_co_u32_e32 v7, vcc, 0, v5, vcc
	v_add_co_u32_e32 v8, vcc, s49, v4
	s_waitcnt vmcnt(6)
	v_mul_f32_e32 v47, v47, v118
	v_addc_co_u32_e32 v9, vcc, 0, v5, vcc
	global_load_dwordx4 v[58:61], v[6:7], off
	global_load_dwordx4 v[50:53], v[8:9], off offset:2048
	v_add_co_u32_e32 v6, vcc, 0x7000, v4
	v_fmac_f32_e32 v47, v46, v116
	s_nop 0
	v_addc_co_u32_e32 v7, vcc, 0, v5, vcc
	global_load_dwordx4 v[14:17], v[2:3], off
	global_load_dwordx4 v[10:13], v[6:7], off offset:2048
	v_add_co_u32_e32 v2, vcc, 0x9000, v4
	v_fmac_f32_e32 v47, v48, v117
	s_nop 0
	v_addc_co_u32_e32 v3, vcc, 0, v5, vcc
	v_add_co_u32_e32 v4, vcc, 0xa000, v4
	v_fmac_f32_e32 v47, v49, v115
	s_nop 0
	v_addc_co_u32_e32 v5, vcc, 0, v5, vcc
	global_load_dwordx4 v[6:9], v[2:3], off
	s_nop 0
	global_load_dwordx4 v[2:5], v[4:5], off offset:2048
	v_add_f32_dpp v46, v47, v47 quad_perm:[1,0,3,2] row_mask:0xf bank_mask:0xf bound_ctrl:1
	s_nop 1
	v_add_f32_dpp v46, v46, v46 quad_perm:[2,3,0,1] row_mask:0xf bank_mask:0xf bound_ctrl:1
	s_nop 1
	v_add_f32_dpp v46, v46, v46 row_ror:4 row_mask:0xf bank_mask:0xf bound_ctrl:1
	s_nop 1
	v_mov_b32_dpp v47, v46 row_ror:8 row_mask:0xf bank_mask:0xf bound_ctrl:1
	s_and_saveexec_b64 s[0:1], s[6:7]
	v_add_f32_e32 v46, v46, v47
	v_add_f32_e32 v46, v119, v46
	ds_write_b32 v99, v46 offset:128
	s_or_b64 exec, exec, s[0:1]
	v_mul_f32_e32 v35, v35, v118
	v_fmac_f32_e32 v35, v34, v116
	v_fmac_f32_e32 v35, v36, v117
	v_fmac_f32_e32 v35, v37, v115
	s_nop 1
	v_add_f32_dpp v34, v35, v35 quad_perm:[1,0,3,2] row_mask:0xf bank_mask:0xf bound_ctrl:1
	s_nop 1
	v_add_f32_dpp v34, v34, v34 quad_perm:[2,3,0,1] row_mask:0xf bank_mask:0xf bound_ctrl:1
	s_nop 1
	v_add_f32_dpp v34, v34, v34 row_ror:4 row_mask:0xf bank_mask:0xf bound_ctrl:1
	s_nop 1
	v_mov_b32_dpp v35, v34 row_ror:8 row_mask:0xf bank_mask:0xf bound_ctrl:1
	s_and_saveexec_b64 s[0:1], s[6:7]
	v_add_f32_e32 v34, v34, v35
	v_add_f32_e32 v34, v119, v34
	ds_write_b32 v99, v34 offset:144
	s_or_b64 exec, exec, s[0:1]
	v_mul_f32_e32 v27, v27, v118
	v_fmac_f32_e32 v27, v26, v116
	v_fmac_f32_e32 v27, v28, v117
	v_fmac_f32_e32 v27, v29, v115
	s_nop 1
	v_add_f32_dpp v26, v27, v27 quad_perm:[1,0,3,2] row_mask:0xf bank_mask:0xf bound_ctrl:1
	s_nop 1
	v_add_f32_dpp v26, v26, v26 quad_perm:[2,3,0,1] row_mask:0xf bank_mask:0xf bound_ctrl:1
	s_nop 1
	v_add_f32_dpp v26, v26, v26 row_ror:4 row_mask:0xf bank_mask:0xf bound_ctrl:1
	s_nop 1
	v_mov_b32_dpp v27, v26 row_ror:8 row_mask:0xf bank_mask:0xf bound_ctrl:1
	s_and_saveexec_b64 s[0:1], s[6:7]
	v_add_f32_e32 v26, v26, v27
	v_add_f32_e32 v26, v119, v26
	ds_write_b32 v99, v26 offset:160
	s_or_b64 exec, exec, s[0:1]
	s_waitcnt vmcnt(11)
; template <int NB>
; __device__ __forceinline__ void sb_decode_task(const Params& P, float* lds, int task) {
;     ...
;     for (int kb = 0; kb < NBT; ++kb) {
;         const float* np = (kb + 1 < NBT) ? Kp + (size_t)(4 * NB * (kb + 1)) * (SH * HD) : Vp;
; #pragma unroll
;         for (int i = 0; i < NB; ++i) nx[i] = *(const float4*)(np + (size_t)(4 * i + g) * (SH * HD));
; #pragma unroll
;         for (int i = 0; i < NB; ++i) { const int s = 4 * NB * kb + 4 * i + g;
;             float part = q0 * cur[i].x + q1 * cur[i].y + q2 * cur[i].z + q3 * cur[i].w; part = sum16(part);
;             if (c == 0) zl[s] = part + bias; }
	v_mul_f32_e32 v19, v19, v118
	v_fmac_f32_e32 v19, v18, v116
	v_fmac_f32_e32 v19, v20, v117
	v_fmac_f32_e32 v19, v21, v115
	s_nop 1
	v_add_f32_dpp v18, v19, v19 quad_perm:[1,0,3,2] row_mask:0xf bank_mask:0xf bound_ctrl:1
	s_nop 1
	v_add_f32_dpp v18, v18, v18 quad_perm:[2,3,0,1] row_mask:0xf bank_mask:0xf bound_ctrl:1
	s_nop 1
	v_add_f32_dpp v18, v18, v18 row_ror:4 row_mask:0xf bank_mask:0xf bound_ctrl:1
	s_nop 1
	v_mov_b32_dpp v19, v18 row_ror:8 row_mask:0xf bank_mask:0xf bound_ctrl:1
	s_and_saveexec_b64 s[0:1], s[6:7]
	v_add_f32_e32 v18, v18, v19
	v_add_f32_e32 v18, v119, v18
	ds_write_b32 v99, v18 offset:176
	s_or_b64 exec, exec, s[0:1]
	v_mul_f32_e32 v18, v23, v118
	v_fmac_f32_e32 v18, v22, v116
	v_fmac_f32_e32 v18, v24, v117
	v_fmac_f32_e32 v18, v25, v115
	s_nop 1
	v_add_f32_dpp v18, v18, v18 quad_perm:[1,0,3,2] row_mask:0xf bank_mask:0xf bound_ctrl:1
	s_nop 1
	v_add_f32_dpp v18, v18, v18 quad_perm:[2,3,0,1] row_mask:0xf bank_mask:0xf bound_ctrl:1
	s_nop 1
	v_add_f32_dpp v18, v18, v18 row_ror:4 row_mask:0xf bank_mask:0xf bound_ctrl:1
	s_nop 1
	v_mov_b32_dpp v19, v18 row_ror:8 row_mask:0xf bank_mask:0xf bound_ctrl:1
	s_and_saveexec_b64 s[0:1], s[6:7]
	v_add_f32_e32 v18, v18, v19
	v_add_f32_e32 v18, v119, v18
	ds_write_b32 v99, v18 offset:192
	s_or_b64 exec, exec, s[0:1]
	s_waitcnt vmcnt(10)
	v_mul_f32_e32 v18, v39, v118
	v_fmac_f32_e32 v18, v38, v116
	v_fmac_f32_e32 v18, v40, v117
	v_fmac_f32_e32 v18, v41, v115
	s_nop 1
	v_add_f32_dpp v18, v18, v18 quad_perm:[1,0,3,2] row_mask:0xf bank_mask:0xf bound_ctrl:1
	s_nop 1
	v_add_f32_dpp v18, v18, v18 quad_perm:[2,3,0,1] row_mask:0xf bank_mask:0xf bound_ctrl:1
	s_nop 1
	v_add_f32_dpp v18, v18, v18 row_ror:4 row_mask:0xf bank_mask:0xf bound_ctrl:1
	s_nop 1
	v_mov_b32_dpp v19, v18 row_ror:8 row_mask:0xf bank_mask:0xf bound_ctrl:1
	s_and_saveexec_b64 s[0:1], s[6:7]
	v_add_f32_e32 v18, v18, v19
	v_add_f32_e32 v18, v119, v18
	ds_write_b32 v99, v18 offset:208
	s_or_b64 exec, exec, s[0:1]
	s_waitcnt vmcnt(9)
	v_mul_f32_e32 v18, v43, v118
	v_fmac_f32_e32 v18, v42, v116
	v_fmac_f32_e32 v18, v44, v117
	v_fmac_f32_e32 v18, v45, v115
	s_nop 1
	v_add_f32_dpp v18, v18, v18 quad_perm:[1,0,3,2] row_mask:0xf bank_mask:0xf bound_ctrl:1
	s_nop 1
	v_add_f32_dpp v18, v18, v18 quad_perm:[2,3,0,1] row_mask:0xf bank_mask:0xf bound_ctrl:1
	s_nop 1
	v_add_f32_dpp v18, v18, v18 row_ror:4 row_mask:0xf bank_mask:0xf bound_ctrl:1
	s_nop 1
	v_mov_b32_dpp v19, v18 row_ror:8 row_mask:0xf bank_mask:0xf bound_ctrl:1
	s_and_saveexec_b64 s[0:1], s[6:7]
	v_add_f32_e32 v18, v18, v19
	v_add_f32_e32 v18, v119, v18
	ds_write_b32 v99, v18 offset:224
	s_or_b64 exec, exec, s[0:1]
	s_waitcnt vmcnt(8)
	v_mul_f32_e32 v18, v31, v118
	v_fmac_f32_e32 v18, v30, v116
	v_fmac_f32_e32 v18, v32, v117
	v_fmac_f32_e32 v18, v33, v115
	s_nop 1
	v_add_f32_dpp v18, v18, v18 quad_perm:[1,0,3,2] row_mask:0xf bank_mask:0xf bound_ctrl:1
	s_nop 1
	v_add_f32_dpp v18, v18, v18 quad_perm:[2,3,0,1] row_mask:0xf bank_mask:0xf bound_ctrl:1
	s_nop 1
	v_add_f32_dpp v18, v18, v18 row_ror:4 row_mask:0xf bank_mask:0xf bound_ctrl:1
	s_nop 1
	v_mov_b32_dpp v19, v18 row_ror:8 row_mask:0xf bank_mask:0xf bound_ctrl:1
	s_and_saveexec_b64 s[0:1], s[6:7]
	v_add_f32_e32 v18, v18, v19
	v_add_f32_e32 v18, v119, v18
	ds_write_b32 v99, v18 offset:240
	s_or_b64 exec, exec, s[0:1]
	s_mov_b64 s[0:1], 0x24000
	v_lshl_add_u64 v[18:19], v[70:71], 0, s[0:1]
	v_lshl_add_u64 v[20:21], v[18:19], 0, v[82:83]
	v_add_co_u32_e32 v22, vcc, 0x1000, v20
	v_mov_b32_e32 v93, v83
	s_nop 0
	v_addc_co_u32_e32 v23, vcc, 0, v21, vcc
	global_load_dwordx4 v[78:81], v[20:21], off
	global_load_dwordx4 v[70:73], v[22:23], off offset:2048
	v_add_co_u32_e32 v22, vcc, 0x3000, v20
	v_lshl_add_u64 v[18:19], v[18:19], 0, v[92:93]
	s_nop 0
	v_addc_co_u32_e32 v23, vcc, 0, v21, vcc
	v_add_co_u32_e32 v24, vcc, s49, v20
	s_nop 1
	v_addc_co_u32_e32 v25, vcc, 0, v21, vcc
	global_load_dwordx4 v[62:65], v[22:23], off
	global_load_dwordx4 v[54:57], v[24:25], off offset:2048
	v_add_co_u32_e32 v22, vcc, 0x7000, v20
	s_nop 1
	v_addc_co_u32_e32 v23, vcc, 0, v21, vcc
	global_load_dwordx4 v[46:49], v[18:19], off
	global_load_dwordx4 v[42:45], v[22:23], off offset:2048
	v_add_co_u32_e32 v18, vcc, 0x9000, v20
	s_nop 1
	v_addc_co_u32_e32 v19, vcc, 0, v21, vcc
	v_add_co_u32_e32 v20, vcc, 0xa000, v20
	s_nop 1
	v_addc_co_u32_e32 v21, vcc, 0, v21, vcc
	global_load_dwordx4 v[38:41], v[18:19], off
	global_load_dwordx4 v[34:37], v[20:21], off offset:2048
	s_waitcnt vmcnt(15)
	v_mul_f32_e32 v18, v75, v118
	v_fmac_f32_e32 v18, v74, v116
	v_fmac_f32_e32 v18, v76, v117
	v_fmac_f32_e32 v18, v77, v115
	s_nop 1
	v_add_f32_dpp v18, v18, v18 quad_perm:[1,0,3,2] row_mask:0xf bank_mask:0xf bound_ctrl:1
	s_nop 1
	v_add_f32_dpp v18, v18, v18 quad_perm:[2,3,0,1] row_mask:0xf bank_mask:0xf bound_ctrl:1
	s_nop 1
	v_add_f32_dpp v18, v18, v18 row_ror:4 row_mask:0xf bank_mask:0xf bound_ctrl:1
	s_nop 1
	v_mov_b32_dpp v19, v18 row_ror:8 row_mask:0xf bank_mask:0xf bound_ctrl:1
	s_and_saveexec_b64 s[0:1], s[6:7]
	v_add_f32_e32 v18, v18, v19
	v_add_f32_e32 v18, v119, v18
	ds_write_b32 v99, v18 offset:256
	s_or_b64 exec, exec, s[0:1]
	s_waitcnt vmcnt(14)
	v_mul_f32_e32 v18, v67, v118
	v_fmac_f32_e32 v18, v66, v116
	v_fmac_f32_e32 v18, v68, v117
	v_fmac_f32_e32 v18, v69, v115
	s_nop 1
	v_add_f32_dpp v18, v18, v18 quad_perm:[1,0,3,2] row_mask:0xf bank_mask:0xf bound_ctrl:1
	s_nop 1
	v_add_f32_dpp v18, v18, v18 quad_perm:[2,3,0,1] row_mask:0xf bank_mask:0xf bound_ctrl:1
	s_nop 1
	v_add_f32_dpp v18, v18, v18 row_ror:4 row_mask:0xf bank_mask:0xf bound_ctrl:1
	s_nop 1
	v_mov_b32_dpp v19, v18 row_ror:8 row_mask:0xf bank_mask:0xf bound_ctrl:1
	s_and_saveexec_b64 s[0:1], s[6:7]
	v_add_f32_e32 v18, v18, v19
	v_add_f32_e32 v18, v119, v18
	ds_write_b32 v99, v18 offset:272
	s_or_b64 exec, exec, s[0:1]
	s_waitcnt vmcnt(13)
; template <int NB>
; __device__ __forceinline__ void sb_decode_task(const Params& P, float* lds, int task) {
;     ...
;     for (int kb = 0; kb < NBT; ++kb) {
;         const float* np = (kb + 1 < NBT) ? Kp + (size_t)(4 * NB * (kb + 1)) * (SH * HD) : Vp;
; #pragma unroll
;         for (int i = 0; i < NB; ++i) nx[i] = *(const float4*)(np + (size_t)(4 * i + g) * (SH * HD));
; #pragma unroll
;         for (int i = 0; i < NB; ++i) { const int s = 4 * NB * kb + 4 * i + g;
;             float part = q0 * cur[i].x + q1 * cur[i].y + q2 * cur[i].z + q3 * cur[i].w; part = sum16(part);
;             if (c == 0) zl[s] = part + bias; }
; #pragma unroll
;         for (int i = 0; i < NB; ++i) cur[i] = nx[i];
;     }
;     asm volatile("s_waitcnt lgkmcnt(0)" ::: "memory");
;     ...
;     float4 o4 = make_float4(0.f, 0.f, 0.f, 0.f);
; #pragma unroll
;     for (int vb = 0; vb < NBT; ++vb) {
;         if (vb + 1 < NBT) {
; #pragma unroll
;             for (int i = 0; i < NB; ++i) nx[i] = *(const float4*)(Vp + (size_t)(4 * NB * (vb + 1) + 4 * i + g) * (SH * HD)); }
	v_mul_f32_e32 v18, v59, v118
	v_fmac_f32_e32 v18, v58, v116
	v_fmac_f32_e32 v18, v60, v117
	v_fmac_f32_e32 v18, v61, v115
	s_nop 1
	v_add_f32_dpp v18, v18, v18 quad_perm:[1,0,3,2] row_mask:0xf bank_mask:0xf bound_ctrl:1
	s_nop 1
	v_add_f32_dpp v18, v18, v18 quad_perm:[2,3,0,1] row_mask:0xf bank_mask:0xf bound_ctrl:1
	s_nop 1
	v_add_f32_dpp v18, v18, v18 row_ror:4 row_mask:0xf bank_mask:0xf bound_ctrl:1
	s_nop 1
	v_mov_b32_dpp v19, v18 row_ror:8 row_mask:0xf bank_mask:0xf bound_ctrl:1
	s_and_saveexec_b64 s[0:1], s[6:7]
	v_add_f32_e32 v18, v18, v19
	v_add_f32_e32 v18, v119, v18
	ds_write_b32 v99, v18 offset:288
	s_or_b64 exec, exec, s[0:1]
	s_waitcnt vmcnt(12)
	v_mul_f32_e32 v18, v51, v118
	v_fmac_f32_e32 v18, v50, v116
	v_fmac_f32_e32 v18, v52, v117
	v_fmac_f32_e32 v18, v53, v115
	s_nop 1
	v_add_f32_dpp v18, v18, v18 quad_perm:[1,0,3,2] row_mask:0xf bank_mask:0xf bound_ctrl:1
	s_nop 1
	v_add_f32_dpp v18, v18, v18 quad_perm:[2,3,0,1] row_mask:0xf bank_mask:0xf bound_ctrl:1
	s_nop 1
	v_add_f32_dpp v18, v18, v18 row_ror:4 row_mask:0xf bank_mask:0xf bound_ctrl:1
	s_nop 1
	v_mov_b32_dpp v19, v18 row_ror:8 row_mask:0xf bank_mask:0xf bound_ctrl:1
	s_and_saveexec_b64 s[0:1], s[6:7]
	v_add_f32_e32 v18, v18, v19
	v_add_f32_e32 v18, v119, v18
	ds_write_b32 v99, v18 offset:304
	s_or_b64 exec, exec, s[0:1]
	s_waitcnt vmcnt(11)
	v_mul_f32_e32 v15, v15, v118
	v_fmac_f32_e32 v15, v14, v116
	v_fmac_f32_e32 v15, v16, v117
	v_fmac_f32_e32 v15, v17, v115
	s_nop 1
	v_add_f32_dpp v14, v15, v15 quad_perm:[1,0,3,2] row_mask:0xf bank_mask:0xf bound_ctrl:1
	s_nop 1
	v_add_f32_dpp v14, v14, v14 quad_perm:[2,3,0,1] row_mask:0xf bank_mask:0xf bound_ctrl:1
	s_nop 1
	v_add_f32_dpp v14, v14, v14 row_ror:4 row_mask:0xf bank_mask:0xf bound_ctrl:1
	s_nop 1
	v_mov_b32_dpp v15, v14 row_ror:8 row_mask:0xf bank_mask:0xf bound_ctrl:1
	s_and_saveexec_b64 s[0:1], s[6:7]
	v_add_f32_e32 v14, v14, v15
	v_add_f32_e32 v14, v119, v14
	ds_write_b32 v99, v14 offset:320
	s_or_b64 exec, exec, s[0:1]
	s_waitcnt vmcnt(10)
	v_mul_f32_e32 v11, v11, v118
	v_fmac_f32_e32 v11, v10, v116
	v_fmac_f32_e32 v11, v12, v117
	v_fmac_f32_e32 v11, v13, v115
	s_nop 1
	v_add_f32_dpp v10, v11, v11 quad_perm:[1,0,3,2] row_mask:0xf bank_mask:0xf bound_ctrl:1
	s_nop 1
	v_add_f32_dpp v10, v10, v10 quad_perm:[2,3,0,1] row_mask:0xf bank_mask:0xf bound_ctrl:1
	s_nop 1
	v_add_f32_dpp v10, v10, v10 row_ror:4 row_mask:0xf bank_mask:0xf bound_ctrl:1
	s_nop 1
	v_mov_b32_dpp v11, v10 row_ror:8 row_mask:0xf bank_mask:0xf bound_ctrl:1
	s_and_saveexec_b64 s[0:1], s[6:7]
	v_add_f32_e32 v10, v10, v11
	v_add_f32_e32 v10, v119, v10
	ds_write_b32 v99, v10 offset:336
	s_or_b64 exec, exec, s[0:1]
	s_waitcnt vmcnt(9)
	v_mul_f32_e32 v7, v7, v118
	v_fmac_f32_e32 v7, v6, v116
	v_fmac_f32_e32 v7, v8, v117
	v_fmac_f32_e32 v7, v9, v115
	s_nop 1
	v_add_f32_dpp v6, v7, v7 quad_perm:[1,0,3,2] row_mask:0xf bank_mask:0xf bound_ctrl:1
	s_nop 1
	v_add_f32_dpp v6, v6, v6 quad_perm:[2,3,0,1] row_mask:0xf bank_mask:0xf bound_ctrl:1
	s_nop 1
	v_add_f32_dpp v6, v6, v6 row_ror:4 row_mask:0xf bank_mask:0xf bound_ctrl:1
	s_nop 1
	v_mov_b32_dpp v7, v6 row_ror:8 row_mask:0xf bank_mask:0xf bound_ctrl:1
	s_and_saveexec_b64 s[0:1], s[6:7]
	v_add_f32_e32 v6, v6, v7
	v_add_f32_e32 v6, v119, v6
	ds_write_b32 v99, v6 offset:352
	s_or_b64 exec, exec, s[0:1]
	s_waitcnt vmcnt(8)
	v_mul_f32_e32 v3, v3, v118
	v_fmac_f32_e32 v3, v2, v116
	v_fmac_f32_e32 v3, v4, v117
	v_fmac_f32_e32 v3, v5, v115
	s_nop 1
	v_add_f32_dpp v2, v3, v3 quad_perm:[1,0,3,2] row_mask:0xf bank_mask:0xf bound_ctrl:1
	s_nop 1
	v_add_f32_dpp v2, v2, v2 quad_perm:[2,3,0,1] row_mask:0xf bank_mask:0xf bound_ctrl:1
	s_nop 1
	v_add_f32_dpp v2, v2, v2 row_ror:4 row_mask:0xf bank_mask:0xf bound_ctrl:1
	s_nop 1
	v_mov_b32_dpp v3, v2 row_ror:8 row_mask:0xf bank_mask:0xf bound_ctrl:1
	s_and_saveexec_b64 s[0:1], s[6:7]
	v_add_f32_e32 v2, v2, v3
	v_add_f32_e32 v2, v119, v2
	ds_write_b32 v99, v2 offset:368
	s_or_b64 exec, exec, s[0:1]
	v_lshlrev_b64 v[2:3], 6, v[94:95]
	v_lshl_add_u64 v[6:7], v[2:3], 2, v[86:87]
	v_lshl_add_u64 v[50:51], v[6:7], 0, v[82:83]
	v_add_co_u32_e32 v2, vcc, 0x1000, v50
	v_mov_b32_e32 v93, v83
	s_nop 0
	v_addc_co_u32_e32 v3, vcc, 0, v51, vcc
	v_add_co_u32_e32 v8, vcc, 0x3000, v50
	v_lshl_add_u64 v[10:11], v[6:7], 0, v[92:93]
	s_nop 0
	v_addc_co_u32_e32 v9, vcc, 0, v51, vcc
	v_add_co_u32_e32 v14, vcc, s49, v50
	global_load_dwordx4 v[30:33], v[50:51], off
	s_nop 0
	global_load_dwordx4 v[2:5], v[2:3], off offset:2048
	v_addc_co_u32_e32 v15, vcc, 0, v51, vcc
	v_add_co_u32_e32 v18, vcc, 0x7000, v50
	global_load_dwordx4 v[6:9], v[8:9], off
	s_nop 0
	global_load_dwordx4 v[10:13], v[10:11], off
	v_addc_co_u32_e32 v19, vcc, 0, v51, vcc
	v_add_co_u32_e32 v22, vcc, 0x9000, v50
	global_load_dwordx4 v[14:17], v[14:15], off offset:2048
	s_nop 0
	global_load_dwordx4 v[18:21], v[18:19], off offset:2048
	v_addc_co_u32_e32 v23, vcc, 0, v51, vcc
	v_add_co_u32_e32 v26, vcc, 0xa000, v50
	s_waitcnt vmcnt(13)
	v_mul_f32_e32 v52, v79, v118
	v_addc_co_u32_e32 v27, vcc, 0, v51, vcc
	global_load_dwordx4 v[22:25], v[22:23], off
	s_nop 0
	global_load_dwordx4 v[26:29], v[26:27], off offset:2048
	v_fmac_f32_e32 v52, v78, v116
	v_fmac_f32_e32 v52, v80, v117
	v_fmac_f32_e32 v52, v81, v115
	s_nop 1
	v_add_f32_dpp v52, v52, v52 quad_perm:[1,0,3,2] row_mask:0xf bank_mask:0xf bound_ctrl:1
	s_nop 1
	v_add_f32_dpp v52, v52, v52 quad_perm:[2,3,0,1] row_mask:0xf bank_mask:0xf bound_ctrl:1
	s_nop 1
	v_add_f32_dpp v52, v52, v52 row_ror:4 row_mask:0xf bank_mask:0xf bound_ctrl:1
	s_nop 1
	v_mov_b32_dpp v53, v52 row_ror:8 row_mask:0xf bank_mask:0xf bound_ctrl:1
	s_and_saveexec_b64 s[0:1], s[6:7]
	v_add_f32_e32 v52, v52, v53
	v_add_f32_e32 v52, v119, v52
	ds_write_b32 v99, v52 offset:384
	s_or_b64 exec, exec, s[0:1]
	s_waitcnt vmcnt(14)
; template <int NB>
; __device__ __forceinline__ void sb_decode_task(const Params& P, float* lds, int task) {
;     ...
;     for (int kb = 0; kb < NBT; ++kb) {
;         const float* np = (kb + 1 < NBT) ? Kp + (size_t)(4 * NB * (kb + 1)) * (SH * HD) : Vp;
; #pragma unroll
;         for (int i = 0; i < NB; ++i) nx[i] = *(const float4*)(np + (size_t)(4 * i + g) * (SH * HD));
; #pragma unroll
;         for (int i = 0; i < NB; ++i) { const int s = 4 * NB * kb + 4 * i + g;
;             float part = q0 * cur[i].x + q1 * cur[i].y + q2 * cur[i].z + q3 * cur[i].w; part = sum16(part);
;             if (c == 0) zl[s] = part + bias; }
; #pragma unroll
;         for (int i = 0; i < NB; ++i) cur[i] = nx[i];
;     }
;     asm volatile("s_waitcnt lgkmcnt(0)" ::: "memory");
;     __builtin_amdgcn_wave_barrier();
;     const float z0 = zl[2 * lane], z1 = zl[2 * lane + 1];
	v_mul_f32_e32 v52, v71, v118
	v_fmac_f32_e32 v52, v70, v116
	v_fmac_f32_e32 v52, v72, v117
	v_fmac_f32_e32 v52, v73, v115
	s_nop 1
	v_add_f32_dpp v52, v52, v52 quad_perm:[1,0,3,2] row_mask:0xf bank_mask:0xf bound_ctrl:1
	s_nop 1
	v_add_f32_dpp v52, v52, v52 quad_perm:[2,3,0,1] row_mask:0xf bank_mask:0xf bound_ctrl:1
	s_nop 1
	v_add_f32_dpp v52, v52, v52 row_ror:4 row_mask:0xf bank_mask:0xf bound_ctrl:1
	s_nop 1
	v_mov_b32_dpp v53, v52 row_ror:8 row_mask:0xf bank_mask:0xf bound_ctrl:1
	s_and_saveexec_b64 s[0:1], s[6:7]
	v_add_f32_e32 v52, v52, v53
	v_add_f32_e32 v52, v119, v52
	ds_write_b32 v99, v52 offset:400
	s_or_b64 exec, exec, s[0:1]
	s_waitcnt vmcnt(13)
	v_mul_f32_e32 v52, v63, v118
	v_fmac_f32_e32 v52, v62, v116
	v_fmac_f32_e32 v52, v64, v117
	v_fmac_f32_e32 v52, v65, v115
	s_nop 1
	v_add_f32_dpp v52, v52, v52 quad_perm:[1,0,3,2] row_mask:0xf bank_mask:0xf bound_ctrl:1
	s_nop 1
	v_add_f32_dpp v52, v52, v52 quad_perm:[2,3,0,1] row_mask:0xf bank_mask:0xf bound_ctrl:1
	s_nop 1
	v_add_f32_dpp v52, v52, v52 row_ror:4 row_mask:0xf bank_mask:0xf bound_ctrl:1
	s_nop 1
	v_mov_b32_dpp v53, v52 row_ror:8 row_mask:0xf bank_mask:0xf bound_ctrl:1
	s_and_saveexec_b64 s[0:1], s[6:7]
	v_add_f32_e32 v52, v52, v53
	v_add_f32_e32 v52, v119, v52
	ds_write_b32 v99, v52 offset:416
	s_or_b64 exec, exec, s[0:1]
	s_waitcnt vmcnt(12)
	v_mul_f32_e32 v52, v55, v118
	v_fmac_f32_e32 v52, v54, v116
	v_fmac_f32_e32 v52, v56, v117
	v_fmac_f32_e32 v52, v57, v115
	s_nop 1
	v_add_f32_dpp v52, v52, v52 quad_perm:[1,0,3,2] row_mask:0xf bank_mask:0xf bound_ctrl:1
	s_nop 1
	v_add_f32_dpp v52, v52, v52 quad_perm:[2,3,0,1] row_mask:0xf bank_mask:0xf bound_ctrl:1
	s_nop 1
	v_add_f32_dpp v52, v52, v52 row_ror:4 row_mask:0xf bank_mask:0xf bound_ctrl:1
	s_nop 1
	v_mov_b32_dpp v53, v52 row_ror:8 row_mask:0xf bank_mask:0xf bound_ctrl:1
	s_and_saveexec_b64 s[0:1], s[6:7]
	v_add_f32_e32 v52, v52, v53
	v_add_f32_e32 v52, v119, v52
	ds_write_b32 v99, v52 offset:432
	s_or_b64 exec, exec, s[0:1]
	s_waitcnt vmcnt(11)
	v_mul_f32_e32 v47, v47, v118
	v_fmac_f32_e32 v47, v46, v116
	v_fmac_f32_e32 v47, v48, v117
	v_fmac_f32_e32 v47, v49, v115
	s_nop 1
	v_add_f32_dpp v46, v47, v47 quad_perm:[1,0,3,2] row_mask:0xf bank_mask:0xf bound_ctrl:1
	s_nop 1
	v_add_f32_dpp v46, v46, v46 quad_perm:[2,3,0,1] row_mask:0xf bank_mask:0xf bound_ctrl:1
	s_nop 1
	v_add_f32_dpp v46, v46, v46 row_ror:4 row_mask:0xf bank_mask:0xf bound_ctrl:1
	s_nop 1
	v_mov_b32_dpp v47, v46 row_ror:8 row_mask:0xf bank_mask:0xf bound_ctrl:1
	s_and_saveexec_b64 s[0:1], s[6:7]
	v_add_f32_e32 v46, v46, v47
	v_add_f32_e32 v46, v119, v46
	ds_write_b32 v99, v46 offset:448
	s_or_b64 exec, exec, s[0:1]
	s_waitcnt vmcnt(10)
	v_mul_f32_e32 v43, v43, v118
	v_fmac_f32_e32 v43, v42, v116
	v_fmac_f32_e32 v43, v44, v117
	v_fmac_f32_e32 v43, v45, v115
	s_nop 1
	v_add_f32_dpp v42, v43, v43 quad_perm:[1,0,3,2] row_mask:0xf bank_mask:0xf bound_ctrl:1
	s_nop 1
	v_add_f32_dpp v42, v42, v42 quad_perm:[2,3,0,1] row_mask:0xf bank_mask:0xf bound_ctrl:1
	s_nop 1
	v_add_f32_dpp v42, v42, v42 row_ror:4 row_mask:0xf bank_mask:0xf bound_ctrl:1
	s_nop 1
	v_mov_b32_dpp v43, v42 row_ror:8 row_mask:0xf bank_mask:0xf bound_ctrl:1
	s_and_saveexec_b64 s[0:1], s[6:7]
	v_add_f32_e32 v42, v42, v43
	v_add_f32_e32 v42, v119, v42
	ds_write_b32 v99, v42 offset:464
	s_or_b64 exec, exec, s[0:1]
	s_waitcnt vmcnt(9)
	v_mul_f32_e32 v39, v39, v118
	v_fmac_f32_e32 v39, v38, v116
	v_fmac_f32_e32 v39, v40, v117
	v_fmac_f32_e32 v39, v41, v115
	s_nop 1
	v_add_f32_dpp v38, v39, v39 quad_perm:[1,0,3,2] row_mask:0xf bank_mask:0xf bound_ctrl:1
	s_nop 1
	v_add_f32_dpp v38, v38, v38 quad_perm:[2,3,0,1] row_mask:0xf bank_mask:0xf bound_ctrl:1
	s_nop 1
	v_add_f32_dpp v38, v38, v38 row_ror:4 row_mask:0xf bank_mask:0xf bound_ctrl:1
	s_nop 1
	v_mov_b32_dpp v39, v38 row_ror:8 row_mask:0xf bank_mask:0xf bound_ctrl:1
	s_and_saveexec_b64 s[0:1], s[6:7]
	v_add_f32_e32 v38, v38, v39
	v_add_f32_e32 v38, v119, v38
	ds_write_b32 v99, v38 offset:480
	s_or_b64 exec, exec, s[0:1]
	s_waitcnt vmcnt(8)
	v_mul_f32_e32 v35, v35, v118
	v_fmac_f32_e32 v35, v34, v116
	v_fmac_f32_e32 v35, v36, v117
	v_fmac_f32_e32 v35, v37, v115
	s_nop 1
	v_add_f32_dpp v34, v35, v35 quad_perm:[1,0,3,2] row_mask:0xf bank_mask:0xf bound_ctrl:1
	s_nop 1
	v_add_f32_dpp v34, v34, v34 quad_perm:[2,3,0,1] row_mask:0xf bank_mask:0xf bound_ctrl:1
	s_nop 1
	v_add_f32_dpp v34, v34, v34 row_ror:4 row_mask:0xf bank_mask:0xf bound_ctrl:1
	s_nop 1
	v_mov_b32_dpp v35, v34 row_ror:8 row_mask:0xf bank_mask:0xf bound_ctrl:1
	s_and_saveexec_b64 s[0:1], s[6:7]
	v_add_f32_e32 v34, v34, v35
	v_add_f32_e32 v34, v119, v34
	ds_write_b32 v99, v34 offset:496
	s_or_b64 exec, exec, s[0:1]
	s_waitcnt lgkmcnt(0)
	ds_read_b64 v[34:35], v100
	s_waitcnt lgkmcnt(0)
; __device__ __forceinline__ float softplus2_(float z2) { return fmaxf(z2, 0.f) + log1pf(exp2f(-fabsf(z2))) * LOG2E; }
; template <int NB>
; __device__ __forceinline__ void sb_decode_task(const Params& P, float* lds, int task) {
;     ...
;     const float sp0 = softplus2_(z0), sp1 = softplus2_(z1);
	v_cmp_gt_f32_e64 vcc, |v34|, s97
	s_nop 1
	v_cndmask_b32_e32 v37, 0, v103, vcc
	v_sub_f32_e64 v37, v37, |v34|
	v_exp_f32_e32 v37, v37
	v_max_f32_e32 v36, v34, v34
	v_max_f32_e32 v38, 0, v36
	v_cndmask_b32_e32 v36, 0, v102, vcc
	v_ldexp_f32 v39, v37, v36
	v_add_f32_e32 v40, 1.0, v39
	v_add_f32_e32 v36, -1.0, v40
	v_sub_f32_e32 v37, v36, v40
	v_add_f32_e32 v37, 1.0, v37
	v_sub_f32_e32 v36, v39, v36
	v_add_f32_e32 v41, v36, v37
	v_frexp_mant_f32_e32 v36, v40
	v_cmp_gt_f32_e32 vcc, s47, v36
	v_cvt_f64_f32_e32 v[36:37], v40
	v_frexp_exp_i32_f64_e32 v36, v[36:37]
	v_subbrev_co_u32_e32 v36, vcc, 0, v36, vcc
	v_sub_u32_e32 v37, 0, v36
	v_ldexp_f32 v40, v40, v37
	v_ldexp_f32 v37, v41, v37
	v_add_f32_e32 v41, -1.0, v40
	v_add_f32_e32 v42, 1.0, v41
	v_sub_f32_e32 v42, v40, v42
	v_add_f32_e32 v42, v37, v42
	v_add_f32_e32 v43, v41, v42
	v_sub_f32_e32 v41, v41, v43
	v_add_f32_e32 v41, v42, v41
	v_add_f32_e32 v42, 1.0, v40
	v_add_f32_e32 v44, -1.0, v42
	v_sub_f32_e32 v40, v40, v44
	v_add_f32_e32 v37, v37, v40
	v_add_f32_e32 v40, v42, v37
	v_sub_f32_e32 v42, v42, v40
	v_add_f32_e32 v37, v37, v42
	v_rcp_f32_e32 v42, v40
	v_cvt_f32_i32_e32 v36, v36
	v_cmp_neq_f32_e32 vcc, s46, v39
	v_mul_f32_e32 v44, v43, v42
	v_mul_f32_e32 v45, v40, v44
	v_fma_f32 v46, v44, v40, -v45
	v_fmac_f32_e32 v46, v44, v37
	v_add_f32_e32 v47, v45, v46
	v_sub_f32_e32 v48, v43, v47
	v_sub_f32_e32 v43, v43, v48
	v_sub_f32_e32 v45, v47, v45
	v_sub_f32_e32 v43, v43, v47
	v_add_f32_e32 v41, v41, v43
	v_sub_f32_e32 v43, v45, v46
	v_add_f32_e32 v41, v43, v41
	v_add_f32_e32 v43, v48, v41
	v_mul_f32_e32 v45, v42, v43
	v_mul_f32_e32 v46, v40, v45
	v_fma_f32 v40, v45, v40, -v46
	v_fmac_f32_e32 v40, v45, v37
	v_sub_f32_e32 v37, v48, v43
	v_add_f32_e32 v37, v41, v37
	v_add_f32_e32 v41, v46, v40
	v_sub_f32_e32 v47, v43, v41
	v_sub_f32_e32 v43, v43, v47
	v_sub_f32_e32 v46, v41, v46
	v_sub_f32_e32 v41, v43, v41
	v_add_f32_e32 v37, v37, v41
	v_sub_f32_e32 v40, v46, v40
	v_add_f32_e32 v37, v40, v37
	v_add_f32_e32 v40, v44, v45
	v_add_f32_e32 v37, v47, v37
	v_sub_f32_e32 v41, v40, v44
	v_mul_f32_e32 v37, v42, v37
	v_sub_f32_e32 v41, v45, v41
	v_add_f32_e32 v37, v41, v37
	v_mul_f32_e32 v44, 0x3f317218, v36
	v_add_f32_e32 v41, v40, v37
	v_fma_f32 v45, v36, s95, -v44
	v_mul_f32_e32 v42, v41, v41
	v_fmac_f32_e32 v45, 0xb102e308, v36
	v_sub_f32_e32 v36, v41, v40
	v_fmamk_f32 v43, v42, 0x3e9b6dac, v1
	v_sub_f32_e32 v36, v37, v36
	v_add_f32_e32 v37, v44, v45
	v_fmaak_f32 v43, v42, v43, 0x3f2aaada
	v_sub_f32_e32 v40, v37, v44
	v_ldexp_f32 v44, v41, 1
	v_mul_f32_e32 v41, v41, v42
	v_mul_f32_e32 v41, v41, v43
	v_add_f32_e32 v42, v44, v41
	v_sub_f32_e32 v43, v42, v44
	v_ldexp_f32 v36, v36, 1
	v_sub_f32_e32 v41, v41, v43
	v_add_f32_e32 v36, v36, v41
	v_add_f32_e32 v41, v42, v36
	v_sub_f32_e32 v42, v41, v42
	v_sub_f32_e32 v36, v36, v42
	v_add_f32_e32 v42, v37, v41
	v_sub_f32_e32 v43, v42, v37
	v_sub_f32_e32 v44, v42, v43
	v_sub_f32_e32 v40, v45, v40
	v_sub_f32_e32 v37, v37, v44
	v_sub_f32_e32 v41, v41, v43
	v_add_f32_e32 v37, v41, v37
	v_add_f32_e32 v41, v40, v36
	v_sub_f32_e32 v43, v41, v40
	v_sub_f32_e32 v44, v41, v43
	v_sub_f32_e32 v40, v40, v44
	v_sub_f32_e32 v36, v36, v43
	v_add_f32_e32 v37, v41, v37
	v_add_f32_e32 v36, v36, v40
	v_add_f32_e32 v40, v42, v37
	v_sub_f32_e32 v41, v40, v42
	v_sub_f32_e32 v37, v37, v41
	v_add_f32_e32 v36, v36, v37
	v_add_f32_e32 v36, v40, v36
	v_cndmask_b32_e32 v36, v104, v36, vcc
	v_cmp_lt_f32_e64 vcc, |v39|, s45
	s_nop 1
	v_cndmask_b32_e32 v36, v36, v39, vcc
	v_cmp_gt_f32_e64 vcc, |v35|, s97
	v_fmac_f32_e32 v38, 0x3fb8aa3b, v36
	v_max_f32_e32 v36, v35, v35
	v_cndmask_b32_e32 v37, 0, v103, vcc
	v_sub_f32_e64 v37, v37, |v35|
	v_exp_f32_e32 v37, v37
	v_max_f32_e32 v39, 0, v36
	v_cndmask_b32_e32 v36, 0, v102, vcc
	v_sub_f32_e32 v34, v34, v38
	v_ldexp_f32 v40, v37, v36
	v_add_f32_e32 v41, 1.0, v40
	v_add_f32_e32 v36, -1.0, v41
	v_sub_f32_e32 v37, v36, v41
	v_add_f32_e32 v37, 1.0, v37
	v_sub_f32_e32 v36, v40, v36
	v_add_f32_e32 v42, v36, v37
	v_frexp_mant_f32_e32 v36, v41
	v_cmp_gt_f32_e32 vcc, s47, v36
	v_cvt_f64_f32_e32 v[36:37], v41
	v_frexp_exp_i32_f64_e32 v36, v[36:37]
	v_subbrev_co_u32_e32 v36, vcc, 0, v36, vcc
	v_sub_u32_e32 v37, 0, v36
	v_ldexp_f32 v41, v41, v37
	v_ldexp_f32 v37, v42, v37
	v_add_f32_e32 v42, -1.0, v41
	v_add_f32_e32 v43, 1.0, v42
	v_sub_f32_e32 v43, v41, v43
	v_add_f32_e32 v43, v37, v43
	v_add_f32_e32 v44, v42, v43
	v_sub_f32_e32 v42, v42, v44
	v_add_f32_e32 v42, v43, v42
	v_add_f32_e32 v43, 1.0, v41
	v_add_f32_e32 v45, -1.0, v43
	v_sub_f32_e32 v41, v41, v45
	v_add_f32_e32 v37, v37, v41
	v_add_f32_e32 v41, v43, v37
	v_sub_f32_e32 v43, v43, v41
	v_add_f32_e32 v37, v37, v43
	v_rcp_f32_e32 v43, v41
	v_cvt_f32_i32_e32 v36, v36
	v_cmp_neq_f32_e32 vcc, s46, v40
	v_mul_f32_e32 v45, v44, v43
	v_mul_f32_e32 v46, v41, v45
	v_fma_f32 v47, v45, v41, -v46
	v_fmac_f32_e32 v47, v45, v37
	v_add_f32_e32 v48, v46, v47
	v_sub_f32_e32 v49, v44, v48
	v_sub_f32_e32 v44, v44, v49
	v_sub_f32_e32 v46, v48, v46
	v_sub_f32_e32 v44, v44, v48
	v_add_f32_e32 v42, v42, v44
	v_sub_f32_e32 v44, v46, v47
	v_add_f32_e32 v42, v44, v42
	v_add_f32_e32 v44, v49, v42
	v_mul_f32_e32 v46, v43, v44
	v_mul_f32_e32 v47, v41, v46
	v_fma_f32 v41, v46, v41, -v47
	v_fmac_f32_e32 v41, v46, v37
	v_sub_f32_e32 v37, v49, v44
	v_add_f32_e32 v37, v42, v37
	v_add_f32_e32 v42, v47, v41
	v_sub_f32_e32 v48, v44, v42
	v_sub_f32_e32 v44, v44, v48
	v_sub_f32_e32 v47, v42, v47
	v_sub_f32_e32 v42, v44, v42
	v_add_f32_e32 v37, v37, v42
	v_sub_f32_e32 v41, v47, v41
	v_add_f32_e32 v37, v41, v37
	v_add_f32_e32 v41, v45, v46
	v_add_f32_e32 v37, v48, v37
	v_sub_f32_e32 v42, v41, v45
	v_mul_f32_e32 v37, v43, v37
; __device__ __forceinline__ float softplus2_(float z2) { return fmaxf(z2, 0.f) + log1pf(exp2f(-fabsf(z2))) * LOG2E; }
; template <int NB>
; __device__ __forceinline__ void sb_decode_task(const Params& P, float* lds, int task) {
;     ...
;     const float sp0 = softplus2_(z0), sp1 = softplus2_(z1);
;     float incl = sp0 + sp1;
; #pragma unroll
;     for (int off = 1; off < 64; off <<= 1) { const float t = __shfl_down(incl, off); if (lane + off < 64) incl += t; }
;     const float excl = incl - (sp0 + sp1);
;     wl[2 * lane] = exp2f(z0 - sp0 - (excl + sp1));
;     wl[2 * lane + 1] = exp2f(z1 - sp1 - excl);
;     const float Ltot = __shfl(incl, 0);
;     asm volatile("s_waitcnt lgkmcnt(0)" ::: "memory");
;     __builtin_amdgcn_wave_barrier();
;     float4 o4 = make_float4(0.f, 0.f, 0.f, 0.f);
; #pragma unroll
;     for (int vb = 0; vb < NBT; ++vb) {
;         if (vb + 1 < NBT) {
; #pragma unroll
;             for (int i = 0; i < NB; ++i) nx[i] = *(const float4*)(Vp + (size_t)(4 * NB * (vb + 1) + 4 * i + g) * (SH * HD)); }
; #pragma unroll
;         for (int i = 0; i < NB; ++i) { const float w = wl[4 * NB * vb + 4 * i + g]; o4.x += w * cur[i].x; o4.y += w * cur[i].y; o4.z += w * cur[i].z; o4.w += w * cur[i].w; }
; #pragma unroll
;         for (int i = 0; i < NB; ++i) cur[i] = nx[i];
;     }
	v_sub_f32_e32 v42, v46, v42
	v_add_f32_e32 v37, v42, v37
	v_mul_f32_e32 v45, 0x3f317218, v36
	v_add_f32_e32 v42, v41, v37
	v_fma_f32 v46, v36, s95, -v45
	v_mul_f32_e32 v43, v42, v42
	v_fmac_f32_e32 v46, 0xb102e308, v36
	v_sub_f32_e32 v36, v42, v41
	v_fmamk_f32 v44, v43, 0x3e9b6dac, v1
	v_sub_f32_e32 v36, v37, v36
	v_add_f32_e32 v37, v45, v46
	v_fmaak_f32 v44, v43, v44, 0x3f2aaada
	v_sub_f32_e32 v41, v37, v45
	v_ldexp_f32 v45, v42, 1
	v_mul_f32_e32 v42, v42, v43
	v_mul_f32_e32 v42, v42, v44
	v_add_f32_e32 v43, v45, v42
	v_sub_f32_e32 v44, v43, v45
	v_ldexp_f32 v36, v36, 1
	v_sub_f32_e32 v42, v42, v44
	v_add_f32_e32 v36, v36, v42
	v_add_f32_e32 v42, v43, v36
	v_sub_f32_e32 v43, v42, v43
	v_sub_f32_e32 v36, v36, v43
	v_add_f32_e32 v43, v37, v42
	v_sub_f32_e32 v44, v43, v37
	v_sub_f32_e32 v45, v43, v44
	v_sub_f32_e32 v41, v46, v41
	v_sub_f32_e32 v37, v37, v45
	v_sub_f32_e32 v42, v42, v44
	v_add_f32_e32 v37, v42, v37
	v_add_f32_e32 v42, v41, v36
	v_sub_f32_e32 v44, v42, v41
	v_sub_f32_e32 v45, v42, v44
	v_sub_f32_e32 v41, v41, v45
	v_sub_f32_e32 v36, v36, v44
	v_add_f32_e32 v37, v42, v37
	v_add_f32_e32 v36, v36, v41
	v_add_f32_e32 v41, v43, v37
	v_sub_f32_e32 v42, v41, v43
	v_sub_f32_e32 v37, v37, v42
	v_add_f32_e32 v36, v36, v37
	v_add_f32_e32 v36, v41, v36
	v_cndmask_b32_e32 v36, v104, v36, vcc
	v_cmp_lt_f32_e64 vcc, |v40|, s45
	s_nop 1
	v_cndmask_b32_e32 v36, v36, v40, vcc
	v_fmac_f32_e32 v39, 0x3fb8aa3b, v36
	v_add_f32_e32 v36, v38, v39
	ds_bpermute_b32 v37, v108, v36
	v_sub_f32_e32 v35, v35, v39
	s_waitcnt lgkmcnt(0)
	v_add_f32_e32 v37, v36, v37
	v_cndmask_b32_e64 v37, v37, v36, s[8:9]
	ds_bpermute_b32 v40, v109, v37
	s_waitcnt lgkmcnt(0)
	v_add_f32_e32 v40, v37, v40
	v_cndmask_b32_e64 v37, v37, v40, s[10:11]
	ds_bpermute_b32 v40, v110, v37
	s_waitcnt lgkmcnt(0)
	v_add_f32_e32 v40, v37, v40
	v_cndmask_b32_e64 v37, v37, v40, s[12:13]
	ds_bpermute_b32 v40, v111, v37
	s_waitcnt lgkmcnt(0)
	v_add_f32_e32 v40, v37, v40
	v_cndmask_b32_e64 v37, v37, v40, s[14:15]
	ds_bpermute_b32 v40, v112, v37
	s_waitcnt lgkmcnt(0)
	v_add_f32_e32 v40, v37, v40
	v_cndmask_b32_e64 v37, v37, v40, s[16:17]
	ds_bpermute_b32 v40, v113, v37
	s_waitcnt lgkmcnt(0)
	v_add_f32_e32 v40, v37, v40
	v_cndmask_b32_e64 v44, v37, v40, s[18:19]
	v_sub_f32_e32 v36, v44, v36
	v_add_f32_e32 v37, v39, v36
	v_sub_f32_e32 v34, v34, v37
	v_cmp_gt_f32_e32 vcc, s24, v34
	v_sub_f32_e32 v35, v35, v36
	s_nop 0
	v_cndmask_b32_e32 v37, 0, v103, vcc
	v_add_f32_e32 v34, v34, v37
	v_cndmask_b32_e32 v37, 0, v102, vcc
	v_cmp_gt_f32_e32 vcc, s24, v35
	v_exp_f32_e32 v34, v34
	s_nop 0
	v_cndmask_b32_e32 v36, 0, v103, vcc
	v_add_f32_e32 v35, v35, v36
	v_exp_f32_e32 v35, v35
	v_cndmask_b32_e32 v36, 0, v102, vcc
	v_ldexp_f32 v34, v34, v37
	v_ldexp_f32 v35, v35, v36
	ds_write_b64 v100, v[34:35] offset:512
	s_waitcnt lgkmcnt(0)
	ds_read2_b32 v[34:35], v99 offset0:128 offset1:132
	ds_read2_b32 v[42:43], v99 offset0:136 offset1:140
	ds_read2_b32 v[66:67], v99 offset0:144 offset1:148
	ds_read2_b32 v[68:69], v99 offset0:152 offset1:156
	ds_read2_b32 v[74:75], v99 offset0:160 offset1:164
	ds_read2_b32 v[76:77], v99 offset0:168 offset1:172
	ds_read2_b32 v[38:39], v99 offset0:176 offset1:180
	ds_read2_b32 v[40:41], v99 offset0:184 offset1:188
	s_waitcnt vmcnt(7) lgkmcnt(7)
	v_pk_fma_f32 v[70:71], v[30:31], v[34:35], 0 op_sel_hi:[1,0,0]
	v_add_co_u32_e32 v30, vcc, s25, v50
	v_pk_fma_f32 v[72:73], v[32:33], v[34:35], 0 op_sel_hi:[1,0,0]
	s_nop 0
	v_addc_co_u32_e32 v31, vcc, 0, v51, vcc
	v_add_co_u32_e32 v34, vcc, s43, v50
	v_mov_b32_e32 v64, v35
	s_nop 0
	v_addc_co_u32_e32 v35, vcc, 0, v51, vcc
	v_add_co_u32_e32 v46, vcc, s44, v50
	s_waitcnt vmcnt(6)
	v_pk_fma_f32 v[2:3], v[2:3], v[64:65], v[70:71] op_sel_hi:[1,0,1]
	v_addc_co_u32_e32 v47, vcc, 0, v51, vcc
	v_add_co_u32_e32 v52, vcc, s26, v50
	global_load_dwordx4 v[46:49], v[46:47], off
	s_nop 0
	v_addc_co_u32_e32 v53, vcc, 0, v51, vcc
	v_add_co_u32_e32 v56, vcc, s27, v50
	global_load_dwordx4 v[52:55], v[52:53], off offset:2048
	s_nop 0
	v_addc_co_u32_e32 v57, vcc, 0, v51, vcc
	v_add_co_u32_e32 v60, vcc, s28, v50
	global_load_dwordx4 v[56:59], v[56:57], off
	s_nop 0
	v_addc_co_u32_e32 v61, vcc, 0, v51, vcc
	global_load_dwordx4 v[60:63], v[60:61], off offset:2048
	s_waitcnt lgkmcnt(6)
	v_mov_b32_e32 v78, v43
	s_waitcnt vmcnt(9)
	v_pk_fma_f32 v[2:3], v[6:7], v[42:43], v[2:3] op_sel_hi:[1,0,1]
	s_waitcnt lgkmcnt(5)
	v_mov_b32_e32 v80, v67
	s_waitcnt vmcnt(7)
	v_pk_fma_f32 v[2:3], v[14:15], v[78:79], v[2:3] op_sel_hi:[1,0,1]
	s_waitcnt lgkmcnt(4)
	v_mov_b32_e32 v94, v69
	v_pk_fma_f32 v[2:3], v[10:11], v[66:67], v[2:3] op_sel_hi:[1,0,1]
	s_waitcnt lgkmcnt(3)
	v_mov_b32_e32 v10, v75
	s_waitcnt vmcnt(6)
	v_pk_fma_f32 v[2:3], v[18:19], v[80:81], v[2:3] op_sel_hi:[1,0,1]
	s_waitcnt lgkmcnt(2)
	v_mov_b32_e32 v14, v77
	s_waitcnt vmcnt(5)
	v_pk_fma_f32 v[2:3], v[22:23], v[68:69], v[2:3] op_sel_hi:[1,0,1]
	global_load_dwordx4 v[30:33], v[30:31], off
	s_waitcnt vmcnt(5)
	v_pk_fma_f32 v[2:3], v[26:27], v[94:95], v[2:3] op_sel_hi:[1,0,1]
	global_load_dwordx4 v[34:37], v[34:35], off offset:2048
	s_waitcnt vmcnt(5)
	v_pk_fma_f32 v[2:3], v[46:47], v[74:75], v[2:3] op_sel_hi:[1,0,1]
	s_waitcnt vmcnt(4)
	v_pk_fma_f32 v[2:3], v[52:53], v[10:11], v[2:3] op_sel_hi:[1,0,1]
	s_waitcnt vmcnt(3)
	v_pk_fma_f32 v[2:3], v[56:57], v[76:77], v[2:3] op_sel_hi:[1,0,1]
	s_waitcnt vmcnt(2)
	v_pk_fma_f32 v[6:7], v[60:61], v[14:15], v[2:3] op_sel_hi:[1,0,1]
	v_pk_fma_f32 v[2:3], v[4:5], v[64:65], v[72:73] op_sel_hi:[1,0,1]
	v_add_co_u32_e32 v4, vcc, s29, v50
	v_pk_fma_f32 v[2:3], v[8:9], v[42:43], v[2:3] op_sel_hi:[1,0,1]
	s_nop 0
	v_addc_co_u32_e32 v5, vcc, 0, v51, vcc
	v_pk_fma_f32 v[2:3], v[16:17], v[78:79], v[2:3] op_sel_hi:[1,0,1]
	s_waitcnt lgkmcnt(0)
; template <int NB>
; __device__ __forceinline__ void sb_decode_task(const Params& P, float* lds, int task) {
;     ...
;     for (int vb = 0; vb < NBT; ++vb) {
;         if (vb + 1 < NBT) {
; #pragma unroll
;             for (int i = 0; i < NB; ++i) nx[i] = *(const float4*)(Vp + (size_t)(4 * NB * (vb + 1) + 4 * i + g) * (SH * HD)); }
; #pragma unroll
;         for (int i = 0; i < NB; ++i) { const float w = wl[4 * NB * vb + 4 * i + g]; o4.x += w * cur[i].x; o4.y += w * cur[i].y; o4.z += w * cur[i].z; o4.w += w * cur[i].w; }
; #pragma unroll
;         for (int i = 0; i < NB; ++i) cur[i] = nx[i];
;     }
	v_mov_b32_e32 v42, v41
	v_pk_fma_f32 v[2:3], v[12:13], v[66:67], v[2:3] op_sel_hi:[1,0,1]
	s_waitcnt vmcnt(1)
	v_pk_fma_f32 v[6:7], v[30:31], v[38:39], v[6:7] op_sel_hi:[1,0,1]
	v_pk_fma_f32 v[2:3], v[20:21], v[80:81], v[2:3] op_sel_hi:[1,0,1]
	s_nop 0
	v_pk_fma_f32 v[2:3], v[24:25], v[68:69], v[2:3] op_sel_hi:[1,0,1]
	s_nop 0
	v_pk_fma_f32 v[2:3], v[28:29], v[94:95], v[2:3] op_sel_hi:[1,0,1]
	v_mov_b32_e32 v28, v39
	v_pk_fma_f32 v[2:3], v[48:49], v[74:75], v[2:3] op_sel_hi:[1,0,1]
	s_waitcnt vmcnt(0)
	v_pk_fma_f32 v[6:7], v[34:35], v[28:29], v[6:7] op_sel_hi:[1,0,1]
	v_pk_fma_f32 v[2:3], v[54:55], v[10:11], v[2:3] op_sel_hi:[1,0,1]
	s_nop 0
	v_pk_fma_f32 v[2:3], v[58:59], v[76:77], v[2:3] op_sel_hi:[1,0,1]
	s_nop 0
	v_pk_fma_f32 v[2:3], v[62:63], v[14:15], v[2:3] op_sel_hi:[1,0,1]
	ds_read2_b32 v[14:15], v99 offset0:192 offset1:196
	ds_read2_b32 v[12:13], v99 offset0:200 offset1:204
	ds_read2_b32 v[10:11], v99 offset0:208 offset1:212
	ds_read2_b32 v[8:9], v99 offset0:216 offset1:220
	global_load_dwordx4 v[16:19], v[4:5], off
	v_add_co_u32_e32 v4, vcc, s68, v50
	v_pk_fma_f32 v[2:3], v[32:33], v[38:39], v[2:3] op_sel_hi:[1,0,1]
	s_nop 0
	v_addc_co_u32_e32 v5, vcc, 0, v51, vcc
	global_load_dwordx4 v[20:23], v[4:5], off offset:2048
	v_add_co_u32_e32 v4, vcc, s69, v50
	v_pk_fma_f32 v[2:3], v[36:37], v[28:29], v[2:3] op_sel_hi:[1,0,1]
	s_nop 0
	v_addc_co_u32_e32 v5, vcc, 0, v51, vcc
	global_load_dwordx4 v[24:27], v[4:5], off
	v_add_co_u32_e32 v4, vcc, s70, v50
	s_waitcnt lgkmcnt(0)
	v_mov_b32_e32 v36, v9
	v_addc_co_u32_e32 v5, vcc, 0, v51, vcc
	global_load_dwordx4 v[46:49], v[4:5], off offset:2048
	v_add_co_u32_e32 v4, vcc, s71, v50
	ds_read2_b32 v[30:31], v99 offset0:224 offset1:228
	s_nop 0
	v_addc_co_u32_e32 v5, vcc, 0, v51, vcc
	global_load_dwordx4 v[52:55], v[4:5], off
	v_add_co_u32_e32 v4, vcc, s72, v50
	s_waitcnt vmcnt(4)
	v_pk_fma_f32 v[2:3], v[18:19], v[40:41], v[2:3] op_sel_hi:[1,0,1]
	v_addc_co_u32_e32 v5, vcc, 0, v51, vcc
	global_load_dwordx4 v[56:59], v[4:5], off offset:2048
	v_add_co_u32_e32 v4, vcc, s73, v50
	s_waitcnt vmcnt(4)
	v_pk_fma_f32 v[2:3], v[22:23], v[42:43], v[2:3] op_sel_hi:[1,0,1]
	v_addc_co_u32_e32 v5, vcc, 0, v51, vcc
	global_load_dwordx4 v[60:63], v[4:5], off
	v_add_co_u32_e32 v4, vcc, s74, v50
	s_waitcnt vmcnt(4)
	v_pk_fma_f32 v[2:3], v[26:27], v[14:15], v[2:3] op_sel_hi:[1,0,1]
	v_addc_co_u32_e32 v5, vcc, 0, v51, vcc
	global_load_dwordx4 v[64:67], v[4:5], off offset:2048
	v_add_co_u32_e32 v4, vcc, s75, v50
	v_mov_b32_e32 v18, v15
	s_nop 0
	v_addc_co_u32_e32 v5, vcc, 0, v51, vcc
	global_load_dwordx4 v[68:71], v[4:5], off
	v_pk_fma_f32 v[6:7], v[16:17], v[40:41], v[6:7] op_sel_hi:[1,0,1]
	s_waitcnt vmcnt(5)
	v_pk_fma_f32 v[2:3], v[48:49], v[18:19], v[2:3] op_sel_hi:[1,0,1]
	v_pk_fma_f32 v[6:7], v[20:21], v[42:43], v[6:7] op_sel_hi:[1,0,1]
	s_waitcnt vmcnt(4)
	v_pk_fma_f32 v[2:3], v[54:55], v[12:13], v[2:3] op_sel_hi:[1,0,1]
	v_mov_b32_e32 v22, v13
	v_pk_fma_f32 v[6:7], v[24:25], v[14:15], v[6:7] op_sel_hi:[1,0,1]
	v_mov_b32_e32 v26, v11
	v_pk_fma_f32 v[6:7], v[46:47], v[18:19], v[6:7] op_sel_hi:[1,0,1]
	s_waitcnt vmcnt(3)
	v_pk_fma_f32 v[2:3], v[58:59], v[22:23], v[2:3] op_sel_hi:[1,0,1]
	v_pk_fma_f32 v[6:7], v[52:53], v[12:13], v[6:7] op_sel_hi:[1,0,1]
	s_waitcnt vmcnt(2)
	v_pk_fma_f32 v[2:3], v[62:63], v[10:11], v[2:3] op_sel_hi:[1,0,1]
	v_pk_fma_f32 v[6:7], v[56:57], v[22:23], v[6:7] op_sel_hi:[1,0,1]
	s_waitcnt vmcnt(1)
	v_pk_fma_f32 v[2:3], v[66:67], v[26:27], v[2:3] op_sel_hi:[1,0,1]
	v_pk_fma_f32 v[6:7], v[60:61], v[10:11], v[6:7] op_sel_hi:[1,0,1]
	s_waitcnt vmcnt(0)
; template <int NB>
; __device__ __forceinline__ void sb_decode_task(const Params& P, float* lds, int task) {
;     ...
;     for (int vb = 0; vb < NBT; ++vb) {
;         if (vb + 1 < NBT) {
; #pragma unroll
;             for (int i = 0; i < NB; ++i) nx[i] = *(const float4*)(Vp + (size_t)(4 * NB * (vb + 1) + 4 * i + g) * (SH * HD)); }
; #pragma unroll
;         for (int i = 0; i < NB; ++i) { const float w = wl[4 * NB * vb + 4 * i + g]; o4.x += w * cur[i].x; o4.y += w * cur[i].y; o4.z += w * cur[i].z; o4.w += w * cur[i].w; }
; #pragma unroll
;         for (int i = 0; i < NB; ++i) cur[i] = nx[i];
;     }
; #pragma unroll
;     for (int off = 16; off < 64; off <<= 1) { o4.x += __shfl_xor(o4.x, off); o4.y += __shfl_xor(o4.y, off); o4.z += __shfl_xor(o4.z, off); o4.w += __shfl_xor(o4.w, off); }
;     if (g == 0) *(float4*)(dpart + (size_t)task * HD + 4 * c) = o4;
;     if (lane == 0) dl[task] = Ltot;
;     __builtin_amdgcn_wave_barrier();
	v_pk_fma_f32 v[32:33], v[70:71], v[8:9], v[2:3] op_sel_hi:[1,0,1]
	v_add_co_u32_e32 v2, vcc, s80, v50
	v_pk_fma_f32 v[6:7], v[64:65], v[26:27], v[6:7] op_sel_hi:[1,0,1]
	s_nop 0
	v_addc_co_u32_e32 v3, vcc, 0, v51, vcc
	v_pk_fma_f32 v[34:35], v[68:69], v[8:9], v[6:7] op_sel_hi:[1,0,1]
	v_add_co_u32_e32 v6, vcc, s81, v50
	global_load_dwordx4 v[2:5], v[2:3], off offset:2048
	s_nop 0
	v_addc_co_u32_e32 v7, vcc, 0, v51, vcc
	v_add_co_u32_e32 v10, vcc, s82, v50
	global_load_dwordx4 v[6:9], v[6:7], off
	s_nop 0
	v_addc_co_u32_e32 v11, vcc, 0, v51, vcc
	v_add_co_u32_e32 v14, vcc, s83, v50
	ds_read2_b32 v[42:43], v99 offset0:232 offset1:236
	ds_read2_b32 v[40:41], v99 offset0:240 offset1:244
	ds_read2_b32 v[38:39], v99 offset0:248 offset1:252
	v_addc_co_u32_e32 v15, vcc, 0, v51, vcc
	v_add_co_u32_e32 v18, vcc, s84, v50
	global_load_dwordx4 v[10:13], v[10:11], off offset:2048
	s_nop 0
	v_addc_co_u32_e32 v19, vcc, 0, v51, vcc
	v_add_co_u32_e32 v22, vcc, s85, v50
	global_load_dwordx4 v[14:17], v[14:15], off
	s_nop 0
	v_addc_co_u32_e32 v23, vcc, 0, v51, vcc
	v_add_co_u32_e32 v26, vcc, s86, v50
	global_load_dwordx4 v[18:21], v[18:19], off offset:2048
	s_nop 0
	v_addc_co_u32_e32 v27, vcc, 0, v51, vcc
	v_add_co_u32_e32 v46, vcc, s87, v50
	global_load_dwordx4 v[22:25], v[22:23], off
	s_nop 0
	v_addc_co_u32_e32 v47, vcc, 0, v51, vcc
	global_load_dwordx4 v[26:29], v[26:27], off offset:2048
	v_add_co_u32_e32 v50, vcc, s88, v50
	global_load_dwordx4 v[46:49], v[46:47], off
	s_nop 0
	v_addc_co_u32_e32 v51, vcc, 0, v51, vcc
	global_load_dwordx4 v[50:53], v[50:51], off offset:2048
	s_waitcnt lgkmcnt(2)
	v_mov_b32_e32 v54, v43
	s_waitcnt lgkmcnt(1)
	v_mov_b32_e32 v56, v41
	s_waitcnt lgkmcnt(0)
	v_mov_b32_e32 v58, v39
	s_waitcnt vmcnt(8)
	v_pk_fma_f32 v[2:3], v[2:3], v[36:37], v[34:35] op_sel_hi:[1,0,1]
	v_mov_b32_e32 v34, v31
	v_pk_fma_f32 v[4:5], v[4:5], v[36:37], v[32:33] op_sel_hi:[1,0,1]
	s_waitcnt vmcnt(7)
	v_pk_fma_f32 v[2:3], v[6:7], v[30:31], v[2:3] op_sel_hi:[1,0,1]
	v_pk_fma_f32 v[4:5], v[8:9], v[30:31], v[4:5] op_sel_hi:[1,0,1]
	s_waitcnt vmcnt(6)
	v_pk_fma_f32 v[2:3], v[10:11], v[34:35], v[2:3] op_sel_hi:[1,0,1]
	v_pk_fma_f32 v[4:5], v[12:13], v[34:35], v[4:5] op_sel_hi:[1,0,1]
	ds_bpermute_b32 v10, v106, v44
	s_waitcnt vmcnt(5)
	v_pk_fma_f32 v[2:3], v[14:15], v[42:43], v[2:3] op_sel_hi:[1,0,1]
	v_pk_fma_f32 v[4:5], v[16:17], v[42:43], v[4:5] op_sel_hi:[1,0,1]
	s_waitcnt vmcnt(4)
	v_pk_fma_f32 v[2:3], v[18:19], v[54:55], v[2:3] op_sel_hi:[1,0,1]
	v_pk_fma_f32 v[4:5], v[20:21], v[54:55], v[4:5] op_sel_hi:[1,0,1]
	s_waitcnt vmcnt(3)
	v_pk_fma_f32 v[2:3], v[22:23], v[40:41], v[2:3] op_sel_hi:[1,0,1]
	v_pk_fma_f32 v[4:5], v[24:25], v[40:41], v[4:5] op_sel_hi:[1,0,1]
	s_waitcnt vmcnt(2)
	v_pk_fma_f32 v[2:3], v[26:27], v[56:57], v[2:3] op_sel_hi:[1,0,1]
	v_pk_fma_f32 v[4:5], v[28:29], v[56:57], v[4:5] op_sel_hi:[1,0,1]
	s_waitcnt vmcnt(1)
	v_pk_fma_f32 v[2:3], v[46:47], v[38:39], v[2:3] op_sel_hi:[1,0,1]
	v_pk_fma_f32 v[4:5], v[48:49], v[38:39], v[4:5] op_sel_hi:[1,0,1]
	s_waitcnt vmcnt(0)
	v_pk_fma_f32 v[2:3], v[50:51], v[58:59], v[2:3] op_sel_hi:[1,0,1]
	ds_bpermute_b32 v6, v107, v2
	ds_bpermute_b32 v7, v107, v3
	v_pk_fma_f32 v[4:5], v[52:53], v[58:59], v[4:5] op_sel_hi:[1,0,1]
	s_waitcnt lgkmcnt(0)
	v_pk_add_f32 v[2:3], v[2:3], v[6:7]
	ds_bpermute_b32 v6, v107, v4
	ds_bpermute_b32 v7, v107, v5
	s_waitcnt lgkmcnt(0)
	v_pk_add_f32 v[4:5], v[4:5], v[6:7]
	ds_bpermute_b32 v6, v114, v2
	ds_bpermute_b32 v7, v114, v3
	ds_bpermute_b32 v8, v114, v4
	ds_bpermute_b32 v9, v114, v5
	s_and_saveexec_b64 s[0:1], s[20:21]
	s_cbranch_execz .LBB0_1415
	s_ashr_i32 s37, s36, 31
	s_lshl_b64 s[90:91], s[36:37], 8
	v_lshl_add_u64 v[12:13], v[88:89], 0, s[90:91]
	s_waitcnt lgkmcnt(2)
	v_pk_add_f32 v[2:3], v[2:3], v[6:7]
	s_waitcnt lgkmcnt(0)
	v_pk_add_f32 v[4:5], v[4:5], v[8:9]
	global_store_dwordx4 v[12:13], v[2:5], off

; __device__ __forceinline__ float bf2f(bf16_t b) { return __uint_as_float(((unsigned)b) << 16); }
; template <int NB>
; __device__ __forceinline__ void sb_decode_task(const Params& P, float* lds, int task) {
;     ...
;     const int h = task % SH, bj = task / SH, b = bj / NPAGES;
;     const int page = P.page_table[bj];
;     const float* Kp = P.cache_k + ((size_t)page * PAGE * SH + h) * HD + 4 * c;
;     const float* Vp = P.cache_v + ((size_t)page * PAGE * SH + h) * HD + 4 * c;
;     const bf16_t* qp = qb + (size_t)(NTOK + b) * SBW + h * 64 + 4 * c;
;     const float q0 = bf2f(qp[0]), q1 = bf2f(qp[1]), q2 = bf2f(qp[2]), q3 = bf2f(qp[3]);
;     const float bias = P.sb_bias[h] * LOG2E;
;     float4 cur[NB], nx[NB];
; #pragma unroll
;     for (int i = 0; i < NB; ++i) cur[i] = *(const float4*)(Kp + (size_t)(4 * i + g) * (SH * HD));
; #pragma unroll
;     for (int kb = 0; kb < NBT; ++kb) {
;         const float* np = (kb + 1 < NBT) ? Kp + (size_t)(4 * NB * (kb + 1)) * (SH * HD) : Vp;
; #pragma unroll
;         for (int i = 0; i < NB; ++i) nx[i] = *(const float4*)(np + (size_t)(4 * i + g) * (SH * HD));
; #pragma unroll
;         for (int i = 0; i < NB; ++i) { const int s = 4 * NB * kb + 4 * i + g;
;             float part = q0 * cur[i].x + q1 * cur[i].y + q2 * cur[i].z + q3 * cur[i].w; part = sum16(part);
;             if (c == 0) zl[s] = part + bias; }
.LBB0_1418:
	s_and_b64 vcc, exec, s[0:1]
	s_cbranch_vccz .LBB0_1267
	v_readlane_b32 s90, v252, 48
	v_readlane_b32 s91, v252, 49
	s_load_dwordx16 s[52:67], s[90:91], 0x0
	s_lshr_b32 s1, s2, 31
	s_add_i32 s0, s2, s1
	s_ashr_i32 s2, s2, 7
	s_mul_i32 s3, s0, 6
	s_add_i32 s2, s2, s1
	s_ashr_i32 s1, s0, 31
	s_sub_i32 s36, s34, s3
	s_lshl_b64 s[0:1], s[0:1], 2
	s_waitcnt lgkmcnt(0)
	s_add_u32 s0, s62, s0
	s_addc_u32 s1, s63, s1
	global_load_dword v2, v83, s[0:1]
	s_add_i32 s0, s2, 0x4000
	s_ashr_i32 s37, s36, 31
	s_mul_hi_i32 s1, s0, 0x300
	s_mulk_i32 s0, 0x300
	s_add_u32 s2, s38, s0
	s_addc_u32 s3, s39, s1
	s_lshl_b32 s0, s36, 6
	s_ashr_i32 s1, s0, 31
	s_lshl_b64 s[0:1], s[0:1], 1
	s_add_u32 s0, s2, s0
	s_addc_u32 s1, s3, s1
	v_readlane_b32 s52, v252, 16
	v_readlane_b32 s53, v252, 17
	v_readlane_b32 s60, v252, 24
	v_readlane_b32 s61, v252, 25
	s_mov_b64 s[52:53], s[60:61]
	v_readlane_b32 s54, v252, 18
	v_readlane_b32 s55, v252, 19
	v_readlane_b32 s56, v252, 20
	v_readlane_b32 s57, v252, 21
	v_readlane_b32 s58, v252, 22
	v_readlane_b32 s59, v252, 23
	v_readlane_b32 s62, v252, 26
	v_readlane_b32 s63, v252, 27
	v_readlane_b32 s64, v252, 28
	v_readlane_b32 s65, v252, 29
	v_readlane_b32 s66, v252, 30
	v_readlane_b32 s67, v252, 31
	s_waitcnt vmcnt(0)
	v_mov_b32_e32 v253, v2
	v_mul_hi_i32 v3, v2, s48
	v_mul_lo_u32 v2, v2, s48
	v_lshl_add_u64 v[42:43], v[2:3], 0, s[36:37]
	v_lshlrev_b64 v[2:3], 8, v[42:43]
	v_lshl_add_u64 v[38:39], v[84:85], 0, v[2:3]
	global_load_dwordx2 v[2:3], v101, s[0:1]
	s_lshl_b64 s[0:1], s[36:37], 2
	s_add_u32 s0, s52, s0
	s_addc_u32 s1, s53, s1
	global_load_dword v6, v83, s[0:1]
	s_waitcnt vmcnt(1)
	v_lshlrev_b32_e32 v45, 16, v2
	v_and_b32_e32 v47, 0xffff0000, v2
	v_lshlrev_b32_e32 v46, 16, v3
	v_and_b32_e32 v44, 0xffff0000, v3
	v_lshl_add_u64 v[2:3], v[38:39], 0, v[82:83]
	v_add_co_u32_e32 v4, vcc, s50, v2
	global_load_dwordx4 v[30:33], v[2:3], off
	s_nop 0
	v_addc_co_u32_e32 v5, vcc, 0, v3, vcc
	global_load_dwordx4 v[26:29], v[4:5], off offset:2048
	v_add_co_u32_e32 v4, vcc, s51, v2
	s_waitcnt vmcnt(2)
	v_mul_f32_e32 v48, 0x3fb8aa3b, v6
	v_addc_co_u32_e32 v5, vcc, 0, v3, vcc
	global_load_dwordx4 v[22:25], v[4:5], off
	v_add_co_u32_e32 v4, vcc, s49, v2
	s_waitcnt vmcnt(2)
	v_mul_f32_e32 v31, v31, v47
	v_addc_co_u32_e32 v5, vcc, 0, v3, vcc
	global_load_dwordx4 v[14:17], v[4:5], off offset:2048
	v_add_co_u32_e32 v4, vcc, s89, v2
	v_fmac_f32_e32 v31, v30, v45
	s_nop 0
	v_addc_co_u32_e32 v5, vcc, 0, v3, vcc
	global_load_dwordx4 v[18:21], v[4:5], off
	v_add_co_u32_e32 v4, vcc, s92, v2
	v_fmac_f32_e32 v31, v32, v46
	s_nop 0
	v_addc_co_u32_e32 v5, vcc, 0, v3, vcc
	global_load_dwordx4 v[6:9], v[4:5], off offset:2048
	v_add_co_u32_e32 v4, vcc, s93, v2
	v_fmac_f32_e32 v31, v33, v44
	s_nop 0
	v_addc_co_u32_e32 v5, vcc, 0, v3, vcc
	v_add_co_u32_e32 v2, vcc, s96, v2
	global_load_dwordx4 v[10:13], v[4:5], off
	s_nop 0
	v_addc_co_u32_e32 v3, vcc, 0, v3, vcc
	global_load_dwordx4 v[2:5], v[2:3], off offset:2048
	v_add_f32_dpp v30, v31, v31 quad_perm:[1,0,3,2] row_mask:0xf bank_mask:0xf bound_ctrl:1
	s_nop 1
	v_add_f32_dpp v30, v30, v30 quad_perm:[2,3,0,1] row_mask:0xf bank_mask:0xf bound_ctrl:1
	s_nop 1
	v_add_f32_dpp v30, v30, v30 row_ror:4 row_mask:0xf bank_mask:0xf bound_ctrl:1
	s_nop 1
	v_mov_b32_dpp v31, v30 row_ror:8 row_mask:0xf bank_mask:0xf bound_ctrl:1
	s_and_saveexec_b64 s[0:1], s[6:7]
	v_add_f32_e32 v30, v30, v31
	v_add_f32_e32 v30, v48, v30
	ds_write_b32 v99, v30
	s_or_b64 exec, exec, s[0:1]
	s_waitcnt vmcnt(6)
	v_mul_f32_e32 v27, v27, v47
	v_fmac_f32_e32 v27, v26, v45
	v_fmac_f32_e32 v27, v28, v46
	v_fmac_f32_e32 v27, v29, v44
	s_nop 1
	v_add_f32_dpp v26, v27, v27 quad_perm:[1,0,3,2] row_mask:0xf bank_mask:0xf bound_ctrl:1
	s_nop 1
	v_add_f32_dpp v26, v26, v26 quad_perm:[2,3,0,1] row_mask:0xf bank_mask:0xf bound_ctrl:1
	s_nop 1
	v_add_f32_dpp v26, v26, v26 row_ror:4 row_mask:0xf bank_mask:0xf bound_ctrl:1
	s_nop 1
	v_mov_b32_dpp v27, v26 row_ror:8 row_mask:0xf bank_mask:0xf bound_ctrl:1
	s_and_saveexec_b64 s[0:1], s[6:7]
	v_add_f32_e32 v26, v26, v27
	v_add_f32_e32 v26, v48, v26
	ds_write_b32 v99, v26 offset:16
	s_or_b64 exec, exec, s[0:1]
	s_waitcnt vmcnt(5)
	v_mul_f32_e32 v23, v23, v47
	v_fmac_f32_e32 v23, v22, v45
	v_fmac_f32_e32 v23, v24, v46
	v_fmac_f32_e32 v23, v25, v44
	s_nop 1
	v_add_f32_dpp v22, v23, v23 quad_perm:[1,0,3,2] row_mask:0xf bank_mask:0xf bound_ctrl:1
	s_nop 1
	v_add_f32_dpp v22, v22, v22 quad_perm:[2,3,0,1] row_mask:0xf bank_mask:0xf bound_ctrl:1
	s_nop 1
	v_add_f32_dpp v22, v22, v22 row_ror:4 row_mask:0xf bank_mask:0xf bound_ctrl:1
	s_nop 1
	v_mov_b32_dpp v23, v22 row_ror:8 row_mask:0xf bank_mask:0xf bound_ctrl:1
	s_and_saveexec_b64 s[0:1], s[6:7]
	v_add_f32_e32 v22, v22, v23
	v_add_f32_e32 v22, v48, v22
	ds_write_b32 v99, v22 offset:32
	s_or_b64 exec, exec, s[0:1]
	s_waitcnt vmcnt(4)
	v_mul_f32_e32 v15, v15, v47
	v_fmac_f32_e32 v15, v14, v45
	v_fmac_f32_e32 v15, v16, v46
	v_fmac_f32_e32 v15, v17, v44
	s_nop 1
	v_add_f32_dpp v14, v15, v15 quad_perm:[1,0,3,2] row_mask:0xf bank_mask:0xf bound_ctrl:1
	s_nop 1
	v_add_f32_dpp v14, v14, v14 quad_perm:[2,3,0,1] row_mask:0xf bank_mask:0xf bound_ctrl:1
	s_nop 1
	v_add_f32_dpp v14, v14, v14 row_ror:4 row_mask:0xf bank_mask:0xf bound_ctrl:1
	s_nop 1
	v_mov_b32_dpp v15, v14 row_ror:8 row_mask:0xf bank_mask:0xf bound_ctrl:1
	s_and_saveexec_b64 s[0:1], s[6:7]
	v_add_f32_e32 v14, v14, v15
	v_add_f32_e32 v14, v48, v14
	ds_write_b32 v99, v14 offset:48
	s_or_b64 exec, exec, s[0:1]
	v_lshl_add_u64 v[14:15], v[38:39], 0, v[82:83]
	v_add_co_u32_e32 v16, vcc, 0xc000, v14
	s_waitcnt vmcnt(3)
; template <int NB>
; __device__ __forceinline__ void sb_decode_task(const Params& P, float* lds, int task) {
;     ...
;     for (int kb = 0; kb < NBT; ++kb) {
;         const float* np = (kb + 1 < NBT) ? Kp + (size_t)(4 * NB * (kb + 1)) * (SH * HD) : Vp;
; #pragma unroll
;         for (int i = 0; i < NB; ++i) nx[i] = *(const float4*)(np + (size_t)(4 * i + g) * (SH * HD));
; #pragma unroll
;         for (int i = 0; i < NB; ++i) { const int s = 4 * NB * kb + 4 * i + g;
;             float part = q0 * cur[i].x + q1 * cur[i].y + q2 * cur[i].z + q3 * cur[i].w; part = sum16(part);
;             if (c == 0) zl[s] = part + bias; }
	v_mul_f32_e32 v19, v19, v47
	v_addc_co_u32_e32 v17, vcc, 0, v15, vcc
	v_add_co_u32_e32 v22, vcc, 0xd000, v14
	v_fmac_f32_e32 v19, v18, v45
	s_nop 0
	v_addc_co_u32_e32 v23, vcc, 0, v15, vcc
	global_load_dwordx4 v[30:33], v[16:17], off
	global_load_dwordx4 v[26:29], v[22:23], off offset:2048
	v_add_co_u32_e32 v16, vcc, 0xf000, v14
	v_fmac_f32_e32 v19, v20, v46
	s_nop 0
	v_addc_co_u32_e32 v17, vcc, 0, v15, vcc
	v_add_co_u32_e32 v14, vcc, 0x10000, v14
	v_fmac_f32_e32 v19, v21, v44
	s_nop 0
	v_addc_co_u32_e32 v15, vcc, 0, v15, vcc
	global_load_dwordx4 v[22:25], v[16:17], off
	s_nop 0
	global_load_dwordx4 v[14:17], v[14:15], off offset:2048
	v_add_f32_dpp v18, v19, v19 quad_perm:[1,0,3,2] row_mask:0xf bank_mask:0xf bound_ctrl:1
	s_nop 1
	v_add_f32_dpp v18, v18, v18 quad_perm:[2,3,0,1] row_mask:0xf bank_mask:0xf bound_ctrl:1
	s_nop 1
	v_add_f32_dpp v18, v18, v18 row_ror:4 row_mask:0xf bank_mask:0xf bound_ctrl:1
	s_nop 1
	v_mov_b32_dpp v19, v18 row_ror:8 row_mask:0xf bank_mask:0xf bound_ctrl:1
	s_and_saveexec_b64 s[0:1], s[6:7]
	v_add_f32_e32 v18, v18, v19
	v_add_f32_e32 v18, v48, v18
	ds_write_b32 v99, v18 offset:64
	s_or_b64 exec, exec, s[0:1]
	s_waitcnt vmcnt(6)
	v_mul_f32_e32 v7, v7, v47
	v_fmac_f32_e32 v7, v6, v45
	v_fmac_f32_e32 v7, v8, v46
	v_fmac_f32_e32 v7, v9, v44
	s_nop 1
	v_add_f32_dpp v6, v7, v7 quad_perm:[1,0,3,2] row_mask:0xf bank_mask:0xf bound_ctrl:1
	s_nop 1
	v_add_f32_dpp v6, v6, v6 quad_perm:[2,3,0,1] row_mask:0xf bank_mask:0xf bound_ctrl:1
	s_nop 1
	v_add_f32_dpp v6, v6, v6 row_ror:4 row_mask:0xf bank_mask:0xf bound_ctrl:1
	s_nop 1
	v_mov_b32_dpp v7, v6 row_ror:8 row_mask:0xf bank_mask:0xf bound_ctrl:1
	s_and_saveexec_b64 s[0:1], s[6:7]
	v_add_f32_e32 v6, v6, v7
	v_add_f32_e32 v6, v48, v6
	ds_write_b32 v99, v6 offset:80
	s_or_b64 exec, exec, s[0:1]
	s_waitcnt vmcnt(5)
	v_mul_f32_e32 v6, v11, v47
	v_fmac_f32_e32 v6, v10, v45
	v_fmac_f32_e32 v6, v12, v46
	v_fmac_f32_e32 v6, v13, v44
	s_nop 1
	v_add_f32_dpp v6, v6, v6 quad_perm:[1,0,3,2] row_mask:0xf bank_mask:0xf bound_ctrl:1
	s_nop 1
	v_add_f32_dpp v6, v6, v6 quad_perm:[2,3,0,1] row_mask:0xf bank_mask:0xf bound_ctrl:1
	s_nop 1
	v_add_f32_dpp v6, v6, v6 row_ror:4 row_mask:0xf bank_mask:0xf bound_ctrl:1
	s_nop 1
	v_mov_b32_dpp v7, v6 row_ror:8 row_mask:0xf bank_mask:0xf bound_ctrl:1
	s_and_saveexec_b64 s[0:1], s[6:7]
	v_add_f32_e32 v6, v6, v7
	v_add_f32_e32 v6, v48, v6
	ds_write_b32 v99, v6 offset:96
	s_or_b64 exec, exec, s[0:1]
	s_waitcnt vmcnt(4)
	v_mul_f32_e32 v3, v3, v47
	v_fmac_f32_e32 v3, v2, v45
	v_fmac_f32_e32 v3, v4, v46
	v_fmac_f32_e32 v3, v5, v44
	s_nop 1
	v_add_f32_dpp v2, v3, v3 quad_perm:[1,0,3,2] row_mask:0xf bank_mask:0xf bound_ctrl:1
	s_nop 1
	v_add_f32_dpp v2, v2, v2 quad_perm:[2,3,0,1] row_mask:0xf bank_mask:0xf bound_ctrl:1
	s_nop 1
	v_add_f32_dpp v2, v2, v2 row_ror:4 row_mask:0xf bank_mask:0xf bound_ctrl:1
	s_nop 1
	v_mov_b32_dpp v3, v2 row_ror:8 row_mask:0xf bank_mask:0xf bound_ctrl:1
	s_and_saveexec_b64 s[0:1], s[6:7]
	v_add_f32_e32 v2, v2, v3
	v_add_f32_e32 v2, v48, v2
	ds_write_b32 v99, v2 offset:112
	s_or_b64 exec, exec, s[0:1]
	v_lshl_add_u64 v[2:3], v[38:39], 0, v[82:83]
	v_add_co_u32_e32 v4, vcc, 0x12000, v2
	s_nop 1
	v_addc_co_u32_e32 v5, vcc, 0, v3, vcc
	v_add_co_u32_e32 v6, vcc, 0x13000, v2
	s_nop 1
	v_addc_co_u32_e32 v7, vcc, 0, v3, vcc
	global_load_dwordx4 v[34:37], v[4:5], off
	global_load_dwordx4 v[18:21], v[6:7], off offset:2048
	v_add_co_u32_e32 v4, vcc, 0x15000, v2
	s_waitcnt vmcnt(5)
	v_mul_f32_e32 v6, v31, v47
	v_addc_co_u32_e32 v5, vcc, 0, v3, vcc
	v_add_co_u32_e32 v2, vcc, 0x16000, v2
	v_fmac_f32_e32 v6, v30, v45
	s_nop 0
	v_addc_co_u32_e32 v3, vcc, 0, v3, vcc
	global_load_dwordx4 v[10:13], v[4:5], off
	s_nop 0
	global_load_dwordx4 v[2:5], v[2:3], off offset:2048
	v_fmac_f32_e32 v6, v32, v46
	v_fmac_f32_e32 v6, v33, v44
	s_nop 1
	v_add_f32_dpp v6, v6, v6 quad_perm:[1,0,3,2] row_mask:0xf bank_mask:0xf bound_ctrl:1
	s_nop 1
	v_add_f32_dpp v6, v6, v6 quad_perm:[2,3,0,1] row_mask:0xf bank_mask:0xf bound_ctrl:1
	s_nop 1
	v_add_f32_dpp v6, v6, v6 row_ror:4 row_mask:0xf bank_mask:0xf bound_ctrl:1
	s_nop 1
	v_mov_b32_dpp v7, v6 row_ror:8 row_mask:0xf bank_mask:0xf bound_ctrl:1
	s_and_saveexec_b64 s[0:1], s[6:7]
	v_add_f32_e32 v6, v6, v7
	v_add_f32_e32 v6, v48, v6
	ds_write_b32 v99, v6 offset:128
	s_or_b64 exec, exec, s[0:1]
	s_waitcnt vmcnt(6)
	v_mul_f32_e32 v6, v27, v47
	v_fmac_f32_e32 v6, v26, v45
	v_fmac_f32_e32 v6, v28, v46
	v_fmac_f32_e32 v6, v29, v44
	s_nop 1
	v_add_f32_dpp v6, v6, v6 quad_perm:[1,0,3,2] row_mask:0xf bank_mask:0xf bound_ctrl:1
	s_nop 1
	v_add_f32_dpp v6, v6, v6 quad_perm:[2,3,0,1] row_mask:0xf bank_mask:0xf bound_ctrl:1
	s_nop 1
	v_add_f32_dpp v6, v6, v6 row_ror:4 row_mask:0xf bank_mask:0xf bound_ctrl:1
	s_nop 1
	v_mov_b32_dpp v7, v6 row_ror:8 row_mask:0xf bank_mask:0xf bound_ctrl:1
	s_and_saveexec_b64 s[0:1], s[6:7]
	v_add_f32_e32 v6, v6, v7
	v_add_f32_e32 v6, v48, v6
	ds_write_b32 v99, v6 offset:144
	s_or_b64 exec, exec, s[0:1]
	s_waitcnt vmcnt(5)
	v_mul_f32_e32 v6, v23, v47
	v_fmac_f32_e32 v6, v22, v45
	v_fmac_f32_e32 v6, v24, v46
	v_fmac_f32_e32 v6, v25, v44
	s_nop 1
	v_add_f32_dpp v6, v6, v6 quad_perm:[1,0,3,2] row_mask:0xf bank_mask:0xf bound_ctrl:1
	s_nop 1
	v_add_f32_dpp v6, v6, v6 quad_perm:[2,3,0,1] row_mask:0xf bank_mask:0xf bound_ctrl:1
	s_nop 1
	v_add_f32_dpp v6, v6, v6 row_ror:4 row_mask:0xf bank_mask:0xf bound_ctrl:1
	s_nop 1
	v_mov_b32_dpp v7, v6 row_ror:8 row_mask:0xf bank_mask:0xf bound_ctrl:1
	s_and_saveexec_b64 s[0:1], s[6:7]
	v_add_f32_e32 v6, v6, v7
	v_add_f32_e32 v6, v48, v6
	ds_write_b32 v99, v6 offset:160
	s_or_b64 exec, exec, s[0:1]
	s_waitcnt vmcnt(4)
; template <int NB>
; __device__ __forceinline__ void sb_decode_task(const Params& P, float* lds, int task) {
;     ...
;     for (int kb = 0; kb < NBT; ++kb) {
;         const float* np = (kb + 1 < NBT) ? Kp + (size_t)(4 * NB * (kb + 1)) * (SH * HD) : Vp;
; #pragma unroll
;         for (int i = 0; i < NB; ++i) nx[i] = *(const float4*)(np + (size_t)(4 * i + g) * (SH * HD));
; #pragma unroll
;         for (int i = 0; i < NB; ++i) { const int s = 4 * NB * kb + 4 * i + g;
;             float part = q0 * cur[i].x + q1 * cur[i].y + q2 * cur[i].z + q3 * cur[i].w; part = sum16(part);
;             if (c == 0) zl[s] = part + bias; }
	v_mul_f32_e32 v6, v15, v47
	v_fmac_f32_e32 v6, v14, v45
	v_fmac_f32_e32 v6, v16, v46
	v_fmac_f32_e32 v6, v17, v44
	s_nop 1
	v_add_f32_dpp v6, v6, v6 quad_perm:[1,0,3,2] row_mask:0xf bank_mask:0xf bound_ctrl:1
	s_nop 1
	v_add_f32_dpp v6, v6, v6 quad_perm:[2,3,0,1] row_mask:0xf bank_mask:0xf bound_ctrl:1
	s_nop 1
	v_add_f32_dpp v6, v6, v6 row_ror:4 row_mask:0xf bank_mask:0xf bound_ctrl:1
	s_nop 1
	v_mov_b32_dpp v7, v6 row_ror:8 row_mask:0xf bank_mask:0xf bound_ctrl:1
	s_and_saveexec_b64 s[0:1], s[6:7]
	v_add_f32_e32 v6, v6, v7
	v_add_f32_e32 v6, v48, v6
	ds_write_b32 v99, v6 offset:176
	s_or_b64 exec, exec, s[0:1]
	v_lshl_add_u64 v[6:7], v[38:39], 0, v[82:83]
	v_add_co_u32_e32 v8, vcc, 0x18000, v6
	s_waitcnt vmcnt(3)
	v_mul_f32_e32 v30, v35, v47
	v_addc_co_u32_e32 v9, vcc, 0, v7, vcc
	v_add_co_u32_e32 v14, vcc, 0x19000, v6
	v_fmac_f32_e32 v30, v34, v45
	s_nop 0
	v_addc_co_u32_e32 v15, vcc, 0, v7, vcc
	global_load_dwordx4 v[26:29], v[8:9], off
	global_load_dwordx4 v[22:25], v[14:15], off offset:2048
	v_add_co_u32_e32 v8, vcc, 0x1b000, v6
	v_fmac_f32_e32 v30, v36, v46
	s_nop 0
	v_addc_co_u32_e32 v9, vcc, 0, v7, vcc
	v_add_co_u32_e32 v6, vcc, 0x1c000, v6
	v_fmac_f32_e32 v30, v37, v44
	s_nop 0
	v_addc_co_u32_e32 v7, vcc, 0, v7, vcc
	global_load_dwordx4 v[14:17], v[8:9], off
	s_nop 0
	global_load_dwordx4 v[6:9], v[6:7], off offset:2048
	v_add_f32_dpp v30, v30, v30 quad_perm:[1,0,3,2] row_mask:0xf bank_mask:0xf bound_ctrl:1
	s_nop 1
	v_add_f32_dpp v30, v30, v30 quad_perm:[2,3,0,1] row_mask:0xf bank_mask:0xf bound_ctrl:1
	s_nop 1
	v_add_f32_dpp v30, v30, v30 row_ror:4 row_mask:0xf bank_mask:0xf bound_ctrl:1
	s_nop 1
	v_mov_b32_dpp v31, v30 row_ror:8 row_mask:0xf bank_mask:0xf bound_ctrl:1
	s_and_saveexec_b64 s[0:1], s[6:7]
	v_add_f32_e32 v30, v30, v31
	v_add_f32_e32 v30, v48, v30
	ds_write_b32 v99, v30 offset:192
	s_or_b64 exec, exec, s[0:1]
	s_waitcnt vmcnt(6)
	v_mul_f32_e32 v19, v19, v47
	v_fmac_f32_e32 v19, v18, v45
	v_fmac_f32_e32 v19, v20, v46
	v_fmac_f32_e32 v19, v21, v44
	s_nop 1
	v_add_f32_dpp v18, v19, v19 quad_perm:[1,0,3,2] row_mask:0xf bank_mask:0xf bound_ctrl:1
	s_nop 1
	v_add_f32_dpp v18, v18, v18 quad_perm:[2,3,0,1] row_mask:0xf bank_mask:0xf bound_ctrl:1
	s_nop 1
	v_add_f32_dpp v18, v18, v18 row_ror:4 row_mask:0xf bank_mask:0xf bound_ctrl:1
	s_nop 1
	v_mov_b32_dpp v19, v18 row_ror:8 row_mask:0xf bank_mask:0xf bound_ctrl:1
	s_and_saveexec_b64 s[0:1], s[6:7]
	v_add_f32_e32 v18, v18, v19
	v_add_f32_e32 v18, v48, v18
	ds_write_b32 v99, v18 offset:208
	s_or_b64 exec, exec, s[0:1]
	s_waitcnt vmcnt(5)
	v_mul_f32_e32 v11, v11, v47
	v_fmac_f32_e32 v11, v10, v45
	v_fmac_f32_e32 v11, v12, v46
	v_fmac_f32_e32 v11, v13, v44
	s_nop 1
	v_add_f32_dpp v10, v11, v11 quad_perm:[1,0,3,2] row_mask:0xf bank_mask:0xf bound_ctrl:1
	s_nop 1
	v_add_f32_dpp v10, v10, v10 quad_perm:[2,3,0,1] row_mask:0xf bank_mask:0xf bound_ctrl:1
	s_nop 1
	v_add_f32_dpp v10, v10, v10 row_ror:4 row_mask:0xf bank_mask:0xf bound_ctrl:1
	s_nop 1
	v_mov_b32_dpp v11, v10 row_ror:8 row_mask:0xf bank_mask:0xf bound_ctrl:1
	s_and_saveexec_b64 s[0:1], s[6:7]
	v_add_f32_e32 v10, v10, v11
	v_add_f32_e32 v10, v48, v10
	ds_write_b32 v99, v10 offset:224
	s_or_b64 exec, exec, s[0:1]
	s_waitcnt vmcnt(4)
	v_mul_f32_e32 v3, v3, v47
	v_fmac_f32_e32 v3, v2, v45
	v_fmac_f32_e32 v3, v4, v46
	v_fmac_f32_e32 v3, v5, v44
	s_nop 1
	v_add_f32_dpp v2, v3, v3 quad_perm:[1,0,3,2] row_mask:0xf bank_mask:0xf bound_ctrl:1
	s_nop 1
	v_add_f32_dpp v2, v2, v2 quad_perm:[2,3,0,1] row_mask:0xf bank_mask:0xf bound_ctrl:1
	s_nop 1
	v_add_f32_dpp v2, v2, v2 row_ror:4 row_mask:0xf bank_mask:0xf bound_ctrl:1
	s_nop 1
	v_mov_b32_dpp v3, v2 row_ror:8 row_mask:0xf bank_mask:0xf bound_ctrl:1
	s_and_saveexec_b64 s[0:1], s[6:7]
	v_add_f32_e32 v2, v2, v3
	v_add_f32_e32 v2, v48, v2
	ds_write_b32 v99, v2 offset:240
	s_or_b64 exec, exec, s[0:1]
	v_lshl_add_u64 v[2:3], v[38:39], 0, v[82:83]
	v_add_co_u32_e32 v4, vcc, 0x1e000, v2
	s_waitcnt vmcnt(3)
	v_mul_f32_e32 v27, v27, v47
	v_addc_co_u32_e32 v5, vcc, 0, v3, vcc
	v_add_co_u32_e32 v10, vcc, 0x1f000, v2
	v_fmac_f32_e32 v27, v26, v45
	s_nop 0
	v_addc_co_u32_e32 v11, vcc, 0, v3, vcc
	global_load_dwordx4 v[30:33], v[4:5], off
	global_load_dwordx4 v[18:21], v[10:11], off offset:2048
	v_add_co_u32_e32 v4, vcc, 0x21000, v2
	v_fmac_f32_e32 v27, v28, v46
	s_nop 0
	v_addc_co_u32_e32 v5, vcc, 0, v3, vcc
	v_add_co_u32_e32 v2, vcc, 0x22000, v2
	v_fmac_f32_e32 v27, v29, v44
	s_nop 0
	v_addc_co_u32_e32 v3, vcc, 0, v3, vcc
	global_load_dwordx4 v[10:13], v[4:5], off
	s_nop 0
	global_load_dwordx4 v[2:5], v[2:3], off offset:2048
	v_add_f32_dpp v26, v27, v27 quad_perm:[1,0,3,2] row_mask:0xf bank_mask:0xf bound_ctrl:1
	s_nop 1
	v_add_f32_dpp v26, v26, v26 quad_perm:[2,3,0,1] row_mask:0xf bank_mask:0xf bound_ctrl:1
	s_nop 1
	v_add_f32_dpp v26, v26, v26 row_ror:4 row_mask:0xf bank_mask:0xf bound_ctrl:1
	s_nop 1
	v_mov_b32_dpp v27, v26 row_ror:8 row_mask:0xf bank_mask:0xf bound_ctrl:1
	s_and_saveexec_b64 s[0:1], s[6:7]
	v_add_f32_e32 v26, v26, v27
	v_add_f32_e32 v26, v48, v26
	ds_write_b32 v99, v26 offset:256
	s_or_b64 exec, exec, s[0:1]
	s_waitcnt vmcnt(6)
	v_mul_f32_e32 v23, v23, v47
	v_fmac_f32_e32 v23, v22, v45
	v_fmac_f32_e32 v23, v24, v46
	v_fmac_f32_e32 v23, v25, v44
	s_nop 1
	v_add_f32_dpp v22, v23, v23 quad_perm:[1,0,3,2] row_mask:0xf bank_mask:0xf bound_ctrl:1
	s_nop 1
	v_add_f32_dpp v22, v22, v22 quad_perm:[2,3,0,1] row_mask:0xf bank_mask:0xf bound_ctrl:1
	s_nop 1
	v_add_f32_dpp v22, v22, v22 row_ror:4 row_mask:0xf bank_mask:0xf bound_ctrl:1
	s_nop 1
	v_mov_b32_dpp v23, v22 row_ror:8 row_mask:0xf bank_mask:0xf bound_ctrl:1
	s_and_saveexec_b64 s[0:1], s[6:7]
	v_add_f32_e32 v22, v22, v23
	v_add_f32_e32 v22, v48, v22
	ds_write_b32 v99, v22 offset:272
	s_or_b64 exec, exec, s[0:1]
	s_waitcnt vmcnt(5)
; template <int NB>
; __device__ __forceinline__ void sb_decode_task(const Params& P, float* lds, int task) {
;     ...
;     for (int kb = 0; kb < NBT; ++kb) {
;         const float* np = (kb + 1 < NBT) ? Kp + (size_t)(4 * NB * (kb + 1)) * (SH * HD) : Vp;
; #pragma unroll
;         for (int i = 0; i < NB; ++i) nx[i] = *(const float4*)(np + (size_t)(4 * i + g) * (SH * HD));
; #pragma unroll
;         for (int i = 0; i < NB; ++i) { const int s = 4 * NB * kb + 4 * i + g;
;             float part = q0 * cur[i].x + q1 * cur[i].y + q2 * cur[i].z + q3 * cur[i].w; part = sum16(part);
;             if (c == 0) zl[s] = part + bias; }
	v_mul_f32_e32 v15, v15, v47
	v_fmac_f32_e32 v15, v14, v45
	v_fmac_f32_e32 v15, v16, v46
	v_fmac_f32_e32 v15, v17, v44
	s_nop 1
	v_add_f32_dpp v14, v15, v15 quad_perm:[1,0,3,2] row_mask:0xf bank_mask:0xf bound_ctrl:1
	s_nop 1
	v_add_f32_dpp v14, v14, v14 quad_perm:[2,3,0,1] row_mask:0xf bank_mask:0xf bound_ctrl:1
	s_nop 1
	v_add_f32_dpp v14, v14, v14 row_ror:4 row_mask:0xf bank_mask:0xf bound_ctrl:1
	s_nop 1
	v_mov_b32_dpp v15, v14 row_ror:8 row_mask:0xf bank_mask:0xf bound_ctrl:1
	s_and_saveexec_b64 s[0:1], s[6:7]
	v_add_f32_e32 v14, v14, v15
	v_add_f32_e32 v14, v48, v14
	ds_write_b32 v99, v14 offset:288
	s_or_b64 exec, exec, s[0:1]
	s_waitcnt vmcnt(4)
	v_mul_f32_e32 v7, v7, v47
	v_fmac_f32_e32 v7, v6, v45
	v_fmac_f32_e32 v7, v8, v46
	v_fmac_f32_e32 v7, v9, v44
	s_nop 1
	v_add_f32_dpp v6, v7, v7 quad_perm:[1,0,3,2] row_mask:0xf bank_mask:0xf bound_ctrl:1
	s_nop 1
	v_add_f32_dpp v6, v6, v6 quad_perm:[2,3,0,1] row_mask:0xf bank_mask:0xf bound_ctrl:1
	s_nop 1
	v_add_f32_dpp v6, v6, v6 row_ror:4 row_mask:0xf bank_mask:0xf bound_ctrl:1
	s_nop 1
	v_mov_b32_dpp v7, v6 row_ror:8 row_mask:0xf bank_mask:0xf bound_ctrl:1
	s_and_saveexec_b64 s[0:1], s[6:7]
	v_add_f32_e32 v6, v6, v7
	v_add_f32_e32 v6, v48, v6
	ds_write_b32 v99, v6 offset:304
	s_or_b64 exec, exec, s[0:1]
	v_lshl_add_u64 v[6:7], v[38:39], 0, v[82:83]
	v_add_co_u32_e32 v8, vcc, 0x24000, v6
	s_waitcnt vmcnt(3)
	v_mul_f32_e32 v22, v31, v47
	v_addc_co_u32_e32 v9, vcc, 0, v7, vcc
	v_add_co_u32_e32 v14, vcc, 0x25000, v6
	v_fmac_f32_e32 v22, v30, v45
	s_nop 0
	v_addc_co_u32_e32 v15, vcc, 0, v7, vcc
	global_load_dwordx4 v[34:37], v[8:9], off
	global_load_dwordx4 v[26:29], v[14:15], off offset:2048
	v_add_co_u32_e32 v8, vcc, 0x27000, v6
	v_fmac_f32_e32 v22, v32, v46
	s_nop 0
	v_addc_co_u32_e32 v9, vcc, 0, v7, vcc
	v_add_co_u32_e32 v6, vcc, 0x28000, v6
	v_fmac_f32_e32 v22, v33, v44
	s_nop 0
	v_addc_co_u32_e32 v7, vcc, 0, v7, vcc
	global_load_dwordx4 v[14:17], v[8:9], off
	s_nop 0
	global_load_dwordx4 v[6:9], v[6:7], off offset:2048
	v_add_f32_dpp v22, v22, v22 quad_perm:[1,0,3,2] row_mask:0xf bank_mask:0xf bound_ctrl:1
	s_nop 1
	v_add_f32_dpp v22, v22, v22 quad_perm:[2,3,0,1] row_mask:0xf bank_mask:0xf bound_ctrl:1
	s_nop 1
	v_add_f32_dpp v22, v22, v22 row_ror:4 row_mask:0xf bank_mask:0xf bound_ctrl:1
	s_nop 1
	v_mov_b32_dpp v23, v22 row_ror:8 row_mask:0xf bank_mask:0xf bound_ctrl:1
	s_and_saveexec_b64 s[0:1], s[6:7]
	v_add_f32_e32 v22, v22, v23
	v_add_f32_e32 v22, v48, v22
	ds_write_b32 v99, v22 offset:320
	s_or_b64 exec, exec, s[0:1]
	s_waitcnt vmcnt(6)
	v_mul_f32_e32 v19, v19, v47
	v_fmac_f32_e32 v19, v18, v45
	v_fmac_f32_e32 v19, v20, v46
	v_fmac_f32_e32 v19, v21, v44
	s_nop 1
	v_add_f32_dpp v18, v19, v19 quad_perm:[1,0,3,2] row_mask:0xf bank_mask:0xf bound_ctrl:1
	s_nop 1
	v_add_f32_dpp v18, v18, v18 quad_perm:[2,3,0,1] row_mask:0xf bank_mask:0xf bound_ctrl:1
	s_nop 1
	v_add_f32_dpp v18, v18, v18 row_ror:4 row_mask:0xf bank_mask:0xf bound_ctrl:1
	s_nop 1
	v_mov_b32_dpp v19, v18 row_ror:8 row_mask:0xf bank_mask:0xf bound_ctrl:1
	s_and_saveexec_b64 s[0:1], s[6:7]
	v_add_f32_e32 v18, v18, v19
	v_add_f32_e32 v18, v48, v18
	ds_write_b32 v99, v18 offset:336
	s_or_b64 exec, exec, s[0:1]
	s_waitcnt vmcnt(5)
	v_mul_f32_e32 v11, v11, v47
	v_fmac_f32_e32 v11, v10, v45
	v_fmac_f32_e32 v11, v12, v46
	v_fmac_f32_e32 v11, v13, v44
	s_nop 1
	v_add_f32_dpp v10, v11, v11 quad_perm:[1,0,3,2] row_mask:0xf bank_mask:0xf bound_ctrl:1
	s_nop 1
	v_add_f32_dpp v10, v10, v10 quad_perm:[2,3,0,1] row_mask:0xf bank_mask:0xf bound_ctrl:1
	s_nop 1
	v_add_f32_dpp v10, v10, v10 row_ror:4 row_mask:0xf bank_mask:0xf bound_ctrl:1
	s_nop 1
	v_mov_b32_dpp v11, v10 row_ror:8 row_mask:0xf bank_mask:0xf bound_ctrl:1
	s_and_saveexec_b64 s[0:1], s[6:7]
	v_add_f32_e32 v10, v10, v11
	v_add_f32_e32 v10, v48, v10
	ds_write_b32 v99, v10 offset:352
	s_or_b64 exec, exec, s[0:1]
	s_waitcnt vmcnt(4)
	v_mul_f32_e32 v3, v3, v47
	v_fmac_f32_e32 v3, v2, v45
	v_fmac_f32_e32 v3, v4, v46
	v_fmac_f32_e32 v3, v5, v44
	s_nop 1
	v_add_f32_dpp v2, v3, v3 quad_perm:[1,0,3,2] row_mask:0xf bank_mask:0xf bound_ctrl:1
	s_nop 1
	v_add_f32_dpp v2, v2, v2 quad_perm:[2,3,0,1] row_mask:0xf bank_mask:0xf bound_ctrl:1
	s_nop 1
	v_add_f32_dpp v2, v2, v2 row_ror:4 row_mask:0xf bank_mask:0xf bound_ctrl:1
	s_nop 1
	v_mov_b32_dpp v3, v2 row_ror:8 row_mask:0xf bank_mask:0xf bound_ctrl:1
	s_and_saveexec_b64 s[0:1], s[6:7]
	v_add_f32_e32 v2, v2, v3
	v_add_f32_e32 v2, v48, v2
	ds_write_b32 v99, v2 offset:368
	s_or_b64 exec, exec, s[0:1]
	v_lshl_add_u64 v[2:3], v[38:39], 0, v[82:83]
	v_add_co_u32_e32 v4, vcc, 0x2a000, v2
	s_nop 1
	v_addc_co_u32_e32 v5, vcc, 0, v3, vcc
	v_add_co_u32_e32 v10, vcc, 0x2b000, v2
	s_nop 1
	v_addc_co_u32_e32 v11, vcc, 0, v3, vcc
	global_load_dwordx4 v[38:41], v[4:5], off
	global_load_dwordx4 v[30:33], v[10:11], off offset:2048
	v_add_co_u32_e32 v4, vcc, 0x2d000, v2
	s_nop 1
	v_addc_co_u32_e32 v5, vcc, 0, v3, vcc
	v_add_co_u32_e32 v2, vcc, 0x2e000, v2
	s_nop 1
	v_addc_co_u32_e32 v3, vcc, 0, v3, vcc
	global_load_dwordx4 v[22:25], v[4:5], off
	global_load_dwordx4 v[18:21], v[2:3], off offset:2048
	s_waitcnt vmcnt(7)
	v_mul_f32_e32 v2, v35, v47
	v_fmac_f32_e32 v2, v34, v45
	v_fmac_f32_e32 v2, v36, v46
	v_fmac_f32_e32 v2, v37, v44
	s_nop 1
	v_add_f32_dpp v2, v2, v2 quad_perm:[1,0,3,2] row_mask:0xf bank_mask:0xf bound_ctrl:1
	s_nop 1
	v_add_f32_dpp v2, v2, v2 quad_perm:[2,3,0,1] row_mask:0xf bank_mask:0xf bound_ctrl:1
	s_nop 1
	v_add_f32_dpp v2, v2, v2 row_ror:4 row_mask:0xf bank_mask:0xf bound_ctrl:1
	s_nop 1
	v_mov_b32_dpp v3, v2 row_ror:8 row_mask:0xf bank_mask:0xf bound_ctrl:1
	s_and_saveexec_b64 s[0:1], s[6:7]
	v_add_f32_e32 v2, v2, v3
	v_add_f32_e32 v2, v48, v2
	ds_write_b32 v99, v2 offset:384
	s_or_b64 exec, exec, s[0:1]
	s_waitcnt vmcnt(6)
; template <int NB>
; __device__ __forceinline__ void sb_decode_task(const Params& P, float* lds, int task) {
;     ...
;     for (int kb = 0; kb < NBT; ++kb) {
;         const float* np = (kb + 1 < NBT) ? Kp + (size_t)(4 * NB * (kb + 1)) * (SH * HD) : Vp;
; #pragma unroll
;         for (int i = 0; i < NB; ++i) nx[i] = *(const float4*)(np + (size_t)(4 * i + g) * (SH * HD));
; #pragma unroll
;         for (int i = 0; i < NB; ++i) { const int s = 4 * NB * kb + 4 * i + g;
;             float part = q0 * cur[i].x + q1 * cur[i].y + q2 * cur[i].z + q3 * cur[i].w; part = sum16(part);
;             if (c == 0) zl[s] = part + bias; }
; #pragma unroll
;         for (int i = 0; i < NB; ++i) cur[i] = nx[i];
;     }
;     asm volatile("s_waitcnt lgkmcnt(0)" ::: "memory");
;     __builtin_amdgcn_wave_barrier();
;     const float z0 = zl[2 * lane], z1 = zl[2 * lane + 1];
	v_mul_f32_e32 v2, v27, v47
	v_fmac_f32_e32 v2, v26, v45
	v_fmac_f32_e32 v2, v28, v46
	v_fmac_f32_e32 v2, v29, v44
	s_nop 1
	v_add_f32_dpp v2, v2, v2 quad_perm:[1,0,3,2] row_mask:0xf bank_mask:0xf bound_ctrl:1
	s_nop 1
	v_add_f32_dpp v2, v2, v2 quad_perm:[2,3,0,1] row_mask:0xf bank_mask:0xf bound_ctrl:1
	s_nop 1
	v_add_f32_dpp v2, v2, v2 row_ror:4 row_mask:0xf bank_mask:0xf bound_ctrl:1
	s_nop 1
	v_mov_b32_dpp v3, v2 row_ror:8 row_mask:0xf bank_mask:0xf bound_ctrl:1
	s_and_saveexec_b64 s[0:1], s[6:7]
	v_add_f32_e32 v2, v2, v3
	v_add_f32_e32 v2, v48, v2
	ds_write_b32 v99, v2 offset:400
	s_or_b64 exec, exec, s[0:1]
	s_waitcnt vmcnt(5)
	v_mul_f32_e32 v2, v15, v47
	v_fmac_f32_e32 v2, v14, v45
	v_fmac_f32_e32 v2, v16, v46
	v_fmac_f32_e32 v2, v17, v44
	s_nop 1
	v_add_f32_dpp v2, v2, v2 quad_perm:[1,0,3,2] row_mask:0xf bank_mask:0xf bound_ctrl:1
	s_nop 1
	v_add_f32_dpp v2, v2, v2 quad_perm:[2,3,0,1] row_mask:0xf bank_mask:0xf bound_ctrl:1
	s_nop 1
	v_add_f32_dpp v2, v2, v2 row_ror:4 row_mask:0xf bank_mask:0xf bound_ctrl:1
	s_nop 1
	v_mov_b32_dpp v3, v2 row_ror:8 row_mask:0xf bank_mask:0xf bound_ctrl:1
	s_and_saveexec_b64 s[0:1], s[6:7]
	v_add_f32_e32 v2, v2, v3
	v_add_f32_e32 v2, v48, v2
	ds_write_b32 v99, v2 offset:416
	s_or_b64 exec, exec, s[0:1]
	s_waitcnt vmcnt(4)
	v_mul_f32_e32 v2, v7, v47
	v_fmac_f32_e32 v2, v6, v45
	v_fmac_f32_e32 v2, v8, v46
	v_fmac_f32_e32 v2, v9, v44
	s_nop 1
	v_add_f32_dpp v2, v2, v2 quad_perm:[1,0,3,2] row_mask:0xf bank_mask:0xf bound_ctrl:1
	s_nop 1
	v_add_f32_dpp v2, v2, v2 quad_perm:[2,3,0,1] row_mask:0xf bank_mask:0xf bound_ctrl:1
	s_nop 1
	v_add_f32_dpp v2, v2, v2 row_ror:4 row_mask:0xf bank_mask:0xf bound_ctrl:1
	s_nop 1
	v_mov_b32_dpp v3, v2 row_ror:8 row_mask:0xf bank_mask:0xf bound_ctrl:1
	s_and_saveexec_b64 s[0:1], s[6:7]
	v_add_f32_e32 v2, v2, v3
	v_add_f32_e32 v2, v48, v2
	ds_write_b32 v99, v2 offset:432
	s_or_b64 exec, exec, s[0:1]
	v_lshlrev_b64 v[2:3], 6, v[42:43]
	v_lshl_add_u64 v[34:35], v[2:3], 2, v[90:91]
	v_add_co_u32_e32 v2, vcc, 0x1000, v34
	s_waitcnt vmcnt(3)
	v_mul_f32_e32 v26, v39, v47
	v_addc_co_u32_e32 v3, vcc, 0, v35, vcc
	v_add_co_u32_e32 v6, vcc, 0x3000, v34
	global_load_dwordx4 v[14:17], v[34:35], off
	s_nop 0
	global_load_dwordx4 v[2:5], v[2:3], off offset:2048
	v_addc_co_u32_e32 v7, vcc, 0, v35, vcc
	v_add_co_u32_e32 v10, vcc, s49, v34
	v_fmac_f32_e32 v26, v38, v45
	s_nop 0
	v_addc_co_u32_e32 v11, vcc, 0, v35, vcc
	global_load_dwordx4 v[6:9], v[6:7], off
	s_nop 0
	global_load_dwordx4 v[10:13], v[10:11], off offset:2048
	v_fmac_f32_e32 v26, v40, v46
	v_fmac_f32_e32 v26, v41, v44
	s_nop 1
	v_add_f32_dpp v26, v26, v26 quad_perm:[1,0,3,2] row_mask:0xf bank_mask:0xf bound_ctrl:1
	s_nop 1
	v_add_f32_dpp v26, v26, v26 quad_perm:[2,3,0,1] row_mask:0xf bank_mask:0xf bound_ctrl:1
	s_nop 1
	v_add_f32_dpp v26, v26, v26 row_ror:4 row_mask:0xf bank_mask:0xf bound_ctrl:1
	s_nop 1
	v_mov_b32_dpp v27, v26 row_ror:8 row_mask:0xf bank_mask:0xf bound_ctrl:1
	s_and_saveexec_b64 s[0:1], s[6:7]
	v_add_f32_e32 v26, v26, v27
	v_add_f32_e32 v26, v48, v26
	ds_write_b32 v99, v26 offset:448
	s_or_b64 exec, exec, s[0:1]
	s_waitcnt vmcnt(6)
	v_mul_f32_e32 v26, v31, v47
	v_fmac_f32_e32 v26, v30, v45
	v_fmac_f32_e32 v26, v32, v46
	v_fmac_f32_e32 v26, v33, v44
	s_nop 1
	v_add_f32_dpp v26, v26, v26 quad_perm:[1,0,3,2] row_mask:0xf bank_mask:0xf bound_ctrl:1
	s_nop 1
	v_add_f32_dpp v26, v26, v26 quad_perm:[2,3,0,1] row_mask:0xf bank_mask:0xf bound_ctrl:1
	s_nop 1
	v_add_f32_dpp v26, v26, v26 row_ror:4 row_mask:0xf bank_mask:0xf bound_ctrl:1
	s_nop 1
	v_mov_b32_dpp v27, v26 row_ror:8 row_mask:0xf bank_mask:0xf bound_ctrl:1
	s_and_saveexec_b64 s[0:1], s[6:7]
	v_add_f32_e32 v26, v26, v27
	v_add_f32_e32 v26, v48, v26
	ds_write_b32 v99, v26 offset:464
	s_or_b64 exec, exec, s[0:1]
	s_waitcnt vmcnt(5)
	v_mul_f32_e32 v23, v23, v47
	v_fmac_f32_e32 v23, v22, v45
	v_fmac_f32_e32 v23, v24, v46
	v_fmac_f32_e32 v23, v25, v44
	s_nop 1
	v_add_f32_dpp v22, v23, v23 quad_perm:[1,0,3,2] row_mask:0xf bank_mask:0xf bound_ctrl:1
	s_nop 1
	v_add_f32_dpp v22, v22, v22 quad_perm:[2,3,0,1] row_mask:0xf bank_mask:0xf bound_ctrl:1
	s_nop 1
	v_add_f32_dpp v22, v22, v22 row_ror:4 row_mask:0xf bank_mask:0xf bound_ctrl:1
	s_nop 1
	v_mov_b32_dpp v23, v22 row_ror:8 row_mask:0xf bank_mask:0xf bound_ctrl:1
	s_and_saveexec_b64 s[0:1], s[6:7]
	v_add_f32_e32 v22, v22, v23
	v_add_f32_e32 v22, v48, v22
	ds_write_b32 v99, v22 offset:480
	s_or_b64 exec, exec, s[0:1]
	s_waitcnt vmcnt(4)
	v_mul_f32_e32 v19, v19, v47
	v_fmac_f32_e32 v19, v18, v45
	v_fmac_f32_e32 v19, v20, v46
	v_fmac_f32_e32 v19, v21, v44
	s_nop 1
	v_add_f32_dpp v18, v19, v19 quad_perm:[1,0,3,2] row_mask:0xf bank_mask:0xf bound_ctrl:1
	s_nop 1
	v_add_f32_dpp v18, v18, v18 quad_perm:[2,3,0,1] row_mask:0xf bank_mask:0xf bound_ctrl:1
	s_nop 1
	v_add_f32_dpp v18, v18, v18 row_ror:4 row_mask:0xf bank_mask:0xf bound_ctrl:1
	s_nop 1
	v_mov_b32_dpp v19, v18 row_ror:8 row_mask:0xf bank_mask:0xf bound_ctrl:1
	s_and_saveexec_b64 s[0:1], s[6:7]
	v_add_f32_e32 v18, v18, v19
	v_add_f32_e32 v18, v48, v18
	ds_write_b32 v99, v18 offset:496
	s_or_b64 exec, exec, s[0:1]
	s_waitcnt lgkmcnt(0)
	ds_read_b64 v[18:19], v100
	s_waitcnt lgkmcnt(0)
; __device__ __forceinline__ float softplus2_(float z2) { return fmaxf(z2, 0.f) + log1pf(exp2f(-fabsf(z2))) * LOG2E; }
; template <int NB>
; __device__ __forceinline__ void sb_decode_task(const Params& P, float* lds, int task) {
;     ...
;     const float sp0 = softplus2_(z0), sp1 = softplus2_(z1);
;     float incl = sp0 + sp1;
	v_cmp_gt_f32_e64 vcc, |v18|, s97
	s_nop 1
	v_cndmask_b32_e32 v21, 0, v103, vcc
	v_sub_f32_e64 v21, v21, |v18|
	v_exp_f32_e32 v21, v21
	v_max_f32_e32 v20, v18, v18
	v_max_f32_e32 v22, 0, v20
	v_cndmask_b32_e32 v20, 0, v102, vcc
	v_ldexp_f32 v23, v21, v20
	v_add_f32_e32 v24, 1.0, v23
	v_add_f32_e32 v20, -1.0, v24
	v_sub_f32_e32 v21, v20, v24
	v_add_f32_e32 v21, 1.0, v21
	v_sub_f32_e32 v20, v23, v20
	v_add_f32_e32 v25, v20, v21
	v_frexp_mant_f32_e32 v20, v24
	v_cmp_gt_f32_e32 vcc, s47, v20
	v_cvt_f64_f32_e32 v[20:21], v24
	v_frexp_exp_i32_f64_e32 v20, v[20:21]
	v_subbrev_co_u32_e32 v20, vcc, 0, v20, vcc
	v_sub_u32_e32 v21, 0, v20
	v_ldexp_f32 v24, v24, v21
	v_ldexp_f32 v21, v25, v21
	v_add_f32_e32 v25, -1.0, v24
	v_add_f32_e32 v26, 1.0, v25
	v_sub_f32_e32 v26, v24, v26
	v_add_f32_e32 v26, v21, v26
	v_add_f32_e32 v27, v25, v26
	v_sub_f32_e32 v25, v25, v27
	v_add_f32_e32 v25, v26, v25
	v_add_f32_e32 v26, 1.0, v24
	v_add_f32_e32 v28, -1.0, v26
	v_sub_f32_e32 v24, v24, v28
	v_add_f32_e32 v21, v21, v24
	v_add_f32_e32 v24, v26, v21
	v_sub_f32_e32 v26, v26, v24
	v_add_f32_e32 v21, v21, v26
	v_rcp_f32_e32 v26, v24
	v_cvt_f32_i32_e32 v20, v20
	v_cmp_neq_f32_e32 vcc, s46, v23
	v_mul_f32_e32 v28, v27, v26
	v_mul_f32_e32 v29, v24, v28
	v_fma_f32 v30, v28, v24, -v29
	v_fmac_f32_e32 v30, v28, v21
	v_add_f32_e32 v31, v29, v30
	v_sub_f32_e32 v32, v27, v31
	v_sub_f32_e32 v27, v27, v32
	v_sub_f32_e32 v29, v31, v29
	v_sub_f32_e32 v27, v27, v31
	v_add_f32_e32 v25, v25, v27
	v_sub_f32_e32 v27, v29, v30
	v_add_f32_e32 v25, v27, v25
	v_add_f32_e32 v27, v32, v25
	v_mul_f32_e32 v29, v26, v27
	v_mul_f32_e32 v30, v24, v29
	v_fma_f32 v24, v29, v24, -v30
	v_fmac_f32_e32 v24, v29, v21
	v_sub_f32_e32 v21, v32, v27
	v_add_f32_e32 v21, v25, v21
	v_add_f32_e32 v25, v30, v24
	v_sub_f32_e32 v31, v27, v25
	v_sub_f32_e32 v27, v27, v31
	v_sub_f32_e32 v30, v25, v30
	v_sub_f32_e32 v25, v27, v25
	v_add_f32_e32 v21, v21, v25
	v_sub_f32_e32 v24, v30, v24
	v_add_f32_e32 v21, v24, v21
	v_add_f32_e32 v24, v28, v29
	v_add_f32_e32 v21, v31, v21
	v_sub_f32_e32 v25, v24, v28
	v_mul_f32_e32 v21, v26, v21
	v_sub_f32_e32 v25, v29, v25
	v_add_f32_e32 v21, v25, v21
	v_mul_f32_e32 v28, 0x3f317218, v20
	v_add_f32_e32 v25, v24, v21
	v_fma_f32 v29, v20, s95, -v28
	v_mul_f32_e32 v26, v25, v25
	v_fmac_f32_e32 v29, 0xb102e308, v20
	v_sub_f32_e32 v20, v25, v24
	v_fmamk_f32 v27, v26, 0x3e9b6dac, v1
	v_sub_f32_e32 v20, v21, v20
	v_add_f32_e32 v21, v28, v29
	v_fmaak_f32 v27, v26, v27, 0x3f2aaada
	v_sub_f32_e32 v24, v21, v28
	v_ldexp_f32 v28, v25, 1
	v_mul_f32_e32 v25, v25, v26
	v_mul_f32_e32 v25, v25, v27
	v_add_f32_e32 v26, v28, v25
	v_sub_f32_e32 v27, v26, v28
	v_ldexp_f32 v20, v20, 1
	v_sub_f32_e32 v25, v25, v27
	v_add_f32_e32 v20, v20, v25
	v_add_f32_e32 v25, v26, v20
	v_sub_f32_e32 v26, v25, v26
	v_sub_f32_e32 v20, v20, v26
	v_add_f32_e32 v26, v21, v25
	v_sub_f32_e32 v27, v26, v21
	v_sub_f32_e32 v28, v26, v27
	v_sub_f32_e32 v24, v29, v24
	v_sub_f32_e32 v21, v21, v28
	v_sub_f32_e32 v25, v25, v27
	v_add_f32_e32 v21, v25, v21
	v_add_f32_e32 v25, v24, v20
	v_sub_f32_e32 v27, v25, v24
	v_sub_f32_e32 v28, v25, v27
	v_sub_f32_e32 v24, v24, v28
	v_sub_f32_e32 v20, v20, v27
	v_add_f32_e32 v21, v25, v21
	v_add_f32_e32 v20, v20, v24
	v_add_f32_e32 v24, v26, v21
	v_sub_f32_e32 v25, v24, v26
	v_sub_f32_e32 v21, v21, v25
	v_add_f32_e32 v20, v20, v21
	v_add_f32_e32 v20, v24, v20
	v_cndmask_b32_e32 v20, v104, v20, vcc
	v_cmp_lt_f32_e64 vcc, |v23|, s45
	s_nop 1
	v_cndmask_b32_e32 v20, v20, v23, vcc
	v_cmp_gt_f32_e64 vcc, |v19|, s97
	v_fmac_f32_e32 v22, 0x3fb8aa3b, v20
	v_max_f32_e32 v20, v19, v19
	v_cndmask_b32_e32 v21, 0, v103, vcc
	v_sub_f32_e64 v21, v21, |v19|
	v_exp_f32_e32 v21, v21
	v_max_f32_e32 v23, 0, v20
	v_cndmask_b32_e32 v20, 0, v102, vcc
	v_sub_f32_e32 v18, v18, v22
	v_ldexp_f32 v24, v21, v20
	v_add_f32_e32 v25, 1.0, v24
	v_add_f32_e32 v20, -1.0, v25
	v_sub_f32_e32 v21, v20, v25
	v_add_f32_e32 v21, 1.0, v21
	v_sub_f32_e32 v20, v24, v20
	v_add_f32_e32 v26, v20, v21
	v_frexp_mant_f32_e32 v20, v25
	v_cmp_gt_f32_e32 vcc, s47, v20
	v_cvt_f64_f32_e32 v[20:21], v25
	v_frexp_exp_i32_f64_e32 v20, v[20:21]
	v_subbrev_co_u32_e32 v20, vcc, 0, v20, vcc
	v_sub_u32_e32 v21, 0, v20
	v_ldexp_f32 v25, v25, v21
	v_ldexp_f32 v21, v26, v21
	v_add_f32_e32 v26, -1.0, v25
	v_add_f32_e32 v27, 1.0, v26
	v_sub_f32_e32 v27, v25, v27
	v_add_f32_e32 v27, v21, v27
	v_add_f32_e32 v28, v26, v27
	v_sub_f32_e32 v26, v26, v28
	v_add_f32_e32 v26, v27, v26
	v_add_f32_e32 v27, 1.0, v25
	v_add_f32_e32 v29, -1.0, v27
	v_sub_f32_e32 v25, v25, v29
	v_add_f32_e32 v21, v21, v25
	v_add_f32_e32 v25, v27, v21
	v_sub_f32_e32 v27, v27, v25
	v_add_f32_e32 v21, v21, v27
	v_rcp_f32_e32 v27, v25
	v_cvt_f32_i32_e32 v20, v20
	v_cmp_neq_f32_e32 vcc, s46, v24
	v_mul_f32_e32 v29, v28, v27
	v_mul_f32_e32 v30, v25, v29
	v_fma_f32 v31, v29, v25, -v30
	v_fmac_f32_e32 v31, v29, v21
	v_add_f32_e32 v32, v30, v31
	v_sub_f32_e32 v33, v28, v32
	v_sub_f32_e32 v28, v28, v33
	v_sub_f32_e32 v30, v32, v30
	v_sub_f32_e32 v28, v28, v32
	v_add_f32_e32 v26, v26, v28
	v_sub_f32_e32 v28, v30, v31
	v_add_f32_e32 v26, v28, v26
	v_add_f32_e32 v28, v33, v26
	v_mul_f32_e32 v30, v27, v28
	v_mul_f32_e32 v31, v25, v30
	v_fma_f32 v25, v30, v25, -v31
	v_fmac_f32_e32 v25, v30, v21
	v_sub_f32_e32 v21, v33, v28
	v_add_f32_e32 v21, v26, v21
	v_add_f32_e32 v26, v31, v25
	v_sub_f32_e32 v32, v28, v26
	v_sub_f32_e32 v28, v28, v32
	v_sub_f32_e32 v31, v26, v31
	v_sub_f32_e32 v26, v28, v26
	v_add_f32_e32 v21, v21, v26
	v_sub_f32_e32 v25, v31, v25
	v_add_f32_e32 v21, v25, v21
	v_add_f32_e32 v25, v29, v30
	v_add_f32_e32 v21, v32, v21
	v_sub_f32_e32 v26, v25, v29
	v_mul_f32_e32 v21, v27, v21
; __device__ __forceinline__ float softplus2_(float z2) { return fmaxf(z2, 0.f) + log1pf(exp2f(-fabsf(z2))) * LOG2E; }
; template <int NB>
; __device__ __forceinline__ void sb_decode_task(const Params& P, float* lds, int task) {
;     ...
;     const float sp0 = softplus2_(z0), sp1 = softplus2_(z1);
;     float incl = sp0 + sp1;
; #pragma unroll
;     for (int off = 1; off < 64; off <<= 1) { const float t = __shfl_down(incl, off); if (lane + off < 64) incl += t; }
;     const float excl = incl - (sp0 + sp1);
;     wl[2 * lane] = exp2f(z0 - sp0 - (excl + sp1));
;     wl[2 * lane + 1] = exp2f(z1 - sp1 - excl);
;     const float Ltot = __shfl(incl, 0);
;     asm volatile("s_waitcnt lgkmcnt(0)" ::: "memory");
;     __builtin_amdgcn_wave_barrier();
;     float4 o4 = make_float4(0.f, 0.f, 0.f, 0.f);
; #pragma unroll
;     for (int vb = 0; vb < NBT; ++vb) {
;         if (vb + 1 < NBT) {
; #pragma unroll
;             for (int i = 0; i < NB; ++i) nx[i] = *(const float4*)(Vp + (size_t)(4 * NB * (vb + 1) + 4 * i + g) * (SH * HD)); }
; #pragma unroll
;         for (int i = 0; i < NB; ++i) { const float w = wl[4 * NB * vb + 4 * i + g]; o4.x += w * cur[i].x; o4.y += w * cur[i].y; o4.z += w * cur[i].z; o4.w += w * cur[i].w; }
	v_sub_f32_e32 v26, v30, v26
	v_add_f32_e32 v21, v26, v21
	v_mul_f32_e32 v29, 0x3f317218, v20
	v_add_f32_e32 v26, v25, v21
	v_fma_f32 v30, v20, s95, -v29
	v_mul_f32_e32 v27, v26, v26
	v_fmac_f32_e32 v30, 0xb102e308, v20
	v_sub_f32_e32 v20, v26, v25
	v_fmamk_f32 v28, v27, 0x3e9b6dac, v1
	v_sub_f32_e32 v20, v21, v20
	v_add_f32_e32 v21, v29, v30
	v_fmaak_f32 v28, v27, v28, 0x3f2aaada
	v_sub_f32_e32 v25, v21, v29
	v_ldexp_f32 v29, v26, 1
	v_mul_f32_e32 v26, v26, v27
	v_mul_f32_e32 v26, v26, v28
	v_add_f32_e32 v27, v29, v26
	v_sub_f32_e32 v28, v27, v29
	v_ldexp_f32 v20, v20, 1
	v_sub_f32_e32 v26, v26, v28
	v_add_f32_e32 v20, v20, v26
	v_add_f32_e32 v26, v27, v20
	v_sub_f32_e32 v27, v26, v27
	v_sub_f32_e32 v20, v20, v27
	v_add_f32_e32 v27, v21, v26
	v_sub_f32_e32 v28, v27, v21
	v_sub_f32_e32 v29, v27, v28
	v_sub_f32_e32 v25, v30, v25
	v_sub_f32_e32 v21, v21, v29
	v_sub_f32_e32 v26, v26, v28
	v_add_f32_e32 v21, v26, v21
	v_add_f32_e32 v26, v25, v20
	v_sub_f32_e32 v28, v26, v25
	v_sub_f32_e32 v29, v26, v28
	v_sub_f32_e32 v25, v25, v29
	v_sub_f32_e32 v20, v20, v28
	v_add_f32_e32 v21, v26, v21
	v_add_f32_e32 v20, v20, v25
	v_add_f32_e32 v25, v27, v21
	v_sub_f32_e32 v26, v25, v27
	v_sub_f32_e32 v21, v21, v26
	v_add_f32_e32 v20, v20, v21
	v_add_f32_e32 v20, v25, v20
	v_cndmask_b32_e32 v20, v104, v20, vcc
	v_cmp_lt_f32_e64 vcc, |v24|, s45
	v_and_b32_e32 v21, 63, v105
	s_nop 0
	v_cndmask_b32_e32 v20, v20, v24, vcc
	v_cmp_ne_u32_e32 vcc, 63, v21
	v_fmac_f32_e32 v23, 0x3fb8aa3b, v20
	v_add_f32_e32 v20, v22, v23
	v_addc_co_u32_e32 v24, vcc, 0, v105, vcc
	v_lshlrev_b32_e32 v46, 2, v24
	ds_bpermute_b32 v24, v46, v20
	v_cmp_gt_u32_e32 vcc, 62, v21
	v_sub_f32_e32 v19, v19, v23
	s_waitcnt lgkmcnt(0)
	v_add_f32_e32 v24, v20, v24
	v_cndmask_b32_e64 v25, 0, 2, vcc
	v_cndmask_b32_e64 v24, v24, v20, s[8:9]
	v_add_lshl_u32 v47, v25, v105, 2
	ds_bpermute_b32 v25, v47, v24
	v_cmp_gt_u32_e32 vcc, 60, v21
	s_waitcnt lgkmcnt(0)
	v_add_f32_e32 v25, v24, v25
	v_cndmask_b32_e64 v24, v24, v25, s[10:11]
	v_cndmask_b32_e64 v25, 0, 4, vcc
	v_add_lshl_u32 v48, v25, v105, 2
	ds_bpermute_b32 v25, v48, v24
	v_cmp_gt_u32_e32 vcc, 56, v21
	s_waitcnt lgkmcnt(0)
	v_add_f32_e32 v25, v24, v25
	v_cndmask_b32_e64 v24, v24, v25, s[12:13]
	v_cndmask_b32_e64 v25, 0, 8, vcc
	v_add_lshl_u32 v49, v25, v105, 2
	ds_bpermute_b32 v25, v49, v24
	v_cmp_gt_u32_e32 vcc, 48, v21
	s_waitcnt lgkmcnt(0)
	v_add_f32_e32 v25, v24, v25
	v_cndmask_b32_e64 v21, 0, 16, vcc
	v_cndmask_b32_e64 v24, v24, v25, s[14:15]
	v_add_lshl_u32 v50, v21, v105, 2
	ds_bpermute_b32 v21, v50, v24
	s_waitcnt lgkmcnt(0)
	v_add_f32_e32 v21, v24, v21
	v_cndmask_b32_e64 v21, v24, v21, s[16:17]
	v_lshlrev_b32_e32 v24, 2, v105
	v_or_b32_e32 v51, 0x80, v24
	ds_bpermute_b32 v25, v51, v21
	v_and_b32_e32 v44, 0x100, v24
	s_waitcnt lgkmcnt(0)
	v_add_f32_e32 v25, v21, v25
	v_cndmask_b32_e64 v31, v21, v25, s[18:19]
	v_sub_f32_e32 v20, v31, v20
	v_add_f32_e32 v21, v23, v20
	v_sub_f32_e32 v18, v18, v21
	v_cmp_gt_f32_e32 vcc, s24, v18
	v_sub_f32_e32 v19, v19, v20
	s_nop 0
	v_cndmask_b32_e32 v21, 0, v103, vcc
	v_add_f32_e32 v18, v18, v21
	v_cndmask_b32_e32 v21, 0, v102, vcc
	v_cmp_gt_f32_e32 vcc, s24, v19
	v_exp_f32_e32 v18, v18
	s_nop 0
	v_cndmask_b32_e32 v20, 0, v103, vcc
	v_add_f32_e32 v19, v19, v20
	v_exp_f32_e32 v19, v19
	v_cndmask_b32_e32 v20, 0, v102, vcc
	v_ldexp_f32 v18, v18, v21
	v_ldexp_f32 v19, v19, v20
	ds_write_b64 v100, v[18:19] offset:512
	s_waitcnt lgkmcnt(0)
	ds_read2_b32 v[18:19], v99 offset0:128 offset1:132
	ds_read2_b32 v[32:33], v99 offset0:136 offset1:140
	ds_read2_b32 v[62:63], v99 offset0:144 offset1:148
	ds_read2_b32 v[64:65], v99 offset0:152 offset1:156
	ds_read2_b32 v[66:67], v99 offset0:160 offset1:164
	ds_read2_b32 v[68:69], v99 offset0:168 offset1:172
	s_waitcnt vmcnt(3) lgkmcnt(5)
	v_pk_fma_f32 v[36:37], v[14:15], v[18:19], 0 op_sel_hi:[1,0,0]
	v_add_co_u32_e32 v14, vcc, s89, v34
	v_pk_fma_f32 v[60:61], v[16:17], v[18:19], 0 op_sel_hi:[1,0,0]
	s_nop 0
	v_addc_co_u32_e32 v15, vcc, 0, v35, vcc
	v_add_co_u32_e32 v18, vcc, s92, v34
	v_mov_b32_e32 v30, v19
	s_nop 0
	v_addc_co_u32_e32 v19, vcc, 0, v35, vcc
	v_add_co_u32_e32 v22, vcc, s93, v34
	s_waitcnt vmcnt(2)
	v_pk_fma_f32 v[2:3], v[2:3], v[30:31], v[36:37] op_sel_hi:[1,0,1]
	v_addc_co_u32_e32 v23, vcc, 0, v35, vcc
	v_add_co_u32_e32 v26, vcc, s96, v34
	s_waitcnt vmcnt(1) lgkmcnt(4)
	v_pk_fma_f32 v[2:3], v[6:7], v[32:33], v[2:3] op_sel_hi:[1,0,1]
	v_addc_co_u32_e32 v27, vcc, 0, v35, vcc
	v_add_co_u32_e32 v6, vcc, s44, v34
	global_load_dwordx4 v[14:17], v[14:15], off
	s_nop 0
	v_addc_co_u32_e32 v7, vcc, 0, v35, vcc
	global_load_dwordx4 v[18:21], v[18:19], off offset:2048
	v_mov_b32_e32 v70, v33
	global_load_dwordx4 v[36:39], v[6:7], off
	v_add_co_u32_e32 v6, vcc, s26, v34
	global_load_dwordx4 v[22:25], v[22:23], off
	s_nop 0
	v_addc_co_u32_e32 v7, vcc, 0, v35, vcc
	global_load_dwordx4 v[26:29], v[26:27], off offset:2048
	s_waitcnt vmcnt(5)
	v_pk_fma_f32 v[2:3], v[10:11], v[70:71], v[2:3] op_sel_hi:[1,0,1]
	global_load_dwordx4 v[40:43], v[6:7], off offset:2048
	v_add_co_u32_e32 v6, vcc, s27, v34
	s_waitcnt lgkmcnt(2)
	v_mov_b32_e32 v10, v65
	v_addc_co_u32_e32 v7, vcc, 0, v35, vcc
	global_load_dwordx4 v[52:55], v[6:7], off
	v_add_co_u32_e32 v6, vcc, s28, v34
	s_waitcnt vmcnt(6)
	v_pk_fma_f32 v[2:3], v[14:15], v[62:63], v[2:3] op_sel_hi:[1,0,1]
	v_addc_co_u32_e32 v7, vcc, 0, v35, vcc
	global_load_dwordx4 v[56:59], v[6:7], off offset:2048
	v_mov_b32_e32 v6, v63
	s_waitcnt vmcnt(6)
	v_pk_fma_f32 v[2:3], v[18:19], v[6:7], v[2:3] op_sel_hi:[1,0,1]
	s_waitcnt lgkmcnt(1)
	v_mov_b32_e32 v14, v67
	s_waitcnt lgkmcnt(0)
	v_mov_b32_e32 v18, v69
	s_waitcnt vmcnt(4)
; template <int NB>
; __device__ __forceinline__ void sb_decode_task(const Params& P, float* lds, int task) {
;     ...
;     for (int vb = 0; vb < NBT; ++vb) {
;         if (vb + 1 < NBT) {
; #pragma unroll
;             for (int i = 0; i < NB; ++i) nx[i] = *(const float4*)(Vp + (size_t)(4 * NB * (vb + 1) + 4 * i + g) * (SH * HD)); }
; #pragma unroll
;         for (int i = 0; i < NB; ++i) { const float w = wl[4 * NB * vb + 4 * i + g]; o4.x += w * cur[i].x; o4.y += w * cur[i].y; o4.z += w * cur[i].z; o4.w += w * cur[i].w; }
; #pragma unroll
;         for (int i = 0; i < NB; ++i) cur[i] = nx[i];
;     }
	v_pk_fma_f32 v[2:3], v[22:23], v[64:65], v[2:3] op_sel_hi:[1,0,1]
	s_waitcnt vmcnt(3)
	v_pk_fma_f32 v[2:3], v[26:27], v[10:11], v[2:3] op_sel_hi:[1,0,1]
	s_nop 0
	v_pk_fma_f32 v[2:3], v[36:37], v[66:67], v[2:3] op_sel_hi:[1,0,1]
	s_waitcnt vmcnt(2)
	v_pk_fma_f32 v[2:3], v[40:41], v[14:15], v[2:3] op_sel_hi:[1,0,1]
	s_waitcnt vmcnt(1)
	v_pk_fma_f32 v[2:3], v[52:53], v[68:69], v[2:3] op_sel_hi:[1,0,1]
	s_waitcnt vmcnt(0)
	v_pk_fma_f32 v[56:57], v[56:57], v[18:19], v[2:3] op_sel_hi:[1,0,1]
	v_pk_fma_f32 v[2:3], v[4:5], v[30:31], v[60:61] op_sel_hi:[1,0,1]
	s_nop 0
	v_pk_fma_f32 v[2:3], v[8:9], v[32:33], v[2:3] op_sel_hi:[1,0,1]
	ds_read2_b32 v[8:9], v99 offset0:176 offset1:180
	v_pk_fma_f32 v[2:3], v[12:13], v[70:71], v[2:3] op_sel_hi:[1,0,1]
	s_waitcnt lgkmcnt(0)
	v_mov_b32_e32 v76, v9
	v_pk_fma_f32 v[2:3], v[16:17], v[62:63], v[2:3] op_sel_hi:[1,0,1]
	s_nop 0
	v_pk_fma_f32 v[2:3], v[20:21], v[6:7], v[2:3] op_sel_hi:[1,0,1]
	s_nop 0
	v_pk_fma_f32 v[2:3], v[24:25], v[64:65], v[2:3] op_sel_hi:[1,0,1]
	s_nop 0
	v_pk_fma_f32 v[2:3], v[28:29], v[10:11], v[2:3] op_sel_hi:[1,0,1]
	s_nop 0
	v_pk_fma_f32 v[2:3], v[38:39], v[66:67], v[2:3] op_sel_hi:[1,0,1]
	s_nop 0
	v_pk_fma_f32 v[2:3], v[42:43], v[14:15], v[2:3] op_sel_hi:[1,0,1]
	s_nop 0
	v_pk_fma_f32 v[2:3], v[54:55], v[68:69], v[2:3] op_sel_hi:[1,0,1]
	s_nop 0
	v_pk_fma_f32 v[6:7], v[58:59], v[18:19], v[2:3] op_sel_hi:[1,0,1]
	v_add_co_u32_e32 v2, vcc, s25, v34
	s_nop 1
	v_addc_co_u32_e32 v3, vcc, 0, v35, vcc
	global_load_dwordx4 v[10:13], v[2:3], off
	v_add_co_u32_e32 v2, vcc, s43, v34
	s_waitcnt vmcnt(0)
	v_pk_fma_f32 v[10:11], v[10:11], v[8:9], v[56:57] op_sel_hi:[1,0,1]
	v_addc_co_u32_e32 v3, vcc, 0, v35, vcc
	global_load_dwordx4 v[14:17], v[2:3], off offset:2048
	v_add_co_u32_e32 v2, vcc, s80, v34
	ds_read2_b32 v[32:33], v99 offset0:184 offset1:188
	ds_read2_b32 v[68:69], v99 offset0:192 offset1:196
	ds_read2_b32 v[70:71], v99 offset0:200 offset1:204
	ds_read2_b32 v[72:73], v99 offset0:208 offset1:212
	ds_read2_b32 v[74:75], v99 offset0:216 offset1:220
	v_addc_co_u32_e32 v3, vcc, 0, v35, vcc
	v_add_co_u32_e32 v18, vcc, s29, v34
	global_load_dwordx4 v[2:5], v[2:3], off offset:2048
	s_nop 0
	v_addc_co_u32_e32 v19, vcc, 0, v35, vcc
	v_add_co_u32_e32 v22, vcc, s68, v34
	global_load_dwordx4 v[18:21], v[18:19], off
	s_nop 0
	v_addc_co_u32_e32 v23, vcc, 0, v35, vcc
	v_add_co_u32_e32 v26, vcc, s69, v34
	global_load_dwordx4 v[22:25], v[22:23], off offset:2048
	s_nop 0
	v_addc_co_u32_e32 v27, vcc, 0, v35, vcc
	v_add_co_u32_e32 v36, vcc, s70, v34
	global_load_dwordx4 v[26:29], v[26:27], off
	s_nop 0
	v_addc_co_u32_e32 v37, vcc, 0, v35, vcc
	v_add_co_u32_e32 v40, vcc, s71, v34
	global_load_dwordx4 v[36:39], v[36:37], off offset:2048
	s_nop 0
	v_addc_co_u32_e32 v41, vcc, 0, v35, vcc
	v_add_co_u32_e32 v52, vcc, s72, v34
	global_load_dwordx4 v[40:43], v[40:41], off
	s_nop 0
	v_addc_co_u32_e32 v53, vcc, 0, v35, vcc
	global_load_dwordx4 v[52:55], v[52:53], off offset:2048
	v_pk_fma_f32 v[6:7], v[12:13], v[8:9], v[6:7] op_sel_hi:[1,0,1]
	s_waitcnt lgkmcnt(4)
	v_mov_b32_e32 v78, v33
	s_waitcnt lgkmcnt(0)
	v_mov_b32_e32 v30, v75
	s_waitcnt vmcnt(7)
	v_pk_fma_f32 v[10:11], v[14:15], v[76:77], v[10:11] op_sel_hi:[1,0,1]
	v_add_co_u32_e32 v14, vcc, s73, v34
	v_pk_fma_f32 v[6:7], v[16:17], v[76:77], v[6:7] op_sel_hi:[1,0,1]
	s_nop 0
	v_addc_co_u32_e32 v15, vcc, 0, v35, vcc
	global_load_dwordx4 v[56:59], v[14:15], off
	v_add_co_u32_e32 v14, vcc, s74, v34
	s_nop 1
	v_addc_co_u32_e32 v15, vcc, 0, v35, vcc
	global_load_dwordx4 v[60:63], v[14:15], off offset:2048
	v_add_co_u32_e32 v14, vcc, s75, v34
	s_nop 1
	v_addc_co_u32_e32 v15, vcc, 0, v35, vcc
	global_load_dwordx4 v[64:67], v[14:15], off
	s_waitcnt vmcnt(8)
	v_pk_fma_f32 v[10:11], v[18:19], v[32:33], v[10:11] op_sel_hi:[1,0,1]
	v_pk_fma_f32 v[6:7], v[20:21], v[32:33], v[6:7] op_sel_hi:[1,0,1]
	s_waitcnt vmcnt(7)
	v_pk_fma_f32 v[10:11], v[22:23], v[78:79], v[10:11] op_sel_hi:[1,0,1]
	v_pk_fma_f32 v[6:7], v[24:25], v[78:79], v[6:7] op_sel_hi:[1,0,1]
	v_mov_b32_e32 v14, v69
	s_waitcnt vmcnt(6)
	v_pk_fma_f32 v[10:11], v[26:27], v[68:69], v[10:11] op_sel_hi:[1,0,1]
	v_pk_fma_f32 v[6:7], v[28:29], v[68:69], v[6:7] op_sel_hi:[1,0,1]
	v_mov_b32_e32 v18, v71
	v_mov_b32_e32 v22, v73
	s_waitcnt vmcnt(5)
	v_pk_fma_f32 v[10:11], v[36:37], v[14:15], v[10:11] op_sel_hi:[1,0,1]
	v_pk_fma_f32 v[6:7], v[38:39], v[14:15], v[6:7] op_sel_hi:[1,0,1]
	ds_read2_b32 v[38:39], v99 offset0:224 offset1:228
	ds_read2_b32 v[32:33], v99 offset0:232 offset1:236
	s_waitcnt vmcnt(4)
; template <int NB>
; __device__ __forceinline__ void sb_decode_task(const Params& P, float* lds, int task) {
;     ...
;     for (int vb = 0; vb < NBT; ++vb) {
;         if (vb + 1 < NBT) {
; #pragma unroll
;             for (int i = 0; i < NB; ++i) nx[i] = *(const float4*)(Vp + (size_t)(4 * NB * (vb + 1) + 4 * i + g) * (SH * HD)); }
; #pragma unroll
;         for (int i = 0; i < NB; ++i) { const float w = wl[4 * NB * vb + 4 * i + g]; o4.x += w * cur[i].x; o4.y += w * cur[i].y; o4.z += w * cur[i].z; o4.w += w * cur[i].w; }
; #pragma unroll
;         for (int i = 0; i < NB; ++i) cur[i] = nx[i];
;     }
; #pragma unroll
;     for (int off = 16; off < 64; off <<= 1) { o4.x += __shfl_xor(o4.x, off); o4.y += __shfl_xor(o4.y, off); o4.z += __shfl_xor(o4.z, off); o4.w += __shfl_xor(o4.w, off); }
;     if (g == 0) *(float4*)(dpart + (size_t)task * HD + 4 * c) = o4;
;     if (lane == 0) dl[task] = Ltot;
	v_pk_fma_f32 v[10:11], v[40:41], v[70:71], v[10:11] op_sel_hi:[1,0,1]
	v_pk_fma_f32 v[6:7], v[42:43], v[70:71], v[6:7] op_sel_hi:[1,0,1]
	s_waitcnt vmcnt(3)
	v_pk_fma_f32 v[10:11], v[52:53], v[18:19], v[10:11] op_sel_hi:[1,0,1]
	v_pk_fma_f32 v[6:7], v[54:55], v[18:19], v[6:7] op_sel_hi:[1,0,1]
	s_waitcnt vmcnt(2)
	v_pk_fma_f32 v[10:11], v[56:57], v[72:73], v[10:11] op_sel_hi:[1,0,1]
	v_pk_fma_f32 v[6:7], v[58:59], v[72:73], v[6:7] op_sel_hi:[1,0,1]
	s_waitcnt vmcnt(1)
	v_pk_fma_f32 v[10:11], v[60:61], v[22:23], v[10:11] op_sel_hi:[1,0,1]
	v_pk_fma_f32 v[6:7], v[62:63], v[22:23], v[6:7] op_sel_hi:[1,0,1]
	s_waitcnt vmcnt(0)
	v_pk_fma_f32 v[26:27], v[64:65], v[74:75], v[10:11] op_sel_hi:[1,0,1]
	v_pk_fma_f32 v[36:37], v[66:67], v[74:75], v[6:7] op_sel_hi:[1,0,1]
	v_add_co_u32_e32 v6, vcc, s81, v34
	v_and_b32_e32 v10, 64, v105
	s_nop 0
	v_addc_co_u32_e32 v7, vcc, 0, v35, vcc
	v_add_u32_e32 v60, 64, v10
	v_xor_b32_e32 v10, 16, v105
	v_cmp_lt_i32_e32 vcc, v10, v60
	global_load_dwordx4 v[6:9], v[6:7], off
	ds_read2_b32 v[42:43], v99 offset0:240 offset1:244
	ds_read2_b32 v[40:41], v99 offset0:248 offset1:252
	v_cndmask_b32_e32 v10, v105, v10, vcc
	v_lshlrev_b32_e32 v45, 2, v10
	v_add_co_u32_e32 v10, vcc, s82, v34
	v_pk_fma_f32 v[2:3], v[2:3], v[30:31], v[26:27] op_sel_hi:[1,0,1]
	s_nop 0
	v_addc_co_u32_e32 v11, vcc, 0, v35, vcc
	v_add_co_u32_e32 v14, vcc, s83, v34
	global_load_dwordx4 v[10:13], v[10:11], off offset:2048
	s_nop 0
	v_addc_co_u32_e32 v15, vcc, 0, v35, vcc
	v_add_co_u32_e32 v18, vcc, s84, v34
	global_load_dwordx4 v[14:17], v[14:15], off
	s_nop 0
	v_addc_co_u32_e32 v19, vcc, 0, v35, vcc
	v_add_co_u32_e32 v22, vcc, s85, v34
	global_load_dwordx4 v[18:21], v[18:19], off offset:2048
	s_nop 0
	v_addc_co_u32_e32 v23, vcc, 0, v35, vcc
	v_add_co_u32_e32 v26, vcc, s86, v34
	global_load_dwordx4 v[22:25], v[22:23], off
	s_nop 0
	v_addc_co_u32_e32 v27, vcc, 0, v35, vcc
	v_add_co_u32_e32 v52, vcc, s87, v34
	global_load_dwordx4 v[26:29], v[26:27], off offset:2048
	s_nop 0
	v_addc_co_u32_e32 v53, vcc, 0, v35, vcc
	v_add_co_u32_e32 v34, vcc, s88, v34
	global_load_dwordx4 v[52:55], v[52:53], off
	s_nop 0
	v_addc_co_u32_e32 v35, vcc, 0, v35, vcc
	global_load_dwordx4 v[56:59], v[34:35], off offset:2048
	v_pk_fma_f32 v[4:5], v[4:5], v[30:31], v[36:37] op_sel_hi:[1,0,1]
	s_waitcnt vmcnt(7) lgkmcnt(3)
	v_pk_fma_f32 v[2:3], v[6:7], v[38:39], v[2:3] op_sel_hi:[1,0,1]
	v_mov_b32_e32 v6, v39
	v_pk_fma_f32 v[4:5], v[8:9], v[38:39], v[4:5] op_sel_hi:[1,0,1]
	s_waitcnt vmcnt(6)
	v_pk_fma_f32 v[2:3], v[10:11], v[6:7], v[2:3] op_sel_hi:[1,0,1]
	v_pk_fma_f32 v[4:5], v[12:13], v[6:7], v[4:5] op_sel_hi:[1,0,1]
	s_waitcnt lgkmcnt(2)
	v_mov_b32_e32 v10, v33
	s_waitcnt vmcnt(5)
	v_pk_fma_f32 v[4:5], v[16:17], v[32:33], v[4:5] op_sel_hi:[1,0,1]
	v_pk_fma_f32 v[2:3], v[14:15], v[32:33], v[2:3] op_sel_hi:[1,0,1]
	s_waitcnt lgkmcnt(1)
	v_mov_b32_e32 v14, v43
	s_waitcnt vmcnt(4)
	v_pk_fma_f32 v[4:5], v[20:21], v[10:11], v[4:5] op_sel_hi:[1,0,1]
	v_pk_fma_f32 v[2:3], v[18:19], v[10:11], v[2:3] op_sel_hi:[1,0,1]
	s_waitcnt lgkmcnt(0)
	v_mov_b32_e32 v18, v41
	ds_bpermute_b32 v10, v44, v31
	s_waitcnt vmcnt(3)
	v_pk_fma_f32 v[4:5], v[24:25], v[42:43], v[4:5] op_sel_hi:[1,0,1]
	v_pk_fma_f32 v[2:3], v[22:23], v[42:43], v[2:3] op_sel_hi:[1,0,1]
	s_waitcnt vmcnt(2)
	v_pk_fma_f32 v[4:5], v[28:29], v[14:15], v[4:5] op_sel_hi:[1,0,1]
	v_pk_fma_f32 v[2:3], v[26:27], v[14:15], v[2:3] op_sel_hi:[1,0,1]
	s_waitcnt vmcnt(1)
	v_pk_fma_f32 v[4:5], v[54:55], v[40:41], v[4:5] op_sel_hi:[1,0,1]
	v_pk_fma_f32 v[2:3], v[52:53], v[40:41], v[2:3] op_sel_hi:[1,0,1]
	s_waitcnt vmcnt(0)
	v_pk_fma_f32 v[4:5], v[58:59], v[18:19], v[4:5] op_sel_hi:[1,0,1]
	ds_bpermute_b32 v6, v45, v4
	ds_bpermute_b32 v7, v45, v5
	v_pk_fma_f32 v[2:3], v[56:57], v[18:19], v[2:3] op_sel_hi:[1,0,1]
	ds_bpermute_b32 v22, v45, v2
	ds_bpermute_b32 v23, v45, v3
	s_waitcnt lgkmcnt(2)
	v_pk_add_f32 v[4:5], v[4:5], v[6:7]
	v_xor_b32_e32 v6, 32, v105
	v_cmp_lt_i32_e32 vcc, v6, v60
	s_waitcnt lgkmcnt(0)
	v_pk_add_f32 v[2:3], v[2:3], v[22:23]
	v_cndmask_b32_e32 v6, v105, v6, vcc
	v_lshlrev_b32_e32 v52, 2, v6
	ds_bpermute_b32 v6, v52, v2
	ds_bpermute_b32 v7, v52, v3
	ds_bpermute_b32 v8, v52, v4
	ds_bpermute_b32 v9, v52, v5
	s_and_saveexec_b64 s[0:1], s[20:21]
	s_cbranch_execz .LBB0_1485
	s_ashr_i32 s35, s34, 31
	s_lshl_b64 s[2:3], s[34:35], 8
	v_lshl_add_u64 v[12:13], v[88:89], 0, s[2:3]
	s_waitcnt lgkmcnt(2)
	v_pk_add_f32 v[2:3], v[2:3], v[6:7]
	s_waitcnt lgkmcnt(0)
	v_pk_add_f32 v[4:5], v[4:5], v[8:9]
	global_store_dwordx4 v[12:13], v[2:5], off

; __device__ __forceinline__ float bf2f(bf16_t b) { return __uint_as_float(((unsigned)b) << 16); }
; template <int NB>
; __device__ __forceinline__ void sb_decode_task(const Params& P, float* lds, int task) {
;     ...
;     constexpr int NBT = 32 / NB;
;     const int h = task % SH, bj = task / SH, b = bj / NPAGES;
;     const int page = P.page_table[bj];
;     const float* Kp = P.cache_k + ((size_t)page * PAGE * SH + h) * HD + 4 * c;
;     const float* Vp = P.cache_v + ((size_t)page * PAGE * SH + h) * HD + 4 * c;
;     const bf16_t* qp = qb + (size_t)(NTOK + b) * SBW + h * 64 + 4 * c;
;     const float q0 = bf2f(qp[0]), q1 = bf2f(qp[1]), q2 = bf2f(qp[2]), q3 = bf2f(qp[3]);
;     const float bias = P.sb_bias[h] * LOG2E;
;     float4 cur[NB], nx[NB];
; #pragma unroll
;     for (int i = 0; i < NB; ++i) cur[i] = *(const float4*)(Kp + (size_t)(4 * i + g) * (SH * HD));
; #pragma unroll
;     for (int kb = 0; kb < NBT; ++kb) {
;         const float* np = (kb + 1 < NBT) ? Kp + (size_t)(4 * NB * (kb + 1)) * (SH * HD) : Vp;
; #pragma unroll
;         for (int i = 0; i < NB; ++i) nx[i] = *(const float4*)(np + (size_t)(4 * i + g) * (SH * HD));
; #pragma unroll
;         for (int i = 0; i < NB; ++i) { const int s = 4 * NB * kb + 4 * i + g;
;             float part = q0 * cur[i].x + q1 * cur[i].y + q2 * cur[i].z + q3 * cur[i].w; part = sum16(part);
;             if (c == 0) zl[s] = part + bias; }
.LBB0_1487:
	s_or_b64 exec, exec, s[0:1]
	v_readlane_b32 s36, v252, 48
	s_add_i32 s34, s34, 1
	v_readlane_b32 s37, v252, 49
	s_mul_hi_i32 s1, s34, 0x2aaaaaab
	s_load_dwordx16 s[52:67], s[36:37], 0x0
	s_lshr_b32 s3, s1, 31
	s_add_i32 s0, s1, s3
	s_ashr_i32 s1, s1, 7
	s_mul_i32 s2, s0, 6
	s_add_i32 s33, s1, s3
	s_ashr_i32 s1, s0, 31
	s_sub_i32 s2, s34, s2
	s_lshl_b64 s[0:1], s[0:1], 2
	s_waitcnt lgkmcnt(0)
	s_add_u32 s0, s62, s0
	s_addc_u32 s1, s63, s1
	v_mov_b32_e32 v2, v253
	s_add_i32 s0, s33, 0x4000
	s_ashr_i32 s3, s2, 31
	s_mul_hi_i32 s1, s0, 0x300
	s_mulk_i32 s0, 0x300
	s_add_u32 s33, s38, s0
	s_addc_u32 s35, s39, s1
	s_lshl_b32 s0, s2, 6
	s_ashr_i32 s1, s0, 31
	s_lshl_b64 s[0:1], s[0:1], 1
	s_add_u32 s0, s33, s0
	s_addc_u32 s1, s35, s1
	v_readlane_b32 s52, v252, 16
	v_readlane_b32 s53, v252, 17
	v_readlane_b32 s60, v252, 24
	v_readlane_b32 s61, v252, 25
	s_mov_b64 s[52:53], s[60:61]
	v_readlane_b32 s54, v252, 18
	v_readlane_b32 s55, v252, 19
	v_readlane_b32 s56, v252, 20
	v_readlane_b32 s57, v252, 21
	v_readlane_b32 s58, v252, 22
	v_readlane_b32 s59, v252, 23
	v_readlane_b32 s62, v252, 26
	v_readlane_b32 s63, v252, 27
	v_readlane_b32 s64, v252, 28
	v_readlane_b32 s65, v252, 29
	v_readlane_b32 s66, v252, 30
	v_readlane_b32 s67, v252, 31
	v_mul_hi_i32 v3, v2, s48
	v_mul_lo_u32 v2, v2, s48
	v_lshl_add_u64 v[42:43], v[2:3], 0, s[2:3]
	v_lshlrev_b64 v[2:3], 8, v[42:43]
	v_lshl_add_u64 v[38:39], v[84:85], 0, v[2:3]
	global_load_dwordx2 v[2:3], v101, s[0:1]
	s_lshl_b64 s[0:1], s[2:3], 2
	s_add_u32 s0, s52, s0
	s_addc_u32 s1, s53, s1
	global_load_dword v6, v83, s[0:1]
	s_waitcnt vmcnt(1)
	v_lshlrev_b32_e32 v54, 16, v2
	v_and_b32_e32 v56, 0xffff0000, v2
	v_lshlrev_b32_e32 v55, 16, v3
	v_and_b32_e32 v53, 0xffff0000, v3
	v_lshl_add_u64 v[2:3], v[38:39], 0, v[82:83]
	v_add_co_u32_e32 v4, vcc, s50, v2
	global_load_dwordx4 v[30:33], v[2:3], off
	s_nop 0
	v_addc_co_u32_e32 v5, vcc, 0, v3, vcc
	global_load_dwordx4 v[26:29], v[4:5], off offset:2048
	v_add_co_u32_e32 v4, vcc, s51, v2
	s_waitcnt vmcnt(2)
	v_mul_f32_e32 v57, 0x3fb8aa3b, v6
	v_addc_co_u32_e32 v5, vcc, 0, v3, vcc
	global_load_dwordx4 v[22:25], v[4:5], off
	v_add_co_u32_e32 v4, vcc, s49, v2
	s_waitcnt vmcnt(2)
	v_mul_f32_e32 v31, v31, v56
	v_addc_co_u32_e32 v5, vcc, 0, v3, vcc
	global_load_dwordx4 v[14:17], v[4:5], off offset:2048
	v_add_co_u32_e32 v4, vcc, s89, v2
	v_fmac_f32_e32 v31, v30, v54
	s_nop 0
	v_addc_co_u32_e32 v5, vcc, 0, v3, vcc
	global_load_dwordx4 v[18:21], v[4:5], off
	v_add_co_u32_e32 v4, vcc, s92, v2
	v_fmac_f32_e32 v31, v32, v55
	s_nop 0
	v_addc_co_u32_e32 v5, vcc, 0, v3, vcc
	global_load_dwordx4 v[6:9], v[4:5], off offset:2048
	v_add_co_u32_e32 v4, vcc, s93, v2
	v_fmac_f32_e32 v31, v33, v53
	s_nop 0
	v_addc_co_u32_e32 v5, vcc, 0, v3, vcc
	v_add_co_u32_e32 v2, vcc, s96, v2
	global_load_dwordx4 v[10:13], v[4:5], off
	s_nop 0
	v_addc_co_u32_e32 v3, vcc, 0, v3, vcc
	global_load_dwordx4 v[2:5], v[2:3], off offset:2048
	v_add_f32_dpp v30, v31, v31 quad_perm:[1,0,3,2] row_mask:0xf bank_mask:0xf bound_ctrl:1
	s_nop 1
	v_add_f32_dpp v30, v30, v30 quad_perm:[2,3,0,1] row_mask:0xf bank_mask:0xf bound_ctrl:1
	s_nop 1
	v_add_f32_dpp v30, v30, v30 row_ror:4 row_mask:0xf bank_mask:0xf bound_ctrl:1
	s_nop 1
	v_mov_b32_dpp v31, v30 row_ror:8 row_mask:0xf bank_mask:0xf bound_ctrl:1
	s_and_saveexec_b64 s[0:1], s[6:7]
	v_add_f32_e32 v30, v30, v31
	v_add_f32_e32 v30, v57, v30
	ds_write_b32 v99, v30
	s_or_b64 exec, exec, s[0:1]
	s_waitcnt vmcnt(6)
	v_mul_f32_e32 v27, v27, v56
	v_fmac_f32_e32 v27, v26, v54
	v_fmac_f32_e32 v27, v28, v55
	v_fmac_f32_e32 v27, v29, v53
	s_nop 1
	v_add_f32_dpp v26, v27, v27 quad_perm:[1,0,3,2] row_mask:0xf bank_mask:0xf bound_ctrl:1
	s_nop 1
	v_add_f32_dpp v26, v26, v26 quad_perm:[2,3,0,1] row_mask:0xf bank_mask:0xf bound_ctrl:1
	s_nop 1
	v_add_f32_dpp v26, v26, v26 row_ror:4 row_mask:0xf bank_mask:0xf bound_ctrl:1
	s_nop 1
	v_mov_b32_dpp v27, v26 row_ror:8 row_mask:0xf bank_mask:0xf bound_ctrl:1
	s_and_saveexec_b64 s[0:1], s[6:7]
	v_add_f32_e32 v26, v26, v27
	v_add_f32_e32 v26, v57, v26
	ds_write_b32 v99, v26 offset:16
	s_or_b64 exec, exec, s[0:1]
	s_waitcnt vmcnt(5)
	v_mul_f32_e32 v23, v23, v56
	v_fmac_f32_e32 v23, v22, v54
	v_fmac_f32_e32 v23, v24, v55
	v_fmac_f32_e32 v23, v25, v53
	s_nop 1
	v_add_f32_dpp v22, v23, v23 quad_perm:[1,0,3,2] row_mask:0xf bank_mask:0xf bound_ctrl:1
	s_nop 1
	v_add_f32_dpp v22, v22, v22 quad_perm:[2,3,0,1] row_mask:0xf bank_mask:0xf bound_ctrl:1
	s_nop 1
	v_add_f32_dpp v22, v22, v22 row_ror:4 row_mask:0xf bank_mask:0xf bound_ctrl:1
	s_nop 1
	v_mov_b32_dpp v23, v22 row_ror:8 row_mask:0xf bank_mask:0xf bound_ctrl:1
	s_and_saveexec_b64 s[0:1], s[6:7]
	v_add_f32_e32 v22, v22, v23
	v_add_f32_e32 v22, v57, v22
	ds_write_b32 v99, v22 offset:32
	s_or_b64 exec, exec, s[0:1]
	s_waitcnt vmcnt(4)
	v_mul_f32_e32 v15, v15, v56
	v_fmac_f32_e32 v15, v14, v54
	v_fmac_f32_e32 v15, v16, v55
	v_fmac_f32_e32 v15, v17, v53
	s_nop 1
	v_add_f32_dpp v14, v15, v15 quad_perm:[1,0,3,2] row_mask:0xf bank_mask:0xf bound_ctrl:1
	s_nop 1
	v_add_f32_dpp v14, v14, v14 quad_perm:[2,3,0,1] row_mask:0xf bank_mask:0xf bound_ctrl:1
	s_nop 1
	v_add_f32_dpp v14, v14, v14 row_ror:4 row_mask:0xf bank_mask:0xf bound_ctrl:1
	s_nop 1
	v_mov_b32_dpp v15, v14 row_ror:8 row_mask:0xf bank_mask:0xf bound_ctrl:1
	s_and_saveexec_b64 s[0:1], s[6:7]
	v_add_f32_e32 v14, v14, v15
	v_add_f32_e32 v14, v57, v14
	ds_write_b32 v99, v14 offset:48
	s_or_b64 exec, exec, s[0:1]
	v_lshl_add_u64 v[14:15], v[38:39], 0, v[82:83]
	v_add_co_u32_e32 v16, vcc, 0xc000, v14
	s_waitcnt vmcnt(3)
; template <int NB>
; __device__ __forceinline__ void sb_decode_task(const Params& P, float* lds, int task) {
;     ...
;     for (int kb = 0; kb < NBT; ++kb) {
;         const float* np = (kb + 1 < NBT) ? Kp + (size_t)(4 * NB * (kb + 1)) * (SH * HD) : Vp;
; #pragma unroll
;         for (int i = 0; i < NB; ++i) nx[i] = *(const float4*)(np + (size_t)(4 * i + g) * (SH * HD));
; #pragma unroll
;         for (int i = 0; i < NB; ++i) { const int s = 4 * NB * kb + 4 * i + g;
;             float part = q0 * cur[i].x + q1 * cur[i].y + q2 * cur[i].z + q3 * cur[i].w; part = sum16(part);
;             if (c == 0) zl[s] = part + bias; }
; #pragma unroll
;         for (int i = 0; i < NB; ++i) cur[i] = nx[i];
	v_mul_f32_e32 v19, v19, v56
	v_addc_co_u32_e32 v17, vcc, 0, v15, vcc
	v_add_co_u32_e32 v22, vcc, 0xd000, v14
	v_fmac_f32_e32 v19, v18, v54
	s_nop 0
	v_addc_co_u32_e32 v23, vcc, 0, v15, vcc
	global_load_dwordx4 v[30:33], v[16:17], off
	global_load_dwordx4 v[26:29], v[22:23], off offset:2048
	v_add_co_u32_e32 v16, vcc, 0xf000, v14
	v_fmac_f32_e32 v19, v20, v55
	s_nop 0
	v_addc_co_u32_e32 v17, vcc, 0, v15, vcc
	v_add_co_u32_e32 v14, vcc, 0x10000, v14
	v_fmac_f32_e32 v19, v21, v53
	s_nop 0
	v_addc_co_u32_e32 v15, vcc, 0, v15, vcc
	global_load_dwordx4 v[22:25], v[16:17], off
	s_nop 0
	global_load_dwordx4 v[14:17], v[14:15], off offset:2048
	v_add_f32_dpp v18, v19, v19 quad_perm:[1,0,3,2] row_mask:0xf bank_mask:0xf bound_ctrl:1
	s_nop 1
	v_add_f32_dpp v18, v18, v18 quad_perm:[2,3,0,1] row_mask:0xf bank_mask:0xf bound_ctrl:1
	s_nop 1
	v_add_f32_dpp v18, v18, v18 row_ror:4 row_mask:0xf bank_mask:0xf bound_ctrl:1
	s_nop 1
	v_mov_b32_dpp v19, v18 row_ror:8 row_mask:0xf bank_mask:0xf bound_ctrl:1
	s_and_saveexec_b64 s[0:1], s[6:7]
	v_add_f32_e32 v18, v18, v19
	v_add_f32_e32 v18, v57, v18
	ds_write_b32 v99, v18 offset:64
	s_or_b64 exec, exec, s[0:1]
	s_waitcnt vmcnt(6)
	v_mul_f32_e32 v7, v7, v56
	v_fmac_f32_e32 v7, v6, v54
	v_fmac_f32_e32 v7, v8, v55
	v_fmac_f32_e32 v7, v9, v53
	s_nop 1
	v_add_f32_dpp v6, v7, v7 quad_perm:[1,0,3,2] row_mask:0xf bank_mask:0xf bound_ctrl:1
	s_nop 1
	v_add_f32_dpp v6, v6, v6 quad_perm:[2,3,0,1] row_mask:0xf bank_mask:0xf bound_ctrl:1
	s_nop 1
	v_add_f32_dpp v6, v6, v6 row_ror:4 row_mask:0xf bank_mask:0xf bound_ctrl:1
	s_nop 1
	v_mov_b32_dpp v7, v6 row_ror:8 row_mask:0xf bank_mask:0xf bound_ctrl:1
	s_and_saveexec_b64 s[0:1], s[6:7]
	v_add_f32_e32 v6, v6, v7
	v_add_f32_e32 v6, v57, v6
	ds_write_b32 v99, v6 offset:80
	s_or_b64 exec, exec, s[0:1]
	s_waitcnt vmcnt(5)
	v_mul_f32_e32 v6, v11, v56
	v_fmac_f32_e32 v6, v10, v54
	v_fmac_f32_e32 v6, v12, v55
	v_fmac_f32_e32 v6, v13, v53
	s_nop 1
	v_add_f32_dpp v6, v6, v6 quad_perm:[1,0,3,2] row_mask:0xf bank_mask:0xf bound_ctrl:1
	s_nop 1
	v_add_f32_dpp v6, v6, v6 quad_perm:[2,3,0,1] row_mask:0xf bank_mask:0xf bound_ctrl:1
	s_nop 1
	v_add_f32_dpp v6, v6, v6 row_ror:4 row_mask:0xf bank_mask:0xf bound_ctrl:1
	s_nop 1
	v_mov_b32_dpp v7, v6 row_ror:8 row_mask:0xf bank_mask:0xf bound_ctrl:1
	s_and_saveexec_b64 s[0:1], s[6:7]
	v_add_f32_e32 v6, v6, v7
	v_add_f32_e32 v6, v57, v6
	ds_write_b32 v99, v6 offset:96
	s_or_b64 exec, exec, s[0:1]
	s_waitcnt vmcnt(4)
	v_mul_f32_e32 v3, v3, v56
	v_fmac_f32_e32 v3, v2, v54
	v_fmac_f32_e32 v3, v4, v55
	v_fmac_f32_e32 v3, v5, v53
	s_nop 1
	v_add_f32_dpp v2, v3, v3 quad_perm:[1,0,3,2] row_mask:0xf bank_mask:0xf bound_ctrl:1
	s_nop 1
	v_add_f32_dpp v2, v2, v2 quad_perm:[2,3,0,1] row_mask:0xf bank_mask:0xf bound_ctrl:1
	s_nop 1
	v_add_f32_dpp v2, v2, v2 row_ror:4 row_mask:0xf bank_mask:0xf bound_ctrl:1
	s_nop 1
	v_mov_b32_dpp v3, v2 row_ror:8 row_mask:0xf bank_mask:0xf bound_ctrl:1
	s_and_saveexec_b64 s[0:1], s[6:7]
	v_add_f32_e32 v2, v2, v3
	v_add_f32_e32 v2, v57, v2
	ds_write_b32 v99, v2 offset:112
	s_or_b64 exec, exec, s[0:1]
	v_lshl_add_u64 v[2:3], v[38:39], 0, v[82:83]
	v_add_co_u32_e32 v4, vcc, 0x12000, v2
	s_nop 1
	v_addc_co_u32_e32 v5, vcc, 0, v3, vcc
	v_add_co_u32_e32 v6, vcc, 0x13000, v2
	s_nop 1
	v_addc_co_u32_e32 v7, vcc, 0, v3, vcc
	global_load_dwordx4 v[34:37], v[4:5], off
	global_load_dwordx4 v[18:21], v[6:7], off offset:2048
	v_add_co_u32_e32 v4, vcc, 0x15000, v2
	s_waitcnt vmcnt(5)
	v_mul_f32_e32 v6, v31, v56
	v_addc_co_u32_e32 v5, vcc, 0, v3, vcc
	v_add_co_u32_e32 v2, vcc, 0x16000, v2
	v_fmac_f32_e32 v6, v30, v54
	s_nop 0
	v_addc_co_u32_e32 v3, vcc, 0, v3, vcc
	global_load_dwordx4 v[10:13], v[4:5], off
	s_nop 0
	global_load_dwordx4 v[2:5], v[2:3], off offset:2048
	v_fmac_f32_e32 v6, v32, v55
	v_fmac_f32_e32 v6, v33, v53
	s_nop 1
	v_add_f32_dpp v6, v6, v6 quad_perm:[1,0,3,2] row_mask:0xf bank_mask:0xf bound_ctrl:1
	s_nop 1
	v_add_f32_dpp v6, v6, v6 quad_perm:[2,3,0,1] row_mask:0xf bank_mask:0xf bound_ctrl:1
	s_nop 1
	v_add_f32_dpp v6, v6, v6 row_ror:4 row_mask:0xf bank_mask:0xf bound_ctrl:1
	s_nop 1
	v_mov_b32_dpp v7, v6 row_ror:8 row_mask:0xf bank_mask:0xf bound_ctrl:1
	s_and_saveexec_b64 s[0:1], s[6:7]
	v_add_f32_e32 v6, v6, v7
	v_add_f32_e32 v6, v57, v6
	ds_write_b32 v99, v6 offset:128
	s_or_b64 exec, exec, s[0:1]
	s_waitcnt vmcnt(6)
	v_mul_f32_e32 v6, v27, v56
	v_fmac_f32_e32 v6, v26, v54
	v_fmac_f32_e32 v6, v28, v55
	v_fmac_f32_e32 v6, v29, v53
	s_nop 1
	v_add_f32_dpp v6, v6, v6 quad_perm:[1,0,3,2] row_mask:0xf bank_mask:0xf bound_ctrl:1
	s_nop 1
	v_add_f32_dpp v6, v6, v6 quad_perm:[2,3,0,1] row_mask:0xf bank_mask:0xf bound_ctrl:1
	s_nop 1
	v_add_f32_dpp v6, v6, v6 row_ror:4 row_mask:0xf bank_mask:0xf bound_ctrl:1
	s_nop 1
	v_mov_b32_dpp v7, v6 row_ror:8 row_mask:0xf bank_mask:0xf bound_ctrl:1
	s_and_saveexec_b64 s[0:1], s[6:7]
	v_add_f32_e32 v6, v6, v7
	v_add_f32_e32 v6, v57, v6
	ds_write_b32 v99, v6 offset:144
	s_or_b64 exec, exec, s[0:1]
	s_waitcnt vmcnt(5)
	v_mul_f32_e32 v6, v23, v56
	v_fmac_f32_e32 v6, v22, v54
	v_fmac_f32_e32 v6, v24, v55
	v_fmac_f32_e32 v6, v25, v53
	s_nop 1
	v_add_f32_dpp v6, v6, v6 quad_perm:[1,0,3,2] row_mask:0xf bank_mask:0xf bound_ctrl:1
	s_nop 1
	v_add_f32_dpp v6, v6, v6 quad_perm:[2,3,0,1] row_mask:0xf bank_mask:0xf bound_ctrl:1
	s_nop 1
	v_add_f32_dpp v6, v6, v6 row_ror:4 row_mask:0xf bank_mask:0xf bound_ctrl:1
	s_nop 1
	v_mov_b32_dpp v7, v6 row_ror:8 row_mask:0xf bank_mask:0xf bound_ctrl:1
	s_and_saveexec_b64 s[0:1], s[6:7]
	v_add_f32_e32 v6, v6, v7
	v_add_f32_e32 v6, v57, v6
	ds_write_b32 v99, v6 offset:160
	s_or_b64 exec, exec, s[0:1]
	s_waitcnt vmcnt(4)
; template <int NB>
; __device__ __forceinline__ void sb_decode_task(const Params& P, float* lds, int task) {
;     ...
;     for (int kb = 0; kb < NBT; ++kb) {
;         const float* np = (kb + 1 < NBT) ? Kp + (size_t)(4 * NB * (kb + 1)) * (SH * HD) : Vp;
; #pragma unroll
;         for (int i = 0; i < NB; ++i) nx[i] = *(const float4*)(np + (size_t)(4 * i + g) * (SH * HD));
; #pragma unroll
;         for (int i = 0; i < NB; ++i) { const int s = 4 * NB * kb + 4 * i + g;
;             float part = q0 * cur[i].x + q1 * cur[i].y + q2 * cur[i].z + q3 * cur[i].w; part = sum16(part);
;             if (c == 0) zl[s] = part + bias; }
; #pragma unroll
;         for (int i = 0; i < NB; ++i) cur[i] = nx[i];
	v_mul_f32_e32 v6, v15, v56
	v_fmac_f32_e32 v6, v14, v54
	v_fmac_f32_e32 v6, v16, v55
	v_fmac_f32_e32 v6, v17, v53
	s_nop 1
	v_add_f32_dpp v6, v6, v6 quad_perm:[1,0,3,2] row_mask:0xf bank_mask:0xf bound_ctrl:1
	s_nop 1
	v_add_f32_dpp v6, v6, v6 quad_perm:[2,3,0,1] row_mask:0xf bank_mask:0xf bound_ctrl:1
	s_nop 1
	v_add_f32_dpp v6, v6, v6 row_ror:4 row_mask:0xf bank_mask:0xf bound_ctrl:1
	s_nop 1
	v_mov_b32_dpp v7, v6 row_ror:8 row_mask:0xf bank_mask:0xf bound_ctrl:1
	s_and_saveexec_b64 s[0:1], s[6:7]
	v_add_f32_e32 v6, v6, v7
	v_add_f32_e32 v6, v57, v6
	ds_write_b32 v99, v6 offset:176
	s_or_b64 exec, exec, s[0:1]
	v_lshl_add_u64 v[6:7], v[38:39], 0, v[82:83]
	v_add_co_u32_e32 v8, vcc, 0x18000, v6
	s_waitcnt vmcnt(3)
	v_mul_f32_e32 v30, v35, v56
	v_addc_co_u32_e32 v9, vcc, 0, v7, vcc
	v_add_co_u32_e32 v14, vcc, 0x19000, v6
	v_fmac_f32_e32 v30, v34, v54
	s_nop 0
	v_addc_co_u32_e32 v15, vcc, 0, v7, vcc
	global_load_dwordx4 v[26:29], v[8:9], off
	global_load_dwordx4 v[22:25], v[14:15], off offset:2048
	v_add_co_u32_e32 v8, vcc, 0x1b000, v6
	v_fmac_f32_e32 v30, v36, v55
	s_nop 0
	v_addc_co_u32_e32 v9, vcc, 0, v7, vcc
	v_add_co_u32_e32 v6, vcc, 0x1c000, v6
	v_fmac_f32_e32 v30, v37, v53
	s_nop 0
	v_addc_co_u32_e32 v7, vcc, 0, v7, vcc
	global_load_dwordx4 v[14:17], v[8:9], off
	s_nop 0
	global_load_dwordx4 v[6:9], v[6:7], off offset:2048
	v_add_f32_dpp v30, v30, v30 quad_perm:[1,0,3,2] row_mask:0xf bank_mask:0xf bound_ctrl:1
	s_nop 1
	v_add_f32_dpp v30, v30, v30 quad_perm:[2,3,0,1] row_mask:0xf bank_mask:0xf bound_ctrl:1
	s_nop 1
	v_add_f32_dpp v30, v30, v30 row_ror:4 row_mask:0xf bank_mask:0xf bound_ctrl:1
	s_nop 1
	v_mov_b32_dpp v31, v30 row_ror:8 row_mask:0xf bank_mask:0xf bound_ctrl:1
	s_and_saveexec_b64 s[0:1], s[6:7]
	v_add_f32_e32 v30, v30, v31
	v_add_f32_e32 v30, v57, v30
	ds_write_b32 v99, v30 offset:192
	s_or_b64 exec, exec, s[0:1]
	s_waitcnt vmcnt(6)
	v_mul_f32_e32 v19, v19, v56
	v_fmac_f32_e32 v19, v18, v54
	v_fmac_f32_e32 v19, v20, v55
	v_fmac_f32_e32 v19, v21, v53
	s_nop 1
	v_add_f32_dpp v18, v19, v19 quad_perm:[1,0,3,2] row_mask:0xf bank_mask:0xf bound_ctrl:1
	s_nop 1
	v_add_f32_dpp v18, v18, v18 quad_perm:[2,3,0,1] row_mask:0xf bank_mask:0xf bound_ctrl:1
	s_nop 1
	v_add_f32_dpp v18, v18, v18 row_ror:4 row_mask:0xf bank_mask:0xf bound_ctrl:1
	s_nop 1
	v_mov_b32_dpp v19, v18 row_ror:8 row_mask:0xf bank_mask:0xf bound_ctrl:1
	s_and_saveexec_b64 s[0:1], s[6:7]
	v_add_f32_e32 v18, v18, v19
	v_add_f32_e32 v18, v57, v18
	ds_write_b32 v99, v18 offset:208
	s_or_b64 exec, exec, s[0:1]
	s_waitcnt vmcnt(5)
	v_mul_f32_e32 v11, v11, v56
	v_fmac_f32_e32 v11, v10, v54
	v_fmac_f32_e32 v11, v12, v55
	v_fmac_f32_e32 v11, v13, v53
	s_nop 1
	v_add_f32_dpp v10, v11, v11 quad_perm:[1,0,3,2] row_mask:0xf bank_mask:0xf bound_ctrl:1
	s_nop 1
	v_add_f32_dpp v10, v10, v10 quad_perm:[2,3,0,1] row_mask:0xf bank_mask:0xf bound_ctrl:1
	s_nop 1
	v_add_f32_dpp v10, v10, v10 row_ror:4 row_mask:0xf bank_mask:0xf bound_ctrl:1
	s_nop 1
	v_mov_b32_dpp v11, v10 row_ror:8 row_mask:0xf bank_mask:0xf bound_ctrl:1
	s_and_saveexec_b64 s[0:1], s[6:7]
	v_add_f32_e32 v10, v10, v11
	v_add_f32_e32 v10, v57, v10
	ds_write_b32 v99, v10 offset:224
	s_or_b64 exec, exec, s[0:1]
	s_waitcnt vmcnt(4)
	v_mul_f32_e32 v3, v3, v56
	v_fmac_f32_e32 v3, v2, v54
	v_fmac_f32_e32 v3, v4, v55
	v_fmac_f32_e32 v3, v5, v53
	s_nop 1
	v_add_f32_dpp v2, v3, v3 quad_perm:[1,0,3,2] row_mask:0xf bank_mask:0xf bound_ctrl:1
	s_nop 1
	v_add_f32_dpp v2, v2, v2 quad_perm:[2,3,0,1] row_mask:0xf bank_mask:0xf bound_ctrl:1
	s_nop 1
	v_add_f32_dpp v2, v2, v2 row_ror:4 row_mask:0xf bank_mask:0xf bound_ctrl:1
	s_nop 1
	v_mov_b32_dpp v3, v2 row_ror:8 row_mask:0xf bank_mask:0xf bound_ctrl:1
	s_and_saveexec_b64 s[0:1], s[6:7]
	v_add_f32_e32 v2, v2, v3
	v_add_f32_e32 v2, v57, v2
	ds_write_b32 v99, v2 offset:240
	s_or_b64 exec, exec, s[0:1]
	v_lshl_add_u64 v[2:3], v[38:39], 0, v[82:83]
	v_add_co_u32_e32 v4, vcc, 0x1e000, v2
	s_waitcnt vmcnt(3)
	v_mul_f32_e32 v27, v27, v56
	v_addc_co_u32_e32 v5, vcc, 0, v3, vcc
	v_add_co_u32_e32 v10, vcc, 0x1f000, v2
	v_fmac_f32_e32 v27, v26, v54
	s_nop 0
	v_addc_co_u32_e32 v11, vcc, 0, v3, vcc
	global_load_dwordx4 v[30:33], v[4:5], off
	global_load_dwordx4 v[18:21], v[10:11], off offset:2048
	v_add_co_u32_e32 v4, vcc, 0x21000, v2
	v_fmac_f32_e32 v27, v28, v55
	s_nop 0
	v_addc_co_u32_e32 v5, vcc, 0, v3, vcc
	v_add_co_u32_e32 v2, vcc, 0x22000, v2
	v_fmac_f32_e32 v27, v29, v53
	s_nop 0
	v_addc_co_u32_e32 v3, vcc, 0, v3, vcc
	global_load_dwordx4 v[10:13], v[4:5], off
	s_nop 0
	global_load_dwordx4 v[2:5], v[2:3], off offset:2048
	v_add_f32_dpp v26, v27, v27 quad_perm:[1,0,3,2] row_mask:0xf bank_mask:0xf bound_ctrl:1
	s_nop 1
	v_add_f32_dpp v26, v26, v26 quad_perm:[2,3,0,1] row_mask:0xf bank_mask:0xf bound_ctrl:1
	s_nop 1
	v_add_f32_dpp v26, v26, v26 row_ror:4 row_mask:0xf bank_mask:0xf bound_ctrl:1
	s_nop 1
	v_mov_b32_dpp v27, v26 row_ror:8 row_mask:0xf bank_mask:0xf bound_ctrl:1
	s_and_saveexec_b64 s[0:1], s[6:7]
	v_add_f32_e32 v26, v26, v27
	v_add_f32_e32 v26, v57, v26
	ds_write_b32 v99, v26 offset:256
	s_or_b64 exec, exec, s[0:1]
	s_waitcnt vmcnt(6)
	v_mul_f32_e32 v23, v23, v56
	v_fmac_f32_e32 v23, v22, v54
	v_fmac_f32_e32 v23, v24, v55
	v_fmac_f32_e32 v23, v25, v53
	s_nop 1
	v_add_f32_dpp v22, v23, v23 quad_perm:[1,0,3,2] row_mask:0xf bank_mask:0xf bound_ctrl:1
	s_nop 1
	v_add_f32_dpp v22, v22, v22 quad_perm:[2,3,0,1] row_mask:0xf bank_mask:0xf bound_ctrl:1
	s_nop 1
	v_add_f32_dpp v22, v22, v22 row_ror:4 row_mask:0xf bank_mask:0xf bound_ctrl:1
	s_nop 1
	v_mov_b32_dpp v23, v22 row_ror:8 row_mask:0xf bank_mask:0xf bound_ctrl:1
	s_and_saveexec_b64 s[0:1], s[6:7]
	v_add_f32_e32 v22, v22, v23
	v_add_f32_e32 v22, v57, v22
	ds_write_b32 v99, v22 offset:272
	s_or_b64 exec, exec, s[0:1]
	s_waitcnt vmcnt(5)
; template <int NB>
; __device__ __forceinline__ void sb_decode_task(const Params& P, float* lds, int task) {
;     ...
;     for (int kb = 0; kb < NBT; ++kb) {
;         const float* np = (kb + 1 < NBT) ? Kp + (size_t)(4 * NB * (kb + 1)) * (SH * HD) : Vp;
; #pragma unroll
;         for (int i = 0; i < NB; ++i) nx[i] = *(const float4*)(np + (size_t)(4 * i + g) * (SH * HD));
; #pragma unroll
;         for (int i = 0; i < NB; ++i) { const int s = 4 * NB * kb + 4 * i + g;
;             float part = q0 * cur[i].x + q1 * cur[i].y + q2 * cur[i].z + q3 * cur[i].w; part = sum16(part);
;             if (c == 0) zl[s] = part + bias; }
; #pragma unroll
;         for (int i = 0; i < NB; ++i) cur[i] = nx[i];
	v_mul_f32_e32 v15, v15, v56
	v_fmac_f32_e32 v15, v14, v54
	v_fmac_f32_e32 v15, v16, v55
	v_fmac_f32_e32 v15, v17, v53
	s_nop 1
	v_add_f32_dpp v14, v15, v15 quad_perm:[1,0,3,2] row_mask:0xf bank_mask:0xf bound_ctrl:1
	s_nop 1
	v_add_f32_dpp v14, v14, v14 quad_perm:[2,3,0,1] row_mask:0xf bank_mask:0xf bound_ctrl:1
	s_nop 1
	v_add_f32_dpp v14, v14, v14 row_ror:4 row_mask:0xf bank_mask:0xf bound_ctrl:1
	s_nop 1
	v_mov_b32_dpp v15, v14 row_ror:8 row_mask:0xf bank_mask:0xf bound_ctrl:1
	s_and_saveexec_b64 s[0:1], s[6:7]
	v_add_f32_e32 v14, v14, v15
	v_add_f32_e32 v14, v57, v14
	ds_write_b32 v99, v14 offset:288
	s_or_b64 exec, exec, s[0:1]
	s_waitcnt vmcnt(4)
	v_mul_f32_e32 v7, v7, v56
	v_fmac_f32_e32 v7, v6, v54
	v_fmac_f32_e32 v7, v8, v55
	v_fmac_f32_e32 v7, v9, v53
	s_nop 1
	v_add_f32_dpp v6, v7, v7 quad_perm:[1,0,3,2] row_mask:0xf bank_mask:0xf bound_ctrl:1
	s_nop 1
	v_add_f32_dpp v6, v6, v6 quad_perm:[2,3,0,1] row_mask:0xf bank_mask:0xf bound_ctrl:1
	s_nop 1
	v_add_f32_dpp v6, v6, v6 row_ror:4 row_mask:0xf bank_mask:0xf bound_ctrl:1
	s_nop 1
	v_mov_b32_dpp v7, v6 row_ror:8 row_mask:0xf bank_mask:0xf bound_ctrl:1
	s_and_saveexec_b64 s[0:1], s[6:7]
	v_add_f32_e32 v6, v6, v7
	v_add_f32_e32 v6, v57, v6
	ds_write_b32 v99, v6 offset:304
	s_or_b64 exec, exec, s[0:1]
	v_lshl_add_u64 v[6:7], v[38:39], 0, v[82:83]
	v_add_co_u32_e32 v8, vcc, 0x24000, v6
	s_waitcnt vmcnt(3)
	v_mul_f32_e32 v22, v31, v56
	v_addc_co_u32_e32 v9, vcc, 0, v7, vcc
	v_add_co_u32_e32 v14, vcc, 0x25000, v6
	v_fmac_f32_e32 v22, v30, v54
	s_nop 0
	v_addc_co_u32_e32 v15, vcc, 0, v7, vcc
	global_load_dwordx4 v[34:37], v[8:9], off
	global_load_dwordx4 v[26:29], v[14:15], off offset:2048
	v_add_co_u32_e32 v8, vcc, 0x27000, v6
	v_fmac_f32_e32 v22, v32, v55
	s_nop 0
	v_addc_co_u32_e32 v9, vcc, 0, v7, vcc
	v_add_co_u32_e32 v6, vcc, 0x28000, v6
	v_fmac_f32_e32 v22, v33, v53
	s_nop 0
	v_addc_co_u32_e32 v7, vcc, 0, v7, vcc
	global_load_dwordx4 v[14:17], v[8:9], off
	s_nop 0
	global_load_dwordx4 v[6:9], v[6:7], off offset:2048
	v_add_f32_dpp v22, v22, v22 quad_perm:[1,0,3,2] row_mask:0xf bank_mask:0xf bound_ctrl:1
	s_nop 1
	v_add_f32_dpp v22, v22, v22 quad_perm:[2,3,0,1] row_mask:0xf bank_mask:0xf bound_ctrl:1
	s_nop 1
	v_add_f32_dpp v22, v22, v22 row_ror:4 row_mask:0xf bank_mask:0xf bound_ctrl:1
	s_nop 1
	v_mov_b32_dpp v23, v22 row_ror:8 row_mask:0xf bank_mask:0xf bound_ctrl:1
	s_and_saveexec_b64 s[0:1], s[6:7]
	v_add_f32_e32 v22, v22, v23
	v_add_f32_e32 v22, v57, v22
	ds_write_b32 v99, v22 offset:320
	s_or_b64 exec, exec, s[0:1]
	s_waitcnt vmcnt(6)
	v_mul_f32_e32 v19, v19, v56
	v_fmac_f32_e32 v19, v18, v54
	v_fmac_f32_e32 v19, v20, v55
	v_fmac_f32_e32 v19, v21, v53
	s_nop 1
	v_add_f32_dpp v18, v19, v19 quad_perm:[1,0,3,2] row_mask:0xf bank_mask:0xf bound_ctrl:1
	s_nop 1
	v_add_f32_dpp v18, v18, v18 quad_perm:[2,3,0,1] row_mask:0xf bank_mask:0xf bound_ctrl:1
	s_nop 1
	v_add_f32_dpp v18, v18, v18 row_ror:4 row_mask:0xf bank_mask:0xf bound_ctrl:1
	s_nop 1
	v_mov_b32_dpp v19, v18 row_ror:8 row_mask:0xf bank_mask:0xf bound_ctrl:1
	s_and_saveexec_b64 s[0:1], s[6:7]
	v_add_f32_e32 v18, v18, v19
	v_add_f32_e32 v18, v57, v18
	ds_write_b32 v99, v18 offset:336
	s_or_b64 exec, exec, s[0:1]
	s_waitcnt vmcnt(5)
	v_mul_f32_e32 v11, v11, v56
	v_fmac_f32_e32 v11, v10, v54
	v_fmac_f32_e32 v11, v12, v55
	v_fmac_f32_e32 v11, v13, v53
	s_nop 1
	v_add_f32_dpp v10, v11, v11 quad_perm:[1,0,3,2] row_mask:0xf bank_mask:0xf bound_ctrl:1
	s_nop 1
	v_add_f32_dpp v10, v10, v10 quad_perm:[2,3,0,1] row_mask:0xf bank_mask:0xf bound_ctrl:1
	s_nop 1
	v_add_f32_dpp v10, v10, v10 row_ror:4 row_mask:0xf bank_mask:0xf bound_ctrl:1
	s_nop 1
	v_mov_b32_dpp v11, v10 row_ror:8 row_mask:0xf bank_mask:0xf bound_ctrl:1
	s_and_saveexec_b64 s[0:1], s[6:7]
	v_add_f32_e32 v10, v10, v11
	v_add_f32_e32 v10, v57, v10
	ds_write_b32 v99, v10 offset:352
	s_or_b64 exec, exec, s[0:1]
	s_waitcnt vmcnt(4)
	v_mul_f32_e32 v3, v3, v56
	v_fmac_f32_e32 v3, v2, v54
	v_fmac_f32_e32 v3, v4, v55
	v_fmac_f32_e32 v3, v5, v53
	s_nop 1
	v_add_f32_dpp v2, v3, v3 quad_perm:[1,0,3,2] row_mask:0xf bank_mask:0xf bound_ctrl:1
	s_nop 1
	v_add_f32_dpp v2, v2, v2 quad_perm:[2,3,0,1] row_mask:0xf bank_mask:0xf bound_ctrl:1
	s_nop 1
	v_add_f32_dpp v2, v2, v2 row_ror:4 row_mask:0xf bank_mask:0xf bound_ctrl:1
	s_nop 1
	v_mov_b32_dpp v3, v2 row_ror:8 row_mask:0xf bank_mask:0xf bound_ctrl:1
	s_and_saveexec_b64 s[0:1], s[6:7]
	v_add_f32_e32 v2, v2, v3
	v_add_f32_e32 v2, v57, v2
	ds_write_b32 v99, v2 offset:368
	s_or_b64 exec, exec, s[0:1]
	v_lshl_add_u64 v[2:3], v[38:39], 0, v[82:83]
	v_add_co_u32_e32 v4, vcc, 0x2a000, v2
	s_nop 1
	v_addc_co_u32_e32 v5, vcc, 0, v3, vcc
	v_add_co_u32_e32 v10, vcc, 0x2b000, v2
	s_nop 1
	v_addc_co_u32_e32 v11, vcc, 0, v3, vcc
	global_load_dwordx4 v[38:41], v[4:5], off
	global_load_dwordx4 v[30:33], v[10:11], off offset:2048
	v_add_co_u32_e32 v4, vcc, 0x2d000, v2
	s_nop 1
	v_addc_co_u32_e32 v5, vcc, 0, v3, vcc
	v_add_co_u32_e32 v2, vcc, 0x2e000, v2
	s_nop 1
	v_addc_co_u32_e32 v3, vcc, 0, v3, vcc
	global_load_dwordx4 v[22:25], v[4:5], off
	global_load_dwordx4 v[18:21], v[2:3], off offset:2048
	s_waitcnt vmcnt(7)
	v_mul_f32_e32 v2, v35, v56
	v_fmac_f32_e32 v2, v34, v54
	v_fmac_f32_e32 v2, v36, v55
	v_fmac_f32_e32 v2, v37, v53
	s_nop 1
	v_add_f32_dpp v2, v2, v2 quad_perm:[1,0,3,2] row_mask:0xf bank_mask:0xf bound_ctrl:1
	s_nop 1
	v_add_f32_dpp v2, v2, v2 quad_perm:[2,3,0,1] row_mask:0xf bank_mask:0xf bound_ctrl:1
	s_nop 1
	v_add_f32_dpp v2, v2, v2 row_ror:4 row_mask:0xf bank_mask:0xf bound_ctrl:1
	s_nop 1
	v_mov_b32_dpp v3, v2 row_ror:8 row_mask:0xf bank_mask:0xf bound_ctrl:1
	s_and_saveexec_b64 s[0:1], s[6:7]
	v_add_f32_e32 v2, v2, v3
	v_add_f32_e32 v2, v57, v2
	ds_write_b32 v99, v2 offset:384
	s_or_b64 exec, exec, s[0:1]
	s_waitcnt vmcnt(6)
; template <int NB>
; __device__ __forceinline__ void sb_decode_task(const Params& P, float* lds, int task) {
;     ...
;     for (int kb = 0; kb < NBT; ++kb) {
;         const float* np = (kb + 1 < NBT) ? Kp + (size_t)(4 * NB * (kb + 1)) * (SH * HD) : Vp;
; #pragma unroll
;         for (int i = 0; i < NB; ++i) nx[i] = *(const float4*)(np + (size_t)(4 * i + g) * (SH * HD));
; #pragma unroll
;         for (int i = 0; i < NB; ++i) { const int s = 4 * NB * kb + 4 * i + g;
;             float part = q0 * cur[i].x + q1 * cur[i].y + q2 * cur[i].z + q3 * cur[i].w; part = sum16(part);
;             if (c == 0) zl[s] = part + bias; }
; #pragma unroll
;         for (int i = 0; i < NB; ++i) cur[i] = nx[i];
;     }
;     asm volatile("s_waitcnt lgkmcnt(0)" ::: "memory");
;     __builtin_amdgcn_wave_barrier();
;     const float z0 = zl[2 * lane], z1 = zl[2 * lane + 1];
	v_mul_f32_e32 v2, v27, v56
	v_fmac_f32_e32 v2, v26, v54
	v_fmac_f32_e32 v2, v28, v55
	v_fmac_f32_e32 v2, v29, v53
	s_nop 1
	v_add_f32_dpp v2, v2, v2 quad_perm:[1,0,3,2] row_mask:0xf bank_mask:0xf bound_ctrl:1
	s_nop 1
	v_add_f32_dpp v2, v2, v2 quad_perm:[2,3,0,1] row_mask:0xf bank_mask:0xf bound_ctrl:1
	s_nop 1
	v_add_f32_dpp v2, v2, v2 row_ror:4 row_mask:0xf bank_mask:0xf bound_ctrl:1
	s_nop 1
	v_mov_b32_dpp v3, v2 row_ror:8 row_mask:0xf bank_mask:0xf bound_ctrl:1
	s_and_saveexec_b64 s[0:1], s[6:7]
	v_add_f32_e32 v2, v2, v3
	v_add_f32_e32 v2, v57, v2
	ds_write_b32 v99, v2 offset:400
	s_or_b64 exec, exec, s[0:1]
	s_waitcnt vmcnt(5)
	v_mul_f32_e32 v2, v15, v56
	v_fmac_f32_e32 v2, v14, v54
	v_fmac_f32_e32 v2, v16, v55
	v_fmac_f32_e32 v2, v17, v53
	s_nop 1
	v_add_f32_dpp v2, v2, v2 quad_perm:[1,0,3,2] row_mask:0xf bank_mask:0xf bound_ctrl:1
	s_nop 1
	v_add_f32_dpp v2, v2, v2 quad_perm:[2,3,0,1] row_mask:0xf bank_mask:0xf bound_ctrl:1
	s_nop 1
	v_add_f32_dpp v2, v2, v2 row_ror:4 row_mask:0xf bank_mask:0xf bound_ctrl:1
	s_nop 1
	v_mov_b32_dpp v3, v2 row_ror:8 row_mask:0xf bank_mask:0xf bound_ctrl:1
	s_and_saveexec_b64 s[0:1], s[6:7]
	v_add_f32_e32 v2, v2, v3
	v_add_f32_e32 v2, v57, v2
	ds_write_b32 v99, v2 offset:416
	s_or_b64 exec, exec, s[0:1]
	s_waitcnt vmcnt(4)
	v_mul_f32_e32 v2, v7, v56
	v_fmac_f32_e32 v2, v6, v54
	v_fmac_f32_e32 v2, v8, v55
	v_fmac_f32_e32 v2, v9, v53
	s_nop 1
	v_add_f32_dpp v2, v2, v2 quad_perm:[1,0,3,2] row_mask:0xf bank_mask:0xf bound_ctrl:1
	s_nop 1
	v_add_f32_dpp v2, v2, v2 quad_perm:[2,3,0,1] row_mask:0xf bank_mask:0xf bound_ctrl:1
	s_nop 1
	v_add_f32_dpp v2, v2, v2 row_ror:4 row_mask:0xf bank_mask:0xf bound_ctrl:1
	s_nop 1
	v_mov_b32_dpp v3, v2 row_ror:8 row_mask:0xf bank_mask:0xf bound_ctrl:1
	s_and_saveexec_b64 s[0:1], s[6:7]
	v_add_f32_e32 v2, v2, v3
	v_add_f32_e32 v2, v57, v2
	ds_write_b32 v99, v2 offset:432
	s_or_b64 exec, exec, s[0:1]
	v_lshlrev_b64 v[2:3], 6, v[42:43]
	v_lshl_add_u64 v[34:35], v[2:3], 2, v[90:91]
	v_add_co_u32_e32 v2, vcc, 0x1000, v34
	s_waitcnt vmcnt(3)
	v_mul_f32_e32 v26, v39, v56
	v_addc_co_u32_e32 v3, vcc, 0, v35, vcc
	v_add_co_u32_e32 v6, vcc, 0x3000, v34
	global_load_dwordx4 v[14:17], v[34:35], off
	s_nop 0
	global_load_dwordx4 v[2:5], v[2:3], off offset:2048
	v_addc_co_u32_e32 v7, vcc, 0, v35, vcc
	v_add_co_u32_e32 v10, vcc, s49, v34
	v_fmac_f32_e32 v26, v38, v54
	s_nop 0
	v_addc_co_u32_e32 v11, vcc, 0, v35, vcc
	global_load_dwordx4 v[6:9], v[6:7], off
	s_nop 0
	global_load_dwordx4 v[10:13], v[10:11], off offset:2048
	v_fmac_f32_e32 v26, v40, v55
	v_fmac_f32_e32 v26, v41, v53
	s_nop 1
	v_add_f32_dpp v26, v26, v26 quad_perm:[1,0,3,2] row_mask:0xf bank_mask:0xf bound_ctrl:1
	s_nop 1
	v_add_f32_dpp v26, v26, v26 quad_perm:[2,3,0,1] row_mask:0xf bank_mask:0xf bound_ctrl:1
	s_nop 1
	v_add_f32_dpp v26, v26, v26 row_ror:4 row_mask:0xf bank_mask:0xf bound_ctrl:1
	s_nop 1
	v_mov_b32_dpp v27, v26 row_ror:8 row_mask:0xf bank_mask:0xf bound_ctrl:1
	s_and_saveexec_b64 s[0:1], s[6:7]
	v_add_f32_e32 v26, v26, v27
	v_add_f32_e32 v26, v57, v26
	ds_write_b32 v99, v26 offset:448
	s_or_b64 exec, exec, s[0:1]
	s_waitcnt vmcnt(6)
	v_mul_f32_e32 v26, v31, v56
	v_fmac_f32_e32 v26, v30, v54
	v_fmac_f32_e32 v26, v32, v55
	v_fmac_f32_e32 v26, v33, v53
	s_nop 1
	v_add_f32_dpp v26, v26, v26 quad_perm:[1,0,3,2] row_mask:0xf bank_mask:0xf bound_ctrl:1
	s_nop 1
	v_add_f32_dpp v26, v26, v26 quad_perm:[2,3,0,1] row_mask:0xf bank_mask:0xf bound_ctrl:1
	s_nop 1
	v_add_f32_dpp v26, v26, v26 row_ror:4 row_mask:0xf bank_mask:0xf bound_ctrl:1
	s_nop 1
	v_mov_b32_dpp v27, v26 row_ror:8 row_mask:0xf bank_mask:0xf bound_ctrl:1
	s_and_saveexec_b64 s[0:1], s[6:7]
	v_add_f32_e32 v26, v26, v27
	v_add_f32_e32 v26, v57, v26
	ds_write_b32 v99, v26 offset:464
	s_or_b64 exec, exec, s[0:1]
	s_waitcnt vmcnt(5)
	v_mul_f32_e32 v23, v23, v56
	v_fmac_f32_e32 v23, v22, v54
	v_fmac_f32_e32 v23, v24, v55
	v_fmac_f32_e32 v23, v25, v53
	s_nop 1
	v_add_f32_dpp v22, v23, v23 quad_perm:[1,0,3,2] row_mask:0xf bank_mask:0xf bound_ctrl:1
	s_nop 1
	v_add_f32_dpp v22, v22, v22 quad_perm:[2,3,0,1] row_mask:0xf bank_mask:0xf bound_ctrl:1
	s_nop 1
	v_add_f32_dpp v22, v22, v22 row_ror:4 row_mask:0xf bank_mask:0xf bound_ctrl:1
	s_nop 1
	v_mov_b32_dpp v23, v22 row_ror:8 row_mask:0xf bank_mask:0xf bound_ctrl:1
	s_and_saveexec_b64 s[0:1], s[6:7]
	v_add_f32_e32 v22, v22, v23
	v_add_f32_e32 v22, v57, v22
	ds_write_b32 v99, v22 offset:480
	s_or_b64 exec, exec, s[0:1]
	s_waitcnt vmcnt(4)
	v_mul_f32_e32 v19, v19, v56
	v_fmac_f32_e32 v19, v18, v54
	v_fmac_f32_e32 v19, v20, v55
	v_fmac_f32_e32 v19, v21, v53
	s_nop 1
	v_add_f32_dpp v18, v19, v19 quad_perm:[1,0,3,2] row_mask:0xf bank_mask:0xf bound_ctrl:1
	s_nop 1
	v_add_f32_dpp v18, v18, v18 quad_perm:[2,3,0,1] row_mask:0xf bank_mask:0xf bound_ctrl:1
	s_nop 1
	v_add_f32_dpp v18, v18, v18 row_ror:4 row_mask:0xf bank_mask:0xf bound_ctrl:1
	s_nop 1
	v_mov_b32_dpp v19, v18 row_ror:8 row_mask:0xf bank_mask:0xf bound_ctrl:1
	s_and_saveexec_b64 s[0:1], s[6:7]
	v_add_f32_e32 v18, v18, v19
	v_add_f32_e32 v18, v57, v18
	ds_write_b32 v99, v18 offset:496
	s_or_b64 exec, exec, s[0:1]
	s_waitcnt lgkmcnt(0)
	ds_read_b64 v[18:19], v100
	s_waitcnt lgkmcnt(0)
; __device__ __forceinline__ float softplus2_(float z2) { return fmaxf(z2, 0.f) + log1pf(exp2f(-fabsf(z2))) * LOG2E; }
; template <int NB>
; __device__ __forceinline__ void sb_decode_task(const Params& P, float* lds, int task) {
;     ...
;     const float sp0 = softplus2_(z0), sp1 = softplus2_(z1);
;     float incl = sp0 + sp1;
	v_cmp_gt_f32_e64 vcc, |v18|, s97
	s_nop 1
	v_cndmask_b32_e32 v21, 0, v103, vcc
	v_sub_f32_e64 v21, v21, |v18|
	v_exp_f32_e32 v21, v21
	v_max_f32_e32 v20, v18, v18
	v_max_f32_e32 v22, 0, v20
	v_cndmask_b32_e32 v20, 0, v102, vcc
	v_ldexp_f32 v23, v21, v20
	v_add_f32_e32 v24, 1.0, v23
	v_add_f32_e32 v20, -1.0, v24
	v_sub_f32_e32 v21, v20, v24
	v_add_f32_e32 v21, 1.0, v21
	v_sub_f32_e32 v20, v23, v20
	v_add_f32_e32 v25, v20, v21
	v_frexp_mant_f32_e32 v20, v24
	v_cmp_gt_f32_e32 vcc, s47, v20
	v_cvt_f64_f32_e32 v[20:21], v24
	v_frexp_exp_i32_f64_e32 v20, v[20:21]
	v_subbrev_co_u32_e32 v20, vcc, 0, v20, vcc
	v_sub_u32_e32 v21, 0, v20
	v_ldexp_f32 v24, v24, v21
	v_ldexp_f32 v21, v25, v21
	v_add_f32_e32 v25, -1.0, v24
	v_add_f32_e32 v26, 1.0, v25
	v_sub_f32_e32 v26, v24, v26
	v_add_f32_e32 v26, v21, v26
	v_add_f32_e32 v27, v25, v26
	v_sub_f32_e32 v25, v25, v27
	v_add_f32_e32 v25, v26, v25
	v_add_f32_e32 v26, 1.0, v24
	v_add_f32_e32 v28, -1.0, v26
	v_sub_f32_e32 v24, v24, v28
	v_add_f32_e32 v21, v21, v24
	v_add_f32_e32 v24, v26, v21
	v_sub_f32_e32 v26, v26, v24
	v_add_f32_e32 v21, v21, v26
	v_rcp_f32_e32 v26, v24
	v_cvt_f32_i32_e32 v20, v20
	v_cmp_neq_f32_e32 vcc, s46, v23
	v_mul_f32_e32 v28, v27, v26
	v_mul_f32_e32 v29, v24, v28
	v_fma_f32 v30, v28, v24, -v29
	v_fmac_f32_e32 v30, v28, v21
	v_add_f32_e32 v31, v29, v30
	v_sub_f32_e32 v32, v27, v31
	v_sub_f32_e32 v27, v27, v32
	v_sub_f32_e32 v29, v31, v29
	v_sub_f32_e32 v27, v27, v31
	v_add_f32_e32 v25, v25, v27
	v_sub_f32_e32 v27, v29, v30
	v_add_f32_e32 v25, v27, v25
	v_add_f32_e32 v27, v32, v25
	v_mul_f32_e32 v29, v26, v27
	v_mul_f32_e32 v30, v24, v29
	v_fma_f32 v24, v29, v24, -v30
	v_fmac_f32_e32 v24, v29, v21
	v_sub_f32_e32 v21, v32, v27
	v_add_f32_e32 v21, v25, v21
	v_add_f32_e32 v25, v30, v24
	v_sub_f32_e32 v31, v27, v25
	v_sub_f32_e32 v27, v27, v31
	v_sub_f32_e32 v30, v25, v30
	v_sub_f32_e32 v25, v27, v25
	v_add_f32_e32 v21, v21, v25
	v_sub_f32_e32 v24, v30, v24
	v_add_f32_e32 v21, v24, v21
	v_add_f32_e32 v24, v28, v29
	v_add_f32_e32 v21, v31, v21
	v_sub_f32_e32 v25, v24, v28
	v_mul_f32_e32 v21, v26, v21
	v_sub_f32_e32 v25, v29, v25
	v_add_f32_e32 v21, v25, v21
	v_mul_f32_e32 v28, 0x3f317218, v20
	v_add_f32_e32 v25, v24, v21
	v_fma_f32 v29, v20, s95, -v28
	v_mul_f32_e32 v26, v25, v25
	v_fmac_f32_e32 v29, 0xb102e308, v20
	v_sub_f32_e32 v20, v25, v24
	v_fmamk_f32 v27, v26, 0x3e9b6dac, v1
	v_sub_f32_e32 v20, v21, v20
	v_add_f32_e32 v21, v28, v29
	v_fmaak_f32 v27, v26, v27, 0x3f2aaada
	v_sub_f32_e32 v24, v21, v28
	v_ldexp_f32 v28, v25, 1
	v_mul_f32_e32 v25, v25, v26
	v_mul_f32_e32 v25, v25, v27
	v_add_f32_e32 v26, v28, v25
	v_sub_f32_e32 v27, v26, v28
	v_ldexp_f32 v20, v20, 1
	v_sub_f32_e32 v25, v25, v27
	v_add_f32_e32 v20, v20, v25
	v_add_f32_e32 v25, v26, v20
	v_sub_f32_e32 v26, v25, v26
	v_sub_f32_e32 v20, v20, v26
	v_add_f32_e32 v26, v21, v25
	v_sub_f32_e32 v27, v26, v21
	v_sub_f32_e32 v28, v26, v27
	v_sub_f32_e32 v24, v29, v24
	v_sub_f32_e32 v21, v21, v28
	v_sub_f32_e32 v25, v25, v27
	v_add_f32_e32 v21, v25, v21
	v_add_f32_e32 v25, v24, v20
	v_sub_f32_e32 v27, v25, v24
	v_sub_f32_e32 v28, v25, v27
	v_sub_f32_e32 v24, v24, v28
	v_sub_f32_e32 v20, v20, v27
	v_add_f32_e32 v21, v25, v21
	v_add_f32_e32 v20, v20, v24
	v_add_f32_e32 v24, v26, v21
	v_sub_f32_e32 v25, v24, v26
	v_sub_f32_e32 v21, v21, v25
	v_add_f32_e32 v20, v20, v21
	v_add_f32_e32 v20, v24, v20
	v_cndmask_b32_e32 v20, v104, v20, vcc
	v_cmp_lt_f32_e64 vcc, |v23|, s45
	s_nop 1
	v_cndmask_b32_e32 v20, v20, v23, vcc
	v_cmp_gt_f32_e64 vcc, |v19|, s97
	v_fmac_f32_e32 v22, 0x3fb8aa3b, v20
	v_max_f32_e32 v20, v19, v19
	v_cndmask_b32_e32 v21, 0, v103, vcc
	v_sub_f32_e64 v21, v21, |v19|
	v_exp_f32_e32 v21, v21
	v_max_f32_e32 v23, 0, v20
	v_cndmask_b32_e32 v20, 0, v102, vcc
	v_sub_f32_e32 v18, v18, v22
	v_ldexp_f32 v24, v21, v20
	v_add_f32_e32 v25, 1.0, v24
	v_add_f32_e32 v20, -1.0, v25
	v_sub_f32_e32 v21, v20, v25
	v_add_f32_e32 v21, 1.0, v21
	v_sub_f32_e32 v20, v24, v20
	v_add_f32_e32 v26, v20, v21
	v_frexp_mant_f32_e32 v20, v25
	v_cmp_gt_f32_e32 vcc, s47, v20
	v_cvt_f64_f32_e32 v[20:21], v25
	v_frexp_exp_i32_f64_e32 v20, v[20:21]
	v_subbrev_co_u32_e32 v20, vcc, 0, v20, vcc
	v_sub_u32_e32 v21, 0, v20
	v_ldexp_f32 v25, v25, v21
	v_ldexp_f32 v21, v26, v21
	v_add_f32_e32 v26, -1.0, v25
	v_add_f32_e32 v27, 1.0, v26
	v_sub_f32_e32 v27, v25, v27
	v_add_f32_e32 v27, v21, v27
	v_add_f32_e32 v28, v26, v27
	v_sub_f32_e32 v26, v26, v28
	v_add_f32_e32 v26, v27, v26
	v_add_f32_e32 v27, 1.0, v25
	v_add_f32_e32 v29, -1.0, v27
	v_sub_f32_e32 v25, v25, v29
	v_add_f32_e32 v21, v21, v25
	v_add_f32_e32 v25, v27, v21
	v_sub_f32_e32 v27, v27, v25
	v_add_f32_e32 v21, v21, v27
	v_rcp_f32_e32 v27, v25
	v_cvt_f32_i32_e32 v20, v20
	v_cmp_neq_f32_e32 vcc, s46, v24
	v_mul_f32_e32 v29, v28, v27
	v_mul_f32_e32 v30, v25, v29
	v_fma_f32 v31, v29, v25, -v30
	v_fmac_f32_e32 v31, v29, v21
	v_add_f32_e32 v32, v30, v31
	v_sub_f32_e32 v33, v28, v32
	v_sub_f32_e32 v28, v28, v33
	v_sub_f32_e32 v30, v32, v30
	v_sub_f32_e32 v28, v28, v32
	v_add_f32_e32 v26, v26, v28
	v_sub_f32_e32 v28, v30, v31
	v_add_f32_e32 v26, v28, v26
	v_add_f32_e32 v28, v33, v26
	v_mul_f32_e32 v30, v27, v28
	v_mul_f32_e32 v31, v25, v30
	v_fma_f32 v25, v30, v25, -v31
	v_fmac_f32_e32 v25, v30, v21
	v_sub_f32_e32 v21, v33, v28
	v_add_f32_e32 v21, v26, v21
	v_add_f32_e32 v26, v31, v25
	v_sub_f32_e32 v32, v28, v26
	v_sub_f32_e32 v28, v28, v32
	v_sub_f32_e32 v31, v26, v31
	v_sub_f32_e32 v26, v28, v26
	v_add_f32_e32 v21, v21, v26
	v_sub_f32_e32 v25, v31, v25
	v_add_f32_e32 v21, v25, v21
	v_add_f32_e32 v25, v29, v30
	v_add_f32_e32 v21, v32, v21
	v_sub_f32_e32 v26, v25, v29
	v_mul_f32_e32 v21, v27, v21
; __device__ __forceinline__ float softplus2_(float z2) { return fmaxf(z2, 0.f) + log1pf(exp2f(-fabsf(z2))) * LOG2E; }
; template <int NB>
; __device__ __forceinline__ void sb_decode_task(const Params& P, float* lds, int task) {
;     ...
;     const float sp0 = softplus2_(z0), sp1 = softplus2_(z1);
;     float incl = sp0 + sp1;
; #pragma unroll
;     for (int off = 1; off < 64; off <<= 1) { const float t = __shfl_down(incl, off); if (lane + off < 64) incl += t; }
;     const float excl = incl - (sp0 + sp1);
;     wl[2 * lane] = exp2f(z0 - sp0 - (excl + sp1));
;     wl[2 * lane + 1] = exp2f(z1 - sp1 - excl);
;     const float Ltot = __shfl(incl, 0);
;     asm volatile("s_waitcnt lgkmcnt(0)" ::: "memory");
;     __builtin_amdgcn_wave_barrier();
;     float4 o4 = make_float4(0.f, 0.f, 0.f, 0.f);
; #pragma unroll
;     for (int vb = 0; vb < NBT; ++vb) {
;         if (vb + 1 < NBT) {
; #pragma unroll
;             for (int i = 0; i < NB; ++i) nx[i] = *(const float4*)(Vp + (size_t)(4 * NB * (vb + 1) + 4 * i + g) * (SH * HD)); }
; #pragma unroll
;         for (int i = 0; i < NB; ++i) { const float w = wl[4 * NB * vb + 4 * i + g]; o4.x += w * cur[i].x; o4.y += w * cur[i].y; o4.z += w * cur[i].z; o4.w += w * cur[i].w; }
	v_sub_f32_e32 v26, v30, v26
	v_add_f32_e32 v21, v26, v21
	v_mul_f32_e32 v29, 0x3f317218, v20
	v_add_f32_e32 v26, v25, v21
	v_fma_f32 v30, v20, s95, -v29
	v_mul_f32_e32 v27, v26, v26
	v_fmac_f32_e32 v30, 0xb102e308, v20
	v_sub_f32_e32 v20, v26, v25
	v_fmamk_f32 v28, v27, 0x3e9b6dac, v1
	v_sub_f32_e32 v20, v21, v20
	v_add_f32_e32 v21, v29, v30
	v_fmaak_f32 v28, v27, v28, 0x3f2aaada
	v_sub_f32_e32 v25, v21, v29
	v_ldexp_f32 v29, v26, 1
	v_mul_f32_e32 v26, v26, v27
	v_mul_f32_e32 v26, v26, v28
	v_add_f32_e32 v27, v29, v26
	v_sub_f32_e32 v28, v27, v29
	v_ldexp_f32 v20, v20, 1
	v_sub_f32_e32 v26, v26, v28
	v_add_f32_e32 v20, v20, v26
	v_add_f32_e32 v26, v27, v20
	v_sub_f32_e32 v27, v26, v27
	v_sub_f32_e32 v20, v20, v27
	v_add_f32_e32 v27, v21, v26
	v_sub_f32_e32 v28, v27, v21
	v_sub_f32_e32 v29, v27, v28
	v_sub_f32_e32 v25, v30, v25
	v_sub_f32_e32 v21, v21, v29
	v_sub_f32_e32 v26, v26, v28
	v_add_f32_e32 v21, v26, v21
	v_add_f32_e32 v26, v25, v20
	v_sub_f32_e32 v28, v26, v25
	v_sub_f32_e32 v29, v26, v28
	v_sub_f32_e32 v25, v25, v29
	v_sub_f32_e32 v20, v20, v28
	v_add_f32_e32 v21, v26, v21
	v_add_f32_e32 v20, v20, v25
	v_add_f32_e32 v25, v27, v21
	v_sub_f32_e32 v26, v25, v27
	v_sub_f32_e32 v21, v21, v26
	v_add_f32_e32 v20, v20, v21
	v_add_f32_e32 v20, v25, v20
	v_cndmask_b32_e32 v20, v104, v20, vcc
	v_cmp_lt_f32_e64 vcc, |v24|, s45
	s_nop 1
	v_cndmask_b32_e32 v20, v20, v24, vcc
	v_fmac_f32_e32 v23, 0x3fb8aa3b, v20
	v_add_f32_e32 v20, v22, v23
	ds_bpermute_b32 v21, v46, v20
	v_sub_f32_e32 v19, v19, v23
	s_waitcnt lgkmcnt(0)
	v_add_f32_e32 v21, v20, v21
	v_cndmask_b32_e64 v21, v21, v20, s[8:9]
	ds_bpermute_b32 v24, v47, v21
	s_waitcnt lgkmcnt(0)
	v_add_f32_e32 v24, v21, v24
	v_cndmask_b32_e64 v21, v21, v24, s[10:11]
	ds_bpermute_b32 v24, v48, v21
	s_waitcnt lgkmcnt(0)
	v_add_f32_e32 v24, v21, v24
	v_cndmask_b32_e64 v21, v21, v24, s[12:13]
	ds_bpermute_b32 v24, v49, v21
	s_waitcnt lgkmcnt(0)
	v_add_f32_e32 v24, v21, v24
	v_cndmask_b32_e64 v21, v21, v24, s[14:15]
	ds_bpermute_b32 v24, v50, v21
	s_waitcnt lgkmcnt(0)
	v_add_f32_e32 v24, v21, v24
	v_cndmask_b32_e64 v21, v21, v24, s[16:17]
	ds_bpermute_b32 v24, v51, v21
	s_waitcnt lgkmcnt(0)
	v_add_f32_e32 v24, v21, v24
	v_cndmask_b32_e64 v31, v21, v24, s[18:19]
	v_sub_f32_e32 v20, v31, v20
	v_add_f32_e32 v21, v23, v20
	v_sub_f32_e32 v18, v18, v21
	v_cmp_gt_f32_e32 vcc, s24, v18
	v_sub_f32_e32 v19, v19, v20
	s_nop 0
	v_cndmask_b32_e32 v21, 0, v103, vcc
	v_add_f32_e32 v18, v18, v21
	v_cndmask_b32_e32 v21, 0, v102, vcc
	v_cmp_gt_f32_e32 vcc, s24, v19
	v_exp_f32_e32 v18, v18
	s_nop 0
	v_cndmask_b32_e32 v20, 0, v103, vcc
	v_add_f32_e32 v19, v19, v20
	v_exp_f32_e32 v19, v19
	v_cndmask_b32_e32 v20, 0, v102, vcc
	v_ldexp_f32 v18, v18, v21
	v_ldexp_f32 v19, v19, v20
	ds_write_b64 v100, v[18:19] offset:512
	s_waitcnt lgkmcnt(0)
	ds_read2_b32 v[18:19], v99 offset0:128 offset1:132
	ds_read2_b32 v[32:33], v99 offset0:136 offset1:140
	ds_read2_b32 v[58:59], v99 offset0:144 offset1:148
	ds_read2_b32 v[60:61], v99 offset0:152 offset1:156
	ds_read2_b32 v[62:63], v99 offset0:160 offset1:164
	ds_read2_b32 v[64:65], v99 offset0:168 offset1:172
	s_waitcnt vmcnt(3) lgkmcnt(5)
	v_pk_fma_f32 v[36:37], v[14:15], v[18:19], 0 op_sel_hi:[1,0,0]
	v_add_co_u32_e32 v14, vcc, s89, v34
	v_pk_fma_f32 v[50:51], v[16:17], v[18:19], 0 op_sel_hi:[1,0,0]
	s_nop 0
	v_addc_co_u32_e32 v15, vcc, 0, v35, vcc
	v_add_co_u32_e32 v18, vcc, s92, v34
	v_mov_b32_e32 v30, v19
	s_nop 0
	v_addc_co_u32_e32 v19, vcc, 0, v35, vcc
	v_add_co_u32_e32 v22, vcc, s93, v34
	s_waitcnt vmcnt(2)
	v_pk_fma_f32 v[2:3], v[2:3], v[30:31], v[36:37] op_sel_hi:[1,0,1]
	v_addc_co_u32_e32 v23, vcc, 0, v35, vcc
	v_add_co_u32_e32 v26, vcc, s96, v34
	s_waitcnt vmcnt(1) lgkmcnt(4)
	v_pk_fma_f32 v[2:3], v[6:7], v[32:33], v[2:3] op_sel_hi:[1,0,1]
	v_addc_co_u32_e32 v27, vcc, 0, v35, vcc
	v_add_co_u32_e32 v6, vcc, s44, v34
	global_load_dwordx4 v[14:17], v[14:15], off
	s_nop 0
	v_addc_co_u32_e32 v7, vcc, 0, v35, vcc
	global_load_dwordx4 v[18:21], v[18:19], off offset:2048
	v_mov_b32_e32 v66, v33
	global_load_dwordx4 v[36:39], v[6:7], off
	v_add_co_u32_e32 v6, vcc, s26, v34
	global_load_dwordx4 v[22:25], v[22:23], off
	s_nop 0
	v_addc_co_u32_e32 v7, vcc, 0, v35, vcc
	global_load_dwordx4 v[26:29], v[26:27], off offset:2048
	s_waitcnt vmcnt(5)
	v_pk_fma_f32 v[2:3], v[10:11], v[66:67], v[2:3] op_sel_hi:[1,0,1]
	global_load_dwordx4 v[40:43], v[6:7], off offset:2048
	v_add_co_u32_e32 v6, vcc, s27, v34
	s_waitcnt lgkmcnt(2)
	v_mov_b32_e32 v10, v61
	v_addc_co_u32_e32 v7, vcc, 0, v35, vcc
	global_load_dwordx4 v[46:49], v[6:7], off
	v_add_co_u32_e32 v6, vcc, s28, v34
	s_waitcnt vmcnt(6)
	v_pk_fma_f32 v[2:3], v[14:15], v[58:59], v[2:3] op_sel_hi:[1,0,1]
	v_addc_co_u32_e32 v7, vcc, 0, v35, vcc
	global_load_dwordx4 v[54:57], v[6:7], off offset:2048
	v_mov_b32_e32 v6, v59
	s_waitcnt vmcnt(6)
	v_pk_fma_f32 v[2:3], v[18:19], v[6:7], v[2:3] op_sel_hi:[1,0,1]
	s_waitcnt lgkmcnt(1)
	v_mov_b32_e32 v14, v63
	s_waitcnt lgkmcnt(0)
	v_mov_b32_e32 v18, v65
	s_waitcnt vmcnt(4)
	v_pk_fma_f32 v[2:3], v[22:23], v[60:61], v[2:3] op_sel_hi:[1,0,1]
	s_waitcnt vmcnt(3)
	v_pk_fma_f32 v[2:3], v[26:27], v[10:11], v[2:3] op_sel_hi:[1,0,1]
	s_nop 0
	v_pk_fma_f32 v[2:3], v[36:37], v[62:63], v[2:3] op_sel_hi:[1,0,1]
	s_waitcnt vmcnt(2)
	v_pk_fma_f32 v[2:3], v[40:41], v[14:15], v[2:3] op_sel_hi:[1,0,1]
	s_waitcnt vmcnt(1)
	v_pk_fma_f32 v[2:3], v[46:47], v[64:65], v[2:3] op_sel_hi:[1,0,1]
	s_waitcnt vmcnt(0)
	v_pk_fma_f32 v[54:55], v[54:55], v[18:19], v[2:3] op_sel_hi:[1,0,1]
	v_pk_fma_f32 v[2:3], v[4:5], v[30:31], v[50:51] op_sel_hi:[1,0,1]
	s_nop 0
	v_pk_fma_f32 v[2:3], v[8:9], v[32:33], v[2:3] op_sel_hi:[1,0,1]
	ds_read2_b32 v[8:9], v99 offset0:176 offset1:180
	v_pk_fma_f32 v[2:3], v[12:13], v[66:67], v[2:3] op_sel_hi:[1,0,1]
	s_waitcnt lgkmcnt(0)
; template <int NB>
; __device__ __forceinline__ void sb_decode_task(const Params& P, float* lds, int task) {
;     ...
;     for (int vb = 0; vb < NBT; ++vb) {
;         if (vb + 1 < NBT) {
; #pragma unroll
;             for (int i = 0; i < NB; ++i) nx[i] = *(const float4*)(Vp + (size_t)(4 * NB * (vb + 1) + 4 * i + g) * (SH * HD)); }
; #pragma unroll
;         for (int i = 0; i < NB; ++i) { const float w = wl[4 * NB * vb + 4 * i + g]; o4.x += w * cur[i].x; o4.y += w * cur[i].y; o4.z += w * cur[i].z; o4.w += w * cur[i].w; }
; #pragma unroll
;         for (int i = 0; i < NB; ++i) cur[i] = nx[i];
;     }
	v_mov_b32_e32 v72, v9
	v_pk_fma_f32 v[2:3], v[16:17], v[58:59], v[2:3] op_sel_hi:[1,0,1]
	s_nop 0
	v_pk_fma_f32 v[2:3], v[20:21], v[6:7], v[2:3] op_sel_hi:[1,0,1]
	s_nop 0
	v_pk_fma_f32 v[2:3], v[24:25], v[60:61], v[2:3] op_sel_hi:[1,0,1]
	s_nop 0
	v_pk_fma_f32 v[2:3], v[28:29], v[10:11], v[2:3] op_sel_hi:[1,0,1]
	s_nop 0
	v_pk_fma_f32 v[2:3], v[38:39], v[62:63], v[2:3] op_sel_hi:[1,0,1]
	s_nop 0
	v_pk_fma_f32 v[2:3], v[42:43], v[14:15], v[2:3] op_sel_hi:[1,0,1]
	s_nop 0
	v_pk_fma_f32 v[2:3], v[48:49], v[64:65], v[2:3] op_sel_hi:[1,0,1]
	s_nop 0
	v_pk_fma_f32 v[6:7], v[56:57], v[18:19], v[2:3] op_sel_hi:[1,0,1]
	v_add_co_u32_e32 v2, vcc, s25, v34
	s_nop 1
	v_addc_co_u32_e32 v3, vcc, 0, v35, vcc
	global_load_dwordx4 v[10:13], v[2:3], off
	v_add_co_u32_e32 v2, vcc, s43, v34
	s_waitcnt vmcnt(0)
	v_pk_fma_f32 v[10:11], v[10:11], v[8:9], v[54:55] op_sel_hi:[1,0,1]
	v_addc_co_u32_e32 v3, vcc, 0, v35, vcc
	global_load_dwordx4 v[14:17], v[2:3], off offset:2048
	v_add_co_u32_e32 v2, vcc, s80, v34
	ds_read2_b32 v[32:33], v99 offset0:184 offset1:188
	ds_read2_b32 v[50:51], v99 offset0:192 offset1:196
	ds_read2_b32 v[66:67], v99 offset0:200 offset1:204
	ds_read2_b32 v[68:69], v99 offset0:208 offset1:212
	ds_read2_b32 v[70:71], v99 offset0:216 offset1:220
	v_addc_co_u32_e32 v3, vcc, 0, v35, vcc
	v_add_co_u32_e32 v18, vcc, s29, v34
	global_load_dwordx4 v[2:5], v[2:3], off offset:2048
	s_nop 0
	v_addc_co_u32_e32 v19, vcc, 0, v35, vcc
	v_add_co_u32_e32 v22, vcc, s68, v34
	global_load_dwordx4 v[18:21], v[18:19], off
	s_nop 0
	v_addc_co_u32_e32 v23, vcc, 0, v35, vcc
	v_add_co_u32_e32 v26, vcc, s69, v34
	global_load_dwordx4 v[22:25], v[22:23], off offset:2048
	s_nop 0
	v_addc_co_u32_e32 v27, vcc, 0, v35, vcc
	v_add_co_u32_e32 v36, vcc, s70, v34
	global_load_dwordx4 v[26:29], v[26:27], off
	s_nop 0
	v_addc_co_u32_e32 v37, vcc, 0, v35, vcc
	v_add_co_u32_e32 v40, vcc, s71, v34
	global_load_dwordx4 v[36:39], v[36:37], off offset:2048
	s_nop 0
	v_addc_co_u32_e32 v41, vcc, 0, v35, vcc
	v_add_co_u32_e32 v46, vcc, s72, v34
	global_load_dwordx4 v[40:43], v[40:41], off
	s_nop 0
	v_addc_co_u32_e32 v47, vcc, 0, v35, vcc
	global_load_dwordx4 v[46:49], v[46:47], off offset:2048
	v_pk_fma_f32 v[6:7], v[12:13], v[8:9], v[6:7] op_sel_hi:[1,0,1]
	s_waitcnt lgkmcnt(4)
	v_mov_b32_e32 v74, v33
	s_waitcnt lgkmcnt(0)
	v_mov_b32_e32 v30, v71
	s_waitcnt vmcnt(7)
	v_pk_fma_f32 v[10:11], v[14:15], v[72:73], v[10:11] op_sel_hi:[1,0,1]
	v_add_co_u32_e32 v14, vcc, s73, v34
	v_pk_fma_f32 v[6:7], v[16:17], v[72:73], v[6:7] op_sel_hi:[1,0,1]
	s_nop 0
	v_addc_co_u32_e32 v15, vcc, 0, v35, vcc
	global_load_dwordx4 v[54:57], v[14:15], off
	v_add_co_u32_e32 v14, vcc, s74, v34
	s_nop 1
	v_addc_co_u32_e32 v15, vcc, 0, v35, vcc
	global_load_dwordx4 v[58:61], v[14:15], off offset:2048
	v_add_co_u32_e32 v14, vcc, s75, v34
	s_nop 1
	v_addc_co_u32_e32 v15, vcc, 0, v35, vcc
	global_load_dwordx4 v[62:65], v[14:15], off
	s_waitcnt vmcnt(8)
	v_pk_fma_f32 v[6:7], v[20:21], v[32:33], v[6:7] op_sel_hi:[1,0,1]
	v_pk_fma_f32 v[10:11], v[18:19], v[32:33], v[10:11] op_sel_hi:[1,0,1]
	s_waitcnt vmcnt(7)
	v_pk_fma_f32 v[6:7], v[24:25], v[74:75], v[6:7] op_sel_hi:[1,0,1]
	v_mov_b32_e32 v14, v51
	s_waitcnt vmcnt(6)
	v_pk_fma_f32 v[6:7], v[28:29], v[50:51], v[6:7] op_sel_hi:[1,0,1]
	v_pk_fma_f32 v[10:11], v[22:23], v[74:75], v[10:11] op_sel_hi:[1,0,1]
	v_mov_b32_e32 v18, v67
	v_pk_fma_f32 v[10:11], v[26:27], v[50:51], v[10:11] op_sel_hi:[1,0,1]
	v_mov_b32_e32 v22, v69
	s_waitcnt vmcnt(5)
	v_pk_fma_f32 v[6:7], v[38:39], v[14:15], v[6:7] op_sel_hi:[1,0,1]
	v_pk_fma_f32 v[10:11], v[36:37], v[14:15], v[10:11] op_sel_hi:[1,0,1]
	ds_read2_b32 v[38:39], v99 offset0:224 offset1:228
	ds_read2_b32 v[32:33], v99 offset0:232 offset1:236
	s_waitcnt vmcnt(4)
	v_pk_fma_f32 v[6:7], v[42:43], v[66:67], v[6:7] op_sel_hi:[1,0,1]
	v_pk_fma_f32 v[10:11], v[40:41], v[66:67], v[10:11] op_sel_hi:[1,0,1]
	s_waitcnt vmcnt(3)
; template <int NB>
; __device__ __forceinline__ void sb_decode_task(const Params& P, float* lds, int task) {
;     ...
;     for (int vb = 0; vb < NBT; ++vb) {
;         if (vb + 1 < NBT) {
; #pragma unroll
;             for (int i = 0; i < NB; ++i) nx[i] = *(const float4*)(Vp + (size_t)(4 * NB * (vb + 1) + 4 * i + g) * (SH * HD)); }
; #pragma unroll
;         for (int i = 0; i < NB; ++i) { const float w = wl[4 * NB * vb + 4 * i + g]; o4.x += w * cur[i].x; o4.y += w * cur[i].y; o4.z += w * cur[i].z; o4.w += w * cur[i].w; }
; #pragma unroll
;         for (int i = 0; i < NB; ++i) cur[i] = nx[i];
;     }
; #pragma unroll
;     for (int off = 16; off < 64; off <<= 1) { o4.x += __shfl_xor(o4.x, off); o4.y += __shfl_xor(o4.y, off); o4.z += __shfl_xor(o4.z, off); o4.w += __shfl_xor(o4.w, off); }
;     if (g == 0) *(float4*)(dpart + (size_t)task * HD + 4 * c) = o4;
;     if (lane == 0) dl[task] = Ltot;
	v_pk_fma_f32 v[6:7], v[48:49], v[18:19], v[6:7] op_sel_hi:[1,0,1]
	v_pk_fma_f32 v[10:11], v[46:47], v[18:19], v[10:11] op_sel_hi:[1,0,1]
	s_waitcnt vmcnt(2)
	v_pk_fma_f32 v[6:7], v[56:57], v[68:69], v[6:7] op_sel_hi:[1,0,1]
	v_pk_fma_f32 v[10:11], v[54:55], v[68:69], v[10:11] op_sel_hi:[1,0,1]
	s_waitcnt vmcnt(1)
	v_pk_fma_f32 v[6:7], v[60:61], v[22:23], v[6:7] op_sel_hi:[1,0,1]
	v_pk_fma_f32 v[10:11], v[58:59], v[22:23], v[10:11] op_sel_hi:[1,0,1]
	s_waitcnt vmcnt(0)
	v_pk_fma_f32 v[36:37], v[64:65], v[70:71], v[6:7] op_sel_hi:[1,0,1]
	v_add_co_u32_e32 v6, vcc, s81, v34
	v_pk_fma_f32 v[26:27], v[62:63], v[70:71], v[10:11] op_sel_hi:[1,0,1]
	s_nop 0
	v_addc_co_u32_e32 v7, vcc, 0, v35, vcc
	v_add_co_u32_e32 v10, vcc, s82, v34
	global_load_dwordx4 v[6:9], v[6:7], off
	s_nop 0
	v_addc_co_u32_e32 v11, vcc, 0, v35, vcc
	v_add_co_u32_e32 v14, vcc, s83, v34
	ds_read2_b32 v[42:43], v99 offset0:240 offset1:244
	ds_read2_b32 v[40:41], v99 offset0:248 offset1:252
	v_addc_co_u32_e32 v15, vcc, 0, v35, vcc
	v_add_co_u32_e32 v18, vcc, s84, v34
	global_load_dwordx4 v[10:13], v[10:11], off offset:2048
	s_nop 0
	v_addc_co_u32_e32 v19, vcc, 0, v35, vcc
	v_add_co_u32_e32 v22, vcc, s85, v34
	v_pk_fma_f32 v[2:3], v[2:3], v[30:31], v[26:27] op_sel_hi:[1,0,1]
	s_nop 0
	v_addc_co_u32_e32 v23, vcc, 0, v35, vcc
	v_add_co_u32_e32 v26, vcc, s86, v34
	global_load_dwordx4 v[14:17], v[14:15], off
	s_nop 0
	v_addc_co_u32_e32 v27, vcc, 0, v35, vcc
	global_load_dwordx4 v[18:21], v[18:19], off offset:2048
	v_add_co_u32_e32 v46, vcc, s87, v34
	global_load_dwordx4 v[22:25], v[22:23], off
	s_nop 0
	v_addc_co_u32_e32 v47, vcc, 0, v35, vcc
	global_load_dwordx4 v[26:29], v[26:27], off offset:2048
	v_add_co_u32_e32 v34, vcc, s88, v34
	global_load_dwordx4 v[46:49], v[46:47], off
	s_nop 0
	v_addc_co_u32_e32 v35, vcc, 0, v35, vcc
	global_load_dwordx4 v[54:57], v[34:35], off offset:2048
	v_pk_fma_f32 v[4:5], v[4:5], v[30:31], v[36:37] op_sel_hi:[1,0,1]
	s_waitcnt vmcnt(7) lgkmcnt(3)
	v_pk_fma_f32 v[2:3], v[6:7], v[38:39], v[2:3] op_sel_hi:[1,0,1]
	v_mov_b32_e32 v6, v39
	v_pk_fma_f32 v[4:5], v[8:9], v[38:39], v[4:5] op_sel_hi:[1,0,1]
	s_waitcnt vmcnt(6)
	v_pk_fma_f32 v[2:3], v[10:11], v[6:7], v[2:3] op_sel_hi:[1,0,1]
	v_pk_fma_f32 v[4:5], v[12:13], v[6:7], v[4:5] op_sel_hi:[1,0,1]
	s_waitcnt lgkmcnt(2)
	v_mov_b32_e32 v10, v33
	s_waitcnt vmcnt(5)
	v_pk_fma_f32 v[2:3], v[14:15], v[32:33], v[2:3] op_sel_hi:[1,0,1]
	v_pk_fma_f32 v[4:5], v[16:17], v[32:33], v[4:5] op_sel_hi:[1,0,1]
	s_waitcnt lgkmcnt(1)
	v_mov_b32_e32 v14, v43
	s_waitcnt vmcnt(4)
	v_pk_fma_f32 v[2:3], v[18:19], v[10:11], v[2:3] op_sel_hi:[1,0,1]
	v_pk_fma_f32 v[4:5], v[20:21], v[10:11], v[4:5] op_sel_hi:[1,0,1]
	s_waitcnt lgkmcnt(0)
	v_mov_b32_e32 v18, v41
	s_waitcnt vmcnt(3)
	v_pk_fma_f32 v[2:3], v[22:23], v[42:43], v[2:3] op_sel_hi:[1,0,1]
	v_pk_fma_f32 v[4:5], v[24:25], v[42:43], v[4:5] op_sel_hi:[1,0,1]
	ds_bpermute_b32 v10, v44, v31
	s_waitcnt vmcnt(2)
	v_pk_fma_f32 v[2:3], v[26:27], v[14:15], v[2:3] op_sel_hi:[1,0,1]
	v_pk_fma_f32 v[4:5], v[28:29], v[14:15], v[4:5] op_sel_hi:[1,0,1]
	s_waitcnt vmcnt(1)
	v_pk_fma_f32 v[2:3], v[46:47], v[40:41], v[2:3] op_sel_hi:[1,0,1]
	v_pk_fma_f32 v[4:5], v[48:49], v[40:41], v[4:5] op_sel_hi:[1,0,1]
	s_waitcnt vmcnt(0)
	v_pk_fma_f32 v[2:3], v[54:55], v[18:19], v[2:3] op_sel_hi:[1,0,1]
	v_pk_fma_f32 v[4:5], v[56:57], v[18:19], v[4:5] op_sel_hi:[1,0,1]
	ds_bpermute_b32 v22, v45, v2
	ds_bpermute_b32 v23, v45, v3
	ds_bpermute_b32 v6, v45, v4
	ds_bpermute_b32 v7, v45, v5
	s_waitcnt lgkmcnt(2)
	v_pk_add_f32 v[2:3], v[2:3], v[22:23]
	s_waitcnt lgkmcnt(0)
	v_pk_add_f32 v[4:5], v[4:5], v[6:7]
	ds_bpermute_b32 v6, v52, v2
	ds_bpermute_b32 v7, v52, v3
	ds_bpermute_b32 v8, v52, v4
	ds_bpermute_b32 v9, v52, v5
	s_and_saveexec_b64 s[0:1], s[20:21]
	s_cbranch_execz .LBB0_1553
	s_ashr_i32 s35, s34, 31
	s_lshl_b64 s[2:3], s[34:35], 8
	v_lshl_add_u64 v[12:13], v[88:89], 0, s[2:3]
	s_waitcnt lgkmcnt(2)
	v_pk_add_f32 v[2:3], v[2:3], v[6:7]
	s_waitcnt lgkmcnt(0)
	v_pk_add_f32 v[4:5], v[4:5], v[8:9]
	global_store_dwordx4 v[12:13], v[2:5], off
